# v39: + P6 epilogues on the tail row tile: waves 4-7 skip, waves 0-3 stop after the 64 valid rows
# speedup vs baseline: 1.1576x; 1.0073x over previous
.LBB0_3328:
	s_cmpk_lt_i32 s8, 0x4000
	s_cbranch_scc1 .Ltep_e2_f
	v_readfirstlane_b32 s64, v208
	s_bitcmp1_b32 s64, 8
	s_cbranch_scc0 .Ltep_e2_f
	s_waitcnt vmcnt(0)
	s_branch .Ltep_e2_e
.Ltep_e2_f:
	v_mov_b32_e32 v0, v208
	v_mov_b32_e32 v3, v1
	v_lshrrev_b32_e32 v4, 3, v0
	v_ashrrev_i32_e32 v2, 1, v0
	v_and_b32_e32 v4, 4, v4
	v_and_or_b32 v8, v2, s34, v4
	v_lshlrev_b32_e32 v4, 2, v8
	v_lshlrev_b32_e32 v2, 2, v3
	v_add3_u32 v2, v2, v4, s33
	ds_read2_b32 v[4:5], v2 offset1:1
	ds_read2_b32 v[6:7], v2 offset0:2 offset1:3
	v_and_b32_e32 v0, 0xdf, v0
	v_or_b32_e32 v0, s10, v0
	v_add_u32_e32 v3, v0, v3
	s_waitcnt lgkmcnt(1)
	v_mul_f32_e32 v4, v128, v4
	v_mul_f32_e32 v4, 0xbfb8aa3b, v4
	v_exp_f32_e32 v4, v4
	s_nop 0
	v_add_f32_e32 v0, 1.0, v4
	v_mul_f32_e32 v4, v129, v5
	v_rcp_f32_e32 v0, v0
	v_mul_f32_e32 v4, 0xbfb8aa3b, v4
	v_exp_f32_e32 v5, v4
	v_add_lshl_u32 v4, v8, s8, 10
	v_max_f32_e32 v0, 0x358637bd, v0
	v_cvt_pk_bf16_f32 v10, v0, s0
	v_add_f32_e32 v0, 1.0, v5
	v_rcp_f32_e32 v5, v0
	v_add_u32_e32 v0, v4, v3
	v_lshl_add_u64 v[8:9], v[0:1], 1, s[62:63]
	global_store_short v[8:9], v10, off
	v_max_f32_e32 v0, 0x358637bd, v5
	v_cvt_pk_bf16_f32 v5, v0, s0
	s_waitcnt lgkmcnt(0)
	v_mul_f32_e32 v0, v130, v6
	v_mul_f32_e32 v0, 0xbfb8aa3b, v0
	v_exp_f32_e32 v6, v0
	v_add_u32_e32 v10, 0x400, v4
	v_add_u32_e32 v0, v10, v3
	v_lshl_add_u64 v[8:9], v[0:1], 1, s[62:63]
	global_store_short v[8:9], v5, off
	v_add_f32_e32 v0, 1.0, v6
	v_mul_f32_e32 v5, v131, v7
	v_rcp_f32_e32 v0, v0
	v_mul_f32_e32 v5, 0xbfb8aa3b, v5
	v_exp_f32_e32 v5, v5
	v_add_u32_e32 v11, 0x800, v4
	v_max_f32_e32 v0, 0x358637bd, v0
	v_cvt_pk_bf16_f32 v8, v0, s0
	v_add_f32_e32 v0, 1.0, v5
	v_rcp_f32_e32 v5, v0
	v_add_u32_e32 v0, v11, v3
	v_lshl_add_u64 v[6:7], v[0:1], 1, s[62:63]
	v_add_u32_e32 v12, 0xc00, v4
	v_max_f32_e32 v0, 0x358637bd, v5
	v_cvt_pk_bf16_f32 v5, v0, s0
	v_add_u32_e32 v0, v12, v3
	global_store_short v[6:7], v8, off
	v_lshl_add_u64 v[6:7], v[0:1], 1, s[62:63]
	global_store_short v[6:7], v5, off
	ds_read2_b32 v[6:7], v2 offset0:8 offset1:9
	ds_read2_b32 v[8:9], v2 offset0:10 offset1:11
	v_add_u32_e32 v13, 0x2000, v4
	v_add_u32_e32 v15, 0x2800, v4
	v_add_u32_e32 v128, 0x2c00, v4
	s_waitcnt lgkmcnt(1)
	v_mul_f32_e32 v0, v132, v6
	v_mul_f32_e32 v0, 0xbfb8aa3b, v0
	v_exp_f32_e32 v0, v0
	v_mul_f32_e32 v5, v133, v7
	v_mul_f32_e32 v5, 0xbfb8aa3b, v5
	v_exp_f32_e32 v5, v5
	v_add_f32_e32 v0, 1.0, v0
	v_rcp_f32_e32 v14, v0
	v_add_u32_e32 v0, v13, v3
	v_lshl_add_u64 v[6:7], v[0:1], 1, s[62:63]
	v_add_f32_e32 v5, 1.0, v5
	v_max_f32_e32 v0, 0x358637bd, v14
	v_cvt_pk_bf16_f32 v0, v0, s0
	v_rcp_f32_e32 v5, v5
	global_store_short v[6:7], v0, off
	s_waitcnt lgkmcnt(0)
	v_mul_f32_e32 v0, v134, v8
	v_mul_f32_e32 v0, 0xbfb8aa3b, v0
	v_exp_f32_e32 v8, v0
	v_add_u32_e32 v14, 0x2400, v4
	v_max_f32_e32 v5, 0x358637bd, v5
	v_add_u32_e32 v0, v14, v3
	v_cvt_pk_bf16_f32 v5, v5, s0
	v_lshl_add_u64 v[6:7], v[0:1], 1, s[62:63]
	global_store_short v[6:7], v5, off
	v_add_f32_e32 v0, 1.0, v8
	v_mul_f32_e32 v5, v135, v9
	v_rcp_f32_e32 v0, v0
	v_mul_f32_e32 v5, 0xbfb8aa3b, v5
	v_exp_f32_e32 v5, v5
	v_max_f32_e32 v0, 0x358637bd, v0
	v_cvt_pk_bf16_f32 v8, v0, s0
	v_add_f32_e32 v0, 1.0, v5
	v_rcp_f32_e32 v5, v0
	v_add_u32_e32 v0, v15, v3
	v_lshl_add_u64 v[6:7], v[0:1], 1, s[62:63]
	global_store_short v[6:7], v8, off
	v_max_f32_e32 v0, 0x358637bd, v5
	v_cvt_pk_bf16_f32 v5, v0, s0
	v_add_u32_e32 v0, v128, v3
	v_lshl_add_u64 v[6:7], v[0:1], 1, s[62:63]
	global_store_short v[6:7], v5, off
	ds_read2_b32 v[6:7], v2 offset0:16 offset1:17
	ds_read2_b32 v[8:9], v2 offset0:18 offset1:19
	v_add_u32_e32 v129, 0x4000, v4
	v_add_u32_e32 v131, 0x4800, v4
	v_add_u32_e32 v132, 0x4c00, v4
	s_waitcnt lgkmcnt(1)
	v_mul_f32_e32 v0, v136, v6
	v_mul_f32_e32 v0, 0xbfb8aa3b, v0
	v_exp_f32_e32 v0, v0
	v_mul_f32_e32 v5, v137, v7
	v_mul_f32_e32 v5, 0xbfb8aa3b, v5
	v_exp_f32_e32 v5, v5
	v_add_f32_e32 v0, 1.0, v0
	v_rcp_f32_e32 v130, v0
	v_add_u32_e32 v0, v129, v3
	v_lshl_add_u64 v[6:7], v[0:1], 1, s[62:63]
	v_add_f32_e32 v5, 1.0, v5
	v_max_f32_e32 v0, 0x358637bd, v130
	v_cvt_pk_bf16_f32 v0, v0, s0
	v_rcp_f32_e32 v5, v5
	global_store_short v[6:7], v0, off
	s_waitcnt lgkmcnt(0)
	v_mul_f32_e32 v0, v138, v8
	v_mul_f32_e32 v0, 0xbfb8aa3b, v0
	v_exp_f32_e32 v8, v0
	v_add_u32_e32 v130, 0x4400, v4
	v_max_f32_e32 v5, 0x358637bd, v5
	v_add_u32_e32 v0, v130, v3
	v_cvt_pk_bf16_f32 v5, v5, s0
	v_lshl_add_u64 v[6:7], v[0:1], 1, s[62:63]
	global_store_short v[6:7], v5, off
	v_add_f32_e32 v0, 1.0, v8
	v_mul_f32_e32 v5, v139, v9
	v_rcp_f32_e32 v0, v0
	v_mul_f32_e32 v5, 0xbfb8aa3b, v5
	v_exp_f32_e32 v5, v5
	v_max_f32_e32 v0, 0x358637bd, v0
	v_cvt_pk_bf16_f32 v8, v0, s0
	v_add_f32_e32 v0, 1.0, v5
	v_rcp_f32_e32 v5, v0
	v_add_u32_e32 v0, v131, v3
	v_lshl_add_u64 v[6:7], v[0:1], 1, s[62:63]
	global_store_short v[6:7], v8, off
	v_max_f32_e32 v0, 0x358637bd, v5
	v_cvt_pk_bf16_f32 v5, v0, s0
	v_add_u32_e32 v0, v132, v3
	v_lshl_add_u64 v[6:7], v[0:1], 1, s[62:63]
	global_store_short v[6:7], v5, off
	ds_read2_b32 v[6:7], v2 offset0:24 offset1:25
	ds_read2_b32 v[8:9], v2 offset0:26 offset1:27
	v_add_u32_e32 v133, 0x6000, v4
	v_add_u32_e32 v135, 0x6800, v4
	v_add_u32_e32 v136, 0x6c00, v4
	s_waitcnt lgkmcnt(1)
	v_mul_f32_e32 v0, v140, v6
	v_mul_f32_e32 v0, 0xbfb8aa3b, v0
	v_exp_f32_e32 v0, v0
	v_mul_f32_e32 v5, v141, v7
	v_mul_f32_e32 v5, 0xbfb8aa3b, v5
	v_exp_f32_e32 v5, v5
	v_add_f32_e32 v0, 1.0, v0
	v_rcp_f32_e32 v134, v0
	v_add_u32_e32 v0, v133, v3
	v_lshl_add_u64 v[6:7], v[0:1], 1, s[62:63]
	v_add_f32_e32 v5, 1.0, v5
	v_max_f32_e32 v0, 0x358637bd, v134
	v_cvt_pk_bf16_f32 v0, v0, s0
	v_rcp_f32_e32 v5, v5
	global_store_short v[6:7], v0, off
	s_waitcnt lgkmcnt(0)
	v_mul_f32_e32 v0, v142, v8
	v_mul_f32_e32 v0, 0xbfb8aa3b, v0
	v_exp_f32_e32 v8, v0
	v_add_u32_e32 v134, 0x6400, v4
	v_max_f32_e32 v5, 0x358637bd, v5
	v_add_u32_e32 v0, v134, v3
	v_cvt_pk_bf16_f32 v5, v5, s0
	v_lshl_add_u64 v[6:7], v[0:1], 1, s[62:63]
	global_store_short v[6:7], v5, off
	v_add_f32_e32 v0, 1.0, v8
	v_mul_f32_e32 v5, v143, v9
	v_rcp_f32_e32 v0, v0
	v_mul_f32_e32 v5, 0xbfb8aa3b, v5
	v_exp_f32_e32 v5, v5
	v_max_f32_e32 v0, 0x358637bd, v0
	v_cvt_pk_bf16_f32 v8, v0, s0
	v_add_f32_e32 v0, 1.0, v5
	v_rcp_f32_e32 v5, v0
	v_add_u32_e32 v0, v135, v3
	v_lshl_add_u64 v[6:7], v[0:1], 1, s[62:63]
	global_store_short v[6:7], v8, off
	v_max_f32_e32 v0, 0x358637bd, v5
	v_cvt_pk_bf16_f32 v5, v0, s0
	v_add_u32_e32 v0, v136, v3
	v_lshl_add_u64 v[6:7], v[0:1], 1, s[62:63]
	global_store_short v[6:7], v5, off
	ds_read2_b32 v[6:7], v2 offset1:1
	ds_read2_b32 v[8:9], v2 offset0:2 offset1:3
	s_waitcnt lgkmcnt(1)
	v_mul_f32_e32 v0, v112, v6
	v_mul_f32_e32 v0, 0xbfb8aa3b, v0
	v_exp_f32_e32 v0, v0
	v_mul_f32_e32 v5, v113, v7
	v_mul_f32_e32 v5, 0xbfb8aa3b, v5
	v_exp_f32_e32 v6, v5
	v_add_f32_e32 v0, 1.0, v0
	v_rcp_f32_e32 v112, v0
	v_add_u32_e32 v5, 32, v3
	v_add_f32_e32 v6, 1.0, v6
	v_add_u32_e32 v0, v4, v5
	v_rcp_f32_e32 v113, v6
	v_lshl_add_u64 v[6:7], v[0:1], 1, s[62:63]
	v_max_f32_e32 v0, 0x358637bd, v112
	v_cvt_pk_bf16_f32 v0, v0, s0
	global_store_short v[6:7], v0, off
	s_waitcnt lgkmcnt(0)
	v_mul_f32_e32 v0, v114, v8
	v_mul_f32_e32 v0, 0xbfb8aa3b, v0
	v_exp_f32_e32 v8, v0
	v_add_u32_e32 v0, v10, v5
	v_lshl_add_u64 v[6:7], v[0:1], 1, s[62:63]
	v_max_f32_e32 v112, 0x358637bd, v113
	v_add_f32_e32 v0, 1.0, v8
	v_mul_f32_e32 v8, v115, v9
	v_rcp_f32_e32 v0, v0
	v_mul_f32_e32 v8, 0xbfb8aa3b, v8
	v_exp_f32_e32 v8, v8
	v_cvt_pk_bf16_f32 v112, v112, s0
	v_max_f32_e32 v0, 0x358637bd, v0
	v_cvt_pk_bf16_f32 v9, v0, s0
	v_add_f32_e32 v0, 1.0, v8
	v_rcp_f32_e32 v8, v0
	v_add_u32_e32 v0, v11, v5
	global_store_short v[6:7], v112, off
	v_lshl_add_u64 v[6:7], v[0:1], 1, s[62:63]
	v_max_f32_e32 v0, 0x358637bd, v8
	v_cvt_pk_bf16_f32 v8, v0, s0
	v_add_u32_e32 v0, v12, v5
	global_store_short v[6:7], v9, off
	v_lshl_add_u64 v[6:7], v[0:1], 1, s[62:63]
	global_store_short v[6:7], v8, off
	ds_read2_b32 v[6:7], v2 offset0:8 offset1:9
	ds_read2_b32 v[8:9], v2 offset0:10 offset1:11
	s_waitcnt lgkmcnt(1)
	v_mul_f32_e32 v0, v116, v6
	v_mul_f32_e32 v0, 0xbfb8aa3b, v0
	v_mul_f32_e32 v6, v117, v7
	v_exp_f32_e32 v7, v0
	v_mul_f32_e32 v6, 0xbfb8aa3b, v6
	v_exp_f32_e32 v6, v6
	v_add_u32_e32 v0, v13, v5
	v_add_f32_e32 v7, 1.0, v7
	v_rcp_f32_e32 v10, v7
	v_add_f32_e32 v6, 1.0, v6
	v_rcp_f32_e32 v11, v6
	v_lshl_add_u64 v[6:7], v[0:1], 1, s[62:63]
	s_waitcnt lgkmcnt(0)
	v_mul_f32_e32 v0, v118, v8
	v_max_f32_e32 v8, 0x358637bd, v10
	v_cvt_pk_bf16_f32 v8, v8, s0
	v_mul_f32_e32 v0, 0xbfb8aa3b, v0
	global_store_short v[6:7], v8, off
	v_exp_f32_e32 v8, v0
	v_add_u32_e32 v0, v14, v5
	v_lshl_add_u64 v[6:7], v[0:1], 1, s[62:63]
	v_max_f32_e32 v10, 0x358637bd, v11
	v_add_f32_e32 v0, 1.0, v8
	v_mul_f32_e32 v8, v119, v9
	v_rcp_f32_e32 v0, v0
	v_mul_f32_e32 v8, 0xbfb8aa3b, v8
	v_exp_f32_e32 v8, v8
	v_cvt_pk_bf16_f32 v10, v10, s0
	v_max_f32_e32 v0, 0x358637bd, v0
	v_cvt_pk_bf16_f32 v9, v0, s0
	v_add_f32_e32 v0, 1.0, v8
	v_rcp_f32_e32 v8, v0
	v_add_u32_e32 v0, v15, v5
	global_store_short v[6:7], v10, off
	v_lshl_add_u64 v[6:7], v[0:1], 1, s[62:63]
	v_max_f32_e32 v0, 0x358637bd, v8
	v_cvt_pk_bf16_f32 v8, v0, s0
	v_add_u32_e32 v0, v128, v5
	global_store_short v[6:7], v9, off
	v_lshl_add_u64 v[6:7], v[0:1], 1, s[62:63]
	global_store_short v[6:7], v8, off
	ds_read2_b32 v[6:7], v2 offset0:16 offset1:17
	ds_read2_b32 v[8:9], v2 offset0:18 offset1:19
	s_waitcnt lgkmcnt(1)
	v_mul_f32_e32 v0, v120, v6
	v_mul_f32_e32 v0, 0xbfb8aa3b, v0
	v_mul_f32_e32 v6, v121, v7
	v_exp_f32_e32 v7, v0
	v_mul_f32_e32 v6, 0xbfb8aa3b, v6
	v_exp_f32_e32 v6, v6
	v_add_u32_e32 v0, v129, v5
	v_add_f32_e32 v7, 1.0, v7
	v_rcp_f32_e32 v10, v7
	v_add_f32_e32 v6, 1.0, v6
	v_rcp_f32_e32 v11, v6
	v_lshl_add_u64 v[6:7], v[0:1], 1, s[62:63]
	s_waitcnt lgkmcnt(0)
	v_mul_f32_e32 v0, v122, v8
	v_max_f32_e32 v8, 0x358637bd, v10
	v_cvt_pk_bf16_f32 v8, v8, s0
	v_mul_f32_e32 v0, 0xbfb8aa3b, v0
	global_store_short v[6:7], v8, off
	v_exp_f32_e32 v8, v0
	v_add_u32_e32 v0, v130, v5
	v_lshl_add_u64 v[6:7], v[0:1], 1, s[62:63]
	v_max_f32_e32 v10, 0x358637bd, v11
	v_add_f32_e32 v0, 1.0, v8
	v_mul_f32_e32 v8, v123, v9
	v_rcp_f32_e32 v0, v0
	v_mul_f32_e32 v8, 0xbfb8aa3b, v8
	v_exp_f32_e32 v8, v8
	v_cvt_pk_bf16_f32 v10, v10, s0
	v_max_f32_e32 v0, 0x358637bd, v0
	v_cvt_pk_bf16_f32 v9, v0, s0
	v_add_f32_e32 v0, 1.0, v8
	v_rcp_f32_e32 v8, v0
	v_add_u32_e32 v0, v131, v5
	global_store_short v[6:7], v10, off
	v_lshl_add_u64 v[6:7], v[0:1], 1, s[62:63]
	v_max_f32_e32 v0, 0x358637bd, v8
	v_cvt_pk_bf16_f32 v8, v0, s0
	v_add_u32_e32 v0, v132, v5
	global_store_short v[6:7], v9, off
	v_lshl_add_u64 v[6:7], v[0:1], 1, s[62:63]
	global_store_short v[6:7], v8, off
	ds_read2_b32 v[6:7], v2 offset0:24 offset1:25
	ds_read2_b32 v[8:9], v2 offset0:26 offset1:27
	s_waitcnt lgkmcnt(1)
	v_mul_f32_e32 v0, v124, v6
	v_mul_f32_e32 v0, 0xbfb8aa3b, v0
	v_mul_f32_e32 v6, v125, v7
	v_exp_f32_e32 v7, v0
	v_mul_f32_e32 v6, 0xbfb8aa3b, v6
	v_exp_f32_e32 v6, v6
	v_add_u32_e32 v0, v133, v5
	v_add_f32_e32 v7, 1.0, v7
	v_rcp_f32_e32 v10, v7
	v_add_f32_e32 v6, 1.0, v6
	v_rcp_f32_e32 v11, v6
	v_lshl_add_u64 v[6:7], v[0:1], 1, s[62:63]
	s_waitcnt lgkmcnt(0)
	v_mul_f32_e32 v0, v126, v8
	v_max_f32_e32 v8, 0x358637bd, v10
	v_cvt_pk_bf16_f32 v8, v8, s0
	v_mul_f32_e32 v0, 0xbfb8aa3b, v0
	global_store_short v[6:7], v8, off
	v_exp_f32_e32 v8, v0
	v_add_u32_e32 v0, v134, v5
	v_lshl_add_u64 v[6:7], v[0:1], 1, s[62:63]
	v_max_f32_e32 v10, 0x358637bd, v11
	v_add_f32_e32 v0, 1.0, v8
	v_mul_f32_e32 v8, v127, v9
	v_rcp_f32_e32 v0, v0
	v_mul_f32_e32 v8, 0xbfb8aa3b, v8
	v_exp_f32_e32 v8, v8
	v_cvt_pk_bf16_f32 v10, v10, s0
	v_max_f32_e32 v0, 0x358637bd, v0
	v_cvt_pk_bf16_f32 v9, v0, s0
	v_add_f32_e32 v0, 1.0, v8
	v_rcp_f32_e32 v8, v0
	v_add_u32_e32 v0, v135, v5
	global_store_short v[6:7], v10, off
	v_lshl_add_u64 v[6:7], v[0:1], 1, s[62:63]
	v_max_f32_e32 v0, 0x358637bd, v8
	v_cvt_pk_bf16_f32 v8, v0, s0
	v_add_u32_e32 v0, v136, v5
	global_store_short v[6:7], v9, off
	v_lshl_add_u64 v[6:7], v[0:1], 1, s[62:63]
	global_store_short v[6:7], v8, off
	ds_read2_b32 v[6:7], v2 offset0:32 offset1:33
	ds_read2_b32 v[8:9], v2 offset0:34 offset1:35
	v_add_u32_e32 v10, 0x8000, v4
	v_add_u32_e32 v13, 0x8c00, v4
	s_waitcnt lgkmcnt(1)
	v_mul_f32_e32 v0, v96, v6
	v_mul_f32_e32 v0, 0xbfb8aa3b, v0
	v_exp_f32_e32 v0, v0
	v_mul_f32_e32 v6, v97, v7
	v_mul_f32_e32 v6, 0xbfb8aa3b, v6
	v_exp_f32_e32 v6, v6
	v_add_f32_e32 v0, 1.0, v0
	v_rcp_f32_e32 v11, v0
	v_add_u32_e32 v0, v10, v3
	v_add_f32_e32 v6, 1.0, v6
	v_rcp_f32_e32 v12, v6
	v_lshl_add_u64 v[6:7], v[0:1], 1, s[62:63]
	v_max_f32_e32 v0, 0x358637bd, v11
	v_cvt_pk_bf16_f32 v0, v0, s0
	global_store_short v[6:7], v0, off
	s_waitcnt lgkmcnt(0)
	v_mul_f32_e32 v0, v98, v8
	v_mul_f32_e32 v0, 0xbfb8aa3b, v0
	v_exp_f32_e32 v8, v0
	v_max_f32_e32 v11, 0x358637bd, v12
	v_add_u32_e32 v12, 0x8400, v4
	v_add_u32_e32 v0, v12, v3
	v_cvt_pk_bf16_f32 v11, v11, s0
	v_lshl_add_u64 v[6:7], v[0:1], 1, s[62:63]
	global_store_short v[6:7], v11, off
	v_add_f32_e32 v0, 1.0, v8
	v_mul_f32_e32 v6, v99, v9
	v_rcp_f32_e32 v0, v0
	v_mul_f32_e32 v6, 0xbfb8aa3b, v6
	v_exp_f32_e32 v6, v6
	v_add_u32_e32 v11, 0x8800, v4
	v_max_f32_e32 v0, 0x358637bd, v0
	v_cvt_pk_bf16_f32 v8, v0, s0
	v_add_f32_e32 v0, 1.0, v6
	v_rcp_f32_e32 v9, v0
	v_add_u32_e32 v0, v11, v3
	v_lshl_add_u64 v[6:7], v[0:1], 1, s[62:63]
	global_store_short v[6:7], v8, off
	v_max_f32_e32 v0, 0x358637bd, v9
	v_cvt_pk_bf16_f32 v8, v0, s0
	v_add_u32_e32 v0, v13, v3
	v_lshl_add_u64 v[6:7], v[0:1], 1, s[62:63]
	global_store_short v[6:7], v8, off
	ds_read2_b32 v[6:7], v2 offset0:40 offset1:41
	ds_read2_b32 v[8:9], v2 offset0:42 offset1:43
	v_add_u32_e32 v14, 0xa000, v4
	v_add_u32_e32 v97, 0xac00, v4
	s_waitcnt lgkmcnt(1)
	v_mul_f32_e32 v0, v100, v6
	v_mul_f32_e32 v0, 0xbfb8aa3b, v0
	v_exp_f32_e32 v0, v0
	v_mul_f32_e32 v6, v101, v7
	v_mul_f32_e32 v6, 0xbfb8aa3b, v6
	v_exp_f32_e32 v6, v6
	v_add_f32_e32 v0, 1.0, v0
	v_rcp_f32_e32 v15, v0
	v_add_u32_e32 v0, v14, v3
	v_add_f32_e32 v6, 1.0, v6
	v_rcp_f32_e32 v96, v6
	v_lshl_add_u64 v[6:7], v[0:1], 1, s[62:63]
	v_max_f32_e32 v0, 0x358637bd, v15
	v_cvt_pk_bf16_f32 v0, v0, s0
	global_store_short v[6:7], v0, off
	s_waitcnt lgkmcnt(0)
	v_mul_f32_e32 v0, v102, v8
	v_mul_f32_e32 v0, 0xbfb8aa3b, v0
	v_exp_f32_e32 v8, v0
	v_max_f32_e32 v15, 0x358637bd, v96
	v_add_u32_e32 v96, 0xa400, v4
	v_add_u32_e32 v0, v96, v3
	v_cvt_pk_bf16_f32 v15, v15, s0
	v_lshl_add_u64 v[6:7], v[0:1], 1, s[62:63]
	global_store_short v[6:7], v15, off
	v_add_f32_e32 v0, 1.0, v8
	v_mul_f32_e32 v6, v103, v9
	v_rcp_f32_e32 v0, v0
	v_mul_f32_e32 v6, 0xbfb8aa3b, v6
	v_exp_f32_e32 v6, v6
	v_add_u32_e32 v15, 0xa800, v4
	v_max_f32_e32 v0, 0x358637bd, v0
	v_cvt_pk_bf16_f32 v8, v0, s0
	v_add_f32_e32 v0, 1.0, v6
	v_rcp_f32_e32 v9, v0
	v_add_u32_e32 v0, v15, v3
	v_lshl_add_u64 v[6:7], v[0:1], 1, s[62:63]
	global_store_short v[6:7], v8, off
	v_max_f32_e32 v0, 0x358637bd, v9
	v_cvt_pk_bf16_f32 v8, v0, s0
	v_add_u32_e32 v0, v97, v3
	v_lshl_add_u64 v[6:7], v[0:1], 1, s[62:63]
	global_store_short v[6:7], v8, off
	ds_read2_b32 v[6:7], v2 offset0:48 offset1:49
	ds_read2_b32 v[8:9], v2 offset0:50 offset1:51
	v_add_u32_e32 v98, 0xc000, v4
	v_add_u32_e32 v101, 0xcc00, v4
	s_waitcnt lgkmcnt(1)
	v_mul_f32_e32 v0, v104, v6
	v_mul_f32_e32 v0, 0xbfb8aa3b, v0
	v_exp_f32_e32 v0, v0
	v_mul_f32_e32 v6, v105, v7
	v_mul_f32_e32 v6, 0xbfb8aa3b, v6
	v_exp_f32_e32 v6, v6
	v_add_f32_e32 v0, 1.0, v0
	v_rcp_f32_e32 v99, v0
	v_add_u32_e32 v0, v98, v3
	v_add_f32_e32 v6, 1.0, v6
	v_rcp_f32_e32 v100, v6
	v_lshl_add_u64 v[6:7], v[0:1], 1, s[62:63]
	v_max_f32_e32 v0, 0x358637bd, v99
	v_cvt_pk_bf16_f32 v0, v0, s0
	global_store_short v[6:7], v0, off
	s_waitcnt lgkmcnt(0)
	v_mul_f32_e32 v0, v106, v8
	v_mul_f32_e32 v0, 0xbfb8aa3b, v0
	v_exp_f32_e32 v8, v0
	v_max_f32_e32 v99, 0x358637bd, v100
	v_add_u32_e32 v100, 0xc400, v4
	v_add_u32_e32 v0, v100, v3
	v_cvt_pk_bf16_f32 v99, v99, s0
	v_lshl_add_u64 v[6:7], v[0:1], 1, s[62:63]
	global_store_short v[6:7], v99, off
	v_add_f32_e32 v0, 1.0, v8
	v_mul_f32_e32 v6, v107, v9
	v_rcp_f32_e32 v0, v0
	v_mul_f32_e32 v6, 0xbfb8aa3b, v6
	v_exp_f32_e32 v6, v6
	v_add_u32_e32 v99, 0xc800, v4
	v_max_f32_e32 v0, 0x358637bd, v0
	v_cvt_pk_bf16_f32 v8, v0, s0
	v_add_f32_e32 v0, 1.0, v6
	v_rcp_f32_e32 v9, v0
	v_add_u32_e32 v0, v99, v3
	v_lshl_add_u64 v[6:7], v[0:1], 1, s[62:63]
	global_store_short v[6:7], v8, off
	v_max_f32_e32 v0, 0x358637bd, v9
	v_cvt_pk_bf16_f32 v8, v0, s0
	v_add_u32_e32 v0, v101, v3
	v_lshl_add_u64 v[6:7], v[0:1], 1, s[62:63]
	global_store_short v[6:7], v8, off
	ds_read2_b32 v[6:7], v2 offset0:56 offset1:57
	ds_read2_b32 v[8:9], v2 offset0:58 offset1:59
	v_add_u32_e32 v102, 0xe000, v4
	v_add_u32_e32 v105, 0xec00, v4
	s_waitcnt lgkmcnt(1)
	v_mul_f32_e32 v0, v108, v6
	v_mul_f32_e32 v0, 0xbfb8aa3b, v0
	v_exp_f32_e32 v0, v0
	v_mul_f32_e32 v6, v109, v7
	v_mul_f32_e32 v6, 0xbfb8aa3b, v6
	v_exp_f32_e32 v6, v6
	v_add_f32_e32 v0, 1.0, v0
	v_rcp_f32_e32 v103, v0
	v_add_u32_e32 v0, v102, v3
	v_add_f32_e32 v6, 1.0, v6
	v_rcp_f32_e32 v104, v6
	v_lshl_add_u64 v[6:7], v[0:1], 1, s[62:63]
	v_max_f32_e32 v0, 0x358637bd, v103
	v_cvt_pk_bf16_f32 v0, v0, s0
	global_store_short v[6:7], v0, off
	s_waitcnt lgkmcnt(0)
	v_mul_f32_e32 v0, v110, v8
	v_mul_f32_e32 v0, 0xbfb8aa3b, v0
	v_exp_f32_e32 v8, v0
	v_max_f32_e32 v103, 0x358637bd, v104
	v_add_u32_e32 v104, 0xe400, v4
	v_add_u32_e32 v0, v104, v3
	v_cvt_pk_bf16_f32 v103, v103, s0
	v_lshl_add_u64 v[6:7], v[0:1], 1, s[62:63]
	global_store_short v[6:7], v103, off
	v_add_f32_e32 v0, 1.0, v8
	v_mul_f32_e32 v6, v111, v9
	v_rcp_f32_e32 v0, v0
	v_mul_f32_e32 v6, 0xbfb8aa3b, v6
	v_exp_f32_e32 v6, v6
	v_add_u32_e32 v103, 0xe800, v4
	v_max_f32_e32 v0, 0x358637bd, v0
	v_cvt_pk_bf16_f32 v8, v0, s0
	v_add_f32_e32 v0, 1.0, v6
	v_rcp_f32_e32 v9, v0
	v_add_u32_e32 v0, v103, v3
	v_lshl_add_u64 v[6:7], v[0:1], 1, s[62:63]
	global_store_short v[6:7], v8, off
	v_max_f32_e32 v0, 0x358637bd, v9
	v_cvt_pk_bf16_f32 v8, v0, s0
	v_add_u32_e32 v0, v105, v3
	v_lshl_add_u64 v[6:7], v[0:1], 1, s[62:63]
	global_store_short v[6:7], v8, off
	ds_read2_b32 v[6:7], v2 offset0:32 offset1:33
	ds_read2_b32 v[8:9], v2 offset0:34 offset1:35
	s_waitcnt lgkmcnt(1)
	v_mul_f32_e32 v0, v64, v6
	v_mul_f32_e32 v0, 0xbfb8aa3b, v0
	v_mul_f32_e32 v6, v65, v7
	v_exp_f32_e32 v7, v0
	v_mul_f32_e32 v6, 0xbfb8aa3b, v6
	v_exp_f32_e32 v6, v6
	v_add_u32_e32 v0, v10, v5
	v_add_f32_e32 v7, 1.0, v7
	v_rcp_f32_e32 v10, v7
	v_add_f32_e32 v6, 1.0, v6
	v_rcp_f32_e32 v64, v6
	v_lshl_add_u64 v[6:7], v[0:1], 1, s[62:63]
	s_waitcnt lgkmcnt(0)
	v_mul_f32_e32 v0, v66, v8
	v_max_f32_e32 v8, 0x358637bd, v10
	v_cvt_pk_bf16_f32 v8, v8, s0
	v_mul_f32_e32 v0, 0xbfb8aa3b, v0
	global_store_short v[6:7], v8, off
	v_exp_f32_e32 v8, v0
	v_add_u32_e32 v0, v12, v5
	v_lshl_add_u64 v[6:7], v[0:1], 1, s[62:63]
	v_max_f32_e32 v10, 0x358637bd, v64
	v_add_f32_e32 v0, 1.0, v8
	v_mul_f32_e32 v8, v67, v9
	v_rcp_f32_e32 v0, v0
	v_mul_f32_e32 v8, 0xbfb8aa3b, v8
	v_exp_f32_e32 v8, v8
	v_cvt_pk_bf16_f32 v10, v10, s0
	v_max_f32_e32 v0, 0x358637bd, v0
	v_cvt_pk_bf16_f32 v9, v0, s0
	v_add_f32_e32 v0, 1.0, v8
	v_rcp_f32_e32 v8, v0
	v_add_u32_e32 v0, v11, v5
	global_store_short v[6:7], v10, off
	v_lshl_add_u64 v[6:7], v[0:1], 1, s[62:63]
	v_max_f32_e32 v0, 0x358637bd, v8
	v_cvt_pk_bf16_f32 v8, v0, s0
	v_add_u32_e32 v0, v13, v5
	global_store_short v[6:7], v9, off
	v_lshl_add_u64 v[6:7], v[0:1], 1, s[62:63]
	global_store_short v[6:7], v8, off
	ds_read2_b32 v[6:7], v2 offset0:40 offset1:41
	ds_read2_b32 v[8:9], v2 offset0:42 offset1:43
	s_waitcnt lgkmcnt(1)
	v_mul_f32_e32 v0, v68, v6
	v_mul_f32_e32 v0, 0xbfb8aa3b, v0
	v_mul_f32_e32 v6, v69, v7
	v_exp_f32_e32 v7, v0
	v_mul_f32_e32 v6, 0xbfb8aa3b, v6
	v_exp_f32_e32 v6, v6
	v_add_u32_e32 v0, v14, v5
	v_add_f32_e32 v7, 1.0, v7
	v_rcp_f32_e32 v10, v7
	v_add_f32_e32 v6, 1.0, v6
	v_rcp_f32_e32 v11, v6
	v_lshl_add_u64 v[6:7], v[0:1], 1, s[62:63]
	s_waitcnt lgkmcnt(0)
	v_mul_f32_e32 v0, v70, v8
	v_max_f32_e32 v8, 0x358637bd, v10
	v_cvt_pk_bf16_f32 v8, v8, s0
	v_mul_f32_e32 v0, 0xbfb8aa3b, v0
	global_store_short v[6:7], v8, off
	v_exp_f32_e32 v8, v0
	v_add_u32_e32 v0, v96, v5
	v_lshl_add_u64 v[6:7], v[0:1], 1, s[62:63]
	v_max_f32_e32 v10, 0x358637bd, v11
	v_add_f32_e32 v0, 1.0, v8
	v_mul_f32_e32 v8, v71, v9
	v_rcp_f32_e32 v0, v0
	v_mul_f32_e32 v8, 0xbfb8aa3b, v8
	v_exp_f32_e32 v8, v8
	v_cvt_pk_bf16_f32 v10, v10, s0
	v_max_f32_e32 v0, 0x358637bd, v0
	v_cvt_pk_bf16_f32 v9, v0, s0
	v_add_f32_e32 v0, 1.0, v8
	v_rcp_f32_e32 v8, v0
	v_add_u32_e32 v0, v15, v5
	global_store_short v[6:7], v10, off
	v_lshl_add_u64 v[6:7], v[0:1], 1, s[62:63]
	v_max_f32_e32 v0, 0x358637bd, v8
	v_cvt_pk_bf16_f32 v8, v0, s0
	v_add_u32_e32 v0, v97, v5
	global_store_short v[6:7], v9, off
	v_lshl_add_u64 v[6:7], v[0:1], 1, s[62:63]
	global_store_short v[6:7], v8, off
	ds_read2_b32 v[6:7], v2 offset0:48 offset1:49
	ds_read2_b32 v[8:9], v2 offset0:50 offset1:51
	s_waitcnt lgkmcnt(1)
	v_mul_f32_e32 v0, v72, v6
	v_mul_f32_e32 v0, 0xbfb8aa3b, v0
	v_mul_f32_e32 v6, v73, v7
	v_exp_f32_e32 v7, v0
	v_mul_f32_e32 v6, 0xbfb8aa3b, v6
	v_exp_f32_e32 v6, v6
	v_add_u32_e32 v0, v98, v5
	v_add_f32_e32 v7, 1.0, v7
	v_rcp_f32_e32 v10, v7
	v_add_f32_e32 v6, 1.0, v6
	v_rcp_f32_e32 v11, v6
	v_lshl_add_u64 v[6:7], v[0:1], 1, s[62:63]
	s_waitcnt lgkmcnt(0)
	v_mul_f32_e32 v0, v74, v8
	v_max_f32_e32 v8, 0x358637bd, v10
	v_cvt_pk_bf16_f32 v8, v8, s0
	v_mul_f32_e32 v0, 0xbfb8aa3b, v0
	global_store_short v[6:7], v8, off
	v_exp_f32_e32 v8, v0
	v_add_u32_e32 v0, v100, v5
	v_lshl_add_u64 v[6:7], v[0:1], 1, s[62:63]
	v_max_f32_e32 v10, 0x358637bd, v11
	v_add_f32_e32 v0, 1.0, v8
	v_mul_f32_e32 v8, v75, v9
	v_rcp_f32_e32 v0, v0
	v_mul_f32_e32 v8, 0xbfb8aa3b, v8
	v_exp_f32_e32 v8, v8
	v_cvt_pk_bf16_f32 v10, v10, s0
	v_max_f32_e32 v0, 0x358637bd, v0
	v_cvt_pk_bf16_f32 v9, v0, s0
	v_add_f32_e32 v0, 1.0, v8
	v_rcp_f32_e32 v8, v0
	v_add_u32_e32 v0, v99, v5
	global_store_short v[6:7], v10, off
	v_lshl_add_u64 v[6:7], v[0:1], 1, s[62:63]
	v_max_f32_e32 v0, 0x358637bd, v8
	v_cvt_pk_bf16_f32 v8, v0, s0
	v_add_u32_e32 v0, v101, v5
	global_store_short v[6:7], v9, off
	v_lshl_add_u64 v[6:7], v[0:1], 1, s[62:63]
	global_store_short v[6:7], v8, off
	ds_read2_b32 v[6:7], v2 offset0:56 offset1:57
	ds_read2_b32 v[8:9], v2 offset0:58 offset1:59
	s_waitcnt lgkmcnt(1)
	v_mul_f32_e32 v0, v76, v6
	v_mul_f32_e32 v0, 0xbfb8aa3b, v0
	v_mul_f32_e32 v6, v77, v7
	v_exp_f32_e32 v7, v0
	v_mul_f32_e32 v6, 0xbfb8aa3b, v6
	v_exp_f32_e32 v6, v6
	v_add_u32_e32 v0, v102, v5
	v_add_f32_e32 v7, 1.0, v7
	v_rcp_f32_e32 v10, v7
	v_add_f32_e32 v6, 1.0, v6
	v_rcp_f32_e32 v11, v6
	v_lshl_add_u64 v[6:7], v[0:1], 1, s[62:63]
	s_waitcnt lgkmcnt(0)
	v_mul_f32_e32 v0, v78, v8
	v_max_f32_e32 v8, 0x358637bd, v10
	v_cvt_pk_bf16_f32 v8, v8, s0
	v_mul_f32_e32 v0, 0xbfb8aa3b, v0
	global_store_short v[6:7], v8, off
	v_exp_f32_e32 v8, v0
	v_add_u32_e32 v0, v104, v5
	v_lshl_add_u64 v[6:7], v[0:1], 1, s[62:63]
	v_max_f32_e32 v10, 0x358637bd, v11
	v_add_f32_e32 v0, 1.0, v8
	v_mul_f32_e32 v8, v79, v9
	v_rcp_f32_e32 v0, v0
	v_mul_f32_e32 v8, 0xbfb8aa3b, v8
	v_exp_f32_e32 v8, v8
	v_cvt_pk_bf16_f32 v10, v10, s0
	v_max_f32_e32 v0, 0x358637bd, v0
	v_cvt_pk_bf16_f32 v9, v0, s0
	v_add_f32_e32 v0, 1.0, v8
	v_rcp_f32_e32 v8, v0
	v_add_u32_e32 v0, v103, v5
	global_store_short v[6:7], v10, off
	v_lshl_add_u64 v[6:7], v[0:1], 1, s[62:63]
	v_max_f32_e32 v0, 0x358637bd, v8
	v_cvt_pk_bf16_f32 v8, v0, s0
	v_add_u32_e32 v0, v105, v5
	global_store_short v[6:7], v9, off
	v_lshl_add_u64 v[6:7], v[0:1], 1, s[62:63]
	global_store_short v[6:7], v8, off
	s_cmpk_lt_i32 s8, 0x4000
	s_cbranch_scc1 .Ltep_e2_c
	s_waitcnt vmcnt(63)
	s_branch .Ltep_e2_e
.Ltep_e2_c:
	ds_read2_b32 v[6:7], v2 offset0:64 offset1:65
	ds_read2_b32 v[8:9], v2 offset0:66 offset1:67
	v_add_u32_e32 v10, 0x10000, v4
	v_add_u32_e32 v13, 0x10c00, v4
	s_waitcnt lgkmcnt(1)
	v_mul_f32_e32 v0, v80, v6
	v_mul_f32_e32 v0, 0xbfb8aa3b, v0
	v_exp_f32_e32 v0, v0
	v_mul_f32_e32 v6, v81, v7
	v_mul_f32_e32 v6, 0xbfb8aa3b, v6
	v_exp_f32_e32 v6, v6
	v_add_f32_e32 v0, 1.0, v0
	v_rcp_f32_e32 v11, v0
	v_add_u32_e32 v0, v10, v3
	v_add_f32_e32 v6, 1.0, v6
	v_rcp_f32_e32 v12, v6
	v_lshl_add_u64 v[6:7], v[0:1], 1, s[62:63]
	v_max_f32_e32 v0, 0x358637bd, v11
	v_cvt_pk_bf16_f32 v0, v0, s0
	global_store_short v[6:7], v0, off
	s_waitcnt lgkmcnt(0)
	v_mul_f32_e32 v0, v82, v8
	v_mul_f32_e32 v0, 0xbfb8aa3b, v0
	v_exp_f32_e32 v8, v0
	v_max_f32_e32 v11, 0x358637bd, v12
	v_add_u32_e32 v12, 0x10400, v4
	v_add_u32_e32 v0, v12, v3
	v_cvt_pk_bf16_f32 v11, v11, s0
	v_lshl_add_u64 v[6:7], v[0:1], 1, s[62:63]
	global_store_short v[6:7], v11, off
	v_add_f32_e32 v0, 1.0, v8
	v_mul_f32_e32 v6, v83, v9
	v_rcp_f32_e32 v0, v0
	v_mul_f32_e32 v6, 0xbfb8aa3b, v6
	v_exp_f32_e32 v6, v6
	v_add_u32_e32 v11, 0x10800, v4
	v_max_f32_e32 v0, 0x358637bd, v0
	v_cvt_pk_bf16_f32 v8, v0, s0
	v_add_f32_e32 v0, 1.0, v6
	v_rcp_f32_e32 v9, v0
	v_add_u32_e32 v0, v11, v3
	v_lshl_add_u64 v[6:7], v[0:1], 1, s[62:63]
	global_store_short v[6:7], v8, off
	v_max_f32_e32 v0, 0x358637bd, v9
	v_cvt_pk_bf16_f32 v8, v0, s0
	v_add_u32_e32 v0, v13, v3
	v_lshl_add_u64 v[6:7], v[0:1], 1, s[62:63]
	global_store_short v[6:7], v8, off
	ds_read2_b32 v[6:7], v2 offset0:72 offset1:73
	ds_read2_b32 v[8:9], v2 offset0:74 offset1:75
	v_add_u32_e32 v14, 0x12000, v4
	v_add_u32_e32 v65, 0x12c00, v4
	s_waitcnt lgkmcnt(1)
	v_mul_f32_e32 v0, v84, v6
	v_mul_f32_e32 v0, 0xbfb8aa3b, v0
	v_exp_f32_e32 v0, v0
	v_mul_f32_e32 v6, v85, v7
	v_mul_f32_e32 v6, 0xbfb8aa3b, v6
	v_exp_f32_e32 v6, v6
	v_add_f32_e32 v0, 1.0, v0
	v_rcp_f32_e32 v15, v0
	v_add_u32_e32 v0, v14, v3
	v_add_f32_e32 v6, 1.0, v6
	v_rcp_f32_e32 v64, v6
	v_lshl_add_u64 v[6:7], v[0:1], 1, s[62:63]
	v_max_f32_e32 v0, 0x358637bd, v15
	v_cvt_pk_bf16_f32 v0, v0, s0
	global_store_short v[6:7], v0, off
	s_waitcnt lgkmcnt(0)
	v_mul_f32_e32 v0, v86, v8
	v_mul_f32_e32 v0, 0xbfb8aa3b, v0
	v_exp_f32_e32 v8, v0
	v_max_f32_e32 v15, 0x358637bd, v64
	v_add_u32_e32 v64, 0x12400, v4
	v_add_u32_e32 v0, v64, v3
	v_cvt_pk_bf16_f32 v15, v15, s0
	v_lshl_add_u64 v[6:7], v[0:1], 1, s[62:63]
	global_store_short v[6:7], v15, off
	v_add_f32_e32 v0, 1.0, v8
	v_mul_f32_e32 v6, v87, v9
	v_rcp_f32_e32 v0, v0
	v_mul_f32_e32 v6, 0xbfb8aa3b, v6
	v_exp_f32_e32 v6, v6
	v_add_u32_e32 v15, 0x12800, v4
	v_max_f32_e32 v0, 0x358637bd, v0
	v_cvt_pk_bf16_f32 v8, v0, s0
	v_add_f32_e32 v0, 1.0, v6
	v_rcp_f32_e32 v9, v0
	v_add_u32_e32 v0, v15, v3
	v_lshl_add_u64 v[6:7], v[0:1], 1, s[62:63]
	global_store_short v[6:7], v8, off
	v_max_f32_e32 v0, 0x358637bd, v9
	v_cvt_pk_bf16_f32 v8, v0, s0
	v_add_u32_e32 v0, v65, v3
	v_lshl_add_u64 v[6:7], v[0:1], 1, s[62:63]
	global_store_short v[6:7], v8, off
	ds_read2_b32 v[6:7], v2 offset0:80 offset1:81
	ds_read2_b32 v[8:9], v2 offset0:82 offset1:83
	v_add_u32_e32 v66, 0x14000, v4
	v_add_u32_e32 v69, 0x14c00, v4
	s_waitcnt lgkmcnt(1)
	v_mul_f32_e32 v0, v88, v6
	v_mul_f32_e32 v0, 0xbfb8aa3b, v0
	v_exp_f32_e32 v0, v0
	v_mul_f32_e32 v6, v89, v7
	v_mul_f32_e32 v6, 0xbfb8aa3b, v6
	v_exp_f32_e32 v6, v6
	v_add_f32_e32 v0, 1.0, v0
	v_rcp_f32_e32 v67, v0
	v_add_u32_e32 v0, v66, v3
	v_add_f32_e32 v6, 1.0, v6
	v_rcp_f32_e32 v68, v6
	v_lshl_add_u64 v[6:7], v[0:1], 1, s[62:63]
	v_max_f32_e32 v0, 0x358637bd, v67
	v_cvt_pk_bf16_f32 v0, v0, s0
	global_store_short v[6:7], v0, off
	s_waitcnt lgkmcnt(0)
	v_mul_f32_e32 v0, v90, v8
	v_mul_f32_e32 v0, 0xbfb8aa3b, v0
	v_exp_f32_e32 v8, v0
	v_max_f32_e32 v67, 0x358637bd, v68
	v_add_u32_e32 v68, 0x14400, v4
	v_add_u32_e32 v0, v68, v3
	v_cvt_pk_bf16_f32 v67, v67, s0
	v_lshl_add_u64 v[6:7], v[0:1], 1, s[62:63]
	global_store_short v[6:7], v67, off
	v_add_f32_e32 v0, 1.0, v8
	v_mul_f32_e32 v6, v91, v9
	v_rcp_f32_e32 v0, v0
	v_mul_f32_e32 v6, 0xbfb8aa3b, v6
	v_exp_f32_e32 v6, v6
	v_add_u32_e32 v67, 0x14800, v4
	v_max_f32_e32 v0, 0x358637bd, v0
	v_cvt_pk_bf16_f32 v8, v0, s0
	v_add_f32_e32 v0, 1.0, v6
	v_rcp_f32_e32 v9, v0
	v_add_u32_e32 v0, v67, v3
	v_lshl_add_u64 v[6:7], v[0:1], 1, s[62:63]
	global_store_short v[6:7], v8, off
	v_max_f32_e32 v0, 0x358637bd, v9
	v_cvt_pk_bf16_f32 v8, v0, s0
	v_add_u32_e32 v0, v69, v3
	v_lshl_add_u64 v[6:7], v[0:1], 1, s[62:63]
	global_store_short v[6:7], v8, off
	ds_read2_b32 v[6:7], v2 offset0:88 offset1:89
	ds_read2_b32 v[8:9], v2 offset0:90 offset1:91
	v_add_u32_e32 v70, 0x16000, v4
	v_add_u32_e32 v73, 0x16c00, v4
	s_waitcnt lgkmcnt(1)
	v_mul_f32_e32 v0, v92, v6
	v_mul_f32_e32 v0, 0xbfb8aa3b, v0
	v_exp_f32_e32 v0, v0
	v_mul_f32_e32 v6, v93, v7
	v_mul_f32_e32 v6, 0xbfb8aa3b, v6
	v_exp_f32_e32 v6, v6
	v_add_f32_e32 v0, 1.0, v0
	v_rcp_f32_e32 v71, v0
	v_add_u32_e32 v0, v70, v3
	v_add_f32_e32 v6, 1.0, v6
	v_rcp_f32_e32 v72, v6
	v_lshl_add_u64 v[6:7], v[0:1], 1, s[62:63]
	v_max_f32_e32 v0, 0x358637bd, v71
	v_cvt_pk_bf16_f32 v0, v0, s0
	global_store_short v[6:7], v0, off
	s_waitcnt lgkmcnt(0)
	v_mul_f32_e32 v0, v94, v8
	v_mul_f32_e32 v0, 0xbfb8aa3b, v0
	v_exp_f32_e32 v8, v0
	v_max_f32_e32 v71, 0x358637bd, v72
	v_add_u32_e32 v72, 0x16400, v4
	v_add_u32_e32 v0, v72, v3
	v_cvt_pk_bf16_f32 v71, v71, s0
	v_lshl_add_u64 v[6:7], v[0:1], 1, s[62:63]
	global_store_short v[6:7], v71, off
	v_add_f32_e32 v0, 1.0, v8
	v_mul_f32_e32 v6, v95, v9
	v_rcp_f32_e32 v0, v0
	v_mul_f32_e32 v6, 0xbfb8aa3b, v6
	v_exp_f32_e32 v6, v6
	v_add_u32_e32 v71, 0x16800, v4
	v_max_f32_e32 v0, 0x358637bd, v0
	v_cvt_pk_bf16_f32 v8, v0, s0
	v_add_f32_e32 v0, 1.0, v6
	v_rcp_f32_e32 v9, v0
	v_add_u32_e32 v0, v71, v3
	v_lshl_add_u64 v[6:7], v[0:1], 1, s[62:63]
	global_store_short v[6:7], v8, off
	v_max_f32_e32 v0, 0x358637bd, v9
	v_cvt_pk_bf16_f32 v8, v0, s0
	v_add_u32_e32 v0, v73, v3
	v_lshl_add_u64 v[6:7], v[0:1], 1, s[62:63]
	global_store_short v[6:7], v8, off
	ds_read2_b32 v[6:7], v2 offset0:64 offset1:65
	ds_read2_b32 v[8:9], v2 offset0:66 offset1:67
	s_waitcnt lgkmcnt(1)
	v_mul_f32_e32 v0, v48, v6
	v_mul_f32_e32 v0, 0xbfb8aa3b, v0
	v_mul_f32_e32 v6, v49, v7
	v_exp_f32_e32 v7, v0
	v_mul_f32_e32 v6, 0xbfb8aa3b, v6
	v_exp_f32_e32 v6, v6
	v_add_u32_e32 v0, v10, v5
	v_add_f32_e32 v7, 1.0, v7
	v_rcp_f32_e32 v10, v7
	v_add_f32_e32 v6, 1.0, v6
	v_rcp_f32_e32 v48, v6
	v_lshl_add_u64 v[6:7], v[0:1], 1, s[62:63]
	s_waitcnt lgkmcnt(0)
	v_mul_f32_e32 v0, v50, v8
	v_max_f32_e32 v8, 0x358637bd, v10
	v_cvt_pk_bf16_f32 v8, v8, s0
	v_mul_f32_e32 v0, 0xbfb8aa3b, v0
	global_store_short v[6:7], v8, off
	v_exp_f32_e32 v8, v0
	v_add_u32_e32 v0, v12, v5
	v_lshl_add_u64 v[6:7], v[0:1], 1, s[62:63]
	v_max_f32_e32 v10, 0x358637bd, v48
	v_add_f32_e32 v0, 1.0, v8
	v_mul_f32_e32 v8, v51, v9
	v_rcp_f32_e32 v0, v0
	v_mul_f32_e32 v8, 0xbfb8aa3b, v8
	v_exp_f32_e32 v8, v8
	v_cvt_pk_bf16_f32 v10, v10, s0
	v_max_f32_e32 v0, 0x358637bd, v0
	v_cvt_pk_bf16_f32 v9, v0, s0
	v_add_f32_e32 v0, 1.0, v8
	v_rcp_f32_e32 v8, v0
	v_add_u32_e32 v0, v11, v5
	global_store_short v[6:7], v10, off
	v_lshl_add_u64 v[6:7], v[0:1], 1, s[62:63]
	v_max_f32_e32 v0, 0x358637bd, v8
	v_cvt_pk_bf16_f32 v8, v0, s0
	v_add_u32_e32 v0, v13, v5
	global_store_short v[6:7], v9, off
	v_lshl_add_u64 v[6:7], v[0:1], 1, s[62:63]
	global_store_short v[6:7], v8, off
	ds_read2_b32 v[6:7], v2 offset0:72 offset1:73
	ds_read2_b32 v[8:9], v2 offset0:74 offset1:75
	s_waitcnt lgkmcnt(1)
	v_mul_f32_e32 v0, v52, v6
	v_mul_f32_e32 v0, 0xbfb8aa3b, v0
	v_mul_f32_e32 v6, v53, v7
	v_exp_f32_e32 v7, v0
	v_mul_f32_e32 v6, 0xbfb8aa3b, v6
	v_exp_f32_e32 v6, v6
	v_add_u32_e32 v0, v14, v5
	v_add_f32_e32 v7, 1.0, v7
	v_rcp_f32_e32 v10, v7
	v_add_f32_e32 v6, 1.0, v6
	v_rcp_f32_e32 v11, v6
	v_lshl_add_u64 v[6:7], v[0:1], 1, s[62:63]
	s_waitcnt lgkmcnt(0)
	v_mul_f32_e32 v0, v54, v8
	v_max_f32_e32 v8, 0x358637bd, v10
	v_cvt_pk_bf16_f32 v8, v8, s0
	v_mul_f32_e32 v0, 0xbfb8aa3b, v0
	global_store_short v[6:7], v8, off
	v_exp_f32_e32 v8, v0
	v_add_u32_e32 v0, v64, v5
	v_lshl_add_u64 v[6:7], v[0:1], 1, s[62:63]
	v_max_f32_e32 v10, 0x358637bd, v11
	v_add_f32_e32 v0, 1.0, v8
	v_mul_f32_e32 v8, v55, v9
	v_rcp_f32_e32 v0, v0
	v_mul_f32_e32 v8, 0xbfb8aa3b, v8
	v_exp_f32_e32 v8, v8
	v_cvt_pk_bf16_f32 v10, v10, s0
	v_max_f32_e32 v0, 0x358637bd, v0
	v_cvt_pk_bf16_f32 v9, v0, s0
	v_add_f32_e32 v0, 1.0, v8
	v_rcp_f32_e32 v8, v0
	v_add_u32_e32 v0, v15, v5
	global_store_short v[6:7], v10, off
	v_lshl_add_u64 v[6:7], v[0:1], 1, s[62:63]
	v_max_f32_e32 v0, 0x358637bd, v8
	v_cvt_pk_bf16_f32 v8, v0, s0
	v_add_u32_e32 v0, v65, v5
	global_store_short v[6:7], v9, off
	v_lshl_add_u64 v[6:7], v[0:1], 1, s[62:63]
	global_store_short v[6:7], v8, off
	ds_read2_b32 v[6:7], v2 offset0:80 offset1:81
	ds_read2_b32 v[8:9], v2 offset0:82 offset1:83
	s_waitcnt lgkmcnt(1)
	v_mul_f32_e32 v0, v56, v6
	v_mul_f32_e32 v0, 0xbfb8aa3b, v0
	v_mul_f32_e32 v6, v57, v7
	v_exp_f32_e32 v7, v0
	v_mul_f32_e32 v6, 0xbfb8aa3b, v6
	v_exp_f32_e32 v6, v6
	v_add_u32_e32 v0, v66, v5
	v_add_f32_e32 v7, 1.0, v7
	v_rcp_f32_e32 v10, v7
	v_add_f32_e32 v6, 1.0, v6
	v_rcp_f32_e32 v11, v6
	v_lshl_add_u64 v[6:7], v[0:1], 1, s[62:63]
	s_waitcnt lgkmcnt(0)
	v_mul_f32_e32 v0, v58, v8
	v_max_f32_e32 v8, 0x358637bd, v10
	v_cvt_pk_bf16_f32 v8, v8, s0
	v_mul_f32_e32 v0, 0xbfb8aa3b, v0
	global_store_short v[6:7], v8, off
	v_exp_f32_e32 v8, v0
	v_add_u32_e32 v0, v68, v5
	v_lshl_add_u64 v[6:7], v[0:1], 1, s[62:63]
	v_max_f32_e32 v10, 0x358637bd, v11
	v_add_f32_e32 v0, 1.0, v8
	v_mul_f32_e32 v8, v59, v9
	v_rcp_f32_e32 v0, v0
	v_mul_f32_e32 v8, 0xbfb8aa3b, v8
	v_exp_f32_e32 v8, v8
	v_cvt_pk_bf16_f32 v10, v10, s0
	v_max_f32_e32 v0, 0x358637bd, v0
	v_cvt_pk_bf16_f32 v9, v0, s0
	v_add_f32_e32 v0, 1.0, v8
	v_rcp_f32_e32 v8, v0
	v_add_u32_e32 v0, v67, v5
	global_store_short v[6:7], v10, off
	v_lshl_add_u64 v[6:7], v[0:1], 1, s[62:63]
	v_max_f32_e32 v0, 0x358637bd, v8
	v_cvt_pk_bf16_f32 v8, v0, s0
	v_add_u32_e32 v0, v69, v5
	global_store_short v[6:7], v9, off
	v_lshl_add_u64 v[6:7], v[0:1], 1, s[62:63]
	global_store_short v[6:7], v8, off
	ds_read2_b32 v[6:7], v2 offset0:88 offset1:89
	ds_read2_b32 v[8:9], v2 offset0:90 offset1:91
	s_waitcnt lgkmcnt(1)
	v_mul_f32_e32 v0, v60, v6
	v_mul_f32_e32 v0, 0xbfb8aa3b, v0
	v_mul_f32_e32 v6, v61, v7
	v_exp_f32_e32 v7, v0
	v_mul_f32_e32 v6, 0xbfb8aa3b, v6
	v_exp_f32_e32 v6, v6
	v_add_u32_e32 v0, v70, v5
	v_add_f32_e32 v7, 1.0, v7
	v_rcp_f32_e32 v10, v7
	v_add_f32_e32 v6, 1.0, v6
	v_rcp_f32_e32 v11, v6
	v_lshl_add_u64 v[6:7], v[0:1], 1, s[62:63]
	s_waitcnt lgkmcnt(0)
	v_mul_f32_e32 v0, v62, v8
	v_max_f32_e32 v8, 0x358637bd, v10
	v_cvt_pk_bf16_f32 v8, v8, s0
	v_mul_f32_e32 v0, 0xbfb8aa3b, v0
	global_store_short v[6:7], v8, off
	v_exp_f32_e32 v8, v0
	v_add_u32_e32 v0, v72, v5
	v_lshl_add_u64 v[6:7], v[0:1], 1, s[62:63]
	v_max_f32_e32 v10, 0x358637bd, v11
	v_add_f32_e32 v0, 1.0, v8
	v_mul_f32_e32 v8, v63, v9
	v_rcp_f32_e32 v0, v0
	v_mul_f32_e32 v8, 0xbfb8aa3b, v8
	v_exp_f32_e32 v8, v8
	v_cvt_pk_bf16_f32 v10, v10, s0
	v_max_f32_e32 v0, 0x358637bd, v0
	v_cvt_pk_bf16_f32 v9, v0, s0
	v_add_f32_e32 v0, 1.0, v8
	v_rcp_f32_e32 v8, v0
	v_add_u32_e32 v0, v71, v5
	global_store_short v[6:7], v10, off
	v_lshl_add_u64 v[6:7], v[0:1], 1, s[62:63]
	v_max_f32_e32 v0, 0x358637bd, v8
	v_cvt_pk_bf16_f32 v8, v0, s0
	v_add_u32_e32 v0, v73, v5
	global_store_short v[6:7], v9, off
	v_lshl_add_u64 v[6:7], v[0:1], 1, s[62:63]
	global_store_short v[6:7], v8, off
	ds_read2_b32 v[6:7], v2 offset0:96 offset1:97
	ds_read2_b32 v[8:9], v2 offset0:98 offset1:99
	v_add_u32_e32 v10, 0x18000, v4
	v_add_u32_e32 v13, 0x18c00, v4
	s_waitcnt lgkmcnt(1)
	v_mul_f32_e32 v0, v32, v6
	v_mul_f32_e32 v0, 0xbfb8aa3b, v0
	v_exp_f32_e32 v0, v0
	v_mul_f32_e32 v6, v33, v7
	v_mul_f32_e32 v6, 0xbfb8aa3b, v6
	v_exp_f32_e32 v6, v6
	v_add_f32_e32 v0, 1.0, v0
	v_rcp_f32_e32 v11, v0
	v_add_u32_e32 v0, v10, v3
	v_add_f32_e32 v6, 1.0, v6
	v_rcp_f32_e32 v12, v6
	v_lshl_add_u64 v[6:7], v[0:1], 1, s[62:63]
	v_max_f32_e32 v0, 0x358637bd, v11
	v_cvt_pk_bf16_f32 v0, v0, s0
	global_store_short v[6:7], v0, off
	s_waitcnt lgkmcnt(0)
	v_mul_f32_e32 v0, v34, v8
	v_mul_f32_e32 v0, 0xbfb8aa3b, v0
	v_exp_f32_e32 v8, v0
	v_max_f32_e32 v11, 0x358637bd, v12
	v_add_u32_e32 v12, 0x18400, v4
	v_add_u32_e32 v0, v12, v3
	v_cvt_pk_bf16_f32 v11, v11, s0
	v_lshl_add_u64 v[6:7], v[0:1], 1, s[62:63]
	global_store_short v[6:7], v11, off
	v_add_f32_e32 v0, 1.0, v8
	v_mul_f32_e32 v6, v35, v9
	v_rcp_f32_e32 v0, v0
	v_mul_f32_e32 v6, 0xbfb8aa3b, v6
	v_exp_f32_e32 v6, v6
	v_add_u32_e32 v11, 0x18800, v4
	v_max_f32_e32 v0, 0x358637bd, v0
	v_cvt_pk_bf16_f32 v8, v0, s0
	v_add_f32_e32 v0, 1.0, v6
	v_rcp_f32_e32 v9, v0
	v_add_u32_e32 v0, v11, v3
	v_lshl_add_u64 v[6:7], v[0:1], 1, s[62:63]
	global_store_short v[6:7], v8, off
	v_max_f32_e32 v0, 0x358637bd, v9
	v_cvt_pk_bf16_f32 v8, v0, s0
	v_add_u32_e32 v0, v13, v3
	v_lshl_add_u64 v[6:7], v[0:1], 1, s[62:63]
	global_store_short v[6:7], v8, off
	ds_read2_b32 v[6:7], v2 offset0:104 offset1:105
	ds_read2_b32 v[8:9], v2 offset0:106 offset1:107
	v_add_u32_e32 v14, 0x1a000, v4
	v_add_u32_e32 v33, 0x1ac00, v4
	s_waitcnt lgkmcnt(1)
	v_mul_f32_e32 v0, v36, v6
	v_mul_f32_e32 v0, 0xbfb8aa3b, v0
	v_exp_f32_e32 v0, v0
	v_mul_f32_e32 v6, v37, v7
	v_mul_f32_e32 v6, 0xbfb8aa3b, v6
	v_exp_f32_e32 v6, v6
	v_add_f32_e32 v0, 1.0, v0
	v_rcp_f32_e32 v15, v0
	v_add_u32_e32 v0, v14, v3
	v_add_f32_e32 v6, 1.0, v6
	v_rcp_f32_e32 v32, v6
	v_lshl_add_u64 v[6:7], v[0:1], 1, s[62:63]
	v_max_f32_e32 v0, 0x358637bd, v15
	v_cvt_pk_bf16_f32 v0, v0, s0
	global_store_short v[6:7], v0, off
	s_waitcnt lgkmcnt(0)
	v_mul_f32_e32 v0, v38, v8
	v_mul_f32_e32 v0, 0xbfb8aa3b, v0
	v_exp_f32_e32 v8, v0
	v_max_f32_e32 v15, 0x358637bd, v32
	v_add_u32_e32 v32, 0x1a400, v4
	v_add_u32_e32 v0, v32, v3
	v_cvt_pk_bf16_f32 v15, v15, s0
	v_lshl_add_u64 v[6:7], v[0:1], 1, s[62:63]
	global_store_short v[6:7], v15, off
	v_add_f32_e32 v0, 1.0, v8
	v_mul_f32_e32 v6, v39, v9
	v_rcp_f32_e32 v0, v0
	v_mul_f32_e32 v6, 0xbfb8aa3b, v6
	v_exp_f32_e32 v6, v6
	v_add_u32_e32 v15, 0x1a800, v4
	v_max_f32_e32 v0, 0x358637bd, v0
	v_cvt_pk_bf16_f32 v8, v0, s0
	v_add_f32_e32 v0, 1.0, v6
	v_rcp_f32_e32 v9, v0
	v_add_u32_e32 v0, v15, v3
	v_lshl_add_u64 v[6:7], v[0:1], 1, s[62:63]
	global_store_short v[6:7], v8, off
	v_max_f32_e32 v0, 0x358637bd, v9
	v_cvt_pk_bf16_f32 v8, v0, s0
	v_add_u32_e32 v0, v33, v3
	v_lshl_add_u64 v[6:7], v[0:1], 1, s[62:63]
	global_store_short v[6:7], v8, off
	ds_read2_b32 v[6:7], v2 offset0:112 offset1:113
	ds_read2_b32 v[8:9], v2 offset0:114 offset1:115
	v_add_u32_e32 v34, 0x1c000, v4
	v_add_u32_e32 v37, 0x1cc00, v4
	s_waitcnt lgkmcnt(1)
	v_mul_f32_e32 v0, v40, v6
	v_mul_f32_e32 v0, 0xbfb8aa3b, v0
	v_exp_f32_e32 v0, v0
	v_mul_f32_e32 v6, v41, v7
	v_mul_f32_e32 v6, 0xbfb8aa3b, v6
	v_exp_f32_e32 v6, v6
	v_add_f32_e32 v0, 1.0, v0
	v_rcp_f32_e32 v35, v0
	v_add_u32_e32 v0, v34, v3
	v_add_f32_e32 v6, 1.0, v6
	v_rcp_f32_e32 v36, v6
	v_lshl_add_u64 v[6:7], v[0:1], 1, s[62:63]
	v_max_f32_e32 v0, 0x358637bd, v35
	v_cvt_pk_bf16_f32 v0, v0, s0
	global_store_short v[6:7], v0, off
	s_waitcnt lgkmcnt(0)
	v_mul_f32_e32 v0, v42, v8
	v_mul_f32_e32 v0, 0xbfb8aa3b, v0
	v_exp_f32_e32 v8, v0
	v_max_f32_e32 v35, 0x358637bd, v36
	v_add_u32_e32 v36, 0x1c400, v4
	v_add_u32_e32 v0, v36, v3
	v_cvt_pk_bf16_f32 v35, v35, s0
	v_lshl_add_u64 v[6:7], v[0:1], 1, s[62:63]
	global_store_short v[6:7], v35, off
	v_add_f32_e32 v0, 1.0, v8
	v_mul_f32_e32 v6, v43, v9
	v_rcp_f32_e32 v0, v0
	v_mul_f32_e32 v6, 0xbfb8aa3b, v6
	v_exp_f32_e32 v6, v6
	v_add_u32_e32 v35, 0x1c800, v4
	v_max_f32_e32 v0, 0x358637bd, v0
	v_cvt_pk_bf16_f32 v8, v0, s0
	v_add_f32_e32 v0, 1.0, v6
	v_rcp_f32_e32 v9, v0
	v_add_u32_e32 v0, v35, v3
	v_lshl_add_u64 v[6:7], v[0:1], 1, s[62:63]
	global_store_short v[6:7], v8, off
	v_max_f32_e32 v0, 0x358637bd, v9
	v_cvt_pk_bf16_f32 v8, v0, s0
	v_add_u32_e32 v0, v37, v3
	v_lshl_add_u64 v[6:7], v[0:1], 1, s[62:63]
	global_store_short v[6:7], v8, off
	ds_read2_b32 v[6:7], v2 offset0:120 offset1:121
	ds_read2_b32 v[8:9], v2 offset0:122 offset1:123
	v_add_u32_e32 v38, 0x1e000, v4
	s_waitcnt lgkmcnt(1)
	v_mul_f32_e32 v0, v44, v6
	v_mul_f32_e32 v0, 0xbfb8aa3b, v0
	v_exp_f32_e32 v0, v0
	v_mul_f32_e32 v6, v45, v7
	v_mul_f32_e32 v6, 0xbfb8aa3b, v6
	v_exp_f32_e32 v6, v6
	v_add_f32_e32 v0, 1.0, v0
	v_rcp_f32_e32 v39, v0
	v_add_u32_e32 v0, v38, v3
	v_add_f32_e32 v6, 1.0, v6
	v_rcp_f32_e32 v40, v6
	v_lshl_add_u64 v[6:7], v[0:1], 1, s[62:63]
	v_max_f32_e32 v0, 0x358637bd, v39
	v_cvt_pk_bf16_f32 v0, v0, s0
	global_store_short v[6:7], v0, off
	s_waitcnt lgkmcnt(0)
	v_mul_f32_e32 v0, v46, v8
	v_mul_f32_e32 v0, 0xbfb8aa3b, v0
	v_exp_f32_e32 v8, v0
	v_max_f32_e32 v39, 0x358637bd, v40
	v_add_u32_e32 v40, 0x1e400, v4
	v_add_u32_e32 v0, v40, v3
	v_cvt_pk_bf16_f32 v39, v39, s0
	v_lshl_add_u64 v[6:7], v[0:1], 1, s[62:63]
	global_store_short v[6:7], v39, off
	v_add_f32_e32 v0, 1.0, v8
	v_mul_f32_e32 v6, v47, v9
	v_rcp_f32_e32 v0, v0
	v_mul_f32_e32 v6, 0xbfb8aa3b, v6
	v_exp_f32_e32 v6, v6
	v_add_u32_e32 v39, 0x1e800, v4
	v_max_f32_e32 v0, 0x358637bd, v0
	v_cvt_pk_bf16_f32 v8, v0, s0
	v_add_f32_e32 v0, 1.0, v6
	v_rcp_f32_e32 v9, v0
	v_add_u32_e32 v0, v39, v3
	v_lshl_add_u64 v[6:7], v[0:1], 1, s[62:63]
	v_add_u32_e32 v4, 0x1ec00, v4
	v_max_f32_e32 v0, 0x358637bd, v9
	global_store_short v[6:7], v8, off
	v_cvt_pk_bf16_f32 v8, v0, s0
	v_add_u32_e32 v0, v4, v3
	v_lshl_add_u64 v[6:7], v[0:1], 1, s[62:63]
	global_store_short v[6:7], v8, off
	ds_read2_b32 v[6:7], v2 offset0:96 offset1:97
	ds_read2_b32 v[8:9], v2 offset0:98 offset1:99
	s_waitcnt lgkmcnt(1)
	v_mul_f32_e32 v0, v16, v6
	v_mul_f32_e32 v0, 0xbfb8aa3b, v0
	v_exp_f32_e32 v6, v0
	v_add_u32_e32 v0, v10, v5
	v_mul_f32_e32 v3, v17, v7
	v_mul_f32_e32 v3, 0xbfb8aa3b, v3
	v_add_f32_e32 v6, 1.0, v6
	v_rcp_f32_e32 v10, v6
	v_lshl_add_u64 v[6:7], v[0:1], 1, s[62:63]
	s_waitcnt lgkmcnt(0)
	v_mul_f32_e32 v0, v18, v8
	v_exp_f32_e32 v3, v3
	v_max_f32_e32 v8, 0x358637bd, v10
	v_cvt_pk_bf16_f32 v8, v8, s0
	v_mul_f32_e32 v0, 0xbfb8aa3b, v0
	global_store_short v[6:7], v8, off
	v_exp_f32_e32 v8, v0
	v_add_f32_e32 v3, 1.0, v3
	v_add_u32_e32 v0, v12, v5
	v_rcp_f32_e32 v3, v3
	v_lshl_add_u64 v[6:7], v[0:1], 1, s[62:63]
	v_add_f32_e32 v0, 1.0, v8
	v_mul_f32_e32 v8, v19, v9
	v_rcp_f32_e32 v0, v0
	v_mul_f32_e32 v8, 0xbfb8aa3b, v8
	v_exp_f32_e32 v8, v8
	v_max_f32_e32 v3, 0x358637bd, v3
	v_cvt_pk_bf16_f32 v3, v3, s0
	v_max_f32_e32 v0, 0x358637bd, v0
	global_store_short v[6:7], v3, off
	v_cvt_pk_bf16_f32 v3, v0, s0
	v_add_f32_e32 v0, 1.0, v8
	v_rcp_f32_e32 v8, v0
	v_add_u32_e32 v0, v11, v5
	v_lshl_add_u64 v[6:7], v[0:1], 1, s[62:63]
	global_store_short v[6:7], v3, off
	v_max_f32_e32 v0, 0x358637bd, v8
	v_cvt_pk_bf16_f32 v3, v0, s0
	v_add_u32_e32 v0, v13, v5
	v_lshl_add_u64 v[6:7], v[0:1], 1, s[62:63]
	global_store_short v[6:7], v3, off
	ds_read2_b32 v[6:7], v2 offset0:104 offset1:105
	ds_read2_b32 v[8:9], v2 offset0:106 offset1:107
	s_waitcnt lgkmcnt(1)
	v_mul_f32_e32 v0, v20, v6
	v_mul_f32_e32 v0, 0xbfb8aa3b, v0
	v_exp_f32_e32 v6, v0
	v_mul_f32_e32 v3, v21, v7
	v_add_u32_e32 v0, v14, v5
	v_mul_f32_e32 v3, 0xbfb8aa3b, v3
	v_add_f32_e32 v6, 1.0, v6
	v_rcp_f32_e32 v10, v6
	v_lshl_add_u64 v[6:7], v[0:1], 1, s[62:63]
	s_waitcnt lgkmcnt(0)
	v_mul_f32_e32 v0, v22, v8
	v_exp_f32_e32 v3, v3
	v_max_f32_e32 v8, 0x358637bd, v10
	v_cvt_pk_bf16_f32 v8, v8, s0
	v_mul_f32_e32 v0, 0xbfb8aa3b, v0
	global_store_short v[6:7], v8, off
	v_exp_f32_e32 v8, v0
	v_add_f32_e32 v3, 1.0, v3
	v_add_u32_e32 v0, v32, v5
	v_rcp_f32_e32 v3, v3
	v_lshl_add_u64 v[6:7], v[0:1], 1, s[62:63]
	v_add_f32_e32 v0, 1.0, v8
	v_mul_f32_e32 v8, v23, v9
	v_rcp_f32_e32 v0, v0
	v_mul_f32_e32 v8, 0xbfb8aa3b, v8
	v_exp_f32_e32 v8, v8
	v_max_f32_e32 v3, 0x358637bd, v3
	v_cvt_pk_bf16_f32 v3, v3, s0
	v_max_f32_e32 v0, 0x358637bd, v0
	global_store_short v[6:7], v3, off
	v_cvt_pk_bf16_f32 v3, v0, s0
	v_add_f32_e32 v0, 1.0, v8
	v_rcp_f32_e32 v8, v0
	v_add_u32_e32 v0, v15, v5
	v_lshl_add_u64 v[6:7], v[0:1], 1, s[62:63]
	global_store_short v[6:7], v3, off
	v_max_f32_e32 v0, 0x358637bd, v8
	v_cvt_pk_bf16_f32 v3, v0, s0
	v_add_u32_e32 v0, v33, v5
	v_lshl_add_u64 v[6:7], v[0:1], 1, s[62:63]
	global_store_short v[6:7], v3, off
	ds_read2_b32 v[6:7], v2 offset0:112 offset1:113
	ds_read2_b32 v[8:9], v2 offset0:114 offset1:115
	s_waitcnt lgkmcnt(1)
	v_mul_f32_e32 v0, v24, v6
	v_mul_f32_e32 v0, 0xbfb8aa3b, v0
	v_exp_f32_e32 v6, v0
	v_mul_f32_e32 v3, v25, v7
	v_add_u32_e32 v0, v34, v5
	v_mul_f32_e32 v3, 0xbfb8aa3b, v3
	v_add_f32_e32 v6, 1.0, v6
	v_rcp_f32_e32 v10, v6
	v_lshl_add_u64 v[6:7], v[0:1], 1, s[62:63]
	s_waitcnt lgkmcnt(0)
	v_mul_f32_e32 v0, v26, v8
	v_exp_f32_e32 v3, v3
	v_max_f32_e32 v8, 0x358637bd, v10
	v_cvt_pk_bf16_f32 v8, v8, s0
	v_mul_f32_e32 v0, 0xbfb8aa3b, v0
	global_store_short v[6:7], v8, off
	v_exp_f32_e32 v8, v0
	v_add_f32_e32 v3, 1.0, v3
	v_add_u32_e32 v0, v36, v5
	v_rcp_f32_e32 v3, v3
	v_lshl_add_u64 v[6:7], v[0:1], 1, s[62:63]
	v_add_f32_e32 v0, 1.0, v8
	v_mul_f32_e32 v8, v27, v9
	v_rcp_f32_e32 v0, v0
	v_mul_f32_e32 v8, 0xbfb8aa3b, v8
	v_exp_f32_e32 v8, v8
	v_max_f32_e32 v3, 0x358637bd, v3
	v_cvt_pk_bf16_f32 v3, v3, s0
	v_max_f32_e32 v0, 0x358637bd, v0
	global_store_short v[6:7], v3, off
	v_cvt_pk_bf16_f32 v3, v0, s0
	v_add_f32_e32 v0, 1.0, v8
	v_rcp_f32_e32 v8, v0
	v_add_u32_e32 v0, v35, v5
	v_lshl_add_u64 v[6:7], v[0:1], 1, s[62:63]
	global_store_short v[6:7], v3, off
	v_max_f32_e32 v0, 0x358637bd, v8
	v_cvt_pk_bf16_f32 v3, v0, s0
	v_add_u32_e32 v0, v37, v5
	v_lshl_add_u64 v[6:7], v[0:1], 1, s[62:63]
	global_store_short v[6:7], v3, off
	ds_read2_b32 v[6:7], v2 offset0:120 offset1:121
	ds_read2_b32 v[2:3], v2 offset0:122 offset1:123
	s_waitcnt lgkmcnt(1)
	v_mul_f32_e32 v0, v28, v6
	v_mul_f32_e32 v0, 0xbfb8aa3b, v0
	v_mul_f32_e32 v6, v29, v7
	v_exp_f32_e32 v7, v0
	v_mul_f32_e32 v6, 0xbfb8aa3b, v6
	v_exp_f32_e32 v6, v6
	v_add_u32_e32 v0, v38, v5
	v_add_f32_e32 v7, 1.0, v7
	v_rcp_f32_e32 v8, v7
	v_add_f32_e32 v6, 1.0, v6
	v_rcp_f32_e32 v9, v6
	v_lshl_add_u64 v[6:7], v[0:1], 1, s[62:63]
	s_waitcnt lgkmcnt(0)
	v_mul_f32_e32 v0, v30, v2
	v_max_f32_e32 v2, 0x358637bd, v8
	v_cvt_pk_bf16_f32 v2, v2, s0
	v_mul_f32_e32 v0, 0xbfb8aa3b, v0
	global_store_short v[6:7], v2, off
	v_exp_f32_e32 v2, v0
	v_add_u32_e32 v0, v40, v5
	v_lshl_add_u64 v[6:7], v[0:1], 1, s[62:63]
	v_max_f32_e32 v8, 0x358637bd, v9
	v_add_f32_e32 v0, 1.0, v2
	v_mul_f32_e32 v2, v31, v3
	v_rcp_f32_e32 v0, v0
	v_mul_f32_e32 v2, 0xbfb8aa3b, v2
	v_exp_f32_e32 v2, v2
	v_cvt_pk_bf16_f32 v8, v8, s0
	v_max_f32_e32 v0, 0x358637bd, v0
	global_store_short v[6:7], v8, off
	v_cvt_pk_bf16_f32 v6, v0, s0
	v_add_f32_e32 v0, 1.0, v2
	v_rcp_f32_e32 v7, v0
	v_add_u32_e32 v0, v39, v5
	v_lshl_add_u64 v[2:3], v[0:1], 1, s[62:63]
	global_store_short v[2:3], v6, off
	v_max_f32_e32 v0, 0x358637bd, v7
	v_cvt_pk_bf16_f32 v6, v0, s0
	v_add_u32_e32 v0, v4, v5
	v_lshl_add_u64 v[2:3], v[0:1], 1, s[62:63]
	global_store_short v[2:3], v6, off
.Ltep_e2_e:
	s_add_i32 s37, s37, s92
	s_cmpk_lt_i32 s37, 0x104
	s_cbranch_scc0 .LBB0_3372

.LBB0_3355:
	s_lshl_b64 s[22:23], s[10:11], 10
	s_cmpk_lt_i32 s8, 0x4000
	s_cbranch_scc1 .Ltep_e1_f
	v_readfirstlane_b32 s64, v208
	s_bitcmp1_b32 s64, 8
	s_cbranch_scc0 .Ltep_e1_f
	s_waitcnt vmcnt(0)
	s_branch .Ltep_e1_e
.Ltep_e1_f:
	v_mov_b32_e32 v0, v208
	s_waitcnt vmcnt(7)
	v_mov_b32_e32 v131, v1
	v_lshrrev_b32_e32 v132, 3, v0
	v_ashrrev_i32_e32 v130, 1, v0
	v_and_b32_e32 v132, 4, v132
	s_waitcnt vmcnt(6)
	v_and_or_b32 v136, v130, s34, v132
	v_lshlrev_b32_e32 v132, 2, v136
	v_lshlrev_b32_e32 v130, 2, v131
	v_add3_u32 v130, v130, v132, s33
	ds_read2_b32 v[132:133], v130 offset1:1
	ds_read2_b32 v[134:135], v130 offset0:2 offset1:3
	v_and_b32_e32 v0, 0xdf, v0
	v_or_b32_e32 v0, s10, v0
	s_waitcnt lgkmcnt(1)
	v_mul_f32_e32 v114, v114, v132
	v_mul_f32_e32 v114, 0xbfb8aa3b, v114
	v_exp_f32_e32 v114, v114
	s_nop 0
	v_add_f32_e32 v114, 1.0, v114
	v_rcp_f32_e32 v132, v114
	v_mul_f32_e32 v114, v115, v133
	v_mul_f32_e32 v114, 0xbfb8aa3b, v114
	v_exp_f32_e32 v115, v114
	v_add_u32_e32 v114, v0, v131
	v_add_lshl_u32 v131, v136, s8, 10
	v_cvt_pk_bf16_f32 v137, v132, s0
	v_add_f32_e32 v0, 1.0, v115
	v_rcp_f32_e32 v115, v0
	v_add_u32_e32 v0, v131, v114
	v_lshl_add_u64 v[132:133], v[0:1], 1, s[18:19]
	s_waitcnt lgkmcnt(0)
	v_mul_f32_e32 v0, v116, v134
	v_mul_f32_e32 v0, 0xbfb8aa3b, v0
	v_exp_f32_e32 v116, v0
	v_add_u32_e32 v134, 0x400, v131
	v_add_u32_e32 v0, v134, v114
	global_store_short v[132:133], v137, off
	v_lshl_add_u64 v[132:133], v[0:1], 1, s[18:19]
	v_add_f32_e32 v0, 1.0, v116
	v_mul_f32_e32 v116, v117, v135
	v_mul_f32_e32 v116, 0xbfb8aa3b, v116
	v_rcp_f32_e32 v0, v0
	v_exp_f32_e32 v116, v116
	v_cvt_pk_bf16_f32 v115, v115, s0
	global_store_short v[132:133], v115, off
	v_cvt_pk_bf16_f32 v115, v0, s0
	v_add_f32_e32 v0, 1.0, v116
	v_rcp_f32_e32 v132, v0
	v_add_u32_e32 v135, 0x800, v131
	v_add_u32_e32 v0, v135, v114
	v_add_u32_e32 v136, 0xc00, v131
	v_lshl_add_u64 v[116:117], v[0:1], 1, s[18:19]
	v_add_u32_e32 v0, v136, v114
	global_store_short v[116:117], v115, off
	v_cvt_pk_bf16_f32 v115, v132, s0
	v_lshl_add_u64 v[116:117], v[0:1], 1, s[18:19]
	global_store_short v[116:117], v115, off
	ds_read2_b32 v[116:117], v130 offset0:8 offset1:9
	ds_read2_b32 v[132:133], v130 offset0:10 offset1:11
	v_add_u32_e32 v137, 0x2000, v131
	s_waitcnt vmcnt(8)
	v_add_u32_e32 v138, 0x2c00, v131
	s_waitcnt lgkmcnt(1)
	v_mul_f32_e32 v0, v118, v116
	v_mul_f32_e32 v0, 0xbfb8aa3b, v0
	v_exp_f32_e32 v0, v0
	v_mul_f32_e32 v115, v119, v117
	v_mul_f32_e32 v115, 0xbfb8aa3b, v115
	v_exp_f32_e32 v115, v115
	v_add_f32_e32 v0, 1.0, v0
	v_rcp_f32_e32 v118, v0
	v_add_u32_e32 v0, v137, v114
	v_lshl_add_u64 v[116:117], v[0:1], 1, s[18:19]
	v_add_f32_e32 v115, 1.0, v115
	v_cvt_pk_bf16_f32 v0, v118, s0
	global_store_short v[116:117], v0, off
	s_waitcnt lgkmcnt(0)
	v_mul_f32_e32 v0, v120, v132
	v_mul_f32_e32 v0, 0xbfb8aa3b, v0
	v_exp_f32_e32 v118, v0
	v_add_u32_e32 v132, 0x2400, v131
	v_add_u32_e32 v0, v132, v114
	v_lshl_add_u64 v[116:117], v[0:1], 1, s[18:19]
	v_add_f32_e32 v0, 1.0, v118
	v_mul_f32_e32 v118, v121, v133
	v_rcp_f32_e32 v115, v115
	v_mul_f32_e32 v118, 0xbfb8aa3b, v118
	v_rcp_f32_e32 v0, v0
	v_exp_f32_e32 v118, v118
	v_cvt_pk_bf16_f32 v115, v115, s0
	global_store_short v[116:117], v115, off
	v_cvt_pk_bf16_f32 v115, v0, s0
	v_add_f32_e32 v0, 1.0, v118
	v_rcp_f32_e32 v118, v0
	v_add_u32_e32 v133, 0x2800, v131
	v_add_u32_e32 v0, v133, v114
	v_lshl_add_u64 v[116:117], v[0:1], 1, s[18:19]
	v_add_u32_e32 v0, v138, v114
	global_store_short v[116:117], v115, off
	v_cvt_pk_bf16_f32 v115, v118, s0
	v_lshl_add_u64 v[116:117], v[0:1], 1, s[18:19]
	global_store_short v[116:117], v115, off
	ds_read2_b32 v[116:117], v130 offset0:16 offset1:17
	ds_read2_b32 v[118:119], v130 offset0:18 offset1:19
	s_waitcnt lgkmcnt(1)
	v_mul_f32_e32 v0, v122, v116
	v_mul_f32_e32 v0, 0xbfb8aa3b, v0
	v_exp_f32_e32 v0, v0
	v_add_u32_e32 v122, 0x4000, v131
	v_mul_f32_e32 v115, v123, v117
	v_mul_f32_e32 v115, 0xbfb8aa3b, v115
	v_add_f32_e32 v0, 1.0, v0
	v_rcp_f32_e32 v120, v0
	v_add_u32_e32 v0, v122, v114
	v_lshl_add_u64 v[116:117], v[0:1], 1, s[18:19]
	v_exp_f32_e32 v115, v115
	v_cvt_pk_bf16_f32 v0, v120, s0
	global_store_short v[116:117], v0, off
	s_waitcnt lgkmcnt(0)
	v_mul_f32_e32 v0, v124, v118
	v_mul_f32_e32 v0, 0xbfb8aa3b, v0
	v_exp_f32_e32 v118, v0
	v_add_u32_e32 v123, 0x4400, v131
	v_add_u32_e32 v0, v123, v114
	v_add_f32_e32 v115, 1.0, v115
	v_lshl_add_u64 v[116:117], v[0:1], 1, s[18:19]
	v_add_f32_e32 v0, 1.0, v118
	v_mul_f32_e32 v118, v125, v119
	v_rcp_f32_e32 v115, v115
	v_mul_f32_e32 v118, 0xbfb8aa3b, v118
	v_rcp_f32_e32 v0, v0
	v_exp_f32_e32 v118, v118
	v_cvt_pk_bf16_f32 v115, v115, s0
	global_store_short v[116:117], v115, off
	v_cvt_pk_bf16_f32 v115, v0, s0
	v_add_f32_e32 v0, 1.0, v118
	v_rcp_f32_e32 v118, v0
	v_add_u32_e32 v124, 0x4800, v131
	v_add_u32_e32 v0, v124, v114
	v_add_u32_e32 v125, 0x4c00, v131
	v_lshl_add_u64 v[116:117], v[0:1], 1, s[18:19]
	v_add_u32_e32 v0, v125, v114
	global_store_short v[116:117], v115, off
	v_cvt_pk_bf16_f32 v115, v118, s0
	v_lshl_add_u64 v[116:117], v[0:1], 1, s[18:19]
	global_store_short v[116:117], v115, off
	ds_read2_b32 v[116:117], v130 offset0:24 offset1:25
	ds_read2_b32 v[118:119], v130 offset0:26 offset1:27
	s_waitcnt lgkmcnt(1)
	v_mul_f32_e32 v0, v126, v116
	v_mul_f32_e32 v0, 0xbfb8aa3b, v0
	v_exp_f32_e32 v0, v0
	v_add_u32_e32 v126, 0x6000, v131
	v_mul_f32_e32 v115, v127, v117
	v_mul_f32_e32 v115, 0xbfb8aa3b, v115
	v_add_f32_e32 v0, 1.0, v0
	v_rcp_f32_e32 v120, v0
	v_add_u32_e32 v0, v126, v114
	v_lshl_add_u64 v[116:117], v[0:1], 1, s[18:19]
	v_exp_f32_e32 v115, v115
	v_cvt_pk_bf16_f32 v0, v120, s0
	global_store_short v[116:117], v0, off
	s_waitcnt lgkmcnt(0)
	v_mul_f32_e32 v0, v128, v118
	v_mul_f32_e32 v0, 0xbfb8aa3b, v0
	v_exp_f32_e32 v118, v0
	v_add_u32_e32 v127, 0x6400, v131
	v_add_u32_e32 v0, v127, v114
	v_add_f32_e32 v115, 1.0, v115
	v_lshl_add_u64 v[116:117], v[0:1], 1, s[18:19]
	v_add_f32_e32 v0, 1.0, v118
	v_mul_f32_e32 v118, v129, v119
	v_rcp_f32_e32 v115, v115
	v_mul_f32_e32 v118, 0xbfb8aa3b, v118
	v_rcp_f32_e32 v0, v0
	v_exp_f32_e32 v118, v118
	v_cvt_pk_bf16_f32 v115, v115, s0
	global_store_short v[116:117], v115, off
	v_cvt_pk_bf16_f32 v115, v0, s0
	v_add_f32_e32 v0, 1.0, v118
	v_rcp_f32_e32 v118, v0
	v_add_u32_e32 v128, 0x6800, v131
	v_add_u32_e32 v0, v128, v114
	v_add_u32_e32 v129, 0x6c00, v131
	v_lshl_add_u64 v[116:117], v[0:1], 1, s[18:19]
	v_add_u32_e32 v0, v129, v114
	global_store_short v[116:117], v115, off
	v_cvt_pk_bf16_f32 v115, v118, s0
	v_lshl_add_u64 v[116:117], v[0:1], 1, s[18:19]
	global_store_short v[116:117], v115, off
	ds_read2_b32 v[116:117], v130 offset1:1
	ds_read2_b32 v[118:119], v130 offset0:2 offset1:3
	v_add_u32_e32 v115, 32, v114
	v_add_u32_e32 v0, v131, v115
	v_lshl_add_u64 v[120:121], v[0:1], 1, s[18:19]
	s_waitcnt lgkmcnt(1)
	v_mul_f32_e32 v0, v98, v116
	v_mul_f32_e32 v98, v99, v117
	v_mul_f32_e32 v98, 0xbfb8aa3b, v98
	v_exp_f32_e32 v98, v98
	s_waitcnt lgkmcnt(0)
	v_mul_f32_e32 v99, v100, v118
	v_mul_f32_e32 v0, 0xbfb8aa3b, v0
	v_mul_f32_e32 v99, 0xbfb8aa3b, v99
	v_add_f32_e32 v98, 1.0, v98
	v_exp_f32_e32 v0, v0
	v_rcp_f32_e32 v98, v98
	v_exp_f32_e32 v99, v99
	v_add_f32_e32 v0, 1.0, v0
	v_cvt_pk_bf16_f32 v100, v98, s0
	v_add_f32_e32 v98, 1.0, v99
	v_rcp_f32_e32 v0, v0
	v_rcp_f32_e32 v116, v98
	v_mul_f32_e32 v98, v101, v119
	v_mul_f32_e32 v98, 0xbfb8aa3b, v98
	v_exp_f32_e32 v101, v98
	v_cvt_pk_bf16_f32 v0, v0, s0
	global_store_short v[120:121], v0, off
	v_add_u32_e32 v0, v134, v115
	v_lshl_add_u64 v[98:99], v[0:1], 1, s[18:19]
	v_add_f32_e32 v0, 1.0, v101
	v_rcp_f32_e32 v101, v0
	v_add_u32_e32 v0, v135, v115
	global_store_short v[98:99], v100, off
	v_cvt_pk_bf16_f32 v100, v116, s0
	v_lshl_add_u64 v[98:99], v[0:1], 1, s[18:19]
	v_add_u32_e32 v0, v136, v115
	global_store_short v[98:99], v100, off
	v_cvt_pk_bf16_f32 v100, v101, s0
	v_lshl_add_u64 v[98:99], v[0:1], 1, s[18:19]
	global_store_short v[98:99], v100, off
	ds_read2_b32 v[98:99], v130 offset0:8 offset1:9
	ds_read2_b32 v[100:101], v130 offset0:10 offset1:11
	v_add_u32_e32 v0, v137, v115
	v_lshl_add_u64 v[116:117], v[0:1], 1, s[18:19]
	s_waitcnt lgkmcnt(1)
	v_mul_f32_e32 v0, v102, v98
	v_mul_f32_e32 v98, v103, v99
	v_mul_f32_e32 v98, 0xbfb8aa3b, v98
	v_exp_f32_e32 v98, v98
	s_waitcnt lgkmcnt(0)
	v_mul_f32_e32 v99, v104, v100
	v_mul_f32_e32 v0, 0xbfb8aa3b, v0
	v_mul_f32_e32 v99, 0xbfb8aa3b, v99
	v_add_f32_e32 v98, 1.0, v98
	v_exp_f32_e32 v0, v0
	v_rcp_f32_e32 v98, v98
	v_exp_f32_e32 v99, v99
	v_add_f32_e32 v0, 1.0, v0
	v_cvt_pk_bf16_f32 v100, v98, s0
	v_add_f32_e32 v98, 1.0, v99
	v_rcp_f32_e32 v0, v0
	v_rcp_f32_e32 v102, v98
	v_mul_f32_e32 v98, v105, v101
	v_mul_f32_e32 v98, 0xbfb8aa3b, v98
	v_exp_f32_e32 v101, v98
	v_cvt_pk_bf16_f32 v0, v0, s0
	global_store_short v[116:117], v0, off
	v_add_u32_e32 v0, v132, v115
	v_lshl_add_u64 v[98:99], v[0:1], 1, s[18:19]
	v_add_f32_e32 v0, 1.0, v101
	v_rcp_f32_e32 v101, v0
	v_add_u32_e32 v0, v133, v115
	global_store_short v[98:99], v100, off
	v_cvt_pk_bf16_f32 v100, v102, s0
	v_lshl_add_u64 v[98:99], v[0:1], 1, s[18:19]
	v_add_u32_e32 v0, v138, v115
	global_store_short v[98:99], v100, off
	v_cvt_pk_bf16_f32 v100, v101, s0
	v_lshl_add_u64 v[98:99], v[0:1], 1, s[18:19]
	global_store_short v[98:99], v100, off
	ds_read2_b32 v[98:99], v130 offset0:16 offset1:17
	ds_read2_b32 v[100:101], v130 offset0:18 offset1:19
	v_add_u32_e32 v0, v122, v115
	v_lshl_add_u64 v[102:103], v[0:1], 1, s[18:19]
	s_waitcnt lgkmcnt(1)
	v_mul_f32_e32 v0, v106, v98
	v_mul_f32_e32 v98, v107, v99
	v_mul_f32_e32 v0, 0xbfb8aa3b, v0
	v_mul_f32_e32 v98, 0xbfb8aa3b, v98
	v_exp_f32_e32 v0, v0
	v_exp_f32_e32 v98, v98
	s_waitcnt lgkmcnt(0)
	v_mul_f32_e32 v99, v108, v100
	v_mul_f32_e32 v99, 0xbfb8aa3b, v99
	v_add_f32_e32 v0, 1.0, v0
	v_add_f32_e32 v98, 1.0, v98
	v_rcp_f32_e32 v0, v0
	v_rcp_f32_e32 v98, v98
	v_exp_f32_e32 v99, v99
	v_cvt_pk_bf16_f32 v0, v0, s0
	v_cvt_pk_bf16_f32 v100, v98, s0
	v_add_f32_e32 v98, 1.0, v99
	global_store_short v[102:103], v0, off
	v_rcp_f32_e32 v102, v98
	v_mul_f32_e32 v98, v109, v101
	v_mul_f32_e32 v98, 0xbfb8aa3b, v98
	v_exp_f32_e32 v101, v98
	v_add_u32_e32 v0, v123, v115
	v_lshl_add_u64 v[98:99], v[0:1], 1, s[18:19]
	global_store_short v[98:99], v100, off
	v_add_f32_e32 v0, 1.0, v101
	v_rcp_f32_e32 v101, v0
	v_add_u32_e32 v0, v124, v115
	v_cvt_pk_bf16_f32 v100, v102, s0
	v_lshl_add_u64 v[98:99], v[0:1], 1, s[18:19]
	v_add_u32_e32 v0, v125, v115
	global_store_short v[98:99], v100, off
	v_cvt_pk_bf16_f32 v100, v101, s0
	v_lshl_add_u64 v[98:99], v[0:1], 1, s[18:19]
	global_store_short v[98:99], v100, off
	ds_read2_b32 v[98:99], v130 offset0:24 offset1:25
	ds_read2_b32 v[100:101], v130 offset0:26 offset1:27
	v_add_u32_e32 v0, v126, v115
	v_lshl_add_u64 v[102:103], v[0:1], 1, s[18:19]
	s_waitcnt lgkmcnt(1)
	v_mul_f32_e32 v0, v110, v98
	v_mul_f32_e32 v98, v111, v99
	v_mul_f32_e32 v0, 0xbfb8aa3b, v0
	v_mul_f32_e32 v98, 0xbfb8aa3b, v98
	v_exp_f32_e32 v0, v0
	v_exp_f32_e32 v98, v98
	s_waitcnt lgkmcnt(0)
	v_mul_f32_e32 v99, v112, v100
	v_mul_f32_e32 v99, 0xbfb8aa3b, v99
	v_add_f32_e32 v0, 1.0, v0
	v_add_f32_e32 v98, 1.0, v98
	v_rcp_f32_e32 v0, v0
	v_rcp_f32_e32 v98, v98
	v_exp_f32_e32 v99, v99
	v_cvt_pk_bf16_f32 v0, v0, s0
	v_cvt_pk_bf16_f32 v100, v98, s0
	v_add_f32_e32 v98, 1.0, v99
	global_store_short v[102:103], v0, off
	v_rcp_f32_e32 v102, v98
	v_mul_f32_e32 v98, v113, v101
	v_mul_f32_e32 v98, 0xbfb8aa3b, v98
	v_exp_f32_e32 v101, v98
	v_add_u32_e32 v0, v127, v115
	v_lshl_add_u64 v[98:99], v[0:1], 1, s[18:19]
	global_store_short v[98:99], v100, off
	v_add_f32_e32 v0, 1.0, v101
	v_rcp_f32_e32 v101, v0
	v_add_u32_e32 v0, v128, v115
	v_cvt_pk_bf16_f32 v100, v102, s0
	v_lshl_add_u64 v[98:99], v[0:1], 1, s[18:19]
	v_add_u32_e32 v0, v129, v115
	global_store_short v[98:99], v100, off
	v_cvt_pk_bf16_f32 v100, v101, s0
	v_lshl_add_u64 v[98:99], v[0:1], 1, s[18:19]
	global_store_short v[98:99], v100, off
	ds_read2_b32 v[98:99], v130 offset0:32 offset1:33
	ds_read2_b32 v[100:101], v130 offset0:34 offset1:35
	s_waitcnt lgkmcnt(1)
	v_mul_f32_e32 v0, v82, v98
	v_mul_f32_e32 v0, 0xbfb8aa3b, v0
	v_exp_f32_e32 v0, v0
	v_mul_f32_e32 v82, v83, v99
	v_mul_f32_e32 v82, 0xbfb8aa3b, v82
	v_exp_f32_e32 v82, v82
	v_add_f32_e32 v0, 1.0, v0
	v_rcp_f32_e32 v99, v0
	v_add_u32_e32 v98, 0x8000, v131
	v_add_f32_e32 v82, 1.0, v82
	v_add_u32_e32 v0, v98, v114
	v_rcp_f32_e32 v102, v82
	v_lshl_add_u64 v[82:83], v[0:1], 1, s[18:19]
	v_cvt_pk_bf16_f32 v0, v99, s0
	global_store_short v[82:83], v0, off
	s_waitcnt lgkmcnt(0)
	v_mul_f32_e32 v0, v84, v100
	v_mul_f32_e32 v0, 0xbfb8aa3b, v0
	v_exp_f32_e32 v84, v0
	v_add_u32_e32 v100, 0x8400, v131
	v_add_u32_e32 v0, v100, v114
	v_lshl_add_u64 v[82:83], v[0:1], 1, s[18:19]
	v_add_f32_e32 v0, 1.0, v84
	v_mul_f32_e32 v84, v85, v101
	v_mul_f32_e32 v84, 0xbfb8aa3b, v84
	v_rcp_f32_e32 v0, v0
	v_exp_f32_e32 v84, v84
	v_cvt_pk_bf16_f32 v99, v102, s0
	global_store_short v[82:83], v99, off
	v_cvt_pk_bf16_f32 v85, v0, s0
	v_add_f32_e32 v0, 1.0, v84
	v_rcp_f32_e32 v84, v0
	v_add_u32_e32 v99, 0x8800, v131
	v_add_u32_e32 v0, v99, v114
	v_add_u32_e32 v101, 0x8c00, v131
	v_lshl_add_u64 v[82:83], v[0:1], 1, s[18:19]
	v_add_u32_e32 v0, v101, v114
	global_store_short v[82:83], v85, off
	v_cvt_pk_bf16_f32 v84, v84, s0
	v_lshl_add_u64 v[82:83], v[0:1], 1, s[18:19]
	global_store_short v[82:83], v84, off
	ds_read2_b32 v[82:83], v130 offset0:40 offset1:41
	ds_read2_b32 v[84:85], v130 offset0:42 offset1:43
	v_add_u32_e32 v102, 0xa000, v131
	v_add_u32_e32 v103, 0xac00, v131
	s_waitcnt lgkmcnt(1)
	v_mul_f32_e32 v0, v86, v82
	v_mul_f32_e32 v0, 0xbfb8aa3b, v0
	v_exp_f32_e32 v0, v0
	v_mul_f32_e32 v82, v87, v83
	v_mul_f32_e32 v82, 0xbfb8aa3b, v82
	v_exp_f32_e32 v82, v82
	v_add_f32_e32 v0, 1.0, v0
	v_rcp_f32_e32 v86, v0
	v_add_u32_e32 v0, v102, v114
	v_add_f32_e32 v82, 1.0, v82
	v_rcp_f32_e32 v87, v82
	v_lshl_add_u64 v[82:83], v[0:1], 1, s[18:19]
	v_cvt_pk_bf16_f32 v0, v86, s0
	global_store_short v[82:83], v0, off
	s_waitcnt lgkmcnt(0)
	v_mul_f32_e32 v0, v88, v84
	v_mul_f32_e32 v0, 0xbfb8aa3b, v0
	v_exp_f32_e32 v84, v0
	v_add_u32_e32 v88, 0xa400, v131
	v_add_u32_e32 v0, v88, v114
	v_lshl_add_u64 v[82:83], v[0:1], 1, s[18:19]
	v_add_f32_e32 v0, 1.0, v84
	v_mul_f32_e32 v84, v89, v85
	v_mul_f32_e32 v84, 0xbfb8aa3b, v84
	v_rcp_f32_e32 v0, v0
	v_exp_f32_e32 v84, v84
	v_add_u32_e32 v89, 0xa800, v131
	v_cvt_pk_bf16_f32 v86, v87, s0
	v_cvt_pk_bf16_f32 v85, v0, s0
	v_add_f32_e32 v0, 1.0, v84
	v_rcp_f32_e32 v84, v0
	v_add_u32_e32 v0, v89, v114
	global_store_short v[82:83], v86, off
	v_lshl_add_u64 v[82:83], v[0:1], 1, s[18:19]
	v_add_u32_e32 v0, v103, v114
	global_store_short v[82:83], v85, off
	v_cvt_pk_bf16_f32 v84, v84, s0
	v_lshl_add_u64 v[82:83], v[0:1], 1, s[18:19]
	global_store_short v[82:83], v84, off
	ds_read2_b32 v[82:83], v130 offset0:48 offset1:49
	ds_read2_b32 v[84:85], v130 offset0:50 offset1:51
	s_waitcnt lgkmcnt(1)
	v_mul_f32_e32 v0, v90, v82
	v_mul_f32_e32 v0, 0xbfb8aa3b, v0
	v_exp_f32_e32 v0, v0
	v_mul_f32_e32 v82, v91, v83
	v_mul_f32_e32 v82, 0xbfb8aa3b, v82
	v_exp_f32_e32 v82, v82
	v_add_f32_e32 v0, 1.0, v0
	v_rcp_f32_e32 v86, v0
	v_add_u32_e32 v90, 0xc000, v131
	v_add_f32_e32 v82, 1.0, v82
	v_add_u32_e32 v0, v90, v114
	v_rcp_f32_e32 v87, v82
	v_lshl_add_u64 v[82:83], v[0:1], 1, s[18:19]
	v_cvt_pk_bf16_f32 v0, v86, s0
	global_store_short v[82:83], v0, off
	s_waitcnt lgkmcnt(0)
	v_mul_f32_e32 v0, v92, v84
	v_mul_f32_e32 v0, 0xbfb8aa3b, v0
	v_exp_f32_e32 v84, v0
	v_add_u32_e32 v91, 0xc400, v131
	v_add_u32_e32 v0, v91, v114
	v_lshl_add_u64 v[82:83], v[0:1], 1, s[18:19]
	v_add_f32_e32 v0, 1.0, v84
	v_mul_f32_e32 v84, v93, v85
	v_mul_f32_e32 v84, 0xbfb8aa3b, v84
	v_rcp_f32_e32 v0, v0
	v_exp_f32_e32 v84, v84
	v_add_u32_e32 v92, 0xc800, v131
	v_cvt_pk_bf16_f32 v86, v87, s0
	v_cvt_pk_bf16_f32 v85, v0, s0
	v_add_f32_e32 v0, 1.0, v84
	v_rcp_f32_e32 v84, v0
	v_add_u32_e32 v0, v92, v114
	v_add_u32_e32 v93, 0xcc00, v131
	global_store_short v[82:83], v86, off
	v_lshl_add_u64 v[82:83], v[0:1], 1, s[18:19]
	v_add_u32_e32 v0, v93, v114
	global_store_short v[82:83], v85, off
	v_cvt_pk_bf16_f32 v84, v84, s0
	v_lshl_add_u64 v[82:83], v[0:1], 1, s[18:19]
	global_store_short v[82:83], v84, off
	ds_read2_b32 v[82:83], v130 offset0:56 offset1:57
	ds_read2_b32 v[84:85], v130 offset0:58 offset1:59
	s_waitcnt lgkmcnt(1)
	v_mul_f32_e32 v0, v94, v82
	v_mul_f32_e32 v0, 0xbfb8aa3b, v0
	v_exp_f32_e32 v0, v0
	v_mul_f32_e32 v82, v95, v83
	v_mul_f32_e32 v82, 0xbfb8aa3b, v82
	v_exp_f32_e32 v82, v82
	v_add_f32_e32 v0, 1.0, v0
	v_rcp_f32_e32 v86, v0
	v_add_u32_e32 v94, 0xe000, v131
	v_add_f32_e32 v82, 1.0, v82
	v_add_u32_e32 v0, v94, v114
	v_rcp_f32_e32 v87, v82
	v_lshl_add_u64 v[82:83], v[0:1], 1, s[18:19]
	v_cvt_pk_bf16_f32 v0, v86, s0
	global_store_short v[82:83], v0, off
	s_waitcnt lgkmcnt(0)
	v_mul_f32_e32 v0, v96, v84
	v_mul_f32_e32 v0, 0xbfb8aa3b, v0
	v_exp_f32_e32 v84, v0
	v_add_u32_e32 v95, 0xe400, v131
	v_add_u32_e32 v0, v95, v114
	v_lshl_add_u64 v[82:83], v[0:1], 1, s[18:19]
	v_add_f32_e32 v0, 1.0, v84
	v_mul_f32_e32 v84, v97, v85
	v_mul_f32_e32 v84, 0xbfb8aa3b, v84
	v_rcp_f32_e32 v0, v0
	v_exp_f32_e32 v84, v84
	v_add_u32_e32 v96, 0xe800, v131
	v_cvt_pk_bf16_f32 v86, v87, s0
	v_cvt_pk_bf16_f32 v85, v0, s0
	v_add_f32_e32 v0, 1.0, v84
	v_rcp_f32_e32 v84, v0
	v_add_u32_e32 v0, v96, v114
	v_add_u32_e32 v97, 0xec00, v131
	global_store_short v[82:83], v86, off
	v_lshl_add_u64 v[82:83], v[0:1], 1, s[18:19]
	v_add_u32_e32 v0, v97, v114
	global_store_short v[82:83], v85, off
	v_cvt_pk_bf16_f32 v84, v84, s0
	v_lshl_add_u64 v[82:83], v[0:1], 1, s[18:19]
	global_store_short v[82:83], v84, off
	ds_read2_b32 v[82:83], v130 offset0:32 offset1:33
	ds_read2_b32 v[84:85], v130 offset0:34 offset1:35
	v_add_u32_e32 v0, v98, v115
	v_lshl_add_u64 v[86:87], v[0:1], 1, s[18:19]
	s_waitcnt lgkmcnt(1)
	v_mul_f32_e32 v0, v34, v82
	v_mul_f32_e32 v34, v35, v83
	v_mul_f32_e32 v34, 0xbfb8aa3b, v34
	v_exp_f32_e32 v34, v34
	s_waitcnt lgkmcnt(0)
	v_mul_f32_e32 v35, v36, v84
	v_mul_f32_e32 v0, 0xbfb8aa3b, v0
	v_mul_f32_e32 v35, 0xbfb8aa3b, v35
	v_add_f32_e32 v34, 1.0, v34
	v_exp_f32_e32 v0, v0
	v_rcp_f32_e32 v34, v34
	v_exp_f32_e32 v35, v35
	v_add_f32_e32 v0, 1.0, v0
	v_cvt_pk_bf16_f32 v36, v34, s0
	v_add_f32_e32 v34, 1.0, v35
	v_rcp_f32_e32 v0, v0
	v_rcp_f32_e32 v82, v34
	v_mul_f32_e32 v34, v37, v85
	v_mul_f32_e32 v34, 0xbfb8aa3b, v34
	v_exp_f32_e32 v37, v34
	v_cvt_pk_bf16_f32 v0, v0, s0
	global_store_short v[86:87], v0, off
	v_add_u32_e32 v0, v100, v115
	v_lshl_add_u64 v[34:35], v[0:1], 1, s[18:19]
	v_add_f32_e32 v0, 1.0, v37
	v_rcp_f32_e32 v37, v0
	v_add_u32_e32 v0, v99, v115
	global_store_short v[34:35], v36, off
	v_cvt_pk_bf16_f32 v36, v82, s0
	v_lshl_add_u64 v[34:35], v[0:1], 1, s[18:19]
	v_add_u32_e32 v0, v101, v115
	global_store_short v[34:35], v36, off
	v_cvt_pk_bf16_f32 v36, v37, s0
	v_lshl_add_u64 v[34:35], v[0:1], 1, s[18:19]
	global_store_short v[34:35], v36, off
	ds_read2_b32 v[34:35], v130 offset0:40 offset1:41
	ds_read2_b32 v[36:37], v130 offset0:42 offset1:43
	v_add_u32_e32 v0, v102, v115
	v_lshl_add_u64 v[82:83], v[0:1], 1, s[18:19]
	s_waitcnt lgkmcnt(1)
	v_mul_f32_e32 v0, v38, v34
	v_mul_f32_e32 v34, v39, v35
	v_mul_f32_e32 v34, 0xbfb8aa3b, v34
	v_exp_f32_e32 v34, v34
	s_waitcnt lgkmcnt(0)
	v_mul_f32_e32 v35, v40, v36
	v_mul_f32_e32 v0, 0xbfb8aa3b, v0
	v_mul_f32_e32 v35, 0xbfb8aa3b, v35
	v_add_f32_e32 v34, 1.0, v34
	v_exp_f32_e32 v0, v0
	v_rcp_f32_e32 v34, v34
	v_exp_f32_e32 v35, v35
	v_add_f32_e32 v0, 1.0, v0
	v_cvt_pk_bf16_f32 v36, v34, s0
	v_add_f32_e32 v34, 1.0, v35
	v_rcp_f32_e32 v0, v0
	v_rcp_f32_e32 v38, v34
	v_mul_f32_e32 v34, v41, v37
	v_mul_f32_e32 v34, 0xbfb8aa3b, v34
	v_exp_f32_e32 v37, v34
	v_cvt_pk_bf16_f32 v0, v0, s0
	global_store_short v[82:83], v0, off
	v_add_u32_e32 v0, v88, v115
	v_lshl_add_u64 v[34:35], v[0:1], 1, s[18:19]
	v_add_f32_e32 v0, 1.0, v37
	v_rcp_f32_e32 v37, v0
	v_add_u32_e32 v0, v89, v115
	global_store_short v[34:35], v36, off
	v_cvt_pk_bf16_f32 v36, v38, s0
	v_lshl_add_u64 v[34:35], v[0:1], 1, s[18:19]
	v_add_u32_e32 v0, v103, v115
	global_store_short v[34:35], v36, off
	v_cvt_pk_bf16_f32 v36, v37, s0
	v_lshl_add_u64 v[34:35], v[0:1], 1, s[18:19]
	global_store_short v[34:35], v36, off
	ds_read2_b32 v[34:35], v130 offset0:48 offset1:49
	ds_read2_b32 v[36:37], v130 offset0:50 offset1:51
	v_add_u32_e32 v0, v90, v115
	v_lshl_add_u64 v[38:39], v[0:1], 1, s[18:19]
	s_waitcnt lgkmcnt(1)
	v_mul_f32_e32 v0, v42, v34
	v_mul_f32_e32 v34, v43, v35
	v_mul_f32_e32 v0, 0xbfb8aa3b, v0
	v_mul_f32_e32 v34, 0xbfb8aa3b, v34
	v_exp_f32_e32 v0, v0
	v_exp_f32_e32 v34, v34
	s_waitcnt lgkmcnt(0)
	v_mul_f32_e32 v35, v44, v36
	v_mul_f32_e32 v35, 0xbfb8aa3b, v35
	v_add_f32_e32 v0, 1.0, v0
	v_add_f32_e32 v34, 1.0, v34
	v_rcp_f32_e32 v0, v0
	v_rcp_f32_e32 v34, v34
	v_exp_f32_e32 v35, v35
	v_cvt_pk_bf16_f32 v0, v0, s0
	v_cvt_pk_bf16_f32 v36, v34, s0
	v_add_f32_e32 v34, 1.0, v35
	global_store_short v[38:39], v0, off
	v_rcp_f32_e32 v38, v34
	v_mul_f32_e32 v34, v45, v37
	v_mul_f32_e32 v34, 0xbfb8aa3b, v34
	v_exp_f32_e32 v37, v34
	v_add_u32_e32 v0, v91, v115
	v_lshl_add_u64 v[34:35], v[0:1], 1, s[18:19]
	global_store_short v[34:35], v36, off
	v_add_f32_e32 v0, 1.0, v37
	v_rcp_f32_e32 v37, v0
	v_add_u32_e32 v0, v92, v115
	v_cvt_pk_bf16_f32 v36, v38, s0
	v_lshl_add_u64 v[34:35], v[0:1], 1, s[18:19]
	v_add_u32_e32 v0, v93, v115
	global_store_short v[34:35], v36, off
	v_cvt_pk_bf16_f32 v36, v37, s0
	v_lshl_add_u64 v[34:35], v[0:1], 1, s[18:19]
	global_store_short v[34:35], v36, off
	ds_read2_b32 v[34:35], v130 offset0:56 offset1:57
	ds_read2_b32 v[36:37], v130 offset0:58 offset1:59
	v_add_u32_e32 v0, v94, v115
	v_lshl_add_u64 v[38:39], v[0:1], 1, s[18:19]
	s_waitcnt lgkmcnt(1)
	v_mul_f32_e32 v0, v46, v34
	v_mul_f32_e32 v34, v47, v35
	v_mul_f32_e32 v0, 0xbfb8aa3b, v0
	v_mul_f32_e32 v34, 0xbfb8aa3b, v34
	v_exp_f32_e32 v0, v0
	v_exp_f32_e32 v34, v34
	s_waitcnt lgkmcnt(0)
	v_mul_f32_e32 v35, v48, v36
	v_mul_f32_e32 v35, 0xbfb8aa3b, v35
	v_add_f32_e32 v0, 1.0, v0
	v_add_f32_e32 v34, 1.0, v34
	v_rcp_f32_e32 v0, v0
	v_rcp_f32_e32 v34, v34
	v_exp_f32_e32 v35, v35
	v_cvt_pk_bf16_f32 v0, v0, s0
	v_cvt_pk_bf16_f32 v36, v34, s0
	v_add_f32_e32 v34, 1.0, v35
	global_store_short v[38:39], v0, off
	v_rcp_f32_e32 v38, v34
	v_mul_f32_e32 v34, v49, v37
	v_mul_f32_e32 v34, 0xbfb8aa3b, v34
	v_exp_f32_e32 v37, v34
	v_add_u32_e32 v0, v95, v115
	v_lshl_add_u64 v[34:35], v[0:1], 1, s[18:19]
	global_store_short v[34:35], v36, off
	v_add_f32_e32 v0, 1.0, v37
	v_rcp_f32_e32 v37, v0
	v_add_u32_e32 v0, v96, v115
	v_cvt_pk_bf16_f32 v36, v38, s0
	v_lshl_add_u64 v[34:35], v[0:1], 1, s[18:19]
	v_add_u32_e32 v0, v97, v115
	global_store_short v[34:35], v36, off
	v_cvt_pk_bf16_f32 v36, v37, s0
	v_lshl_add_u64 v[34:35], v[0:1], 1, s[18:19]
	global_store_short v[34:35], v36, off
	s_cmpk_lt_i32 s8, 0x4000
	s_cbranch_scc1 .Ltep_e1_c
	s_waitcnt vmcnt(63)
	s_branch .Ltep_e1_e
.Ltep_e1_c:
	ds_read2_b32 v[34:35], v130 offset0:64 offset1:65
	ds_read2_b32 v[36:37], v130 offset0:66 offset1:67
	v_add_u32_e32 v38, 0x10000, v131
	v_add_u32_e32 v41, 0x10800, v131
	v_add_u32_e32 v42, 0x10c00, v131
	s_waitcnt lgkmcnt(1)
	v_mul_f32_e32 v0, v66, v34
	v_mul_f32_e32 v0, 0xbfb8aa3b, v0
	v_exp_f32_e32 v0, v0
	v_mul_f32_e32 v34, v67, v35
	v_mul_f32_e32 v34, 0xbfb8aa3b, v34
	v_exp_f32_e32 v34, v34
	v_add_f32_e32 v0, 1.0, v0
	v_rcp_f32_e32 v39, v0
	v_add_u32_e32 v0, v38, v114
	v_add_f32_e32 v34, 1.0, v34
	v_rcp_f32_e32 v40, v34
	v_lshl_add_u64 v[34:35], v[0:1], 1, s[18:19]
	v_cvt_pk_bf16_f32 v0, v39, s0
	global_store_short v[34:35], v0, off
	s_waitcnt lgkmcnt(0)
	v_mul_f32_e32 v0, v68, v36
	v_mul_f32_e32 v0, 0xbfb8aa3b, v0
	v_exp_f32_e32 v36, v0
	v_cvt_pk_bf16_f32 v39, v40, s0
	v_add_u32_e32 v40, 0x10400, v131
	v_add_u32_e32 v0, v40, v114
	v_lshl_add_u64 v[34:35], v[0:1], 1, s[18:19]
	v_add_f32_e32 v0, 1.0, v36
	v_mul_f32_e32 v36, v69, v37
	v_mul_f32_e32 v36, 0xbfb8aa3b, v36
	v_rcp_f32_e32 v0, v0
	v_exp_f32_e32 v36, v36
	global_store_short v[34:35], v39, off
	v_cvt_pk_bf16_f32 v37, v0, s0
	v_add_f32_e32 v0, 1.0, v36
	v_rcp_f32_e32 v36, v0
	v_add_u32_e32 v0, v41, v114
	v_lshl_add_u64 v[34:35], v[0:1], 1, s[18:19]
	v_add_u32_e32 v0, v42, v114
	global_store_short v[34:35], v37, off
	v_cvt_pk_bf16_f32 v36, v36, s0
	v_lshl_add_u64 v[34:35], v[0:1], 1, s[18:19]
	global_store_short v[34:35], v36, off
	ds_read2_b32 v[34:35], v130 offset0:72 offset1:73
	ds_read2_b32 v[36:37], v130 offset0:74 offset1:75
	v_add_u32_e32 v43, 0x12000, v131
	v_add_u32_e32 v45, 0x12800, v131
	v_add_u32_e32 v46, 0x12c00, v131
	s_waitcnt lgkmcnt(1)
	v_mul_f32_e32 v0, v70, v34
	v_mul_f32_e32 v0, 0xbfb8aa3b, v0
	v_exp_f32_e32 v0, v0
	v_mul_f32_e32 v34, v71, v35
	v_mul_f32_e32 v34, 0xbfb8aa3b, v34
	v_exp_f32_e32 v34, v34
	v_add_f32_e32 v0, 1.0, v0
	v_rcp_f32_e32 v39, v0
	v_add_u32_e32 v0, v43, v114
	v_add_f32_e32 v34, 1.0, v34
	v_rcp_f32_e32 v44, v34
	v_lshl_add_u64 v[34:35], v[0:1], 1, s[18:19]
	v_cvt_pk_bf16_f32 v0, v39, s0
	global_store_short v[34:35], v0, off
	s_waitcnt lgkmcnt(0)
	v_mul_f32_e32 v0, v72, v36
	v_mul_f32_e32 v0, 0xbfb8aa3b, v0
	v_exp_f32_e32 v36, v0
	v_cvt_pk_bf16_f32 v39, v44, s0
	v_add_u32_e32 v44, 0x12400, v131
	v_add_u32_e32 v0, v44, v114
	v_lshl_add_u64 v[34:35], v[0:1], 1, s[18:19]
	v_add_f32_e32 v0, 1.0, v36
	v_mul_f32_e32 v36, v73, v37
	v_mul_f32_e32 v36, 0xbfb8aa3b, v36
	v_rcp_f32_e32 v0, v0
	v_exp_f32_e32 v36, v36
	global_store_short v[34:35], v39, off
	v_cvt_pk_bf16_f32 v37, v0, s0
	v_add_f32_e32 v0, 1.0, v36
	v_rcp_f32_e32 v36, v0
	v_add_u32_e32 v0, v45, v114
	v_lshl_add_u64 v[34:35], v[0:1], 1, s[18:19]
	v_add_u32_e32 v0, v46, v114
	global_store_short v[34:35], v37, off
	v_cvt_pk_bf16_f32 v36, v36, s0
	v_lshl_add_u64 v[34:35], v[0:1], 1, s[18:19]
	global_store_short v[34:35], v36, off
	ds_read2_b32 v[34:35], v130 offset0:80 offset1:81
	ds_read2_b32 v[36:37], v130 offset0:82 offset1:83
	v_add_u32_e32 v47, 0x14000, v131
	v_add_u32_e32 v49, 0x14800, v131
	v_add_u32_e32 v66, 0x14c00, v131
	s_waitcnt lgkmcnt(1)
	v_mul_f32_e32 v0, v74, v34
	v_mul_f32_e32 v0, 0xbfb8aa3b, v0
	v_exp_f32_e32 v0, v0
	v_mul_f32_e32 v34, v75, v35
	v_mul_f32_e32 v34, 0xbfb8aa3b, v34
	v_exp_f32_e32 v34, v34
	v_add_f32_e32 v0, 1.0, v0
	v_rcp_f32_e32 v39, v0
	v_add_u32_e32 v0, v47, v114
	v_add_f32_e32 v34, 1.0, v34
	v_rcp_f32_e32 v48, v34
	v_lshl_add_u64 v[34:35], v[0:1], 1, s[18:19]
	v_cvt_pk_bf16_f32 v0, v39, s0
	global_store_short v[34:35], v0, off
	s_waitcnt lgkmcnt(0)
	v_mul_f32_e32 v0, v76, v36
	v_mul_f32_e32 v0, 0xbfb8aa3b, v0
	v_exp_f32_e32 v36, v0
	v_cvt_pk_bf16_f32 v39, v48, s0
	v_add_u32_e32 v48, 0x14400, v131
	v_add_u32_e32 v0, v48, v114
	v_lshl_add_u64 v[34:35], v[0:1], 1, s[18:19]
	v_add_f32_e32 v0, 1.0, v36
	v_mul_f32_e32 v36, v77, v37
	v_mul_f32_e32 v36, 0xbfb8aa3b, v36
	v_rcp_f32_e32 v0, v0
	v_exp_f32_e32 v36, v36
	global_store_short v[34:35], v39, off
	v_cvt_pk_bf16_f32 v37, v0, s0
	v_add_f32_e32 v0, 1.0, v36
	v_rcp_f32_e32 v36, v0
	v_add_u32_e32 v0, v49, v114
	v_lshl_add_u64 v[34:35], v[0:1], 1, s[18:19]
	v_add_u32_e32 v0, v66, v114
	global_store_short v[34:35], v37, off
	v_cvt_pk_bf16_f32 v36, v36, s0
	v_lshl_add_u64 v[34:35], v[0:1], 1, s[18:19]
	global_store_short v[34:35], v36, off
	ds_read2_b32 v[34:35], v130 offset0:88 offset1:89
	ds_read2_b32 v[36:37], v130 offset0:90 offset1:91
	v_add_u32_e32 v67, 0x16000, v131
	v_add_u32_e32 v69, 0x16800, v131
	v_add_u32_e32 v70, 0x16c00, v131
	s_waitcnt lgkmcnt(1)
	v_mul_f32_e32 v0, v78, v34
	v_mul_f32_e32 v0, 0xbfb8aa3b, v0
	v_exp_f32_e32 v0, v0
	v_mul_f32_e32 v34, v79, v35
	v_mul_f32_e32 v34, 0xbfb8aa3b, v34
	v_exp_f32_e32 v34, v34
	v_add_f32_e32 v0, 1.0, v0
	v_rcp_f32_e32 v39, v0
	v_add_u32_e32 v0, v67, v114
	v_add_f32_e32 v34, 1.0, v34
	v_rcp_f32_e32 v68, v34
	v_lshl_add_u64 v[34:35], v[0:1], 1, s[18:19]
	v_cvt_pk_bf16_f32 v0, v39, s0
	global_store_short v[34:35], v0, off
	s_waitcnt lgkmcnt(0)
	v_mul_f32_e32 v0, v80, v36
	v_mul_f32_e32 v0, 0xbfb8aa3b, v0
	v_exp_f32_e32 v36, v0
	v_cvt_pk_bf16_f32 v39, v68, s0
	v_add_u32_e32 v68, 0x16400, v131
	v_add_u32_e32 v0, v68, v114
	v_lshl_add_u64 v[34:35], v[0:1], 1, s[18:19]
	v_add_f32_e32 v0, 1.0, v36
	v_mul_f32_e32 v36, v81, v37
	v_mul_f32_e32 v36, 0xbfb8aa3b, v36
	v_rcp_f32_e32 v0, v0
	v_exp_f32_e32 v36, v36
	global_store_short v[34:35], v39, off
	v_cvt_pk_bf16_f32 v37, v0, s0
	v_add_f32_e32 v0, 1.0, v36
	v_rcp_f32_e32 v36, v0
	v_add_u32_e32 v0, v69, v114
	v_lshl_add_u64 v[34:35], v[0:1], 1, s[18:19]
	v_add_u32_e32 v0, v70, v114
	global_store_short v[34:35], v37, off
	v_cvt_pk_bf16_f32 v36, v36, s0
	v_lshl_add_u64 v[34:35], v[0:1], 1, s[18:19]
	global_store_short v[34:35], v36, off
	ds_read2_b32 v[34:35], v130 offset0:64 offset1:65
	ds_read2_b32 v[36:37], v130 offset0:66 offset1:67
	v_add_u32_e32 v0, v38, v115
	v_lshl_add_u64 v[38:39], v[0:1], 1, s[18:19]
	s_waitcnt lgkmcnt(1)
	v_mul_f32_e32 v0, v50, v34
	v_mul_f32_e32 v34, v51, v35
	v_mul_f32_e32 v0, 0xbfb8aa3b, v0
	v_mul_f32_e32 v34, 0xbfb8aa3b, v34
	v_exp_f32_e32 v0, v0
	v_exp_f32_e32 v34, v34
	s_waitcnt lgkmcnt(0)
	v_mul_f32_e32 v35, v52, v36
	v_mul_f32_e32 v35, 0xbfb8aa3b, v35
	v_add_f32_e32 v0, 1.0, v0
	v_add_f32_e32 v34, 1.0, v34
	v_rcp_f32_e32 v0, v0
	v_rcp_f32_e32 v34, v34
	v_exp_f32_e32 v35, v35
	v_cvt_pk_bf16_f32 v0, v0, s0
	v_cvt_pk_bf16_f32 v36, v34, s0
	v_add_f32_e32 v34, 1.0, v35
	global_store_short v[38:39], v0, off
	v_rcp_f32_e32 v38, v34
	v_mul_f32_e32 v34, v53, v37
	v_mul_f32_e32 v34, 0xbfb8aa3b, v34
	v_exp_f32_e32 v37, v34
	v_add_u32_e32 v0, v40, v115
	v_lshl_add_u64 v[34:35], v[0:1], 1, s[18:19]
	global_store_short v[34:35], v36, off
	v_add_f32_e32 v0, 1.0, v37
	v_rcp_f32_e32 v37, v0
	v_add_u32_e32 v0, v41, v115
	v_cvt_pk_bf16_f32 v36, v38, s0
	v_lshl_add_u64 v[34:35], v[0:1], 1, s[18:19]
	v_add_u32_e32 v0, v42, v115
	global_store_short v[34:35], v36, off
	v_cvt_pk_bf16_f32 v36, v37, s0
	v_lshl_add_u64 v[34:35], v[0:1], 1, s[18:19]
	global_store_short v[34:35], v36, off
	ds_read2_b32 v[34:35], v130 offset0:72 offset1:73
	ds_read2_b32 v[36:37], v130 offset0:74 offset1:75
	v_add_u32_e32 v0, v43, v115
	v_lshl_add_u64 v[38:39], v[0:1], 1, s[18:19]
	s_waitcnt lgkmcnt(1)
	v_mul_f32_e32 v0, v54, v34
	v_mul_f32_e32 v34, v55, v35
	v_mul_f32_e32 v0, 0xbfb8aa3b, v0
	v_mul_f32_e32 v34, 0xbfb8aa3b, v34
	v_exp_f32_e32 v0, v0
	v_exp_f32_e32 v34, v34
	s_waitcnt lgkmcnt(0)
	v_mul_f32_e32 v35, v56, v36
	v_mul_f32_e32 v35, 0xbfb8aa3b, v35
	v_add_f32_e32 v0, 1.0, v0
	v_add_f32_e32 v34, 1.0, v34
	v_rcp_f32_e32 v0, v0
	v_rcp_f32_e32 v34, v34
	v_exp_f32_e32 v35, v35
	v_cvt_pk_bf16_f32 v0, v0, s0
	v_cvt_pk_bf16_f32 v36, v34, s0
	v_add_f32_e32 v34, 1.0, v35
	global_store_short v[38:39], v0, off
	v_rcp_f32_e32 v38, v34
	v_mul_f32_e32 v34, v57, v37
	v_mul_f32_e32 v34, 0xbfb8aa3b, v34
	v_exp_f32_e32 v37, v34
	v_add_u32_e32 v0, v44, v115
	v_lshl_add_u64 v[34:35], v[0:1], 1, s[18:19]
	global_store_short v[34:35], v36, off
	v_add_f32_e32 v0, 1.0, v37
	v_rcp_f32_e32 v37, v0
	v_add_u32_e32 v0, v45, v115
	v_cvt_pk_bf16_f32 v36, v38, s0
	v_lshl_add_u64 v[34:35], v[0:1], 1, s[18:19]
	v_add_u32_e32 v0, v46, v115
	global_store_short v[34:35], v36, off
	v_cvt_pk_bf16_f32 v36, v37, s0
	v_lshl_add_u64 v[34:35], v[0:1], 1, s[18:19]
	global_store_short v[34:35], v36, off
	ds_read2_b32 v[34:35], v130 offset0:80 offset1:81
	ds_read2_b32 v[36:37], v130 offset0:82 offset1:83
	v_add_u32_e32 v0, v47, v115
	v_lshl_add_u64 v[38:39], v[0:1], 1, s[18:19]
	s_waitcnt lgkmcnt(1)
	v_mul_f32_e32 v0, v58, v34
	v_mul_f32_e32 v34, v59, v35
	v_mul_f32_e32 v0, 0xbfb8aa3b, v0
	v_mul_f32_e32 v34, 0xbfb8aa3b, v34
	v_exp_f32_e32 v0, v0
	v_exp_f32_e32 v34, v34
	s_waitcnt lgkmcnt(0)
	v_mul_f32_e32 v35, v60, v36
	v_mul_f32_e32 v35, 0xbfb8aa3b, v35
	v_add_f32_e32 v0, 1.0, v0
	v_add_f32_e32 v34, 1.0, v34
	v_rcp_f32_e32 v0, v0
	v_rcp_f32_e32 v34, v34
	v_exp_f32_e32 v35, v35
	v_cvt_pk_bf16_f32 v0, v0, s0
	v_cvt_pk_bf16_f32 v36, v34, s0
	v_add_f32_e32 v34, 1.0, v35
	global_store_short v[38:39], v0, off
	v_rcp_f32_e32 v38, v34
	v_mul_f32_e32 v34, v61, v37
	v_mul_f32_e32 v34, 0xbfb8aa3b, v34
	v_exp_f32_e32 v37, v34
	v_add_u32_e32 v0, v48, v115
	v_lshl_add_u64 v[34:35], v[0:1], 1, s[18:19]
	global_store_short v[34:35], v36, off
	v_add_f32_e32 v0, 1.0, v37
	v_rcp_f32_e32 v37, v0
	v_add_u32_e32 v0, v49, v115
	v_cvt_pk_bf16_f32 v36, v38, s0
	v_lshl_add_u64 v[34:35], v[0:1], 1, s[18:19]
	v_add_u32_e32 v0, v66, v115
	global_store_short v[34:35], v36, off
	v_cvt_pk_bf16_f32 v36, v37, s0
	v_lshl_add_u64 v[34:35], v[0:1], 1, s[18:19]
	global_store_short v[34:35], v36, off
	ds_read2_b32 v[34:35], v130 offset0:88 offset1:89
	ds_read2_b32 v[36:37], v130 offset0:90 offset1:91
	v_add_u32_e32 v0, v67, v115
	v_lshl_add_u64 v[38:39], v[0:1], 1, s[18:19]
	s_waitcnt lgkmcnt(1)
	v_mul_f32_e32 v0, v62, v34
	v_mul_f32_e32 v34, v63, v35
	v_mul_f32_e32 v0, 0xbfb8aa3b, v0
	v_mul_f32_e32 v34, 0xbfb8aa3b, v34
	v_exp_f32_e32 v0, v0
	v_exp_f32_e32 v34, v34
	s_waitcnt lgkmcnt(0)
	v_mul_f32_e32 v35, v64, v36
	v_mul_f32_e32 v35, 0xbfb8aa3b, v35
	v_add_f32_e32 v0, 1.0, v0
	v_add_f32_e32 v34, 1.0, v34
	v_rcp_f32_e32 v0, v0
	v_rcp_f32_e32 v34, v34
	v_exp_f32_e32 v35, v35
	v_cvt_pk_bf16_f32 v0, v0, s0
	v_cvt_pk_bf16_f32 v36, v34, s0
	v_add_f32_e32 v34, 1.0, v35
	global_store_short v[38:39], v0, off
	v_rcp_f32_e32 v38, v34
	v_mul_f32_e32 v34, v65, v37
	v_mul_f32_e32 v34, 0xbfb8aa3b, v34
	v_exp_f32_e32 v37, v34
	v_add_u32_e32 v0, v68, v115
	v_lshl_add_u64 v[34:35], v[0:1], 1, s[18:19]
	global_store_short v[34:35], v36, off
	v_add_f32_e32 v0, 1.0, v37
	v_rcp_f32_e32 v37, v0
	v_add_u32_e32 v0, v69, v115
	v_cvt_pk_bf16_f32 v36, v38, s0
	v_lshl_add_u64 v[34:35], v[0:1], 1, s[18:19]
	v_add_u32_e32 v0, v70, v115
	global_store_short v[34:35], v36, off
	v_cvt_pk_bf16_f32 v36, v37, s0
	v_lshl_add_u64 v[34:35], v[0:1], 1, s[18:19]
	global_store_short v[34:35], v36, off
	ds_read2_b32 v[34:35], v130 offset0:96 offset1:97
	ds_read2_b32 v[36:37], v130 offset0:98 offset1:99
	s_waitcnt lgkmcnt(1)
	v_mul_f32_e32 v0, v18, v34
	v_mul_f32_e32 v0, 0xbfb8aa3b, v0
	v_exp_f32_e32 v0, v0
	v_mul_f32_e32 v18, v19, v35
	v_mul_f32_e32 v18, 0xbfb8aa3b, v18
	v_exp_f32_e32 v18, v18
	v_add_f32_e32 v0, 1.0, v0
	v_rcp_f32_e32 v35, v0
	v_add_u32_e32 v34, 0x18000, v131
	v_add_f32_e32 v18, 1.0, v18
	v_add_u32_e32 v0, v34, v114
	v_rcp_f32_e32 v38, v18
	v_lshl_add_u64 v[18:19], v[0:1], 1, s[18:19]
	v_cvt_pk_bf16_f32 v0, v35, s0
	global_store_short v[18:19], v0, off
	s_waitcnt lgkmcnt(0)
	v_mul_f32_e32 v0, v20, v36
	v_mul_f32_e32 v0, 0xbfb8aa3b, v0
	v_exp_f32_e32 v20, v0
	v_add_u32_e32 v36, 0x18400, v131
	v_add_u32_e32 v0, v36, v114
	v_lshl_add_u64 v[18:19], v[0:1], 1, s[18:19]
	v_add_f32_e32 v0, 1.0, v20
	v_mul_f32_e32 v20, v21, v37
	v_mul_f32_e32 v20, 0xbfb8aa3b, v20
	v_rcp_f32_e32 v0, v0
	v_exp_f32_e32 v20, v20
	v_cvt_pk_bf16_f32 v35, v38, s0
	global_store_short v[18:19], v35, off
	v_cvt_pk_bf16_f32 v21, v0, s0
	v_add_f32_e32 v0, 1.0, v20
	v_rcp_f32_e32 v20, v0
	v_add_u32_e32 v35, 0x18800, v131
	v_add_u32_e32 v0, v35, v114
	v_add_u32_e32 v37, 0x18c00, v131
	v_lshl_add_u64 v[18:19], v[0:1], 1, s[18:19]
	v_add_u32_e32 v0, v37, v114
	global_store_short v[18:19], v21, off
	v_cvt_pk_bf16_f32 v20, v20, s0
	v_lshl_add_u64 v[18:19], v[0:1], 1, s[18:19]
	global_store_short v[18:19], v20, off
	ds_read2_b32 v[18:19], v130 offset0:104 offset1:105
	ds_read2_b32 v[20:21], v130 offset0:106 offset1:107
	v_add_u32_e32 v38, 0x1a000, v131
	v_add_u32_e32 v39, 0x1ac00, v131
	s_waitcnt lgkmcnt(1)
	v_mul_f32_e32 v0, v22, v18
	v_mul_f32_e32 v0, 0xbfb8aa3b, v0
	v_exp_f32_e32 v0, v0
	v_mul_f32_e32 v18, v23, v19
	v_mul_f32_e32 v18, 0xbfb8aa3b, v18
	v_exp_f32_e32 v18, v18
	v_add_f32_e32 v0, 1.0, v0
	v_rcp_f32_e32 v22, v0
	v_add_u32_e32 v0, v38, v114
	v_add_f32_e32 v18, 1.0, v18
	v_rcp_f32_e32 v23, v18
	v_lshl_add_u64 v[18:19], v[0:1], 1, s[18:19]
	v_cvt_pk_bf16_f32 v0, v22, s0
	global_store_short v[18:19], v0, off
	s_waitcnt lgkmcnt(0)
	v_mul_f32_e32 v0, v24, v20
	v_mul_f32_e32 v0, 0xbfb8aa3b, v0
	v_exp_f32_e32 v20, v0
	v_add_u32_e32 v24, 0x1a400, v131
	v_add_u32_e32 v0, v24, v114
	v_lshl_add_u64 v[18:19], v[0:1], 1, s[18:19]
	v_add_f32_e32 v0, 1.0, v20
	v_mul_f32_e32 v20, v25, v21
	v_mul_f32_e32 v20, 0xbfb8aa3b, v20
	v_rcp_f32_e32 v0, v0
	v_exp_f32_e32 v20, v20
	v_add_u32_e32 v25, 0x1a800, v131
	v_cvt_pk_bf16_f32 v22, v23, s0
	v_cvt_pk_bf16_f32 v21, v0, s0
	v_add_f32_e32 v0, 1.0, v20
	v_rcp_f32_e32 v20, v0
	v_add_u32_e32 v0, v25, v114
	global_store_short v[18:19], v22, off
	v_lshl_add_u64 v[18:19], v[0:1], 1, s[18:19]
	v_add_u32_e32 v0, v39, v114
	global_store_short v[18:19], v21, off
	v_cvt_pk_bf16_f32 v20, v20, s0
	v_lshl_add_u64 v[18:19], v[0:1], 1, s[18:19]
	global_store_short v[18:19], v20, off
	ds_read2_b32 v[18:19], v130 offset0:112 offset1:113
	ds_read2_b32 v[20:21], v130 offset0:114 offset1:115
	s_waitcnt lgkmcnt(1)
	v_mul_f32_e32 v0, v26, v18
	v_mul_f32_e32 v0, 0xbfb8aa3b, v0
	v_exp_f32_e32 v0, v0
	v_mul_f32_e32 v18, v27, v19
	v_mul_f32_e32 v18, 0xbfb8aa3b, v18
	v_exp_f32_e32 v18, v18
	v_add_f32_e32 v0, 1.0, v0
	v_rcp_f32_e32 v22, v0
	v_add_u32_e32 v26, 0x1c000, v131
	v_add_f32_e32 v18, 1.0, v18
	v_add_u32_e32 v0, v26, v114
	v_rcp_f32_e32 v23, v18
	v_lshl_add_u64 v[18:19], v[0:1], 1, s[18:19]
	v_cvt_pk_bf16_f32 v0, v22, s0
	global_store_short v[18:19], v0, off
	s_waitcnt lgkmcnt(0)
	v_mul_f32_e32 v0, v28, v20
	v_mul_f32_e32 v0, 0xbfb8aa3b, v0
	v_exp_f32_e32 v20, v0
	v_add_u32_e32 v27, 0x1c400, v131
	v_add_u32_e32 v0, v27, v114
	v_lshl_add_u64 v[18:19], v[0:1], 1, s[18:19]
	v_add_f32_e32 v0, 1.0, v20
	v_mul_f32_e32 v20, v29, v21
	v_mul_f32_e32 v20, 0xbfb8aa3b, v20
	v_rcp_f32_e32 v0, v0
	v_exp_f32_e32 v20, v20
	v_add_u32_e32 v28, 0x1c800, v131
	v_cvt_pk_bf16_f32 v22, v23, s0
	v_cvt_pk_bf16_f32 v21, v0, s0
	v_add_f32_e32 v0, 1.0, v20
	v_rcp_f32_e32 v20, v0
	v_add_u32_e32 v0, v28, v114
	v_add_u32_e32 v29, 0x1cc00, v131
	global_store_short v[18:19], v22, off
	v_lshl_add_u64 v[18:19], v[0:1], 1, s[18:19]
	v_add_u32_e32 v0, v29, v114
	global_store_short v[18:19], v21, off
	v_cvt_pk_bf16_f32 v20, v20, s0
	v_lshl_add_u64 v[18:19], v[0:1], 1, s[18:19]
	global_store_short v[18:19], v20, off
	ds_read2_b32 v[18:19], v130 offset0:120 offset1:121
	ds_read2_b32 v[20:21], v130 offset0:122 offset1:123
	s_waitcnt lgkmcnt(1)
	v_mul_f32_e32 v0, v30, v18
	v_mul_f32_e32 v0, 0xbfb8aa3b, v0
	v_exp_f32_e32 v0, v0
	v_mul_f32_e32 v18, v31, v19
	v_mul_f32_e32 v18, 0xbfb8aa3b, v18
	v_exp_f32_e32 v18, v18
	v_add_f32_e32 v0, 1.0, v0
	v_rcp_f32_e32 v22, v0
	v_add_u32_e32 v30, 0x1e000, v131
	v_add_f32_e32 v18, 1.0, v18
	v_add_u32_e32 v0, v30, v114
	v_rcp_f32_e32 v23, v18
	v_lshl_add_u64 v[18:19], v[0:1], 1, s[18:19]
	v_cvt_pk_bf16_f32 v0, v22, s0
	global_store_short v[18:19], v0, off
	s_waitcnt lgkmcnt(0)
	v_mul_f32_e32 v0, v32, v20
	v_mul_f32_e32 v0, 0xbfb8aa3b, v0
	v_exp_f32_e32 v20, v0
	v_add_u32_e32 v31, 0x1e400, v131
	v_add_u32_e32 v0, v31, v114
	v_lshl_add_u64 v[18:19], v[0:1], 1, s[18:19]
	v_add_f32_e32 v0, 1.0, v20
	v_mul_f32_e32 v20, v33, v21
	v_mul_f32_e32 v20, 0xbfb8aa3b, v20
	v_rcp_f32_e32 v0, v0
	v_exp_f32_e32 v20, v20
	v_add_u32_e32 v32, 0x1e800, v131
	v_cvt_pk_bf16_f32 v22, v23, s0
	v_cvt_pk_bf16_f32 v21, v0, s0
	v_add_f32_e32 v0, 1.0, v20
	v_rcp_f32_e32 v20, v0
	v_add_u32_e32 v0, v32, v114
	v_add_u32_e32 v33, 0x1ec00, v131
	global_store_short v[18:19], v22, off
	v_lshl_add_u64 v[18:19], v[0:1], 1, s[18:19]
	v_add_u32_e32 v0, v33, v114
	global_store_short v[18:19], v21, off
	v_cvt_pk_bf16_f32 v20, v20, s0
	v_lshl_add_u64 v[18:19], v[0:1], 1, s[18:19]
	global_store_short v[18:19], v20, off
	ds_read2_b32 v[18:19], v130 offset0:96 offset1:97
	ds_read2_b32 v[20:21], v130 offset0:98 offset1:99
	v_add_u32_e32 v0, v34, v115
	v_lshl_add_u64 v[22:23], v[0:1], 1, s[18:19]
	s_waitcnt lgkmcnt(1)
	v_mul_f32_e32 v0, v2, v18
	v_mul_f32_e32 v2, v3, v19
	v_mul_f32_e32 v2, 0xbfb8aa3b, v2
	v_exp_f32_e32 v2, v2
	s_waitcnt lgkmcnt(0)
	v_mul_f32_e32 v3, v4, v20
	v_mul_f32_e32 v0, 0xbfb8aa3b, v0
	v_mul_f32_e32 v3, 0xbfb8aa3b, v3
	v_add_f32_e32 v2, 1.0, v2
	v_exp_f32_e32 v0, v0
	v_rcp_f32_e32 v2, v2
	v_exp_f32_e32 v3, v3
	v_add_f32_e32 v0, 1.0, v0
	v_cvt_pk_bf16_f32 v4, v2, s0
	v_add_f32_e32 v2, 1.0, v3
	v_rcp_f32_e32 v0, v0
	v_rcp_f32_e32 v18, v2
	v_mul_f32_e32 v2, v5, v21
	v_mul_f32_e32 v2, 0xbfb8aa3b, v2
	v_exp_f32_e32 v5, v2
	v_cvt_pk_bf16_f32 v0, v0, s0
	global_store_short v[22:23], v0, off
	v_add_u32_e32 v0, v36, v115
	v_lshl_add_u64 v[2:3], v[0:1], 1, s[18:19]
	v_add_f32_e32 v0, 1.0, v5
	v_rcp_f32_e32 v5, v0
	v_add_u32_e32 v0, v35, v115
	global_store_short v[2:3], v4, off
	v_cvt_pk_bf16_f32 v4, v18, s0
	v_lshl_add_u64 v[2:3], v[0:1], 1, s[18:19]
	v_add_u32_e32 v0, v37, v115
	global_store_short v[2:3], v4, off
	v_cvt_pk_bf16_f32 v4, v5, s0
	v_lshl_add_u64 v[2:3], v[0:1], 1, s[18:19]
	global_store_short v[2:3], v4, off
	ds_read2_b32 v[2:3], v130 offset0:104 offset1:105
	ds_read2_b32 v[4:5], v130 offset0:106 offset1:107
	v_add_u32_e32 v0, v38, v115
	v_lshl_add_u64 v[18:19], v[0:1], 1, s[18:19]
	s_waitcnt lgkmcnt(1)
	v_mul_f32_e32 v0, v6, v2
	v_mul_f32_e32 v2, v7, v3
	v_mul_f32_e32 v2, 0xbfb8aa3b, v2
	v_exp_f32_e32 v2, v2
	s_waitcnt lgkmcnt(0)
	v_mul_f32_e32 v3, v8, v4
	v_mul_f32_e32 v0, 0xbfb8aa3b, v0
	v_mul_f32_e32 v3, 0xbfb8aa3b, v3
	v_add_f32_e32 v2, 1.0, v2
	v_exp_f32_e32 v0, v0
	v_rcp_f32_e32 v2, v2
	v_exp_f32_e32 v3, v3
	v_add_f32_e32 v0, 1.0, v0
	v_cvt_pk_bf16_f32 v4, v2, s0
	v_add_f32_e32 v2, 1.0, v3
	v_rcp_f32_e32 v0, v0
	v_rcp_f32_e32 v6, v2
	v_mul_f32_e32 v2, v9, v5
	v_mul_f32_e32 v2, 0xbfb8aa3b, v2
	v_exp_f32_e32 v5, v2
	v_cvt_pk_bf16_f32 v0, v0, s0
	global_store_short v[18:19], v0, off
	v_add_u32_e32 v0, v24, v115
	v_lshl_add_u64 v[2:3], v[0:1], 1, s[18:19]
	v_add_f32_e32 v0, 1.0, v5
	v_rcp_f32_e32 v5, v0
	v_add_u32_e32 v0, v25, v115
	global_store_short v[2:3], v4, off
	v_cvt_pk_bf16_f32 v4, v6, s0
	v_lshl_add_u64 v[2:3], v[0:1], 1, s[18:19]
	v_add_u32_e32 v0, v39, v115
	global_store_short v[2:3], v4, off
	v_cvt_pk_bf16_f32 v4, v5, s0
	v_lshl_add_u64 v[2:3], v[0:1], 1, s[18:19]
	global_store_short v[2:3], v4, off
	ds_read2_b32 v[2:3], v130 offset0:112 offset1:113
	ds_read2_b32 v[4:5], v130 offset0:114 offset1:115
	v_add_u32_e32 v0, v26, v115
	v_lshl_add_u64 v[6:7], v[0:1], 1, s[18:19]
	s_waitcnt lgkmcnt(1)
	v_mul_f32_e32 v0, v10, v2
	v_mul_f32_e32 v2, v11, v3
	v_mul_f32_e32 v0, 0xbfb8aa3b, v0
	v_mul_f32_e32 v2, 0xbfb8aa3b, v2
	v_exp_f32_e32 v0, v0
	v_exp_f32_e32 v2, v2
	s_waitcnt lgkmcnt(0)
	v_mul_f32_e32 v3, v12, v4
	v_mul_f32_e32 v3, 0xbfb8aa3b, v3
	v_add_f32_e32 v0, 1.0, v0
	v_add_f32_e32 v2, 1.0, v2
	v_rcp_f32_e32 v0, v0
	v_rcp_f32_e32 v2, v2
	v_exp_f32_e32 v3, v3
	v_cvt_pk_bf16_f32 v0, v0, s0
	v_cvt_pk_bf16_f32 v4, v2, s0
	v_add_f32_e32 v2, 1.0, v3
	global_store_short v[6:7], v0, off
	v_rcp_f32_e32 v6, v2
	v_mul_f32_e32 v2, v13, v5
	v_mul_f32_e32 v2, 0xbfb8aa3b, v2
	v_exp_f32_e32 v5, v2
	v_add_u32_e32 v0, v27, v115
	v_lshl_add_u64 v[2:3], v[0:1], 1, s[18:19]
	global_store_short v[2:3], v4, off
	v_add_f32_e32 v0, 1.0, v5
	v_rcp_f32_e32 v5, v0
	v_add_u32_e32 v0, v28, v115
	v_cvt_pk_bf16_f32 v4, v6, s0
	v_lshl_add_u64 v[2:3], v[0:1], 1, s[18:19]
	v_add_u32_e32 v0, v29, v115
	global_store_short v[2:3], v4, off
	v_cvt_pk_bf16_f32 v4, v5, s0
	v_lshl_add_u64 v[2:3], v[0:1], 1, s[18:19]
	global_store_short v[2:3], v4, off
	ds_read2_b32 v[2:3], v130 offset0:120 offset1:121
	ds_read2_b32 v[4:5], v130 offset0:122 offset1:123
	v_add_u32_e32 v0, v30, v115
	v_lshl_add_u64 v[6:7], v[0:1], 1, s[18:19]
	s_waitcnt lgkmcnt(1)
	v_mul_f32_e32 v0, v14, v2
	v_mul_f32_e32 v2, v15, v3
	v_mul_f32_e32 v0, 0xbfb8aa3b, v0
	v_mul_f32_e32 v2, 0xbfb8aa3b, v2
	v_exp_f32_e32 v0, v0
	v_exp_f32_e32 v2, v2
	s_waitcnt lgkmcnt(0)
	v_mul_f32_e32 v3, v16, v4
	v_mul_f32_e32 v3, 0xbfb8aa3b, v3
	v_add_f32_e32 v0, 1.0, v0
	v_add_f32_e32 v2, 1.0, v2
	v_rcp_f32_e32 v0, v0
	v_rcp_f32_e32 v2, v2
	v_exp_f32_e32 v3, v3
	v_cvt_pk_bf16_f32 v0, v0, s0
	v_cvt_pk_bf16_f32 v4, v2, s0
	v_add_f32_e32 v2, 1.0, v3
	global_store_short v[6:7], v0, off
	v_rcp_f32_e32 v6, v2
	v_mul_f32_e32 v2, v17, v5
	v_mul_f32_e32 v2, 0xbfb8aa3b, v2
	v_exp_f32_e32 v5, v2
	v_add_u32_e32 v0, v31, v115
	v_lshl_add_u64 v[2:3], v[0:1], 1, s[18:19]
	global_store_short v[2:3], v4, off
	v_add_f32_e32 v0, 1.0, v5
	v_rcp_f32_e32 v5, v0
	v_add_u32_e32 v0, v32, v115
	v_cvt_pk_bf16_f32 v4, v6, s0
	v_lshl_add_u64 v[2:3], v[0:1], 1, s[18:19]
	v_add_u32_e32 v0, v33, v115
	global_store_short v[2:3], v4, off
	v_cvt_pk_bf16_f32 v4, v5, s0
	v_lshl_add_u64 v[2:3], v[0:1], 1, s[18:19]
	global_store_short v[2:3], v4, off
.Ltep_e1_e:
	v_mov_b32_e32 v0, v208
	s_mov_b32 s9, 16
	v_bfe_u32 v184, v0, 6, 2
	v_and_b32_e32 v185, 31, v0
	v_bfe_u32 v186, v0, 5, 1
	v_ashrrev_i32_e32 v2, 1, v0
	v_ashrrev_i32_e32 v35, 3, v0
	s_lshl_b64 s[22:23], s[22:23], 1
	v_lshlrev_b32_e32 v0, 4, v0
	s_add_u32 s22, s90, s22
	v_and_b32_e32 v34, 0x70, v0
	v_and_b32_e32 v187, 0xffffff80, v2
	s_addc_u32 s23, s91, s23
	v_lshl_or_b32 v0, v35, 11, v34
	s_cmp_gt_i32 s9, 1
	s_cselect_b32 s11, 0x80, 0
	v_add_u32_e32 v178, 0x20000, v0
	v_add_u32_e32 v180, 0x40000, v0
	v_add_u32_e32 v182, 0x60000, v0
	global_load_dwordx4 v[2:5], v0, s[6:7]
	global_load_dwordx4 v[6:9], v0, s[22:23]
	global_load_dwordx4 v[10:13], v178, s[6:7]
	global_load_dwordx4 v[14:17], v178, s[22:23]
	global_load_dwordx4 v[18:21], v180, s[6:7]
	global_load_dwordx4 v[22:25], v180, s[22:23]
	global_load_dwordx4 v[26:29], v182, s[6:7]
	global_load_dwordx4 v[30:33], v182, s[22:23]
	s_add_u32 s6, s6, s11
	s_addc_u32 s7, s7, 0
	s_add_u32 s22, s22, s11
	s_addc_u32 s23, s23, 0
	global_load_dwordx4 v[144:147], v0, s[6:7]
	global_load_dwordx4 v[156:159], v0, s[22:23]
	global_load_dwordx4 v[148:151], v178, s[6:7]
	global_load_dwordx4 v[152:155], v178, s[22:23]
	global_load_dwordx4 v[172:175], v180, s[6:7]
	global_load_dwordx4 v[160:163], v180, s[22:23]
	global_load_dwordx4 v[164:167], v182, s[6:7]
	global_load_dwordx4 v[168:171], v182, s[22:23]
	s_add_i32 s11, s9, -2
	v_mad_u64_u32 v[176:177], s[6:7], v35, s36, v[34:35]
	s_cmp_gt_i32 s9, 2
	s_cselect_b64 s[6:7], -1, 0
	v_mov_b32_e32 v179, v1
	v_mov_b32_e32 v181, v1
	v_mov_b32_e32 v183, v1
	s_mov_b64 s[22:23], -1
	s_and_b64 vcc, exec, s[20:21]
	s_waitcnt vmcnt(15)
	ds_write_b128 v176, v[2:5]
	s_waitcnt vmcnt(14)
	ds_write_b128 v176, v[6:9] offset:36864
	s_waitcnt vmcnt(13)
	ds_write_b128 v176, v[10:13] offset:9216
	s_waitcnt vmcnt(11)
	ds_write_b128 v176, v[18:21] offset:18432
	s_waitcnt vmcnt(9)
	ds_write_b128 v176, v[26:29] offset:27648
	ds_write_b128 v176, v[14:17] offset:46080
	ds_write_b128 v176, v[22:25] offset:55296
	s_waitcnt vmcnt(8)
	ds_write_b128 v176, v[30:33] offset:64512
	v_cndmask_b32_e64 v2, 0, 1, s[6:7]
	v_cmp_ne_u32_e64 s[6:7], 1, v2
	s_waitcnt lgkmcnt(0)
	s_cbranch_vccz .LBB0_3365
	s_and_b64 vcc, exec, s[6:7]
	s_barrier
	s_cbranch_vccnz .LBB0_3361
	v_or_b32_e32 v2, v187, v185
	s_add_u32 s20, s14, 0x345bb00
	v_mul_lo_u32 v50, v2, s36
	v_lshlrev_b32_e32 v2, 3, v186
	v_lshl_or_b32 v3, v184, 6, v185
	s_addc_u32 s21, s15, 0
	v_mul_u32_u24_e32 v51, 0x90, v3
	v_lshl_add_u64 v[34:35], s[20:21], 0, v[0:1]
	v_lshl_add_u64 v[36:37], s[20:21], 0, v[178:179]
	v_lshl_add_u64 v[38:39], s[20:21], 0, v[180:181]
	v_lshl_add_u64 v[40:41], s[20:21], 0, v[182:183]
	s_or_b32 s20, s12, 0x100
	s_mov_b32 s21, s13
	v_mov_b32_e32 v64, 0
	v_lshlrev_b32_e32 v52, 1, v2
	s_waitcnt vmcnt(7)
	v_mov_b64_e32 v[2:3], v[144:145]
	s_waitcnt vmcnt(5)
	v_mov_b64_e32 v[6:7], v[148:149]
	s_waitcnt vmcnt(3)
	v_mov_b64_e32 v[10:11], v[172:173]
	s_waitcnt vmcnt(1)
	v_mov_b64_e32 v[14:15], v[164:165]
	v_mov_b64_e32 v[18:19], v[156:157]
	v_mov_b64_e32 v[26:27], v[152:153]
	v_mov_b64_e32 v[22:23], v[160:161]
	s_waitcnt vmcnt(0)
	v_mov_b64_e32 v[30:31], v[168:169]
	v_lshl_add_u64 v[42:43], s[20:21], 0, v[0:1]
	v_lshl_add_u64 v[44:45], s[20:21], 0, v[178:179]
	v_lshl_add_u64 v[46:47], s[20:21], 0, v[180:181]
	v_lshl_add_u64 v[48:49], s[20:21], 0, v[182:183]
	s_mov_b32 s22, 0
	s_mov_b64 s[20:21], s[90:91]
	v_mov_b64_e32 v[4:5], v[146:147]
	v_mov_b64_e32 v[8:9], v[150:151]
	v_mov_b64_e32 v[12:13], v[174:175]
	v_mov_b64_e32 v[16:17], v[166:167]
	v_mov_b64_e32 v[20:21], v[158:159]
	v_mov_b64_e32 v[28:29], v[154:155]
	v_mov_b64_e32 v[24:25], v[162:163]
	v_mov_b64_e32 v[32:33], v[170:171]
	v_mov_b32_e32 v65, v64
	v_mov_b32_e32 v66, v64
	v_mov_b32_e32 v67, v64
	v_mov_b32_e32 v68, v64
	v_mov_b32_e32 v69, v64
	v_mov_b32_e32 v70, v64
	v_mov_b32_e32 v71, v64
	v_mov_b32_e32 v72, v64
	v_mov_b32_e32 v73, v64
	v_mov_b32_e32 v74, v64
	v_mov_b32_e32 v75, v64
	v_mov_b32_e32 v76, v64
	v_mov_b32_e32 v77, v64
	v_mov_b32_e32 v78, v64
	v_mov_b32_e32 v79, v64
	v_mov_b32_e32 v96, v64
	v_mov_b32_e32 v97, v64
	v_mov_b32_e32 v98, v64
	v_mov_b32_e32 v99, v64
	v_mov_b32_e32 v100, v64
	v_mov_b32_e32 v101, v64
	v_mov_b32_e32 v102, v64
	v_mov_b32_e32 v103, v64
	v_mov_b32_e32 v104, v64
	v_mov_b32_e32 v105, v64
	v_mov_b32_e32 v106, v64
	v_mov_b32_e32 v107, v64
	v_mov_b32_e32 v108, v64
	v_mov_b32_e32 v109, v64
	v_mov_b32_e32 v110, v64
	v_mov_b32_e32 v111, v64
	v_mov_b32_e32 v112, v64
	v_mov_b32_e32 v113, v64
	v_mov_b32_e32 v114, v64
	v_mov_b32_e32 v115, v64
	v_mov_b32_e32 v116, v64
	v_mov_b32_e32 v117, v64
	v_mov_b32_e32 v118, v64
	v_mov_b32_e32 v119, v64
	v_mov_b32_e32 v120, v64
	v_mov_b32_e32 v121, v64
	v_mov_b32_e32 v122, v64
	v_mov_b32_e32 v123, v64
	v_mov_b32_e32 v124, v64
	v_mov_b32_e32 v125, v64
	v_mov_b32_e32 v126, v64
	v_mov_b32_e32 v127, v64
	v_mov_b32_e32 v128, v64
	v_mov_b32_e32 v129, v64
	v_mov_b32_e32 v130, v64
	v_mov_b32_e32 v131, v64
	v_mov_b32_e32 v132, v64
	v_mov_b32_e32 v133, v64
	v_mov_b32_e32 v134, v64
	v_mov_b32_e32 v135, v64
	v_mov_b32_e32 v136, v64
	v_mov_b32_e32 v137, v64
	v_mov_b32_e32 v138, v64
	v_mov_b32_e32 v139, v64
	v_mov_b32_e32 v140, v64
	v_mov_b32_e32 v141, v64
	v_mov_b32_e32 v142, v64
	v_mov_b32_e32 v143, v64

.LBB0_3373:
	s_cmpk_lt_i32 s0, 0x4000
	s_cbranch_scc1 .Ltep_e4_f
	v_readfirstlane_b32 s64, v208
	s_bitcmp1_b32 s64, 8
	s_cbranch_scc0 .Ltep_e4_f
	s_waitcnt vmcnt(0)
	s_branch .Ltep_e4_e
.Ltep_e4_f:
	s_waitcnt vmcnt(0)
	v_mov_b32_e32 v0, v208
	v_mov_b32_e32 v2, v1
	v_lshrrev_b32_e32 v3, 1, v0
	v_and_b32_e32 v3, 0x3fff80, v3
	v_lshrrev_b32_e32 v4, 3, v0
	v_add_u32_e32 v3, s0, v3
	v_and_b32_e32 v0, 0xdf, v0
	v_and_or_b32 v3, v4, 4, v3
	v_or_b32_e32 v0, s6, v0
	v_lshlrev_b32_e32 v5, 10, v3
	v_add_u32_e32 v4, v0, v2
	v_add_u32_e32 v0, v5, v4
	v_lshlrev_b64 v[2:3], 1, v[0:1]
	v_lshl_add_u64 v[6:7], s[18:19], 0, v[2:3]
	v_lshl_add_u64 v[2:3], s[62:63], 0, v[2:3]
	global_load_ushort v192, v[6:7], off
	global_load_ushort v193, v[2:3], off
	v_mov_b32_e32 v233, v1
	v_or_b32_e32 v230,0x400,v5
	v_add_u32_e32 v232,v230,v4
	v_lshlrev_b64 v[234:235],1,v[232:233]
	v_lshl_add_u64 v[236:237],s[18:19],0,v[234:235]
	global_load_ushort v194, v[236:237], off
	v_mov_b32_e32 v233, v1
	v_or_b32_e32 v231,0x800,v5
	v_add_u32_e32 v232,v231,v4
	v_lshlrev_b64 v[234:235],1,v[232:233]
	v_lshl_add_u64 v[236:237],s[18:19],0,v[234:235]
	global_load_ushort v195, v[236:237], off
	v_mov_b32_e32 v233, v1
	v_or_b32_e32 v231,0x2000,v5
	v_add_u32_e32 v232,v231,v4
	v_lshlrev_b64 v[234:235],1,v[232:233]
	v_lshl_add_u64 v[236:237],s[18:19],0,v[234:235]
	global_load_ushort v196, v[236:237], off
	v_mov_b32_e32 v233, v1
	v_or_b32_e32 v231,0x4000,v5
	v_add_u32_e32 v232,v231,v4
	v_lshlrev_b64 v[234:235],1,v[232:233]
	v_lshl_add_u64 v[236:237],s[18:19],0,v[234:235]
	global_load_ushort v197, v[236:237], off
	v_mov_b32_e32 v233, v1
	v_or_b32_e32 v230,0x400,v5
	v_add_u32_e32 v232,v230,v4
	v_lshlrev_b64 v[234:235],1,v[232:233]
	v_lshl_add_u64 v[234:235],s[62:63],0,v[234:235]
	global_load_ushort v198, v[234:235], off
	v_mov_b32_e32 v233, v1
	v_or_b32_e32 v230,0xc00,v5
	v_add_u32_e32 v232,v230,v4
	v_lshlrev_b64 v[234:235],1,v[232:233]
	v_lshl_add_u64 v[236:237],s[18:19],0,v[234:235]
	global_load_ushort v199, v[236:237], off
	v_mov_b32_e32 v233, v1
	v_or_b32_e32 v231,0x2800,v5
	v_add_u32_e32 v232,v231,v4
	v_lshlrev_b64 v[234:235],1,v[232:233]
	v_lshl_add_u64 v[236:237],s[18:19],0,v[234:235]
	global_load_ushort v201, v[236:237], off
	v_mov_b32_e32 v233, v1
	v_or_b32_e32 v231,0x6000,v5
	v_add_u32_e32 v232,v231,v4
	v_lshlrev_b64 v[234:235],1,v[232:233]
	v_lshl_add_u64 v[236:237],s[18:19],0,v[234:235]
	global_load_ushort v202, v[236:237], off
	v_mov_b32_e32 v233, v1
	v_or_b32_e32 v231,0x800,v5
	v_add_u32_e32 v232,v231,v4
	v_lshlrev_b64 v[234:235],1,v[232:233]
	v_lshl_add_u64 v[236:237],s[62:63],0,v[234:235]
	global_load_ushort v203, v[236:237], off
	v_mov_b32_e32 v233, v1
	v_or_b32_e32 v230,0x2400,v5
	v_add_u32_e32 v232,v230,v4
	v_lshlrev_b64 v[234:235],1,v[232:233]
	v_lshl_add_u64 v[236:237],s[18:19],0,v[234:235]
	global_load_ushort v204, v[236:237], off
	v_mov_b32_e32 v233, v1
	v_or_b32_e32 v231,0x4800,v5
	v_add_u32_e32 v232,v231,v4
	v_lshlrev_b64 v[234:235],1,v[232:233]
	v_lshl_add_u64 v[236:237],s[18:19],0,v[234:235]
	global_load_ushort v205, v[236:237], off
	v_mov_b32_e32 v233, v1
	v_or_b32_e32 v230,0xc00,v5
	v_add_u32_e32 v232,v230,v4
	v_lshlrev_b64 v[234:235],1,v[232:233]
	v_lshl_add_u64 v[236:237],s[62:63],0,v[234:235]
	global_load_ushort v206, v[236:237], off
	v_mov_b32_e32 v233, v1
	v_or_b32_e32 v230,0x2c00,v5
	v_add_u32_e32 v232,v230,v4
	v_lshlrev_b64 v[234:235],1,v[232:233]
	v_lshl_add_u64 v[236:237],s[18:19],0,v[234:235]
	global_load_ushort v207, v[236:237], off
	v_mov_b32_e32 v233, v1
	v_or_b32_e32 v230,0x6800,v5
	v_add_u32_e32 v232,v230,v4
	v_lshlrev_b64 v[234:235],1,v[232:233]
	v_lshl_add_u64 v[236:237],s[18:19],0,v[234:235]
	global_load_ushort v209, v[236:237], off
	v_mov_b32_e32 v233, v1
	v_or_b32_e32 v231,0x2000,v5
	v_add_u32_e32 v232,v231,v4
	v_lshlrev_b64 v[234:235],1,v[232:233]
	v_lshl_add_u64 v[236:237],s[62:63],0,v[234:235]
	global_load_ushort v210, v[236:237], off
	v_mov_b32_e32 v233, v1
	v_or_b32_e32 v230,0x4400,v5
	v_add_u32_e32 v232,v230,v4
	v_lshlrev_b64 v[234:235],1,v[232:233]
	v_lshl_add_u64 v[236:237],s[18:19],0,v[234:235]
	global_load_ushort v211, v[236:237], off
	v_mov_b32_e32 v233, v1
	v_or_b32_e32 v230,0x2400,v5
	v_add_u32_e32 v232,v230,v4
	v_lshlrev_b64 v[234:235],1,v[232:233]
	v_lshl_add_u64 v[236:237],s[62:63],0,v[234:235]
	global_load_ushort v212, v[236:237], off
	v_mov_b32_e32 v233, v1
	v_or_b32_e32 v230,0x4c00,v5
	v_add_u32_e32 v232,v230,v4
	v_lshlrev_b64 v[234:235],1,v[232:233]
	v_lshl_add_u64 v[236:237],s[18:19],0,v[234:235]
	global_load_ushort v213, v[236:237], off
	v_mov_b32_e32 v233, v1
	v_or_b32_e32 v231,0x2800,v5
	v_add_u32_e32 v232,v231,v4
	v_lshlrev_b64 v[234:235],1,v[232:233]
	v_lshl_add_u64 v[236:237],s[62:63],0,v[234:235]
	global_load_ushort v214, v[236:237], off
	v_mov_b32_e32 v233, v1
	v_or_b32_e32 v231,0x6400,v5
	v_add_u32_e32 v232,v231,v4
	v_lshlrev_b64 v[234:235],1,v[232:233]
	v_lshl_add_u64 v[236:237],s[18:19],0,v[234:235]
	global_load_ushort v215, v[236:237], off
	v_mov_b32_e32 v233, v1
	v_or_b32_e32 v230,0x2c00,v5
	v_add_u32_e32 v232,v230,v4
	v_lshlrev_b64 v[234:235],1,v[232:233]
	v_lshl_add_u64 v[236:237],s[62:63],0,v[234:235]
	global_load_ushort v216, v[236:237], off
	v_mov_b32_e32 v233, v1
	v_or_b32_e32 v230,0x6c00,v5
	v_add_u32_e32 v232,v230,v4
	v_lshlrev_b64 v[234:235],1,v[232:233]
	v_lshl_add_u64 v[236:237],s[18:19],0,v[234:235]
	global_load_ushort v217, v[236:237], off
	v_mov_b32_e32 v233, v1
	v_or_b32_e32 v231,0x4000,v5
	v_add_u32_e32 v232,v231,v4
	v_lshlrev_b64 v[234:235],1,v[232:233]
	v_lshl_add_u64 v[236:237],s[62:63],0,v[234:235]
	global_load_ushort v218, v[236:237], off
	v_mov_b32_e32 v233, v1
	v_or_b32_e32 v230,0x4400,v5
	v_add_u32_e32 v232,v230,v4
	v_lshlrev_b64 v[234:235],1,v[232:233]
	v_lshl_add_u64 v[236:237],s[62:63],0,v[234:235]
	global_load_ushort v219, v[236:237], off
	v_mov_b32_e32 v233, v1
	v_or_b32_e32 v231,0x4800,v5
	v_add_u32_e32 v232,v231,v4
	v_lshlrev_b64 v[234:235],1,v[232:233]
	v_lshl_add_u64 v[236:237],s[62:63],0,v[234:235]
	global_load_ushort v220, v[236:237], off
	v_mov_b32_e32 v233, v1
	v_or_b32_e32 v230,0x4c00,v5
	v_add_u32_e32 v232,v230,v4
	v_lshlrev_b64 v[234:235],1,v[232:233]
	v_lshl_add_u64 v[236:237],s[62:63],0,v[234:235]
	global_load_ushort v221, v[236:237], off
	v_mov_b32_e32 v233, v1
	v_or_b32_e32 v231,0x6000,v5
	v_add_u32_e32 v232,v231,v4
	v_lshlrev_b64 v[234:235],1,v[232:233]
	v_lshl_add_u64 v[236:237],s[62:63],0,v[234:235]
	global_load_ushort v222, v[236:237], off
	v_mov_b32_e32 v233, v1
	v_or_b32_e32 v231,0x6400,v5
	v_add_u32_e32 v232,v231,v4
	v_lshlrev_b64 v[234:235],1,v[232:233]
	v_lshl_add_u64 v[236:237],s[62:63],0,v[234:235]
	global_load_ushort v223, v[236:237], off
	v_mov_b32_e32 v233, v1
	v_or_b32_e32 v230,0x6800,v5
	v_add_u32_e32 v232,v230,v4
	v_lshlrev_b64 v[234:235],1,v[232:233]
	v_lshl_add_u64 v[236:237],s[62:63],0,v[234:235]
	global_load_ushort v224, v[236:237], off
	v_mov_b32_e32 v233, v1
	v_or_b32_e32 v230,0x6c00,v5
	v_add_u32_e32 v232,v230,v4
	v_lshlrev_b64 v[234:235],1,v[232:233]
	v_lshl_add_u64 v[236:237],s[62:63],0,v[234:235]
	global_load_ushort v225, v[236:237], off
	v_mov_b32_e32 v235, v1
	v_or_b32_e32 v230,0x6c00,v5
	v_add_u32_e32 v232,32,v4
	v_add_u32_e32 v234,v230,v232
	v_lshlrev_b64 v[236:237],1,v[234:235]
	v_lshl_add_u64 v[240:241],s[18:19],0,v[236:237]
	global_load_ushort v226, v[240:241], off
	v_mov_b32_e32 v233, v1
	v_add_u32_e32 v230,32,v4
	v_add_u32_e32 v232,v5,v230
	v_lshlrev_b64 v[234:235],1,v[232:233]
	v_lshl_add_u64 v[236:237],s[18:19],0,v[234:235]
	global_load_ushort v227, v[236:237], off
	v_mov_b32_e32 v233, v1
	v_add_u32_e32 v230,32,v4
	v_add_u32_e32 v232,v5,v230
	v_lshlrev_b64 v[234:235],1,v[232:233]
	v_lshl_add_u64 v[234:235],s[62:63],0,v[234:235]
	global_load_ushort v228, v[234:235], off
	v_mov_b32_e32 v235, v1
	v_or_b32_e32 v230,0x400,v5
	v_add_u32_e32 v232,32,v4
	v_add_u32_e32 v234,v230,v232
	v_lshlrev_b64 v[236:237],1,v[234:235]
	v_lshl_add_u64 v[240:241],s[18:19],0,v[236:237]
	global_load_ushort v229, v[240:241], off
	v_or_b32_e32 v170, 0x400, v5
	v_or_b32_e32 v171, 0x800, v5
	v_add_u32_e32 v0, v170, v4
	v_or_b32_e32 v172, 0xc00, v5
	v_lshlrev_b64 v[2:3], 1, v[0:1]
	v_add_u32_e32 v0, v171, v4
	v_or_b32_e32 v173, 0x2000, v5
	v_lshlrev_b64 v[10:11], 1, v[0:1]
	v_add_u32_e32 v0, v172, v4
	v_or_b32_e32 v174, 0x2400, v5
	v_lshlrev_b64 v[14:15], 1, v[0:1]
	v_add_u32_e32 v0, v173, v4
	v_or_b32_e32 v175, 0x2800, v5
	v_lshlrev_b64 v[144:145], 1, v[0:1]
	v_add_u32_e32 v0, v174, v4
	v_or_b32_e32 v176, 0x2c00, v5
	v_lshlrev_b64 v[148:149], 1, v[0:1]
	v_add_u32_e32 v0, v175, v4
	v_or_b32_e32 v177, 0x4000, v5
	v_lshlrev_b64 v[150:151], 1, v[0:1]
	v_add_u32_e32 v0, v176, v4
	v_lshlrev_b64 v[152:153], 1, v[0:1]
	v_add_u32_e32 v0, v177, v4
	v_lshlrev_b64 v[154:155], 1, v[0:1]
	v_lshl_add_u64 v[8:9], s[18:19], 0, v[2:3]
	v_lshl_add_u64 v[2:3], s[62:63], 0, v[2:3]
	v_lshl_add_u64 v[12:13], s[18:19], 0, v[10:11]
	v_lshl_add_u64 v[146:147], s[18:19], 0, v[144:145]
	v_lshl_add_u64 v[156:157], s[18:19], 0, v[154:155]
	v_or_b32_e32 v180, 0x4400, v5
	v_or_b32_e32 v181, 0x4800, v5
	v_or_b32_e32 v182, 0x4c00, v5
	v_or_b32_e32 v183, 0x6000, v5
	v_or_b32_e32 v189, 0x6400, v5
	v_or_b32_e32 v190, 0x6800, v5
	s_waitcnt vmcnt(35)
	v_lshlrev_b32_e32 v0, 16, v192
	v_mov_b32_e32 v233, v1
	v_add_u32_e32 v230,32,v4
	v_add_u32_e32 v232,v171,v230
	v_lshlrev_b64 v[234:235],1,v[232:233]
	v_lshl_add_u64 v[236:237],s[18:19],0,v[234:235]
	global_load_ushort v192, v[236:237], off
	s_waitcnt vmcnt(35)
	v_lshlrev_b32_e32 v158, 16, v193
	v_mov_b32_e32 v233, v1
	v_add_u32_e32 v230,32,v4
	v_add_u32_e32 v232,v173,v230
	v_lshlrev_b64 v[234:235],1,v[232:233]
	v_lshl_add_u64 v[236:237],s[18:19],0,v[234:235]
	global_load_ushort v193, v[236:237], off
	v_fmac_f32_e32 v0, v128, v158
	v_cvt_pk_bf16_f32 v0, v0, s0
	global_store_short v[6:7], v0, off
	v_add_u32_e32 v0, v180, v4
	v_lshlrev_b64 v[158:159], 1, v[0:1]
	v_add_u32_e32 v0, v181, v4
	v_lshlrev_b64 v[160:161], 1, v[0:1]
	v_add_u32_e32 v0, v182, v4
	v_lshlrev_b64 v[162:163], 1, v[0:1]
	v_add_u32_e32 v0, v183, v4
	v_lshlrev_b64 v[164:165], 1, v[0:1]
	v_lshl_add_u64 v[6:7], s[18:19], 0, v[14:15]
	v_lshl_add_u64 v[2:3], s[62:63], 0, v[10:11]
	v_lshl_add_u64 v[10:11], s[18:19], 0, v[150:151]
	v_lshl_add_u64 v[166:167], s[18:19], 0, v[164:165]
	s_waitcnt vmcnt(36)
	v_lshlrev_b32_e32 v0, 16, v194
	v_mov_b32_e32 v233, v1
	v_add_u32_e32 v230,32,v4
	v_add_u32_e32 v232,v177,v230
	v_lshlrev_b64 v[234:235],1,v[232:233]
	v_lshl_add_u64 v[236:237],s[18:19],0,v[234:235]
	global_load_ushort v194, v[236:237], off
	s_waitcnt vmcnt(33)
	v_lshlrev_b32_e32 v128, 16, v198
	v_mov_b32_e32 v233, v1
	v_add_u32_e32 v230,32,v4
	v_add_u32_e32 v232,v170,v230
	v_lshlrev_b64 v[234:235],1,v[232:233]
	v_lshl_add_u64 v[236:237],s[62:63],0,v[234:235]
	global_load_ushort v198, v[236:237], off
	v_fmac_f32_e32 v0, v129, v128
	v_cvt_pk_bf16_f32 v0, v0, s0
	global_store_short v[8:9], v0, off
	v_lshlrev_b32_e32 v128, 16, v195
	v_mov_b32_e32 v233, v1
	v_add_u32_e32 v230,32,v4
	v_add_u32_e32 v232,v172,v230
	v_lshlrev_b64 v[234:235],1,v[232:233]
	v_lshl_add_u64 v[236:237],s[18:19],0,v[234:235]
	global_load_ushort v195, v[236:237], off
	v_lshl_add_u64 v[8:9], s[18:19], 0, v[148:149]
	v_lshl_add_u64 v[2:3], s[62:63], 0, v[14:15]
	v_lshl_add_u64 v[14:15], s[18:19], 0, v[160:161]
	s_waitcnt vmcnt(32)
	v_lshlrev_b32_e32 v0, 16, v203
	v_mov_b32_e32 v233, v1
	v_add_u32_e32 v230,32,v4
	v_add_u32_e32 v232,v175,v230
	v_lshlrev_b64 v[234:235],1,v[232:233]
	v_lshl_add_u64 v[236:237],s[18:19],0,v[234:235]
	global_load_ushort v203, v[236:237], off
	v_fmac_f32_e32 v128, v130, v0
	v_cvt_pk_bf16_f32 v0, v128, s0
	global_store_short v[12:13], v0, off
	v_add_u32_e32 v0, v189, v4
	v_lshlrev_b64 v[128:129], 1, v[0:1]
	v_add_u32_e32 v0, v190, v4
	v_lshl_add_u64 v[2:3], s[62:63], 0, v[144:145]
	v_lshlrev_b64 v[144:145], 1, v[0:1]
	v_lshlrev_b32_e32 v0, 16, v199
	v_mov_b32_e32 v233, v1
	v_add_u32_e32 v230,32,v4
	v_add_u32_e32 v232,v183,v230
	v_lshlrev_b64 v[234:235],1,v[232:233]
	v_lshl_add_u64 v[236:237],s[18:19],0,v[234:235]
	global_load_ushort v199, v[236:237], off
	v_lshl_add_u64 v[12:13], s[18:19], 0, v[152:153]
	v_lshl_add_u64 v[168:169], s[18:19], 0, v[144:145]
	s_waitcnt vmcnt(32)
	v_lshlrev_b32_e32 v130, 16, v206
	v_mov_b32_e32 v233, v1
	v_add_u32_e32 v230,32,v4
	v_add_u32_e32 v232,v171,v230
	v_lshlrev_b64 v[234:235],1,v[232:233]
	v_lshl_add_u64 v[236:237],s[62:63],0,v[234:235]
	global_load_ushort v206, v[236:237], off
	v_fmac_f32_e32 v0, v131, v130
	v_cvt_pk_bf16_f32 v0, v0, s0
	global_store_short v[6:7], v0, off
	v_lshlrev_b32_e32 v130, 16, v196
	v_mov_b32_e32 v233, v1
	v_add_u32_e32 v230,32,v4
	v_add_u32_e32 v232,v174,v230
	v_lshlrev_b64 v[234:235],1,v[232:233]
	v_lshl_add_u64 v[236:237],s[18:19],0,v[234:235]
	global_load_ushort v196, v[236:237], off
	v_lshl_add_u64 v[2:3], s[62:63], 0, v[148:149]
	v_lshl_add_u64 v[6:7], s[18:19], 0, v[158:159]
	v_or_b32_e32 v178, 0x6c00, v5
	s_waitcnt vmcnt(32)
	v_lshlrev_b32_e32 v0, 16, v210
	v_mov_b32_e32 v233, v1
	v_add_u32_e32 v230,32,v4
	v_add_u32_e32 v232,v181,v230
	v_lshlrev_b64 v[234:235],1,v[232:233]
	v_lshl_add_u64 v[236:237],s[18:19],0,v[234:235]
	global_load_ushort v210, v[236:237], off
	v_fmac_f32_e32 v130, v132, v0
	v_cvt_pk_bf16_f32 v0, v130, s0
	global_store_short v[146:147], v0, off
	v_lshlrev_b32_e32 v132, 16, v204
	v_mov_b32_e32 v233, v1
	v_add_u32_e32 v230,32,v4
	v_add_u32_e32 v232,v172,v230
	v_lshlrev_b64 v[234:235],1,v[232:233]
	v_lshl_add_u64 v[236:237],s[62:63],0,v[234:235]
	global_load_ushort v204, v[236:237], off
	v_lshl_add_u64 v[2:3], s[62:63], 0, v[150:151]
	v_lshl_add_u64 v[130:131], s[18:19], 0, v[162:163]
	s_waitcnt vmcnt(33)
	v_lshlrev_b32_e32 v0, 16, v212
	v_mov_b32_e32 v233, v1
	v_add_u32_e32 v230,32,v4
	v_add_u32_e32 v232,v176,v230
	v_lshlrev_b64 v[234:235],1,v[232:233]
	v_lshl_add_u64 v[236:237],s[18:19],0,v[234:235]
	global_load_ushort v212, v[236:237], off
	v_fmac_f32_e32 v132, v133, v0
	v_cvt_pk_bf16_f32 v0, v132, s0
	global_store_short v[8:9], v0, off
	v_lshl_add_u64 v[8:9], s[18:19], 0, v[128:129]
	v_lshlrev_b32_e32 v132, 16, v201
	v_mov_b32_e32 v233, v1
	v_add_u32_e32 v230,32,v4
	v_add_u32_e32 v232,v190,v230
	v_lshlrev_b64 v[234:235],1,v[232:233]
	v_lshl_add_u64 v[236:237],s[18:19],0,v[234:235]
	global_load_ushort v201, v[236:237], off
	v_lshl_add_u64 v[2:3], s[62:63], 0, v[152:153]
	s_waitcnt vmcnt(34)
	v_lshlrev_b32_e32 v0, 16, v214
	v_mov_b32_e32 v233, v1
	v_add_u32_e32 v230,32,v4
	v_add_u32_e32 v232,v173,v230
	v_lshlrev_b64 v[234:235],1,v[232:233]
	v_lshl_add_u64 v[236:237],s[62:63],0,v[234:235]
	global_load_ushort v214, v[236:237], off
	v_fmac_f32_e32 v132, v134, v0
	v_cvt_pk_bf16_f32 v0, v132, s0
	global_store_short v[10:11], v0, off
	v_add_u32_e32 v0, v178, v4
	v_lshlrev_b64 v[132:133], 1, v[0:1]
	v_lshlrev_b32_e32 v0, 16, v207
	v_mov_b32_e32 v233, v1
	v_add_u32_e32 v230,32,v4
	v_add_u32_e32 v232,v180,v230
	v_lshlrev_b64 v[234:235],1,v[232:233]
	v_lshl_add_u64 v[236:237],s[18:19],0,v[234:235]
	global_load_ushort v207, v[236:237], off
	v_lshl_add_u64 v[10:11], s[62:63], 0, v[154:155]
	v_lshl_add_u64 v[2:3], s[18:19], 0, v[132:133]
	s_waitcnt vmcnt(35)
	v_lshlrev_b32_e32 v134, 16, v216
	v_mov_b32_e32 v233, v1
	v_add_u32_e32 v230,32,v4
	v_add_u32_e32 v232,v174,v230
	v_lshlrev_b64 v[234:235],1,v[232:233]
	v_lshl_add_u64 v[236:237],s[62:63],0,v[234:235]
	global_load_ushort v216, v[236:237], off
	v_fmac_f32_e32 v0, v135, v134
	v_cvt_pk_bf16_f32 v0, v0, s0
	global_store_short v[12:13], v0, off
	v_lshlrev_b32_e32 v12, 16, v197
	v_mov_b32_e32 v233, v1
	v_add_u32_e32 v230,32,v4
	v_add_u32_e32 v232,v182,v230
	v_lshlrev_b64 v[234:235],1,v[232:233]
	v_lshl_add_u64 v[236:237],s[18:19],0,v[234:235]
	global_load_ushort v197, v[236:237], off
	v_lshl_add_u64 v[10:11], s[62:63], 0, v[158:159]
	s_waitcnt vmcnt(36)
	v_lshlrev_b32_e32 v0, 16, v218
	v_mov_b32_e32 v233, v1
	v_add_u32_e32 v230,32,v4
	v_add_u32_e32 v232,v175,v230
	v_lshlrev_b64 v[234:235],1,v[232:233]
	v_lshl_add_u64 v[236:237],s[62:63],0,v[234:235]
	global_load_ushort v218, v[236:237], off
	v_fmac_f32_e32 v12, v136, v0
	v_cvt_pk_bf16_f32 v0, v12, s0
	global_store_short v[156:157], v0, off
	v_lshlrev_b32_e32 v12, 16, v211
	v_mov_b32_e32 v233, v1
	v_add_u32_e32 v230,32,v4
	v_add_u32_e32 v232,v189,v230
	v_lshlrev_b64 v[234:235],1,v[232:233]
	v_lshl_add_u64 v[236:237],s[18:19],0,v[234:235]
	global_load_ushort v211, v[236:237], off
	v_lshl_add_u64 v[10:11], s[62:63], 0, v[160:161]
	s_waitcnt vmcnt(38)
	v_lshlrev_b32_e32 v0, 16, v219
	v_mov_b32_e32 v233, v1
	v_add_u32_e32 v230,32,v4
	v_add_u32_e32 v232,v176,v230
	v_lshlrev_b64 v[234:235],1,v[232:233]
	v_lshl_add_u64 v[236:237],s[62:63],0,v[234:235]
	global_load_ushort v219, v[236:237], off
	v_fmac_f32_e32 v12, v137, v0
	v_cvt_pk_bf16_f32 v0, v12, s0
	global_store_short v[6:7], v0, off
	v_lshlrev_b32_e32 v10, 16, v205
	v_mov_b32_e32 v233, v1
	v_add_u32_e32 v230,32,v4
	v_add_u32_e32 v232,v177,v230
	v_lshlrev_b64 v[234:235],1,v[232:233]
	v_lshl_add_u64 v[236:237],s[62:63],0,v[234:235]
	global_load_ushort v205, v[236:237], off
	v_lshl_add_u64 v[6:7], s[62:63], 0, v[162:163]
	s_waitcnt vmcnt(40)
	v_lshlrev_b32_e32 v0, 16, v220
	v_mov_b32_e32 v233, v1
	v_add_u32_e32 v230,32,v4
	v_add_u32_e32 v232,v180,v230
	v_lshlrev_b64 v[234:235],1,v[232:233]
	v_lshl_add_u64 v[236:237],s[62:63],0,v[234:235]
	global_load_ushort v220, v[236:237], off
	v_fmac_f32_e32 v10, v138, v0
	v_cvt_pk_bf16_f32 v0, v10, s0
	global_store_short v[14:15], v0, off
	v_lshlrev_b32_e32 v10, 16, v213
	v_mov_b32_e32 v233, v1
	v_add_u32_e32 v230,32,v4
	v_add_u32_e32 v232,v181,v230
	v_lshlrev_b64 v[234:235],1,v[232:233]
	v_lshl_add_u64 v[236:237],s[62:63],0,v[234:235]
	global_load_ushort v213, v[236:237], off
	v_lshl_add_u64 v[6:7], s[62:63], 0, v[164:165]
	s_waitcnt vmcnt(42)
	v_lshlrev_b32_e32 v0, 16, v221
	v_mov_b32_e32 v233, v1
	v_add_u32_e32 v230,32,v4
	v_add_u32_e32 v232,v182,v230
	v_lshlrev_b64 v[234:235],1,v[232:233]
	v_lshl_add_u64 v[236:237],s[62:63],0,v[234:235]
	global_load_ushort v221, v[236:237], off
	v_fmac_f32_e32 v10, v139, v0
	v_cvt_pk_bf16_f32 v0, v10, s0
	global_store_short v[130:131], v0, off
	v_lshlrev_b32_e32 v10, 16, v202
	v_mov_b32_e32 v233, v1
	v_add_u32_e32 v230,32,v4
	v_add_u32_e32 v232,v183,v230
	v_lshlrev_b64 v[234:235],1,v[232:233]
	v_lshl_add_u64 v[236:237],s[62:63],0,v[234:235]
	global_load_ushort v202, v[236:237], off
	v_lshl_add_u64 v[6:7], s[62:63], 0, v[128:129]
	s_waitcnt vmcnt(44)
	v_lshlrev_b32_e32 v0, 16, v222
	v_mov_b32_e32 v233, v1
	v_add_u32_e32 v230,32,v4
	v_add_u32_e32 v232,v189,v230
	v_lshlrev_b64 v[234:235],1,v[232:233]
	v_lshl_add_u64 v[236:237],s[62:63],0,v[234:235]
	global_load_ushort v222, v[236:237], off
	v_fmac_f32_e32 v10, v140, v0
	v_cvt_pk_bf16_f32 v0, v10, s0
	global_store_short v[166:167], v0, off
	v_lshlrev_b32_e32 v10, 16, v215
	v_mov_b32_e32 v233, v1
	v_add_u32_e32 v230,32,v4
	v_add_u32_e32 v232,v190,v230
	v_lshlrev_b64 v[234:235],1,v[232:233]
	v_lshl_add_u64 v[236:237],s[62:63],0,v[234:235]
	global_load_ushort v215, v[236:237], off
	v_lshl_add_u64 v[6:7], s[62:63], 0, v[144:145]
	s_waitcnt vmcnt(46)
	v_lshlrev_b32_e32 v0, 16, v223
	v_mov_b32_e32 v233, v1
	v_add_u32_e32 v230,32,v4
	v_add_u32_e32 v232,v178,v230
	v_lshlrev_b64 v[234:235],1,v[232:233]
	v_lshl_add_u64 v[236:237],s[62:63],0,v[234:235]
	global_load_ushort v223, v[236:237], off
	v_fmac_f32_e32 v10, v141, v0
	v_cvt_pk_bf16_f32 v0, v10, s0
	global_store_short v[8:9], v0, off
	v_lshlrev_b32_e32 v8, 16, v209
	v_mov_b32_e32 v233, v1
	v_or_b32_e32 v231,0x8000,v5
	v_add_u32_e32 v232,v231,v4
	v_lshlrev_b64 v[234:235],1,v[232:233]
	v_lshl_add_u64 v[236:237],s[18:19],0,v[234:235]
	global_load_ushort v209, v[236:237], off
	v_lshl_add_u64 v[6:7], s[62:63], 0, v[132:133]
	s_waitcnt vmcnt(48)
	v_lshlrev_b32_e32 v0, 16, v224
	v_mov_b32_e32 v233, v1
	v_or_b32_e32 v231,0x8000,v5
	v_add_u32_e32 v232,v231,v4
	v_lshlrev_b64 v[234:235],1,v[232:233]
	v_lshl_add_u64 v[234:235],s[62:63],0,v[234:235]
	global_load_ushort v224, v[234:235], off
	v_fmac_f32_e32 v8, v142, v0
	v_cvt_pk_bf16_f32 v0, v8, s0
	global_store_short v[168:169], v0, off
	v_add_u32_e32 v6, 32, v4
	v_add_u32_e32 v0, v5, v6
	v_lshlrev_b64 v[8:9], 1, v[0:1]
	v_add_u32_e32 v0, v170, v6
	v_lshlrev_b64 v[12:13], 1, v[0:1]
	v_add_u32_e32 v0, v171, v6
	v_lshlrev_b64 v[14:15], 1, v[0:1]
	v_add_u32_e32 v0, v172, v6
	v_lshlrev_b64 v[128:129], 1, v[0:1]
	v_add_u32_e32 v0, v173, v6
	v_lshlrev_b64 v[130:131], 1, v[0:1]
	v_add_u32_e32 v0, v174, v6
	v_lshlrev_b64 v[132:133], 1, v[0:1]
	v_add_u32_e32 v0, v175, v6
	v_lshlrev_b64 v[134:135], 1, v[0:1]
	v_add_u32_e32 v0, v176, v6
	v_lshlrev_b64 v[136:137], 1, v[0:1]
	v_add_u32_e32 v0, v177, v6
	v_lshlrev_b64 v[138:139], 1, v[0:1]
	v_add_u32_e32 v0, v180, v6
	v_lshlrev_b64 v[140:141], 1, v[0:1]
	v_add_u32_e32 v0, v181, v6
	v_lshlrev_b64 v[144:145], 1, v[0:1]
	v_add_u32_e32 v0, v182, v6
	v_lshlrev_b64 v[146:147], 1, v[0:1]
	v_add_u32_e32 v0, v183, v6
	v_lshlrev_b64 v[148:149], 1, v[0:1]
	v_add_u32_e32 v0, v189, v6
	v_lshlrev_b64 v[150:151], 1, v[0:1]
	v_add_u32_e32 v0, v190, v6
	v_lshlrev_b64 v[152:153], 1, v[0:1]
	v_add_u32_e32 v0, v178, v6
	v_lshlrev_b64 v[154:155], 1, v[0:1]
	v_lshlrev_b32_e32 v0, 16, v217
	v_mov_b32_e32 v233, v1
	v_or_b32_e32 v230,0x8400,v5
	v_add_u32_e32 v232,v230,v4
	v_lshlrev_b64 v[234:235],1,v[232:233]
	v_lshl_add_u64 v[236:237],s[18:19],0,v[234:235]
	global_load_ushort v217, v[236:237], off
	v_lshl_add_u64 v[10:11], s[18:19], 0, v[8:9]
	v_lshl_add_u64 v[156:157], s[18:19], 0, v[154:155]
	v_lshl_add_u64 v[8:9], s[62:63], 0, v[8:9]
	v_lshl_add_u64 v[158:159], s[18:19], 0, v[138:139]
	v_lshl_add_u64 v[160:161], s[18:19], 0, v[148:149]
	s_waitcnt vmcnt(50)
	v_lshlrev_b32_e32 v7, 16, v225
	v_mov_b32_e32 v233, v1
	v_or_b32_e32 v231,0x8800,v5
	v_add_u32_e32 v232,v231,v4
	v_lshlrev_b64 v[234:235],1,v[232:233]
	v_lshl_add_u64 v[236:237],s[18:19],0,v[234:235]
	global_load_ushort v225, v[236:237], off
	v_fmac_f32_e32 v0, v143, v7
	v_cvt_pk_bf16_f32 v0, v0, s0
	global_store_short v[2:3], v0, off
	s_nop 0
	v_lshl_add_u64 v[2:3], s[18:19], 0, v[12:13]
	v_lshl_add_u64 v[8:9], s[62:63], 0, v[12:13]
	v_lshl_add_u64 v[12:13], s[18:19], 0, v[14:15]
	v_lshl_add_u64 v[142:143], s[18:19], 0, v[130:131]
	s_waitcnt vmcnt(50)
	v_lshlrev_b32_e32 v0, 16, v227
	v_mov_b32_e32 v233, v1
	v_or_b32_e32 v231,0xa000,v5
	v_add_u32_e32 v232,v231,v4
	v_lshlrev_b64 v[234:235],1,v[232:233]
	v_lshl_add_u64 v[236:237],s[18:19],0,v[234:235]
	global_load_ushort v227, v[236:237], off
	s_waitcnt vmcnt(50)
	v_lshlrev_b32_e32 v7, 16, v228
	v_mov_b32_e32 v233, v1
	v_or_b32_e32 v231,0xc000,v5
	v_add_u32_e32 v232,v231,v4
	v_lshlrev_b64 v[234:235],1,v[232:233]
	v_lshl_add_u64 v[236:237],s[18:19],0,v[234:235]
	global_load_ushort v228, v[236:237], off
	v_fmac_f32_e32 v0, v112, v7
	v_cvt_pk_bf16_f32 v0, v0, s0
	global_store_short v[10:11], v0, off
	s_waitcnt vmcnt(51)
	v_lshlrev_b32_e32 v7, 16, v229
	v_mov_b32_e32 v233, v1
	v_or_b32_e32 v230,0x8400,v5
	v_add_u32_e32 v232,v230,v4
	v_lshlrev_b64 v[234:235],1,v[232:233]
	v_lshl_add_u64 v[234:235],s[62:63],0,v[234:235]
	global_load_ushort v229, v[234:235], off
	v_lshl_add_u64 v[10:11], s[18:19], 0, v[128:129]
	v_lshl_add_u64 v[8:9], s[62:63], 0, v[14:15]
	v_lshl_add_u64 v[14:15], s[18:19], 0, v[134:135]
	s_waitcnt vmcnt(47)
	v_lshlrev_b32_e32 v0, 16, v198
	v_mov_b32_e32 v233, v1
	v_or_b32_e32 v230,0x8c00,v5
	v_add_u32_e32 v232,v230,v4
	v_lshlrev_b64 v[234:235],1,v[232:233]
	v_lshl_add_u64 v[236:237],s[18:19],0,v[234:235]
	global_load_ushort v198, v[236:237], off
	v_fmac_f32_e32 v7, v113, v0
	v_cvt_pk_bf16_f32 v0, v7, s0
	global_store_short v[2:3], v0, off
	v_lshlrev_b32_e32 v7, 16, v192
	v_mov_b32_e32 v233, v1
	v_or_b32_e32 v231,0xa800,v5
	v_add_u32_e32 v232,v231,v4
	v_lshlrev_b64 v[234:235],1,v[232:233]
	v_lshl_add_u64 v[236:237],s[18:19],0,v[234:235]
	global_load_ushort v192, v[236:237], off
	v_lshl_add_u64 v[8:9], s[18:19], 0, v[132:133]
	v_lshl_add_u64 v[2:3], s[62:63], 0, v[128:129]
	v_lshl_add_u64 v[112:113], s[18:19], 0, v[144:145]
	v_lshl_add_u64 v[128:129], s[18:19], 0, v[152:153]
	s_waitcnt vmcnt(44)
	v_lshlrev_b32_e32 v0, 16, v206
	v_mov_b32_e32 v233, v1
	v_or_b32_e32 v231,0xe000,v5
	v_add_u32_e32 v232,v231,v4
	v_lshlrev_b64 v[234:235],1,v[232:233]
	v_lshl_add_u64 v[236:237],s[18:19],0,v[234:235]
	global_load_ushort v206, v[236:237], off
	v_fmac_f32_e32 v7, v114, v0
	v_cvt_pk_bf16_f32 v0, v7, s0
	global_store_short v[12:13], v0, off
	v_lshlrev_b32_e32 v7, 16, v195
	v_mov_b32_e32 v233, v1
	v_or_b32_e32 v231,0x8800,v5
	v_add_u32_e32 v232,v231,v4
	v_lshlrev_b64 v[234:235],1,v[232:233]
	v_lshl_add_u64 v[236:237],s[62:63],0,v[234:235]
	global_load_ushort v195, v[236:237], off
	v_lshl_add_u64 v[12:13], s[18:19], 0, v[136:137]
	v_lshl_add_u64 v[2:3], s[62:63], 0, v[130:131]
	s_waitcnt vmcnt(42)
	v_lshlrev_b32_e32 v0, 16, v204
	v_mov_b32_e32 v233, v1
	v_or_b32_e32 v230,0xa400,v5
	v_add_u32_e32 v232,v230,v4
	v_lshlrev_b64 v[234:235],1,v[232:233]
	v_lshl_add_u64 v[236:237],s[18:19],0,v[234:235]
	global_load_ushort v204, v[236:237], off
	v_fmac_f32_e32 v7, v115, v0
	v_cvt_pk_bf16_f32 v0, v7, s0
	global_store_short v[10:11], v0, off
	v_lshlrev_b32_e32 v7, 16, v193
	v_mov_b32_e32 v233, v1
	v_or_b32_e32 v231,0xc800,v5
	v_add_u32_e32 v232,v231,v4
	v_lshlrev_b64 v[234:235],1,v[232:233]
	v_lshl_add_u64 v[236:237],s[18:19],0,v[234:235]
	global_load_ushort v193, v[236:237], off
	v_lshl_add_u64 v[2:3], s[62:63], 0, v[132:133]
	v_lshl_add_u64 v[10:11], s[18:19], 0, v[140:141]
	v_lshl_add_u64 v[114:115], s[18:19], 0, v[146:147]
	s_waitcnt vmcnt(41)
	v_lshlrev_b32_e32 v0, 16, v214
	v_mov_b32_e32 v233, v1
	v_or_b32_e32 v230,0x8c00,v5
	v_add_u32_e32 v232,v230,v4
	v_lshlrev_b64 v[234:235],1,v[232:233]
	v_lshl_add_u64 v[236:237],s[62:63],0,v[234:235]
	global_load_ushort v214, v[236:237], off
	v_fmac_f32_e32 v7, v116, v0
	v_cvt_pk_bf16_f32 v0, v7, s0
	global_store_short v[142:143], v0, off
	v_lshlrev_b32_e32 v7, 16, v196
	v_mov_b32_e32 v233, v1
	v_or_b32_e32 v230,0xac00,v5
	v_add_u32_e32 v232,v230,v4
	v_lshlrev_b64 v[234:235],1,v[232:233]
	v_lshl_add_u64 v[236:237],s[18:19],0,v[234:235]
	global_load_ushort v196, v[236:237], off
	v_lshl_add_u64 v[2:3], s[62:63], 0, v[134:135]
	s_waitcnt vmcnt(41)
	v_lshlrev_b32_e32 v0, 16, v216
	v_mov_b32_e32 v233, v1
	v_or_b32_e32 v230,0xe800,v5
	v_add_u32_e32 v232,v230,v4
	v_lshlrev_b64 v[234:235],1,v[232:233]
	v_lshl_add_u64 v[236:237],s[18:19],0,v[234:235]
	global_load_ushort v216, v[236:237], off
	v_fmac_f32_e32 v7, v117, v0
	v_cvt_pk_bf16_f32 v0, v7, s0
	global_store_short v[8:9], v0, off
	v_lshl_add_u64 v[8:9], s[18:19], 0, v[150:151]
	v_lshlrev_b32_e32 v7, 16, v203
	v_mov_b32_e32 v233, v1
	v_or_b32_e32 v231,0xa000,v5
	v_add_u32_e32 v232,v231,v4
	v_lshlrev_b64 v[234:235],1,v[232:233]
	v_lshl_add_u64 v[236:237],s[62:63],0,v[234:235]
	global_load_ushort v203, v[236:237], off
	v_lshl_add_u64 v[2:3], s[62:63], 0, v[136:137]
	s_waitcnt vmcnt(41)
	v_lshlrev_b32_e32 v0, 16, v218
	v_mov_b32_e32 v233, v1
	v_or_b32_e32 v230,0xc400,v5
	v_add_u32_e32 v232,v230,v4
	v_lshlrev_b64 v[234:235],1,v[232:233]
	v_lshl_add_u64 v[236:237],s[18:19],0,v[234:235]
	global_load_ushort v218, v[236:237], off
	v_fmac_f32_e32 v7, v118, v0
	v_cvt_pk_bf16_f32 v0, v7, s0
	global_store_short v[14:15], v0, off
	v_lshlrev_b32_e32 v7, 16, v212
	v_mov_b32_e32 v233, v1
	v_or_b32_e32 v230,0xa400,v5
	v_add_u32_e32 v232,v230,v4
	v_lshlrev_b64 v[234:235],1,v[232:233]
	v_lshl_add_u64 v[236:237],s[62:63],0,v[234:235]
	global_load_ushort v212, v[236:237], off
	v_lshl_add_u64 v[2:3], s[62:63], 0, v[138:139]
	s_waitcnt vmcnt(41)
	v_lshlrev_b32_e32 v0, 16, v219
	v_mov_b32_e32 v233, v1
	v_or_b32_e32 v230,0xcc00,v5
	v_add_u32_e32 v232,v230,v4
	v_lshlrev_b64 v[234:235],1,v[232:233]
	v_lshl_add_u64 v[236:237],s[18:19],0,v[234:235]
	global_load_ushort v219, v[236:237], off
	v_fmac_f32_e32 v7, v119, v0
	v_cvt_pk_bf16_f32 v0, v7, s0
	global_store_short v[12:13], v0, off
	v_lshlrev_b32_e32 v7, 16, v194
	v_mov_b32_e32 v233, v1
	v_or_b32_e32 v231,0xa800,v5
	v_add_u32_e32 v232,v231,v4
	v_lshlrev_b64 v[234:235],1,v[232:233]
	v_lshl_add_u64 v[236:237],s[62:63],0,v[234:235]
	global_load_ushort v194, v[236:237], off
	v_lshl_add_u64 v[2:3], s[62:63], 0, v[140:141]
	s_waitcnt vmcnt(42)
	v_lshlrev_b32_e32 v0, 16, v205
	v_mov_b32_e32 v233, v1
	v_or_b32_e32 v231,0xe400,v5
	v_add_u32_e32 v232,v231,v4
	v_lshlrev_b64 v[234:235],1,v[232:233]
	v_lshl_add_u64 v[236:237],s[18:19],0,v[234:235]
	global_load_ushort v205, v[236:237], off
	v_fmac_f32_e32 v7, v120, v0
	v_cvt_pk_bf16_f32 v0, v7, s0
	global_store_short v[158:159], v0, off
	v_lshlrev_b32_e32 v7, 16, v207
	v_mov_b32_e32 v233, v1
	v_or_b32_e32 v230,0xac00,v5
	v_add_u32_e32 v232,v230,v4
	v_lshlrev_b64 v[234:235],1,v[232:233]
	v_lshl_add_u64 v[236:237],s[62:63],0,v[234:235]
	global_load_ushort v207, v[236:237], off
	v_lshl_add_u64 v[2:3], s[62:63], 0, v[144:145]
	s_waitcnt vmcnt(44)
	v_lshlrev_b32_e32 v0, 16, v220
	v_mov_b32_e32 v233, v1
	v_or_b32_e32 v230,0xec00,v5
	v_add_u32_e32 v232,v230,v4
	v_lshlrev_b64 v[234:235],1,v[232:233]
	v_lshl_add_u64 v[236:237],s[18:19],0,v[234:235]
	global_load_ushort v220, v[236:237], off
	v_fmac_f32_e32 v7, v121, v0
	v_cvt_pk_bf16_f32 v0, v7, s0
	global_store_short v[10:11], v0, off
	v_lshlrev_b32_e32 v7, 16, v210
	v_mov_b32_e32 v233, v1
	v_or_b32_e32 v231,0xc000,v5
	v_add_u32_e32 v232,v231,v4
	v_lshlrev_b64 v[234:235],1,v[232:233]
	v_lshl_add_u64 v[236:237],s[62:63],0,v[234:235]
	global_load_ushort v210, v[236:237], off
	v_lshl_add_u64 v[2:3], s[62:63], 0, v[146:147]
	s_waitcnt vmcnt(45)
	v_lshlrev_b32_e32 v0, 16, v213
	v_mov_b32_e32 v233, v1
	v_or_b32_e32 v230,0xc400,v5
	v_add_u32_e32 v232,v230,v4
	v_lshlrev_b64 v[234:235],1,v[232:233]
	v_lshl_add_u64 v[236:237],s[62:63],0,v[234:235]
	global_load_ushort v213, v[236:237], off
	v_fmac_f32_e32 v7, v122, v0
	v_cvt_pk_bf16_f32 v0, v7, s0
	global_store_short v[112:113], v0, off
	v_lshlrev_b32_e32 v7, 16, v197
	v_mov_b32_e32 v233, v1
	v_or_b32_e32 v231,0xc800,v5
	v_add_u32_e32 v232,v231,v4
	v_lshlrev_b64 v[234:235],1,v[232:233]
	v_lshl_add_u64 v[236:237],s[62:63],0,v[234:235]
	global_load_ushort v197, v[236:237], off
	v_lshl_add_u64 v[2:3], s[62:63], 0, v[148:149]
	s_waitcnt vmcnt(47)
	v_lshlrev_b32_e32 v0, 16, v221
	v_mov_b32_e32 v233, v1
	v_or_b32_e32 v230,0xcc00,v5
	v_add_u32_e32 v232,v230,v4
	v_lshlrev_b64 v[234:235],1,v[232:233]
	v_lshl_add_u64 v[236:237],s[62:63],0,v[234:235]
	global_load_ushort v221, v[236:237], off
	v_fmac_f32_e32 v7, v123, v0
	v_cvt_pk_bf16_f32 v0, v7, s0
	global_store_short v[114:115], v0, off
	v_lshlrev_b32_e32 v7, 16, v199
	v_mov_b32_e32 v233, v1
	v_or_b32_e32 v231,0xe000,v5
	v_add_u32_e32 v232,v231,v4
	v_lshlrev_b64 v[234:235],1,v[232:233]
	v_lshl_add_u64 v[236:237],s[62:63],0,v[234:235]
	global_load_ushort v199, v[236:237], off
	v_lshl_add_u64 v[2:3], s[62:63], 0, v[150:151]
	s_waitcnt vmcnt(48)
	v_lshlrev_b32_e32 v0, 16, v202
	v_mov_b32_e32 v233, v1
	v_or_b32_e32 v231,0xe400,v5
	v_add_u32_e32 v232,v231,v4
	v_lshlrev_b64 v[234:235],1,v[232:233]
	v_lshl_add_u64 v[236:237],s[62:63],0,v[234:235]
	global_load_ushort v202, v[236:237], off
	v_fmac_f32_e32 v7, v124, v0
	v_cvt_pk_bf16_f32 v0, v7, s0
	global_store_short v[160:161], v0, off
	v_lshlrev_b32_e32 v7, 16, v211
	v_mov_b32_e32 v233, v1
	v_or_b32_e32 v230,0xe800,v5
	v_add_u32_e32 v232,v230,v4
	v_lshlrev_b64 v[234:235],1,v[232:233]
	v_lshl_add_u64 v[236:237],s[62:63],0,v[234:235]
	global_load_ushort v211, v[236:237], off
	v_lshl_add_u64 v[2:3], s[62:63], 0, v[152:153]
	s_waitcnt vmcnt(50)
	v_lshlrev_b32_e32 v0, 16, v222
	v_mov_b32_e32 v233, v1
	v_or_b32_e32 v230,0xec00,v5
	v_add_u32_e32 v232,v230,v4
	v_lshlrev_b64 v[234:235],1,v[232:233]
	v_lshl_add_u64 v[236:237],s[62:63],0,v[234:235]
	global_load_ushort v222, v[236:237], off
	v_fmac_f32_e32 v7, v125, v0
	v_cvt_pk_bf16_f32 v0, v7, s0
	global_store_short v[8:9], v0, off
	v_lshlrev_b32_e32 v2, 16, v201
	v_mov_b32_e32 v233, v1
	v_or_b32_e32 v230,0xec00,v5
	v_add_u32_e32 v232,v230,v6
	v_lshlrev_b64 v[230:231],1,v[232:233]
	v_lshl_add_u64 v[234:235],s[18:19],0,v[230:231]
	global_load_ushort v201, v[234:235], off
	s_waitcnt vmcnt(51)
	v_lshlrev_b32_e32 v0, 16, v215
	v_mov_b32_e32 v233, v1
	v_or_b32_e32 v231,0x8000,v5
	v_add_u32_e32 v232,v231,v6
	v_lshlrev_b64 v[234:235],1,v[232:233]
	v_lshl_add_u64 v[236:237],s[18:19],0,v[234:235]
	global_load_ushort v215, v[236:237], off
	v_fmac_f32_e32 v2, v126, v0
	v_cvt_pk_bf16_f32 v0, v2, s0
	global_store_short v[128:129], v0, off
	v_lshl_add_u64 v[2:3], s[62:63], 0, v[154:155]
	v_lshlrev_b32_e32 v2, 16, v226
	v_mov_b32_e32 v233, v1
	v_or_b32_e32 v231,0x8000,v5
	v_add_u32_e32 v232,v231,v6
	v_lshlrev_b64 v[234:235],1,v[232:233]
	v_lshl_add_u64 v[234:235],s[62:63],0,v[234:235]
	global_load_ushort v226, v[234:235], off
	s_waitcnt vmcnt(53)
	v_lshlrev_b32_e32 v0, 16, v223
	v_mov_b32_e32 v233, v1
	v_or_b32_e32 v230,0x8400,v5
	v_add_u32_e32 v232,v230,v6
	v_lshlrev_b64 v[234:235],1,v[232:233]
	v_lshl_add_u64 v[236:237],s[18:19],0,v[234:235]
	global_load_ushort v223, v[236:237], off
	v_fmac_f32_e32 v2, v127, v0
	v_cvt_pk_bf16_f32 v0, v2, s0
	global_store_short v[156:157], v0, off
	v_or_b32_e32 v7, 0x8000, v5
	v_add_u32_e32 v0, v7, v4
	v_lshlrev_b64 v[2:3], 1, v[0:1]
	v_lshl_add_u64 v[8:9], s[18:19], 0, v[2:3]
	v_lshl_add_u64 v[2:3], s[62:63], 0, v[2:3]
	v_or_b32_e32 v140, 0x8400, v5
	v_or_b32_e32 v141, 0x8800, v5
	v_add_u32_e32 v0, v140, v4
	v_or_b32_e32 v142, 0x8c00, v5
	v_lshlrev_b64 v[2:3], 1, v[0:1]
	v_add_u32_e32 v0, v141, v4
	v_or_b32_e32 v143, 0xa000, v5
	v_lshlrev_b64 v[12:13], 1, v[0:1]
	v_add_u32_e32 v0, v142, v4
	v_or_b32_e32 v144, 0xa400, v5
	v_lshlrev_b64 v[112:113], 1, v[0:1]
	v_add_u32_e32 v0, v143, v4
	v_or_b32_e32 v145, 0xa800, v5
	v_lshlrev_b64 v[114:115], 1, v[0:1]
	v_add_u32_e32 v0, v144, v4
	v_or_b32_e32 v146, 0xac00, v5
	v_lshlrev_b64 v[118:119], 1, v[0:1]
	v_add_u32_e32 v0, v145, v4
	v_or_b32_e32 v147, 0xc000, v5
	v_lshlrev_b64 v[120:121], 1, v[0:1]
	v_add_u32_e32 v0, v146, v4
	v_lshlrev_b64 v[122:123], 1, v[0:1]
	v_add_u32_e32 v0, v147, v4
	v_lshlrev_b64 v[124:125], 1, v[0:1]
	v_lshl_add_u64 v[10:11], s[18:19], 0, v[2:3]
	v_lshl_add_u64 v[2:3], s[62:63], 0, v[2:3]
	v_lshl_add_u64 v[14:15], s[18:19], 0, v[12:13]
	v_lshl_add_u64 v[116:117], s[18:19], 0, v[114:115]
	v_lshl_add_u64 v[126:127], s[18:19], 0, v[124:125]
	v_or_b32_e32 v150, 0xc400, v5
	v_or_b32_e32 v151, 0xc800, v5
	v_or_b32_e32 v152, 0xcc00, v5
	v_or_b32_e32 v153, 0xe000, v5
	v_or_b32_e32 v159, 0xe400, v5
	v_or_b32_e32 v160, 0xe800, v5
	s_waitcnt vmcnt(53)
	v_lshlrev_b32_e32 v0, 16, v209
	v_mov_b32_e32 v231, v1
	v_add_u32_e32 v230,v141,v6
	v_lshlrev_b64 v[232:233],1,v[230:231]
	v_lshl_add_u64 v[234:235],s[18:19],0,v[232:233]
	global_load_ushort v209, v[234:235], off
	s_waitcnt vmcnt(53)
	v_lshlrev_b32_e32 v128, 16, v224
	v_mov_b32_e32 v231, v1
	v_add_u32_e32 v230,v143,v6
	v_lshlrev_b64 v[232:233],1,v[230:231]
	v_lshl_add_u64 v[234:235],s[18:19],0,v[232:233]
	global_load_ushort v224, v[234:235], off
	v_fmac_f32_e32 v0, v96, v128
	v_cvt_pk_bf16_f32 v0, v0, s0
	global_store_short v[8:9], v0, off
	v_add_u32_e32 v0, v150, v4
	v_lshlrev_b64 v[128:129], 1, v[0:1]
	v_add_u32_e32 v0, v151, v4
	v_lshlrev_b64 v[130:131], 1, v[0:1]
	v_add_u32_e32 v0, v152, v4
	v_lshlrev_b64 v[132:133], 1, v[0:1]
	v_add_u32_e32 v0, v153, v4
	v_lshlrev_b64 v[134:135], 1, v[0:1]
	v_lshl_add_u64 v[8:9], s[18:19], 0, v[112:113]
	v_lshl_add_u64 v[2:3], s[62:63], 0, v[12:13]
	v_lshl_add_u64 v[12:13], s[18:19], 0, v[120:121]
	v_lshl_add_u64 v[136:137], s[18:19], 0, v[134:135]
	s_waitcnt vmcnt(53)
	v_lshlrev_b32_e32 v0, 16, v217
	v_mov_b32_e32 v231, v1
	v_add_u32_e32 v230,v147,v6
	v_lshlrev_b64 v[232:233],1,v[230:231]
	v_lshl_add_u64 v[234:235],s[18:19],0,v[232:233]
	global_load_ushort v217, v[234:235], off
	s_waitcnt vmcnt(48)
	v_lshlrev_b32_e32 v96, 16, v229
	v_mov_b32_e32 v231, v1
	v_add_u32_e32 v230,v140,v6
	v_lshlrev_b64 v[232:233],1,v[230:231]
	v_lshl_add_u64 v[234:235],s[62:63],0,v[232:233]
	global_load_ushort v229, v[234:235], off
	v_fmac_f32_e32 v0, v97, v96
	v_cvt_pk_bf16_f32 v0, v0, s0
	global_store_short v[10:11], v0, off
	v_lshl_add_u64 v[2:3], s[62:63], 0, v[112:113]
	v_lshlrev_b32_e32 v112, 16, v225
	v_mov_b32_e32 v231, v1
	v_add_u32_e32 v230,v142,v6
	v_lshlrev_b64 v[232:233],1,v[230:231]
	v_lshl_add_u64 v[234:235],s[18:19],0,v[232:233]
	global_load_ushort v225, v[234:235], off
	v_lshl_add_u64 v[10:11], s[18:19], 0, v[118:119]
	v_lshl_add_u64 v[96:97], s[18:19], 0, v[130:131]
	s_waitcnt vmcnt(45)
	v_lshlrev_b32_e32 v0, 16, v195
	v_mov_b32_e32 v231, v1
	v_add_u32_e32 v230,v145,v6
	v_lshlrev_b64 v[232:233],1,v[230:231]
	v_lshl_add_u64 v[234:235],s[18:19],0,v[232:233]
	global_load_ushort v195, v[234:235], off
	v_fmac_f32_e32 v112, v98, v0
	v_cvt_pk_bf16_f32 v0, v112, s0
	global_store_short v[14:15], v0, off
	v_add_u32_e32 v0, v159, v4
	v_lshlrev_b64 v[112:113], 1, v[0:1]
	v_add_u32_e32 v0, v160, v4
	v_lshl_add_u64 v[2:3], s[62:63], 0, v[114:115]
	v_lshlrev_b64 v[114:115], 1, v[0:1]
	v_lshlrev_b32_e32 v0, 16, v198
	v_mov_b32_e32 v231, v1
	v_add_u32_e32 v230,v153,v6
	v_lshlrev_b64 v[232:233],1,v[230:231]
	v_lshl_add_u64 v[234:235],s[18:19],0,v[232:233]
	global_load_ushort v198, v[234:235], off
	v_lshl_add_u64 v[14:15], s[18:19], 0, v[122:123]
	v_lshl_add_u64 v[138:139], s[18:19], 0, v[114:115]
	s_waitcnt vmcnt(44)
	v_lshlrev_b32_e32 v98, 16, v214
	v_mov_b32_e32 v231, v1
	v_add_u32_e32 v230,v141,v6
	v_lshlrev_b64 v[232:233],1,v[230:231]
	v_lshl_add_u64 v[234:235],s[62:63],0,v[232:233]
	global_load_ushort v214, v[234:235], off
	v_fmac_f32_e32 v0, v99, v98
	v_cvt_pk_bf16_f32 v0, v0, s0
	global_store_short v[8:9], v0, off
	v_lshlrev_b32_e32 v98, 16, v227
	v_mov_b32_e32 v231, v1
	v_add_u32_e32 v230,v144,v6
	v_lshlrev_b64 v[232:233],1,v[230:231]
	v_lshl_add_u64 v[234:235],s[18:19],0,v[232:233]
	global_load_ushort v227, v[234:235], off
	v_lshl_add_u64 v[2:3], s[62:63], 0, v[118:119]
	v_lshl_add_u64 v[8:9], s[18:19], 0, v[128:129]
	s_waitcnt vmcnt(42)
	v_lshlrev_b32_e32 v0, 16, v203
	v_mov_b32_e32 v231, v1
	v_add_u32_e32 v230,v151,v6
	v_lshlrev_b64 v[232:233],1,v[230:231]
	v_lshl_add_u64 v[234:235],s[18:19],0,v[232:233]
	global_load_ushort v203, v[234:235], off
	v_fmac_f32_e32 v98, v100, v0
	v_cvt_pk_bf16_f32 v0, v98, s0
	global_store_short v[116:117], v0, off
	v_lshlrev_b32_e32 v100, 16, v204
	v_mov_b32_e32 v231, v1
	v_add_u32_e32 v230,v142,v6
	v_lshlrev_b64 v[232:233],1,v[230:231]
	v_lshl_add_u64 v[234:235],s[62:63],0,v[232:233]
	global_load_ushort v204, v[234:235], off
	v_lshl_add_u64 v[2:3], s[62:63], 0, v[120:121]
	v_lshl_add_u64 v[98:99], s[18:19], 0, v[132:133]
	s_waitcnt vmcnt(42)
	v_lshlrev_b32_e32 v0, 16, v212
	v_mov_b32_e32 v231, v1
	v_add_u32_e32 v230,v146,v6
	v_lshlrev_b64 v[232:233],1,v[230:231]
	v_lshl_add_u64 v[234:235],s[18:19],0,v[232:233]
	global_load_ushort v212, v[234:235], off
	v_fmac_f32_e32 v100, v101, v0
	v_cvt_pk_bf16_f32 v0, v100, s0
	global_store_short v[10:11], v0, off
	v_lshl_add_u64 v[10:11], s[18:19], 0, v[112:113]
	v_lshlrev_b32_e32 v100, 16, v192
	v_mov_b32_e32 v231, v1
	v_add_u32_e32 v230,v160,v6
	v_lshlrev_b64 v[232:233],1,v[230:231]
	v_lshl_add_u64 v[234:235],s[18:19],0,v[232:233]
	global_load_ushort v192, v[234:235], off
	v_lshl_add_u64 v[2:3], s[62:63], 0, v[122:123]
	v_or_b32_e32 v122, 0xec00, v5
	s_waitcnt vmcnt(42)
	v_lshlrev_b32_e32 v0, 16, v194
	v_mov_b32_e32 v231, v1
	v_add_u32_e32 v230,v143,v6
	v_lshlrev_b64 v[232:233],1,v[230:231]
	v_lshl_add_u64 v[234:235],s[62:63],0,v[232:233]
	global_load_ushort v194, v[234:235], off
	v_fmac_f32_e32 v100, v102, v0
	v_cvt_pk_bf16_f32 v0, v100, s0
	global_store_short v[12:13], v0, off
	v_add_u32_e32 v0, v122, v4
	v_lshlrev_b64 v[100:101], 1, v[0:1]
	v_lshlrev_b32_e32 v0, 16, v196
	v_mov_b32_e32 v231, v1
	v_add_u32_e32 v230,v150,v6
	v_lshlrev_b64 v[232:233],1,v[230:231]
	v_lshl_add_u64 v[234:235],s[18:19],0,v[232:233]
	global_load_ushort v196, v[234:235], off
	v_lshl_add_u64 v[12:13], s[62:63], 0, v[124:125]
	v_lshl_add_u64 v[2:3], s[18:19], 0, v[100:101]
	s_waitcnt vmcnt(42)
	v_lshlrev_b32_e32 v102, 16, v207
	v_mov_b32_e32 v231, v1
	v_add_u32_e32 v230,v144,v6
	v_lshlrev_b64 v[232:233],1,v[230:231]
	v_lshl_add_u64 v[234:235],s[62:63],0,v[232:233]
	global_load_ushort v207, v[234:235], off
	v_fmac_f32_e32 v0, v103, v102
	v_cvt_pk_bf16_f32 v0, v0, s0
	global_store_short v[14:15], v0, off
	v_lshlrev_b32_e32 v14, 16, v228
	v_mov_b32_e32 v231, v1
	v_add_u32_e32 v230,v152,v6
	v_lshlrev_b64 v[232:233],1,v[230:231]
	v_lshl_add_u64 v[234:235],s[18:19],0,v[232:233]
	global_load_ushort v228, v[234:235], off
	v_lshl_add_u64 v[12:13], s[62:63], 0, v[128:129]
	s_waitcnt vmcnt(42)
	v_lshlrev_b32_e32 v0, 16, v210
	v_mov_b32_e32 v231, v1
	v_add_u32_e32 v230,v145,v6
	v_lshlrev_b64 v[232:233],1,v[230:231]
	v_lshl_add_u64 v[234:235],s[62:63],0,v[232:233]
	global_load_ushort v210, v[234:235], off
	v_fmac_f32_e32 v14, v104, v0
	v_cvt_pk_bf16_f32 v0, v14, s0
	global_store_short v[126:127], v0, off
	v_lshlrev_b32_e32 v14, 16, v218
	v_mov_b32_e32 v231, v1
	v_add_u32_e32 v230,v159,v6
	v_lshlrev_b64 v[232:233],1,v[230:231]
	v_lshl_add_u64 v[234:235],s[18:19],0,v[232:233]
	global_load_ushort v218, v[234:235], off
	v_lshl_add_u64 v[12:13], s[62:63], 0, v[130:131]
	s_waitcnt vmcnt(44)
	v_lshlrev_b32_e32 v0, 16, v213
	v_mov_b32_e32 v231, v1
	v_add_u32_e32 v230,v146,v6
	v_lshlrev_b64 v[232:233],1,v[230:231]
	v_lshl_add_u64 v[234:235],s[62:63],0,v[232:233]
	global_load_ushort v213, v[234:235], off
	v_fmac_f32_e32 v14, v105, v0
	v_cvt_pk_bf16_f32 v0, v14, s0
	global_store_short v[8:9], v0, off
	v_lshlrev_b32_e32 v12, 16, v193
	v_mov_b32_e32 v231, v1
	v_add_u32_e32 v230,v147,v6
	v_lshlrev_b64 v[232:233],1,v[230:231]
	v_lshl_add_u64 v[234:235],s[62:63],0,v[232:233]
	global_load_ushort v193, v[234:235], off
	v_lshl_add_u64 v[8:9], s[62:63], 0, v[132:133]
	s_waitcnt vmcnt(45)
	v_lshlrev_b32_e32 v0, 16, v197
	v_mov_b32_e32 v231, v1
	v_add_u32_e32 v230,v150,v6
	v_lshlrev_b64 v[232:233],1,v[230:231]
	v_lshl_add_u64 v[234:235],s[62:63],0,v[232:233]
	global_load_ushort v197, v[234:235], off
	v_fmac_f32_e32 v12, v106, v0
	v_cvt_pk_bf16_f32 v0, v12, s0
	global_store_short v[96:97], v0, off
	v_lshlrev_b32_e32 v12, 16, v219
	v_mov_b32_e32 v231, v1
	v_add_u32_e32 v230,v151,v6
	v_lshlrev_b64 v[232:233],1,v[230:231]
	v_lshl_add_u64 v[234:235],s[62:63],0,v[232:233]
	global_load_ushort v219, v[234:235], off
	v_lshl_add_u64 v[8:9], s[62:63], 0, v[134:135]
	s_waitcnt vmcnt(47)
	v_lshlrev_b32_e32 v0, 16, v221
	v_mov_b32_e32 v231, v1
	v_add_u32_e32 v230,v152,v6
	v_lshlrev_b64 v[232:233],1,v[230:231]
	v_lshl_add_u64 v[234:235],s[62:63],0,v[232:233]
	global_load_ushort v221, v[234:235], off
	v_fmac_f32_e32 v12, v107, v0
	v_cvt_pk_bf16_f32 v0, v12, s0
	global_store_short v[98:99], v0, off
	v_lshlrev_b32_e32 v12, 16, v206
	v_mov_b32_e32 v231, v1
	v_add_u32_e32 v230,v153,v6
	v_lshlrev_b64 v[232:233],1,v[230:231]
	v_lshl_add_u64 v[234:235],s[62:63],0,v[232:233]
	global_load_ushort v206, v[234:235], off
	v_lshl_add_u64 v[8:9], s[62:63], 0, v[112:113]
	s_waitcnt vmcnt(48)
	v_lshlrev_b32_e32 v0, 16, v199
	v_mov_b32_e32 v231, v1
	v_add_u32_e32 v230,v159,v6
	v_lshlrev_b64 v[232:233],1,v[230:231]
	v_lshl_add_u64 v[234:235],s[62:63],0,v[232:233]
	global_load_ushort v199, v[234:235], off
	v_fmac_f32_e32 v12, v108, v0
	v_cvt_pk_bf16_f32 v0, v12, s0
	global_store_short v[136:137], v0, off
	v_lshlrev_b32_e32 v12, 16, v205
	v_mov_b32_e32 v231, v1
	v_add_u32_e32 v230,v160,v6
	v_lshlrev_b64 v[232:233],1,v[230:231]
	v_lshl_add_u64 v[234:235],s[62:63],0,v[232:233]
	global_load_ushort v205, v[234:235], off
	v_lshl_add_u64 v[8:9], s[62:63], 0, v[114:115]
	s_waitcnt vmcnt(50)
	v_lshlrev_b32_e32 v0, 16, v202
	v_mov_b32_e32 v231, v1
	v_add_u32_e32 v230,v122,v6
	v_lshlrev_b64 v[232:233],1,v[230:231]
	v_lshl_add_u64 v[234:235],s[62:63],0,v[232:233]
	global_load_ushort v202, v[234:235], off
	v_fmac_f32_e32 v12, v109, v0
	v_cvt_pk_bf16_f32 v0, v12, s0
	global_store_short v[10:11], v0, off
	v_lshlrev_b32_e32 v10, 16, v216
	v_mov_b32_e32 v233, v1
	v_or_b32_e32 v231,0x10000,v5
	v_add_u32_e32 v232,v231,v4
	v_lshlrev_b64 v[234:235],1,v[232:233]
	v_lshl_add_u64 v[236:237],s[18:19],0,v[234:235]
	global_load_ushort v216, v[236:237], off
	v_lshl_add_u64 v[8:9], s[62:63], 0, v[100:101]
	s_waitcnt vmcnt(51)
	v_lshlrev_b32_e32 v0, 16, v211
	v_mov_b32_e32 v233, v1
	v_or_b32_e32 v231,0x10000,v5
	v_add_u32_e32 v232,v231,v4
	v_lshlrev_b64 v[234:235],1,v[232:233]
	v_lshl_add_u64 v[234:235],s[62:63],0,v[234:235]
	global_load_ushort v211, v[234:235], off
	v_fmac_f32_e32 v10, v110, v0
	v_cvt_pk_bf16_f32 v0, v10, s0
	global_store_short v[138:139], v0, off
	v_add_u32_e32 v0, v7, v6
	v_lshlrev_b64 v[8:9], 1, v[0:1]
	v_add_u32_e32 v0, v140, v6
	v_lshlrev_b64 v[12:13], 1, v[0:1]
	v_add_u32_e32 v0, v141, v6
	v_lshlrev_b64 v[14:15], 1, v[0:1]
	v_add_u32_e32 v0, v142, v6
	v_lshlrev_b64 v[96:97], 1, v[0:1]
	v_add_u32_e32 v0, v143, v6
	v_lshlrev_b64 v[98:99], 1, v[0:1]
	v_add_u32_e32 v0, v144, v6
	v_lshlrev_b64 v[100:101], 1, v[0:1]
	v_add_u32_e32 v0, v145, v6
	v_lshlrev_b64 v[102:103], 1, v[0:1]
	v_add_u32_e32 v0, v146, v6
	v_lshlrev_b64 v[104:105], 1, v[0:1]
	v_add_u32_e32 v0, v147, v6
	v_lshlrev_b64 v[106:107], 1, v[0:1]
	v_add_u32_e32 v0, v150, v6
	v_lshlrev_b64 v[108:109], 1, v[0:1]
	v_add_u32_e32 v0, v151, v6
	v_lshlrev_b64 v[112:113], 1, v[0:1]
	v_add_u32_e32 v0, v152, v6
	v_lshlrev_b64 v[114:115], 1, v[0:1]
	v_add_u32_e32 v0, v153, v6
	v_lshlrev_b64 v[116:117], 1, v[0:1]
	v_add_u32_e32 v0, v159, v6
	v_lshlrev_b64 v[118:119], 1, v[0:1]
	v_add_u32_e32 v0, v160, v6
	v_lshlrev_b64 v[120:121], 1, v[0:1]
	v_add_u32_e32 v0, v122, v6
	v_lshlrev_b64 v[122:123], 1, v[0:1]
	v_lshlrev_b32_e32 v0, 16, v220
	v_mov_b32_e32 v233, v1
	v_or_b32_e32 v230,0x10400,v5
	v_add_u32_e32 v232,v230,v4
	v_lshlrev_b64 v[234:235],1,v[232:233]
	v_lshl_add_u64 v[236:237],s[18:19],0,v[234:235]
	global_load_ushort v220, v[236:237], off
	v_lshl_add_u64 v[10:11], s[18:19], 0, v[8:9]
	v_lshl_add_u64 v[124:125], s[18:19], 0, v[122:123]
	v_lshl_add_u64 v[8:9], s[62:63], 0, v[8:9]
	v_lshl_add_u64 v[126:127], s[18:19], 0, v[106:107]
	s_waitcnt vmcnt(53)
	v_lshlrev_b32_e32 v110, 16, v222
	v_mov_b32_e32 v233, v1
	v_or_b32_e32 v231,0x10800,v5
	v_add_u32_e32 v232,v231,v4
	v_lshlrev_b64 v[234:235],1,v[232:233]
	v_lshl_add_u64 v[236:237],s[18:19],0,v[234:235]
	global_load_ushort v222, v[236:237], off
	v_fmac_f32_e32 v0, v111, v110
	v_cvt_pk_bf16_f32 v0, v0, s0
	global_store_short v[2:3], v0, off
	s_nop 0
	v_lshl_add_u64 v[2:3], s[18:19], 0, v[12:13]
	v_lshl_add_u64 v[8:9], s[62:63], 0, v[12:13]
	v_lshl_add_u64 v[12:13], s[18:19], 0, v[14:15]
	v_lshl_add_u64 v[110:111], s[18:19], 0, v[98:99]
	s_waitcnt vmcnt(52)
	v_lshlrev_b32_e32 v0, 16, v215
	v_mov_b32_e32 v233, v1
	v_or_b32_e32 v231,0x12000,v5
	v_add_u32_e32 v232,v231,v4
	v_lshlrev_b64 v[234:235],1,v[232:233]
	v_lshl_add_u64 v[236:237],s[18:19],0,v[234:235]
	global_load_ushort v215, v[236:237], off
	s_waitcnt vmcnt(51)
	v_lshlrev_b32_e32 v128, 16, v226
	v_mov_b32_e32 v233, v1
	v_or_b32_e32 v231,0x14000,v5
	v_add_u32_e32 v232,v231,v4
	v_lshlrev_b64 v[234:235],1,v[232:233]
	v_lshl_add_u64 v[236:237],s[18:19],0,v[234:235]
	global_load_ushort v226, v[236:237], off
	v_fmac_f32_e32 v0, v80, v128
	v_cvt_pk_bf16_f32 v0, v0, s0
	global_store_short v[10:11], v0, off
	s_waitcnt vmcnt(52)
	v_lshlrev_b32_e32 v80, 16, v223
	v_mov_b32_e32 v233, v1
	v_or_b32_e32 v230,0x10400,v5
	v_add_u32_e32 v232,v230,v4
	v_lshlrev_b64 v[234:235],1,v[232:233]
	v_lshl_add_u64 v[234:235],s[62:63],0,v[234:235]
	global_load_ushort v223, v[234:235], off
	v_lshl_add_u64 v[10:11], s[18:19], 0, v[96:97]
	v_lshl_add_u64 v[8:9], s[62:63], 0, v[14:15]
	v_lshl_add_u64 v[14:15], s[18:19], 0, v[102:103]
	v_lshl_add_u64 v[128:129], s[18:19], 0, v[116:117]
	s_waitcnt vmcnt(47)
	v_lshlrev_b32_e32 v0, 16, v229
	v_mov_b32_e32 v233, v1
	v_or_b32_e32 v230,0x10c00,v5
	v_add_u32_e32 v232,v230,v4
	v_lshlrev_b64 v[234:235],1,v[232:233]
	v_lshl_add_u64 v[236:237],s[18:19],0,v[234:235]
	global_load_ushort v229, v[236:237], off
	v_fmac_f32_e32 v80, v81, v0
	v_cvt_pk_bf16_f32 v0, v80, s0
	global_store_short v[2:3], v0, off
	v_lshl_add_u64 v[2:3], s[62:63], 0, v[96:97]
	v_lshlrev_b32_e32 v96, 16, v209
	v_mov_b32_e32 v233, v1
	v_or_b32_e32 v231,0x12800,v5
	v_add_u32_e32 v232,v231,v4
	v_lshlrev_b64 v[234:235],1,v[232:233]
	v_lshl_add_u64 v[236:237],s[18:19],0,v[234:235]
	global_load_ushort v209, v[236:237], off
	v_lshl_add_u64 v[8:9], s[18:19], 0, v[100:101]
	v_lshl_add_u64 v[80:81], s[18:19], 0, v[112:113]
	s_waitcnt vmcnt(44)
	v_lshlrev_b32_e32 v0, 16, v214
	v_mov_b32_e32 v233, v1
	v_or_b32_e32 v231,0x16000,v5
	v_add_u32_e32 v232,v231,v4
	v_lshlrev_b64 v[234:235],1,v[232:233]
	v_lshl_add_u64 v[236:237],s[18:19],0,v[234:235]
	global_load_ushort v214, v[236:237], off
	v_fmac_f32_e32 v96, v82, v0
	v_cvt_pk_bf16_f32 v0, v96, s0
	global_store_short v[12:13], v0, off
	v_lshlrev_b32_e32 v82, 16, v225
	v_mov_b32_e32 v233, v1
	v_or_b32_e32 v231,0x10800,v5
	v_add_u32_e32 v232,v231,v4
	v_lshlrev_b64 v[234:235],1,v[232:233]
	v_lshl_add_u64 v[236:237],s[62:63],0,v[234:235]
	global_load_ushort v225, v[236:237], off
	v_lshl_add_u64 v[12:13], s[18:19], 0, v[104:105]
	v_lshl_add_u64 v[2:3], s[62:63], 0, v[98:99]
	v_lshl_add_u64 v[96:97], s[18:19], 0, v[120:121]
	s_waitcnt vmcnt(42)
	v_lshlrev_b32_e32 v0, 16, v204
	v_mov_b32_e32 v233, v1
	v_or_b32_e32 v230,0x12400,v5
	v_add_u32_e32 v232,v230,v4
	v_lshlrev_b64 v[234:235],1,v[232:233]
	v_lshl_add_u64 v[236:237],s[18:19],0,v[234:235]
	global_load_ushort v204, v[236:237], off
	v_fmac_f32_e32 v82, v83, v0
	v_cvt_pk_bf16_f32 v0, v82, s0
	global_store_short v[10:11], v0, off
	v_lshlrev_b32_e32 v82, 16, v224
	v_mov_b32_e32 v233, v1
	v_or_b32_e32 v231,0x14800,v5
	v_add_u32_e32 v232,v231,v4
	v_lshlrev_b64 v[234:235],1,v[232:233]
	v_lshl_add_u64 v[236:237],s[18:19],0,v[234:235]
	global_load_ushort v224, v[236:237], off
	v_lshl_add_u64 v[2:3], s[62:63], 0, v[100:101]
	v_lshl_add_u64 v[10:11], s[18:19], 0, v[108:109]
	s_waitcnt vmcnt(41)
	v_lshlrev_b32_e32 v0, 16, v194
	v_mov_b32_e32 v233, v1
	v_or_b32_e32 v230,0x10c00,v5
	v_add_u32_e32 v232,v230,v4
	v_lshlrev_b64 v[234:235],1,v[232:233]
	v_lshl_add_u64 v[236:237],s[62:63],0,v[234:235]
	global_load_ushort v194, v[236:237], off
	v_fmac_f32_e32 v82, v84, v0
	v_cvt_pk_bf16_f32 v0, v82, s0
	global_store_short v[110:111], v0, off
	v_lshlrev_b32_e32 v84, 16, v227
	v_mov_b32_e32 v233, v1
	v_or_b32_e32 v230,0x12c00,v5
	v_add_u32_e32 v232,v230,v4
	v_lshlrev_b64 v[234:235],1,v[232:233]
	v_lshl_add_u64 v[236:237],s[18:19],0,v[234:235]
	global_load_ushort v227, v[236:237], off
	v_lshl_add_u64 v[2:3], s[62:63], 0, v[102:103]
	v_lshl_add_u64 v[82:83], s[18:19], 0, v[114:115]
	s_waitcnt vmcnt(41)
	v_lshlrev_b32_e32 v0, 16, v207
	v_mov_b32_e32 v233, v1
	v_or_b32_e32 v230,0x16800,v5
	v_add_u32_e32 v232,v230,v4
	v_lshlrev_b64 v[234:235],1,v[232:233]
	v_lshl_add_u64 v[236:237],s[18:19],0,v[234:235]
	global_load_ushort v207, v[236:237], off
	v_fmac_f32_e32 v84, v85, v0
	v_cvt_pk_bf16_f32 v0, v84, s0
	global_store_short v[8:9], v0, off
	v_lshl_add_u64 v[8:9], s[18:19], 0, v[118:119]
	v_lshlrev_b32_e32 v84, 16, v195
	v_mov_b32_e32 v233, v1
	v_or_b32_e32 v231,0x12000,v5
	v_add_u32_e32 v232,v231,v4
	v_lshlrev_b64 v[234:235],1,v[232:233]
	v_lshl_add_u64 v[236:237],s[62:63],0,v[234:235]
	global_load_ushort v195, v[236:237], off
	v_lshl_add_u64 v[2:3], s[62:63], 0, v[104:105]
	s_waitcnt vmcnt(41)
	v_lshlrev_b32_e32 v0, 16, v210
	v_mov_b32_e32 v233, v1
	v_or_b32_e32 v230,0x14400,v5
	v_add_u32_e32 v232,v230,v4
	v_lshlrev_b64 v[234:235],1,v[232:233]
	v_lshl_add_u64 v[236:237],s[18:19],0,v[234:235]
	global_load_ushort v210, v[236:237], off
	v_fmac_f32_e32 v84, v86, v0
	v_cvt_pk_bf16_f32 v0, v84, s0
	global_store_short v[14:15], v0, off
	v_lshlrev_b32_e32 v14, 16, v212
	v_mov_b32_e32 v233, v1
	v_or_b32_e32 v230,0x12400,v5
	v_add_u32_e32 v232,v230,v4
	v_lshlrev_b64 v[234:235],1,v[232:233]
	v_lshl_add_u64 v[236:237],s[62:63],0,v[234:235]
	global_load_ushort v212, v[236:237], off
	v_lshl_add_u64 v[2:3], s[62:63], 0, v[106:107]
	s_waitcnt vmcnt(41)
	v_lshlrev_b32_e32 v0, 16, v213
	v_mov_b32_e32 v233, v1
	v_or_b32_e32 v230,0x14c00,v5
	v_add_u32_e32 v232,v230,v4
	v_lshlrev_b64 v[234:235],1,v[232:233]
	v_lshl_add_u64 v[236:237],s[18:19],0,v[234:235]
	global_load_ushort v213, v[236:237], off
	v_fmac_f32_e32 v14, v87, v0
	v_cvt_pk_bf16_f32 v0, v14, s0
	global_store_short v[12:13], v0, off
	v_lshlrev_b32_e32 v12, 16, v217
	v_mov_b32_e32 v233, v1
	v_or_b32_e32 v231,0x12800,v5
	v_add_u32_e32 v232,v231,v4
	v_lshlrev_b64 v[234:235],1,v[232:233]
	v_lshl_add_u64 v[236:237],s[62:63],0,v[234:235]
	global_load_ushort v217, v[236:237], off
	v_lshl_add_u64 v[2:3], s[62:63], 0, v[108:109]
	s_waitcnt vmcnt(42)
	v_lshlrev_b32_e32 v0, 16, v193
	v_mov_b32_e32 v233, v1
	v_or_b32_e32 v231,0x16400,v5
	v_add_u32_e32 v232,v231,v4
	v_lshlrev_b64 v[234:235],1,v[232:233]
	v_lshl_add_u64 v[236:237],s[18:19],0,v[234:235]
	global_load_ushort v193, v[236:237], off
	v_fmac_f32_e32 v12, v88, v0
	v_cvt_pk_bf16_f32 v0, v12, s0
	global_store_short v[126:127], v0, off
	v_lshlrev_b32_e32 v12, 16, v196
	v_mov_b32_e32 v233, v1
	v_or_b32_e32 v230,0x12c00,v5
	v_add_u32_e32 v232,v230,v4
	v_lshlrev_b64 v[234:235],1,v[232:233]
	v_lshl_add_u64 v[236:237],s[62:63],0,v[234:235]
	global_load_ushort v196, v[236:237], off
	v_lshl_add_u64 v[2:3], s[62:63], 0, v[112:113]
	s_waitcnt vmcnt(44)
	v_lshlrev_b32_e32 v0, 16, v197
	v_mov_b32_e32 v233, v1
	v_or_b32_e32 v230,0x16c00,v5
	v_add_u32_e32 v232,v230,v4
	v_lshlrev_b64 v[234:235],1,v[232:233]
	v_lshl_add_u64 v[236:237],s[18:19],0,v[234:235]
	global_load_ushort v197, v[236:237], off
	v_fmac_f32_e32 v12, v89, v0
	v_cvt_pk_bf16_f32 v0, v12, s0
	global_store_short v[10:11], v0, off
	v_lshlrev_b32_e32 v10, 16, v203
	v_mov_b32_e32 v233, v1
	v_or_b32_e32 v231,0x14000,v5
	v_add_u32_e32 v232,v231,v4
	v_lshlrev_b64 v[234:235],1,v[232:233]
	v_lshl_add_u64 v[236:237],s[62:63],0,v[234:235]
	global_load_ushort v203, v[236:237], off
	v_lshl_add_u64 v[2:3], s[62:63], 0, v[114:115]
	s_waitcnt vmcnt(45)
	v_lshlrev_b32_e32 v0, 16, v219
	v_mov_b32_e32 v233, v1
	v_or_b32_e32 v230,0x14400,v5
	v_add_u32_e32 v232,v230,v4
	v_lshlrev_b64 v[234:235],1,v[232:233]
	v_lshl_add_u64 v[236:237],s[62:63],0,v[234:235]
	global_load_ushort v219, v[236:237], off
	v_fmac_f32_e32 v10, v90, v0
	v_cvt_pk_bf16_f32 v0, v10, s0
	global_store_short v[80:81], v0, off
	v_lshlrev_b32_e32 v10, 16, v228
	v_mov_b32_e32 v233, v1
	v_or_b32_e32 v231,0x14800,v5
	v_add_u32_e32 v232,v231,v4
	v_lshlrev_b64 v[234:235],1,v[232:233]
	v_lshl_add_u64 v[236:237],s[62:63],0,v[234:235]
	global_load_ushort v228, v[236:237], off
	v_lshl_add_u64 v[2:3], s[62:63], 0, v[116:117]
	s_waitcnt vmcnt(47)
	v_lshlrev_b32_e32 v0, 16, v221
	v_mov_b32_e32 v233, v1
	v_or_b32_e32 v230,0x14c00,v5
	v_add_u32_e32 v232,v230,v4
	v_lshlrev_b64 v[234:235],1,v[232:233]
	v_lshl_add_u64 v[236:237],s[62:63],0,v[234:235]
	global_load_ushort v221, v[236:237], off
	v_fmac_f32_e32 v10, v91, v0
	v_cvt_pk_bf16_f32 v0, v10, s0
	global_store_short v[82:83], v0, off
	v_lshlrev_b32_e32 v10, 16, v198
	v_mov_b32_e32 v233, v1
	v_or_b32_e32 v231,0x16000,v5
	v_add_u32_e32 v232,v231,v4
	v_lshlrev_b64 v[234:235],1,v[232:233]
	v_lshl_add_u64 v[236:237],s[62:63],0,v[234:235]
	global_load_ushort v198, v[236:237], off
	v_lshl_add_u64 v[2:3], s[62:63], 0, v[118:119]
	s_waitcnt vmcnt(48)
	v_lshlrev_b32_e32 v0, 16, v206
	v_mov_b32_e32 v233, v1
	v_or_b32_e32 v231,0x16400,v5
	v_add_u32_e32 v232,v231,v4
	v_lshlrev_b64 v[234:235],1,v[232:233]
	v_lshl_add_u64 v[236:237],s[62:63],0,v[234:235]
	global_load_ushort v206, v[236:237], off
	v_fmac_f32_e32 v10, v92, v0
	v_cvt_pk_bf16_f32 v0, v10, s0
	global_store_short v[128:129], v0, off
	v_lshlrev_b32_e32 v10, 16, v218
	v_mov_b32_e32 v233, v1
	v_or_b32_e32 v230,0x16800,v5
	v_add_u32_e32 v232,v230,v4
	v_lshlrev_b64 v[234:235],1,v[232:233]
	v_lshl_add_u64 v[236:237],s[62:63],0,v[234:235]
	global_load_ushort v218, v[236:237], off
	v_lshl_add_u64 v[2:3], s[62:63], 0, v[120:121]
	s_waitcnt vmcnt(50)
	v_lshlrev_b32_e32 v0, 16, v199
	v_mov_b32_e32 v233, v1
	v_or_b32_e32 v230,0x16c00,v5
	v_add_u32_e32 v232,v230,v4
	v_lshlrev_b64 v[234:235],1,v[232:233]
	v_lshl_add_u64 v[236:237],s[62:63],0,v[234:235]
	global_load_ushort v199, v[236:237], off
	v_fmac_f32_e32 v10, v93, v0
	v_cvt_pk_bf16_f32 v0, v10, s0
	global_store_short v[8:9], v0, off
	v_lshlrev_b32_e32 v2, 16, v192
	v_mov_b32_e32 v233, v1
	v_or_b32_e32 v230,0x16c00,v5
	v_add_u32_e32 v232,v230,v6
	v_lshlrev_b64 v[230:231],1,v[232:233]
	v_lshl_add_u64 v[234:235],s[18:19],0,v[230:231]
	global_load_ushort v192, v[234:235], off
	s_waitcnt vmcnt(51)
	v_lshlrev_b32_e32 v0, 16, v205
	v_mov_b32_e32 v233, v1
	v_or_b32_e32 v231,0x10000,v5
	v_add_u32_e32 v232,v231,v6
	v_lshlrev_b64 v[234:235],1,v[232:233]
	v_lshl_add_u64 v[236:237],s[18:19],0,v[234:235]
	global_load_ushort v205, v[236:237], off
	v_fmac_f32_e32 v2, v94, v0
	v_cvt_pk_bf16_f32 v0, v2, s0
	global_store_short v[96:97], v0, off
	v_lshl_add_u64 v[2:3], s[62:63], 0, v[122:123]
	v_lshlrev_b32_e32 v2, 16, v201
	v_mov_b32_e32 v233, v1
	v_or_b32_e32 v231,0x10000,v5
	v_add_u32_e32 v232,v231,v6
	v_lshlrev_b64 v[234:235],1,v[232:233]
	v_lshl_add_u64 v[234:235],s[62:63],0,v[234:235]
	global_load_ushort v201, v[234:235], off
	s_waitcnt vmcnt(53)
	v_lshlrev_b32_e32 v0, 16, v202
	v_mov_b32_e32 v233, v1
	v_or_b32_e32 v230,0x10400,v5
	v_add_u32_e32 v232,v230,v6
	v_lshlrev_b64 v[234:235],1,v[232:233]
	v_lshl_add_u64 v[236:237],s[18:19],0,v[234:235]
	global_load_ushort v202, v[236:237], off
	v_fmac_f32_e32 v2, v95, v0
	v_cvt_pk_bf16_f32 v0, v2, s0
	global_store_short v[124:125], v0, off
	s_cmpk_lt_i32 s0, 0x4000
	s_cbranch_scc1 .Ltep_e4_c
	s_waitcnt vmcnt(0)
	s_branch .Ltep_e4_e
.Ltep_e4_c:
	v_or_b32_e32 v7, 0x10000, v5
	v_add_u32_e32 v0, v7, v4
	v_lshlrev_b64 v[2:3], 1, v[0:1]
	v_lshl_add_u64 v[8:9], s[18:19], 0, v[2:3]
	v_lshl_add_u64 v[2:3], s[62:63], 0, v[2:3]
	v_or_b32_e32 v108, 0x10400, v5
	v_or_b32_e32 v109, 0x10800, v5
	v_add_u32_e32 v0, v108, v4
	v_or_b32_e32 v110, 0x10c00, v5
	v_lshlrev_b64 v[2:3], 1, v[0:1]
	v_add_u32_e32 v0, v109, v4
	v_or_b32_e32 v111, 0x12000, v5
	v_lshlrev_b64 v[12:13], 1, v[0:1]
	v_add_u32_e32 v0, v110, v4
	v_or_b32_e32 v112, 0x12400, v5
	v_lshlrev_b64 v[80:81], 1, v[0:1]
	v_add_u32_e32 v0, v111, v4
	v_or_b32_e32 v113, 0x12800, v5
	v_lshlrev_b64 v[82:83], 1, v[0:1]
	v_add_u32_e32 v0, v112, v4
	v_or_b32_e32 v114, 0x12c00, v5
	v_lshlrev_b64 v[86:87], 1, v[0:1]
	v_add_u32_e32 v0, v113, v4
	v_or_b32_e32 v115, 0x14000, v5
	v_lshlrev_b64 v[88:89], 1, v[0:1]
	v_add_u32_e32 v0, v114, v4
	v_lshlrev_b64 v[90:91], 1, v[0:1]
	v_add_u32_e32 v0, v115, v4
	v_lshlrev_b64 v[92:93], 1, v[0:1]
	v_lshl_add_u64 v[10:11], s[18:19], 0, v[2:3]
	v_lshl_add_u64 v[2:3], s[62:63], 0, v[2:3]
	v_lshl_add_u64 v[14:15], s[18:19], 0, v[12:13]
	v_lshl_add_u64 v[84:85], s[18:19], 0, v[82:83]
	v_lshl_add_u64 v[94:95], s[18:19], 0, v[92:93]
	v_or_b32_e32 v118, 0x14400, v5
	v_or_b32_e32 v119, 0x14800, v5
	v_or_b32_e32 v120, 0x14c00, v5
	v_or_b32_e32 v121, 0x16000, v5
	v_or_b32_e32 v127, 0x16400, v5
	v_or_b32_e32 v128, 0x16800, v5
	s_waitcnt vmcnt(53)
	v_lshlrev_b32_e32 v0, 16, v216
	v_mov_b32_e32 v231, v1
	v_add_u32_e32 v230,v109,v6
	v_lshlrev_b64 v[232:233],1,v[230:231]
	v_lshl_add_u64 v[234:235],s[18:19],0,v[232:233]
	global_load_ushort v216, v[234:235], off
	s_waitcnt vmcnt(53)
	v_lshlrev_b32_e32 v96, 16, v211
	v_mov_b32_e32 v231, v1
	v_add_u32_e32 v230,v111,v6
	v_lshlrev_b64 v[232:233],1,v[230:231]
	v_lshl_add_u64 v[234:235],s[18:19],0,v[232:233]
	global_load_ushort v211, v[234:235], off
	v_fmac_f32_e32 v0, v64, v96
	v_cvt_pk_bf16_f32 v0, v0, s0
	global_store_short v[8:9], v0, off
	v_add_u32_e32 v0, v118, v4
	v_lshlrev_b64 v[96:97], 1, v[0:1]
	v_add_u32_e32 v0, v119, v4
	v_lshlrev_b64 v[98:99], 1, v[0:1]
	v_add_u32_e32 v0, v120, v4
	v_lshlrev_b64 v[100:101], 1, v[0:1]
	v_add_u32_e32 v0, v121, v4
	v_lshlrev_b64 v[102:103], 1, v[0:1]
	v_lshl_add_u64 v[8:9], s[18:19], 0, v[80:81]
	v_lshl_add_u64 v[2:3], s[62:63], 0, v[12:13]
	v_lshl_add_u64 v[12:13], s[18:19], 0, v[88:89]
	v_lshl_add_u64 v[104:105], s[18:19], 0, v[102:103]
	s_waitcnt vmcnt(53)
	v_lshlrev_b32_e32 v0, 16, v220
	v_mov_b32_e32 v231, v1
	v_add_u32_e32 v230,v115,v6
	v_lshlrev_b64 v[232:233],1,v[230:231]
	v_lshl_add_u64 v[234:235],s[18:19],0,v[232:233]
	global_load_ushort v220, v[234:235], off
	s_waitcnt vmcnt(48)
	v_lshlrev_b32_e32 v64, 16, v223
	v_mov_b32_e32 v231, v1
	v_add_u32_e32 v230,v108,v6
	v_lshlrev_b64 v[232:233],1,v[230:231]
	v_lshl_add_u64 v[234:235],s[62:63],0,v[232:233]
	global_load_ushort v223, v[234:235], off
	v_fmac_f32_e32 v0, v65, v64
	v_cvt_pk_bf16_f32 v0, v0, s0
	global_store_short v[10:11], v0, off
	v_lshl_add_u64 v[2:3], s[62:63], 0, v[80:81]
	v_lshlrev_b32_e32 v80, 16, v222
	v_mov_b32_e32 v231, v1
	v_add_u32_e32 v230,v110,v6
	v_lshlrev_b64 v[232:233],1,v[230:231]
	v_lshl_add_u64 v[234:235],s[18:19],0,v[232:233]
	global_load_ushort v222, v[234:235], off
	v_lshl_add_u64 v[10:11], s[18:19], 0, v[86:87]
	v_lshl_add_u64 v[64:65], s[18:19], 0, v[98:99]
	s_waitcnt vmcnt(45)
	v_lshlrev_b32_e32 v0, 16, v225
	v_mov_b32_e32 v231, v1
	v_add_u32_e32 v230,v113,v6
	v_lshlrev_b64 v[232:233],1,v[230:231]
	v_lshl_add_u64 v[234:235],s[18:19],0,v[232:233]
	global_load_ushort v225, v[234:235], off
	v_fmac_f32_e32 v80, v66, v0
	v_cvt_pk_bf16_f32 v0, v80, s0
	global_store_short v[14:15], v0, off
	v_add_u32_e32 v0, v127, v4
	v_lshlrev_b64 v[80:81], 1, v[0:1]
	v_add_u32_e32 v0, v128, v4
	v_lshl_add_u64 v[2:3], s[62:63], 0, v[82:83]
	v_lshlrev_b64 v[82:83], 1, v[0:1]
	v_lshlrev_b32_e32 v0, 16, v229
	v_mov_b32_e32 v231, v1
	v_add_u32_e32 v230,v121,v6
	v_lshlrev_b64 v[232:233],1,v[230:231]
	v_lshl_add_u64 v[234:235],s[18:19],0,v[232:233]
	global_load_ushort v229, v[234:235], off
	v_lshl_add_u64 v[14:15], s[18:19], 0, v[90:91]
	v_lshl_add_u64 v[106:107], s[18:19], 0, v[82:83]
	s_waitcnt vmcnt(44)
	v_lshlrev_b32_e32 v66, 16, v194
	v_mov_b32_e32 v231, v1
	v_add_u32_e32 v230,v109,v6
	v_lshlrev_b64 v[232:233],1,v[230:231]
	v_lshl_add_u64 v[234:235],s[62:63],0,v[232:233]
	global_load_ushort v194, v[234:235], off
	v_fmac_f32_e32 v0, v67, v66
	v_cvt_pk_bf16_f32 v0, v0, s0
	global_store_short v[8:9], v0, off
	v_lshlrev_b32_e32 v66, 16, v215
	v_mov_b32_e32 v231, v1
	v_add_u32_e32 v230,v112,v6
	v_lshlrev_b64 v[232:233],1,v[230:231]
	v_lshl_add_u64 v[234:235],s[18:19],0,v[232:233]
	global_load_ushort v215, v[234:235], off
	v_lshl_add_u64 v[2:3], s[62:63], 0, v[86:87]
	v_lshl_add_u64 v[8:9], s[18:19], 0, v[96:97]
	s_waitcnt vmcnt(42)
	v_lshlrev_b32_e32 v0, 16, v195
	v_mov_b32_e32 v231, v1
	v_add_u32_e32 v230,v119,v6
	v_lshlrev_b64 v[232:233],1,v[230:231]
	v_lshl_add_u64 v[234:235],s[18:19],0,v[232:233]
	global_load_ushort v195, v[234:235], off
	v_fmac_f32_e32 v66, v68, v0
	v_cvt_pk_bf16_f32 v0, v66, s0
	global_store_short v[84:85], v0, off
	v_lshlrev_b32_e32 v68, 16, v204
	v_mov_b32_e32 v231, v1
	v_add_u32_e32 v230,v110,v6
	v_lshlrev_b64 v[232:233],1,v[230:231]
	v_lshl_add_u64 v[234:235],s[62:63],0,v[232:233]
	global_load_ushort v204, v[234:235], off
	v_lshl_add_u64 v[2:3], s[62:63], 0, v[88:89]
	v_lshl_add_u64 v[66:67], s[18:19], 0, v[100:101]
	s_waitcnt vmcnt(42)
	v_lshlrev_b32_e32 v0, 16, v212
	v_mov_b32_e32 v231, v1
	v_add_u32_e32 v230,v114,v6
	v_lshlrev_b64 v[232:233],1,v[230:231]
	v_lshl_add_u64 v[234:235],s[18:19],0,v[232:233]
	global_load_ushort v212, v[234:235], off
	v_fmac_f32_e32 v68, v69, v0
	v_cvt_pk_bf16_f32 v0, v68, s0
	global_store_short v[10:11], v0, off
	v_lshl_add_u64 v[10:11], s[18:19], 0, v[80:81]
	v_lshlrev_b32_e32 v68, 16, v209
	v_mov_b32_e32 v231, v1
	v_add_u32_e32 v230,v128,v6
	v_lshlrev_b64 v[232:233],1,v[230:231]
	v_lshl_add_u64 v[234:235],s[18:19],0,v[232:233]
	global_load_ushort v209, v[234:235], off
	v_lshl_add_u64 v[2:3], s[62:63], 0, v[90:91]
	v_or_b32_e32 v90, 0x16c00, v5
	s_waitcnt vmcnt(42)
	v_lshlrev_b32_e32 v0, 16, v217
	v_mov_b32_e32 v231, v1
	v_add_u32_e32 v230,v111,v6
	v_lshlrev_b64 v[232:233],1,v[230:231]
	v_lshl_add_u64 v[234:235],s[62:63],0,v[232:233]
	global_load_ushort v217, v[234:235], off
	v_fmac_f32_e32 v68, v70, v0
	v_cvt_pk_bf16_f32 v0, v68, s0
	global_store_short v[12:13], v0, off
	v_add_u32_e32 v0, v90, v4
	v_lshlrev_b64 v[68:69], 1, v[0:1]
	v_lshlrev_b32_e32 v0, 16, v227
	v_mov_b32_e32 v231, v1
	v_add_u32_e32 v230,v118,v6
	v_lshlrev_b64 v[232:233],1,v[230:231]
	v_lshl_add_u64 v[234:235],s[18:19],0,v[232:233]
	global_load_ushort v227, v[234:235], off
	v_lshl_add_u64 v[12:13], s[62:63], 0, v[92:93]
	v_lshl_add_u64 v[2:3], s[18:19], 0, v[68:69]
	s_waitcnt vmcnt(42)
	v_lshlrev_b32_e32 v70, 16, v196
	v_mov_b32_e32 v231, v1
	v_add_u32_e32 v230,v112,v6
	v_lshlrev_b64 v[232:233],1,v[230:231]
	v_lshl_add_u64 v[234:235],s[62:63],0,v[232:233]
	global_load_ushort v196, v[234:235], off
	v_fmac_f32_e32 v0, v71, v70
	v_cvt_pk_bf16_f32 v0, v0, s0
	global_store_short v[14:15], v0, off
	v_lshlrev_b32_e32 v14, 16, v226
	v_mov_b32_e32 v231, v1
	v_add_u32_e32 v230,v120,v6
	v_lshlrev_b64 v[232:233],1,v[230:231]
	v_lshl_add_u64 v[234:235],s[18:19],0,v[232:233]
	global_load_ushort v226, v[234:235], off
	v_lshl_add_u64 v[12:13], s[62:63], 0, v[96:97]
	s_waitcnt vmcnt(42)
	v_lshlrev_b32_e32 v0, 16, v203
	v_mov_b32_e32 v231, v1
	v_add_u32_e32 v230,v113,v6
	v_lshlrev_b64 v[232:233],1,v[230:231]
	v_lshl_add_u64 v[234:235],s[62:63],0,v[232:233]
	global_load_ushort v203, v[234:235], off
	v_fmac_f32_e32 v14, v72, v0
	v_cvt_pk_bf16_f32 v0, v14, s0
	global_store_short v[94:95], v0, off
	v_lshlrev_b32_e32 v14, 16, v210
	v_mov_b32_e32 v231, v1
	v_add_u32_e32 v230,v127,v6
	v_lshlrev_b64 v[232:233],1,v[230:231]
	v_lshl_add_u64 v[234:235],s[18:19],0,v[232:233]
	global_load_ushort v210, v[234:235], off
	v_lshl_add_u64 v[12:13], s[62:63], 0, v[98:99]
	s_waitcnt vmcnt(44)
	v_lshlrev_b32_e32 v0, 16, v219
	v_mov_b32_e32 v231, v1
	v_add_u32_e32 v230,v114,v6
	v_lshlrev_b64 v[232:233],1,v[230:231]
	v_lshl_add_u64 v[234:235],s[62:63],0,v[232:233]
	global_load_ushort v219, v[234:235], off
	v_fmac_f32_e32 v14, v73, v0
	v_cvt_pk_bf16_f32 v0, v14, s0
	global_store_short v[8:9], v0, off
	v_lshlrev_b32_e32 v12, 16, v224
	v_mov_b32_e32 v231, v1
	v_add_u32_e32 v230,v115,v6
	v_lshlrev_b64 v[232:233],1,v[230:231]
	v_lshl_add_u64 v[234:235],s[62:63],0,v[232:233]
	global_load_ushort v224, v[234:235], off
	v_lshl_add_u64 v[8:9], s[62:63], 0, v[100:101]
	s_waitcnt vmcnt(45)
	v_lshlrev_b32_e32 v0, 16, v228
	v_mov_b32_e32 v231, v1
	v_add_u32_e32 v230,v118,v6
	v_lshlrev_b64 v[232:233],1,v[230:231]
	v_lshl_add_u64 v[234:235],s[62:63],0,v[232:233]
	global_load_ushort v228, v[234:235], off
	v_fmac_f32_e32 v12, v74, v0
	v_cvt_pk_bf16_f32 v0, v12, s0
	global_store_short v[64:65], v0, off
	v_lshlrev_b32_e32 v12, 16, v213
	v_mov_b32_e32 v231, v1
	v_add_u32_e32 v230,v119,v6
	v_lshlrev_b64 v[232:233],1,v[230:231]
	v_lshl_add_u64 v[234:235],s[62:63],0,v[232:233]
	global_load_ushort v213, v[234:235], off
	v_lshl_add_u64 v[8:9], s[62:63], 0, v[102:103]
	s_waitcnt vmcnt(47)
	v_lshlrev_b32_e32 v0, 16, v221
	v_mov_b32_e32 v231, v1
	v_add_u32_e32 v230,v120,v6
	v_lshlrev_b64 v[232:233],1,v[230:231]
	v_lshl_add_u64 v[234:235],s[62:63],0,v[232:233]
	global_load_ushort v221, v[234:235], off
	v_fmac_f32_e32 v12, v75, v0
	v_cvt_pk_bf16_f32 v0, v12, s0
	global_store_short v[66:67], v0, off
	v_lshlrev_b32_e32 v12, 16, v214
	v_mov_b32_e32 v231, v1
	v_add_u32_e32 v230,v121,v6
	v_lshlrev_b64 v[232:233],1,v[230:231]
	v_lshl_add_u64 v[234:235],s[62:63],0,v[232:233]
	global_load_ushort v214, v[234:235], off
	v_lshl_add_u64 v[8:9], s[62:63], 0, v[80:81]
	s_waitcnt vmcnt(48)
	v_lshlrev_b32_e32 v0, 16, v198
	v_mov_b32_e32 v231, v1
	v_add_u32_e32 v230,v127,v6
	v_lshlrev_b64 v[232:233],1,v[230:231]
	v_lshl_add_u64 v[234:235],s[62:63],0,v[232:233]
	global_load_ushort v198, v[234:235], off
	v_fmac_f32_e32 v12, v76, v0
	v_cvt_pk_bf16_f32 v0, v12, s0
	global_store_short v[104:105], v0, off
	v_lshlrev_b32_e32 v12, 16, v193
	v_mov_b32_e32 v231, v1
	v_add_u32_e32 v230,v128,v6
	v_lshlrev_b64 v[232:233],1,v[230:231]
	v_lshl_add_u64 v[234:235],s[62:63],0,v[232:233]
	global_load_ushort v193, v[234:235], off
	v_lshl_add_u64 v[8:9], s[62:63], 0, v[82:83]
	s_waitcnt vmcnt(50)
	v_lshlrev_b32_e32 v0, 16, v206
	v_mov_b32_e32 v231, v1
	v_add_u32_e32 v230,v90,v6
	v_lshlrev_b64 v[232:233],1,v[230:231]
	v_lshl_add_u64 v[234:235],s[62:63],0,v[232:233]
	global_load_ushort v206, v[234:235], off
	v_fmac_f32_e32 v12, v77, v0
	v_cvt_pk_bf16_f32 v0, v12, s0
	global_store_short v[10:11], v0, off
	v_lshlrev_b32_e32 v10, 16, v207
	v_mov_b32_e32 v233, v1
	v_or_b32_e32 v231,0x18000,v5
	v_add_u32_e32 v232,v231,v4
	v_lshlrev_b64 v[234:235],1,v[232:233]
	v_lshl_add_u64 v[236:237],s[18:19],0,v[234:235]
	global_load_ushort v207, v[236:237], off
	v_lshl_add_u64 v[8:9], s[62:63], 0, v[68:69]
	s_waitcnt vmcnt(51)
	v_lshlrev_b32_e32 v0, 16, v218
	v_mov_b32_e32 v233, v1
	v_or_b32_e32 v231,0x18000,v5
	v_add_u32_e32 v232,v231,v4
	v_lshlrev_b64 v[234:235],1,v[232:233]
	v_lshl_add_u64 v[234:235],s[62:63],0,v[234:235]
	global_load_ushort v218, v[234:235], off
	v_fmac_f32_e32 v10, v78, v0
	v_cvt_pk_bf16_f32 v0, v10, s0
	global_store_short v[106:107], v0, off
	v_add_u32_e32 v0, v7, v6
	v_lshlrev_b64 v[8:9], 1, v[0:1]
	v_add_u32_e32 v0, v108, v6
	v_lshlrev_b64 v[12:13], 1, v[0:1]
	v_add_u32_e32 v0, v109, v6
	v_lshlrev_b64 v[14:15], 1, v[0:1]
	v_add_u32_e32 v0, v110, v6
	v_lshlrev_b64 v[64:65], 1, v[0:1]
	v_add_u32_e32 v0, v111, v6
	v_lshlrev_b64 v[66:67], 1, v[0:1]
	v_add_u32_e32 v0, v112, v6
	v_lshlrev_b64 v[68:69], 1, v[0:1]
	v_add_u32_e32 v0, v113, v6
	v_lshlrev_b64 v[70:71], 1, v[0:1]
	v_add_u32_e32 v0, v114, v6
	v_lshlrev_b64 v[72:73], 1, v[0:1]
	v_add_u32_e32 v0, v115, v6
	v_lshlrev_b64 v[74:75], 1, v[0:1]
	v_add_u32_e32 v0, v118, v6
	v_lshlrev_b64 v[76:77], 1, v[0:1]
	v_add_u32_e32 v0, v119, v6
	v_lshlrev_b64 v[80:81], 1, v[0:1]
	v_add_u32_e32 v0, v120, v6
	v_lshlrev_b64 v[82:83], 1, v[0:1]
	v_add_u32_e32 v0, v121, v6
	v_lshlrev_b64 v[84:85], 1, v[0:1]
	v_add_u32_e32 v0, v127, v6
	v_lshlrev_b64 v[86:87], 1, v[0:1]
	v_add_u32_e32 v0, v128, v6
	v_lshlrev_b64 v[88:89], 1, v[0:1]
	v_add_u32_e32 v0, v90, v6
	v_lshlrev_b64 v[90:91], 1, v[0:1]
	v_lshlrev_b32_e32 v0, 16, v197
	v_mov_b32_e32 v233, v1
	v_or_b32_e32 v230,0x18400,v5
	v_add_u32_e32 v232,v230,v4
	v_lshlrev_b64 v[234:235],1,v[232:233]
	v_lshl_add_u64 v[236:237],s[18:19],0,v[234:235]
	global_load_ushort v197, v[236:237], off
	v_lshl_add_u64 v[10:11], s[18:19], 0, v[8:9]
	v_lshl_add_u64 v[92:93], s[18:19], 0, v[90:91]
	v_lshl_add_u64 v[8:9], s[62:63], 0, v[8:9]
	v_lshl_add_u64 v[94:95], s[18:19], 0, v[74:75]
	s_waitcnt vmcnt(53)
	v_lshlrev_b32_e32 v78, 16, v199
	v_mov_b32_e32 v233, v1
	v_or_b32_e32 v231,0x18800,v5
	v_add_u32_e32 v232,v231,v4
	v_lshlrev_b64 v[234:235],1,v[232:233]
	v_lshl_add_u64 v[236:237],s[18:19],0,v[234:235]
	global_load_ushort v199, v[236:237], off
	v_fmac_f32_e32 v0, v79, v78
	v_cvt_pk_bf16_f32 v0, v0, s0
	global_store_short v[2:3], v0, off
	s_nop 0
	v_lshl_add_u64 v[2:3], s[18:19], 0, v[12:13]
	v_lshl_add_u64 v[8:9], s[62:63], 0, v[12:13]
	v_lshl_add_u64 v[12:13], s[18:19], 0, v[14:15]
	v_lshl_add_u64 v[78:79], s[18:19], 0, v[66:67]
	s_waitcnt vmcnt(52)
	v_lshlrev_b32_e32 v0, 16, v205
	v_mov_b32_e32 v233, v1
	v_or_b32_e32 v231,0x1a000,v5
	v_add_u32_e32 v232,v231,v4
	v_lshlrev_b64 v[234:235],1,v[232:233]
	v_lshl_add_u64 v[236:237],s[18:19],0,v[234:235]
	global_load_ushort v205, v[236:237], off
	s_waitcnt vmcnt(51)
	v_lshlrev_b32_e32 v96, 16, v201
	v_mov_b32_e32 v233, v1
	v_or_b32_e32 v231,0x1c000,v5
	v_add_u32_e32 v232,v231,v4
	v_lshlrev_b64 v[234:235],1,v[232:233]
	v_lshl_add_u64 v[236:237],s[18:19],0,v[234:235]
	global_load_ushort v201, v[236:237], off
	v_fmac_f32_e32 v0, v48, v96
	v_cvt_pk_bf16_f32 v0, v0, s0
	global_store_short v[10:11], v0, off
	s_waitcnt vmcnt(52)
	v_lshlrev_b32_e32 v48, 16, v202
	v_mov_b32_e32 v233, v1
	v_or_b32_e32 v230,0x18400,v5
	v_add_u32_e32 v232,v230,v4
	v_lshlrev_b64 v[234:235],1,v[232:233]
	v_lshl_add_u64 v[234:235],s[62:63],0,v[234:235]
	global_load_ushort v202, v[234:235], off
	v_lshl_add_u64 v[10:11], s[18:19], 0, v[64:65]
	v_lshl_add_u64 v[8:9], s[62:63], 0, v[14:15]
	v_lshl_add_u64 v[14:15], s[18:19], 0, v[70:71]
	v_lshl_add_u64 v[96:97], s[18:19], 0, v[84:85]
	s_waitcnt vmcnt(47)
	v_lshlrev_b32_e32 v0, 16, v223
	v_mov_b32_e32 v233, v1
	v_or_b32_e32 v230,0x18c00,v5
	v_add_u32_e32 v232,v230,v4
	v_lshlrev_b64 v[234:235],1,v[232:233]
	v_lshl_add_u64 v[236:237],s[18:19],0,v[234:235]
	global_load_ushort v223, v[236:237], off
	v_fmac_f32_e32 v48, v49, v0
	v_cvt_pk_bf16_f32 v0, v48, s0
	global_store_short v[2:3], v0, off
	v_lshl_add_u64 v[2:3], s[62:63], 0, v[64:65]
	v_lshlrev_b32_e32 v64, 16, v216
	v_mov_b32_e32 v233, v1
	v_or_b32_e32 v231,0x1a800,v5
	v_add_u32_e32 v232,v231,v4
	v_lshlrev_b64 v[234:235],1,v[232:233]
	v_lshl_add_u64 v[236:237],s[18:19],0,v[234:235]
	global_load_ushort v216, v[236:237], off
	v_lshl_add_u64 v[8:9], s[18:19], 0, v[68:69]
	v_lshl_add_u64 v[48:49], s[18:19], 0, v[80:81]
	s_waitcnt vmcnt(44)
	v_lshlrev_b32_e32 v0, 16, v194
	v_mov_b32_e32 v233, v1
	v_or_b32_e32 v231,0x1e000,v5
	v_add_u32_e32 v232,v231,v4
	v_lshlrev_b64 v[234:235],1,v[232:233]
	v_lshl_add_u64 v[236:237],s[18:19],0,v[234:235]
	global_load_ushort v194, v[236:237], off
	v_fmac_f32_e32 v64, v50, v0
	v_cvt_pk_bf16_f32 v0, v64, s0
	global_store_short v[12:13], v0, off
	v_lshlrev_b32_e32 v50, 16, v222
	v_mov_b32_e32 v233, v1
	v_or_b32_e32 v231,0x18800,v5
	v_add_u32_e32 v232,v231,v4
	v_lshlrev_b64 v[234:235],1,v[232:233]
	v_lshl_add_u64 v[236:237],s[62:63],0,v[234:235]
	global_load_ushort v222, v[236:237], off
	v_lshl_add_u64 v[12:13], s[18:19], 0, v[72:73]
	v_lshl_add_u64 v[2:3], s[62:63], 0, v[66:67]
	v_lshl_add_u64 v[64:65], s[18:19], 0, v[88:89]
	s_waitcnt vmcnt(42)
	v_lshlrev_b32_e32 v0, 16, v204
	v_mov_b32_e32 v233, v1
	v_or_b32_e32 v230,0x1a400,v5
	v_add_u32_e32 v232,v230,v4
	v_lshlrev_b64 v[234:235],1,v[232:233]
	v_lshl_add_u64 v[236:237],s[18:19],0,v[234:235]
	global_load_ushort v204, v[236:237], off
	v_fmac_f32_e32 v50, v51, v0
	v_cvt_pk_bf16_f32 v0, v50, s0
	global_store_short v[10:11], v0, off
	v_lshlrev_b32_e32 v50, 16, v211
	v_mov_b32_e32 v233, v1
	v_or_b32_e32 v231,0x1c800,v5
	v_add_u32_e32 v232,v231,v4
	v_lshlrev_b64 v[234:235],1,v[232:233]
	v_lshl_add_u64 v[236:237],s[18:19],0,v[234:235]
	global_load_ushort v211, v[236:237], off
	v_lshl_add_u64 v[2:3], s[62:63], 0, v[68:69]
	v_lshl_add_u64 v[10:11], s[18:19], 0, v[76:77]
	s_waitcnt vmcnt(41)
	v_lshlrev_b32_e32 v0, 16, v217
	v_mov_b32_e32 v233, v1
	v_or_b32_e32 v230,0x18c00,v5
	v_add_u32_e32 v232,v230,v4
	v_lshlrev_b64 v[234:235],1,v[232:233]
	v_lshl_add_u64 v[236:237],s[62:63],0,v[234:235]
	global_load_ushort v217, v[236:237], off
	v_fmac_f32_e32 v50, v52, v0
	v_cvt_pk_bf16_f32 v0, v50, s0
	global_store_short v[78:79], v0, off
	v_lshlrev_b32_e32 v52, 16, v215
	v_mov_b32_e32 v233, v1
	v_or_b32_e32 v230,0x1ac00,v5
	v_add_u32_e32 v232,v230,v4
	v_lshlrev_b64 v[234:235],1,v[232:233]
	v_lshl_add_u64 v[236:237],s[18:19],0,v[234:235]
	global_load_ushort v215, v[236:237], off
	v_lshl_add_u64 v[2:3], s[62:63], 0, v[70:71]
	v_lshl_add_u64 v[50:51], s[18:19], 0, v[82:83]
	s_waitcnt vmcnt(41)
	v_lshlrev_b32_e32 v0, 16, v196
	v_mov_b32_e32 v233, v1
	v_or_b32_e32 v230,0x1e800,v5
	v_add_u32_e32 v232,v230,v4
	v_lshlrev_b64 v[234:235],1,v[232:233]
	v_lshl_add_u64 v[236:237],s[18:19],0,v[234:235]
	global_load_ushort v196, v[236:237], off
	v_fmac_f32_e32 v52, v53, v0
	v_cvt_pk_bf16_f32 v0, v52, s0
	global_store_short v[8:9], v0, off
	v_lshl_add_u64 v[8:9], s[18:19], 0, v[86:87]
	v_lshlrev_b32_e32 v52, 16, v225
	v_mov_b32_e32 v233, v1
	v_or_b32_e32 v231,0x1a000,v5
	v_add_u32_e32 v232,v231,v4
	v_lshlrev_b64 v[234:235],1,v[232:233]
	v_lshl_add_u64 v[236:237],s[62:63],0,v[234:235]
	global_load_ushort v225, v[236:237], off
	v_lshl_add_u64 v[2:3], s[62:63], 0, v[72:73]
	s_waitcnt vmcnt(41)
	v_lshlrev_b32_e32 v0, 16, v203
	v_mov_b32_e32 v233, v1
	v_or_b32_e32 v230,0x1c400,v5
	v_add_u32_e32 v232,v230,v4
	v_lshlrev_b64 v[234:235],1,v[232:233]
	v_lshl_add_u64 v[236:237],s[18:19],0,v[234:235]
	global_load_ushort v203, v[236:237], off
	v_fmac_f32_e32 v52, v54, v0
	v_cvt_pk_bf16_f32 v0, v52, s0
	global_store_short v[14:15], v0, off
	v_lshlrev_b32_e32 v14, 16, v212
	v_mov_b32_e32 v233, v1
	v_or_b32_e32 v230,0x1a400,v5
	v_add_u32_e32 v232,v230,v4
	v_lshlrev_b64 v[234:235],1,v[232:233]
	v_lshl_add_u64 v[236:237],s[62:63],0,v[234:235]
	global_load_ushort v212, v[236:237], off
	v_lshl_add_u64 v[2:3], s[62:63], 0, v[74:75]
	s_waitcnt vmcnt(41)
	v_lshlrev_b32_e32 v0, 16, v219
	v_mov_b32_e32 v233, v1
	v_or_b32_e32 v230,0x1cc00,v5
	v_add_u32_e32 v232,v230,v4
	v_lshlrev_b64 v[234:235],1,v[232:233]
	v_lshl_add_u64 v[236:237],s[18:19],0,v[234:235]
	global_load_ushort v219, v[236:237], off
	v_fmac_f32_e32 v14, v55, v0
	v_cvt_pk_bf16_f32 v0, v14, s0
	global_store_short v[12:13], v0, off
	v_lshlrev_b32_e32 v12, 16, v220
	v_mov_b32_e32 v233, v1
	v_or_b32_e32 v231,0x1a800,v5
	v_add_u32_e32 v232,v231,v4
	v_lshlrev_b64 v[234:235],1,v[232:233]
	v_lshl_add_u64 v[236:237],s[62:63],0,v[234:235]
	global_load_ushort v220, v[236:237], off
	v_lshl_add_u64 v[2:3], s[62:63], 0, v[76:77]
	s_waitcnt vmcnt(42)
	v_lshlrev_b32_e32 v0, 16, v224
	v_mov_b32_e32 v233, v1
	v_or_b32_e32 v231,0x1e400,v5
	v_add_u32_e32 v232,v231,v4
	v_lshlrev_b64 v[234:235],1,v[232:233]
	v_lshl_add_u64 v[236:237],s[18:19],0,v[234:235]
	global_load_ushort v224, v[236:237], off
	v_fmac_f32_e32 v12, v56, v0
	v_cvt_pk_bf16_f32 v0, v12, s0
	global_store_short v[94:95], v0, off
	v_lshlrev_b32_e32 v12, 16, v227
	v_mov_b32_e32 v233, v1
	v_or_b32_e32 v230,0x1ac00,v5
	v_add_u32_e32 v232,v230,v4
	v_lshlrev_b64 v[234:235],1,v[232:233]
	v_lshl_add_u64 v[236:237],s[62:63],0,v[234:235]
	global_load_ushort v227, v[236:237], off
	v_lshl_add_u64 v[2:3], s[62:63], 0, v[80:81]
	s_waitcnt vmcnt(44)
	v_lshlrev_b32_e32 v0, 16, v228
	v_mov_b32_e32 v233, v1
	v_or_b32_e32 v230,0x1ec00,v5
	v_add_u32_e32 v232,v230,v4
	v_lshlrev_b64 v[234:235],1,v[232:233]
	v_lshl_add_u64 v[236:237],s[18:19],0,v[234:235]
	global_load_ushort v228, v[236:237], off
	v_fmac_f32_e32 v12, v57, v0
	v_cvt_pk_bf16_f32 v0, v12, s0
	global_store_short v[10:11], v0, off
	v_lshlrev_b32_e32 v10, 16, v195
	v_mov_b32_e32 v233, v1
	v_or_b32_e32 v231,0x1c000,v5
	v_add_u32_e32 v232,v231,v4
	v_lshlrev_b64 v[234:235],1,v[232:233]
	v_lshl_add_u64 v[236:237],s[62:63],0,v[234:235]
	global_load_ushort v195, v[236:237], off
	v_lshl_add_u64 v[2:3], s[62:63], 0, v[82:83]
	s_waitcnt vmcnt(45)
	v_lshlrev_b32_e32 v0, 16, v213
	v_mov_b32_e32 v233, v1
	v_or_b32_e32 v230,0x1c400,v5
	v_add_u32_e32 v232,v230,v4
	v_lshlrev_b64 v[234:235],1,v[232:233]
	v_lshl_add_u64 v[236:237],s[62:63],0,v[234:235]
	global_load_ushort v213, v[236:237], off
	v_fmac_f32_e32 v10, v58, v0
	v_cvt_pk_bf16_f32 v0, v10, s0
	global_store_short v[48:49], v0, off
	v_lshlrev_b32_e32 v10, 16, v226
	v_mov_b32_e32 v233, v1
	v_or_b32_e32 v231,0x1c800,v5
	v_add_u32_e32 v232,v231,v4
	v_lshlrev_b64 v[234:235],1,v[232:233]
	v_lshl_add_u64 v[236:237],s[62:63],0,v[234:235]
	global_load_ushort v226, v[236:237], off
	v_lshl_add_u64 v[2:3], s[62:63], 0, v[84:85]
	s_waitcnt vmcnt(47)
	v_lshlrev_b32_e32 v0, 16, v221
	v_mov_b32_e32 v233, v1
	v_or_b32_e32 v230,0x1cc00,v5
	v_add_u32_e32 v232,v230,v4
	v_lshlrev_b64 v[234:235],1,v[232:233]
	v_lshl_add_u64 v[236:237],s[62:63],0,v[234:235]
	global_load_ushort v221, v[236:237], off
	v_fmac_f32_e32 v10, v59, v0
	v_cvt_pk_bf16_f32 v0, v10, s0
	global_store_short v[50:51], v0, off
	v_lshlrev_b32_e32 v10, 16, v229
	v_mov_b32_e32 v233, v1
	v_or_b32_e32 v231,0x1e000,v5
	v_add_u32_e32 v232,v231,v4
	v_lshlrev_b64 v[234:235],1,v[232:233]
	v_lshl_add_u64 v[236:237],s[62:63],0,v[234:235]
	global_load_ushort v229, v[236:237], off
	v_lshl_add_u64 v[2:3], s[62:63], 0, v[86:87]
	s_waitcnt vmcnt(48)
	v_lshlrev_b32_e32 v0, 16, v214
	v_mov_b32_e32 v233, v1
	v_or_b32_e32 v231,0x1e400,v5
	v_add_u32_e32 v232,v231,v4
	v_lshlrev_b64 v[234:235],1,v[232:233]
	v_lshl_add_u64 v[236:237],s[62:63],0,v[234:235]
	global_load_ushort v214, v[236:237], off
	v_fmac_f32_e32 v10, v60, v0
	v_cvt_pk_bf16_f32 v0, v10, s0
	global_store_short v[96:97], v0, off
	v_lshlrev_b32_e32 v10, 16, v210
	v_mov_b32_e32 v233, v1
	v_or_b32_e32 v230,0x1e800,v5
	v_add_u32_e32 v232,v230,v4
	v_lshlrev_b64 v[234:235],1,v[232:233]
	v_lshl_add_u64 v[236:237],s[62:63],0,v[234:235]
	global_load_ushort v210, v[236:237], off
	v_lshl_add_u64 v[2:3], s[62:63], 0, v[88:89]
	s_waitcnt vmcnt(50)
	v_lshlrev_b32_e32 v0, 16, v198
	v_mov_b32_e32 v233, v1
	v_or_b32_e32 v230,0x1ec00,v5
	v_add_u32_e32 v232,v230,v4
	v_lshlrev_b64 v[234:235],1,v[232:233]
	v_lshl_add_u64 v[234:235],s[62:63],0,v[234:235]
	global_load_ushort v198, v[234:235], off
	v_fmac_f32_e32 v10, v61, v0
	v_cvt_pk_bf16_f32 v0, v10, s0
	global_store_short v[8:9], v0, off
	v_lshlrev_b32_e32 v2, 16, v209
	v_mov_b32_e32 v233, v1
	v_or_b32_e32 v230,0x1ec00,v5
	v_add_u32_e32 v232,v230,v6
	v_lshlrev_b64 v[234:235],1,v[232:233]
	v_lshl_add_u64 v[230:231],s[18:19],0,v[234:235]
	global_load_ushort v209, v[230:231], off
	s_waitcnt vmcnt(51)
	v_lshlrev_b32_e32 v0, 16, v193
	v_mov_b32_e32 v233, v1
	v_or_b32_e32 v231,0x18000,v5
	v_add_u32_e32 v232,v231,v6
	v_lshlrev_b64 v[234:235],1,v[232:233]
	v_lshl_add_u64 v[236:237],s[18:19],0,v[234:235]
	global_load_ushort v193, v[236:237], off
	v_fmac_f32_e32 v2, v62, v0
	v_cvt_pk_bf16_f32 v0, v2, s0
	global_store_short v[64:65], v0, off
	v_lshl_add_u64 v[2:3], s[62:63], 0, v[90:91]
	v_lshlrev_b32_e32 v2, 16, v192
	v_mov_b32_e32 v233, v1
	v_or_b32_e32 v231,0x18000,v5
	v_add_u32_e32 v232,v231,v6
	v_lshlrev_b64 v[234:235],1,v[232:233]
	v_lshl_add_u64 v[234:235],s[62:63],0,v[234:235]
	global_load_ushort v192, v[234:235], off
	s_waitcnt vmcnt(53)
	v_lshlrev_b32_e32 v0, 16, v206
	v_mov_b32_e32 v233, v1
	v_or_b32_e32 v230,0x18400,v5
	v_add_u32_e32 v232,v230,v6
	v_lshlrev_b64 v[234:235],1,v[232:233]
	v_lshl_add_u64 v[236:237],s[18:19],0,v[234:235]
	global_load_ushort v206, v[236:237], off
	v_fmac_f32_e32 v2, v63, v0
	v_cvt_pk_bf16_f32 v0, v2, s0
	global_store_short v[92:93], v0, off
	v_or_b32_e32 v7, 0x18000, v5
	v_add_u32_e32 v0, v7, v4
	v_lshlrev_b64 v[2:3], 1, v[0:1]
	v_lshl_add_u64 v[8:9], s[18:19], 0, v[2:3]
	v_lshl_add_u64 v[2:3], s[62:63], 0, v[2:3]
	v_or_b32_e32 v76, 0x18400, v5
	v_or_b32_e32 v77, 0x18800, v5
	v_add_u32_e32 v0, v76, v4
	v_or_b32_e32 v78, 0x18c00, v5
	v_lshlrev_b64 v[2:3], 1, v[0:1]
	v_add_u32_e32 v0, v77, v4
	v_or_b32_e32 v79, 0x1a000, v5
	v_lshlrev_b64 v[12:13], 1, v[0:1]
	v_add_u32_e32 v0, v78, v4
	v_or_b32_e32 v80, 0x1a400, v5
	v_lshlrev_b64 v[48:49], 1, v[0:1]
	v_add_u32_e32 v0, v79, v4
	v_or_b32_e32 v81, 0x1a800, v5
	v_lshlrev_b64 v[50:51], 1, v[0:1]
	v_add_u32_e32 v0, v80, v4
	v_or_b32_e32 v82, 0x1ac00, v5
	v_lshlrev_b64 v[54:55], 1, v[0:1]
	v_add_u32_e32 v0, v81, v4
	v_or_b32_e32 v83, 0x1c000, v5
	v_lshlrev_b64 v[56:57], 1, v[0:1]
	v_add_u32_e32 v0, v82, v4
	v_lshlrev_b64 v[58:59], 1, v[0:1]
	v_add_u32_e32 v0, v83, v4
	v_lshlrev_b64 v[60:61], 1, v[0:1]
	v_lshl_add_u64 v[10:11], s[18:19], 0, v[2:3]
	v_lshl_add_u64 v[2:3], s[62:63], 0, v[2:3]
	v_lshl_add_u64 v[14:15], s[18:19], 0, v[12:13]
	v_lshl_add_u64 v[52:53], s[18:19], 0, v[50:51]
	v_lshl_add_u64 v[62:63], s[18:19], 0, v[60:61]
	v_or_b32_e32 v86, 0x1c400, v5
	v_or_b32_e32 v87, 0x1c800, v5
	v_or_b32_e32 v88, 0x1cc00, v5
	v_or_b32_e32 v89, 0x1e000, v5
	v_or_b32_e32 v95, 0x1e400, v5
	v_or_b32_e32 v96, 0x1e800, v5
	s_waitcnt vmcnt(53)
	v_lshlrev_b32_e32 v0, 16, v207
	v_mov_b32_e32 v231, v1
	v_add_u32_e32 v230,v77,v6
	v_lshlrev_b64 v[232:233],1,v[230:231]
	v_lshl_add_u64 v[234:235],s[18:19],0,v[232:233]
	global_load_ushort v207, v[234:235], off
	s_waitcnt vmcnt(53)
	v_lshlrev_b32_e32 v64, 16, v218
	v_mov_b32_e32 v231, v1
	v_add_u32_e32 v230,v79,v6
	v_lshlrev_b64 v[232:233],1,v[230:231]
	v_lshl_add_u64 v[234:235],s[18:19],0,v[232:233]
	global_load_ushort v218, v[234:235], off
	v_fmac_f32_e32 v0, v32, v64
	v_cvt_pk_bf16_f32 v0, v0, s0
	global_store_short v[8:9], v0, off
	v_add_u32_e32 v0, v86, v4
	v_lshlrev_b64 v[64:65], 1, v[0:1]
	v_add_u32_e32 v0, v87, v4
	v_lshlrev_b64 v[66:67], 1, v[0:1]
	v_add_u32_e32 v0, v88, v4
	v_lshlrev_b64 v[68:69], 1, v[0:1]
	v_add_u32_e32 v0, v89, v4
	v_lshlrev_b64 v[70:71], 1, v[0:1]
	v_lshl_add_u64 v[8:9], s[18:19], 0, v[48:49]
	v_lshl_add_u64 v[2:3], s[62:63], 0, v[12:13]
	v_lshl_add_u64 v[12:13], s[18:19], 0, v[56:57]
	v_lshl_add_u64 v[72:73], s[18:19], 0, v[70:71]
	s_waitcnt vmcnt(53)
	v_lshlrev_b32_e32 v0, 16, v197
	v_mov_b32_e32 v231, v1
	v_add_u32_e32 v230,v83,v6
	v_lshlrev_b64 v[232:233],1,v[230:231]
	v_lshl_add_u64 v[234:235],s[18:19],0,v[232:233]
	global_load_ushort v197, v[234:235], off
	s_waitcnt vmcnt(48)
	v_lshlrev_b32_e32 v32, 16, v202
	v_mov_b32_e32 v231, v1
	v_add_u32_e32 v230,v76,v6
	v_lshlrev_b64 v[232:233],1,v[230:231]
	v_lshl_add_u64 v[234:235],s[62:63],0,v[232:233]
	global_load_ushort v202, v[234:235], off
	v_fmac_f32_e32 v0, v33, v32
	v_cvt_pk_bf16_f32 v0, v0, s0
	global_store_short v[10:11], v0, off
	v_lshl_add_u64 v[2:3], s[62:63], 0, v[48:49]
	v_lshlrev_b32_e32 v48, 16, v199
	v_mov_b32_e32 v231, v1
	v_add_u32_e32 v230,v78,v6
	v_lshlrev_b64 v[232:233],1,v[230:231]
	v_lshl_add_u64 v[234:235],s[18:19],0,v[232:233]
	global_load_ushort v199, v[234:235], off
	v_lshl_add_u64 v[10:11], s[18:19], 0, v[54:55]
	v_lshl_add_u64 v[32:33], s[18:19], 0, v[66:67]
	s_waitcnt vmcnt(45)
	v_lshlrev_b32_e32 v0, 16, v222
	v_mov_b32_e32 v231, v1
	v_add_u32_e32 v230,v81,v6
	v_lshlrev_b64 v[232:233],1,v[230:231]
	v_lshl_add_u64 v[234:235],s[18:19],0,v[232:233]
	global_load_ushort v222, v[234:235], off
	v_fmac_f32_e32 v48, v34, v0
	v_cvt_pk_bf16_f32 v0, v48, s0
	global_store_short v[14:15], v0, off
	v_add_u32_e32 v0, v95, v4
	v_lshlrev_b64 v[48:49], 1, v[0:1]
	v_add_u32_e32 v0, v96, v4
	v_lshl_add_u64 v[2:3], s[62:63], 0, v[50:51]
	v_lshlrev_b64 v[50:51], 1, v[0:1]
	v_lshlrev_b32_e32 v0, 16, v223
	v_mov_b32_e32 v231, v1
	v_add_u32_e32 v230,v89,v6
	v_lshlrev_b64 v[232:233],1,v[230:231]
	v_lshl_add_u64 v[234:235],s[18:19],0,v[232:233]
	global_load_ushort v223, v[234:235], off
	v_lshl_add_u64 v[14:15], s[18:19], 0, v[58:59]
	v_lshl_add_u64 v[74:75], s[18:19], 0, v[50:51]
	s_waitcnt vmcnt(44)
	v_lshlrev_b32_e32 v34, 16, v217
	v_mov_b32_e32 v231, v1
	v_add_u32_e32 v230,v77,v6
	v_lshlrev_b64 v[232:233],1,v[230:231]
	v_lshl_add_u64 v[234:235],s[62:63],0,v[232:233]
	global_load_ushort v217, v[234:235], off
	v_fmac_f32_e32 v0, v35, v34
	v_cvt_pk_bf16_f32 v0, v0, s0
	global_store_short v[8:9], v0, off
	v_lshlrev_b32_e32 v34, 16, v205
	v_mov_b32_e32 v231, v1
	v_add_u32_e32 v230,v80,v6
	v_lshlrev_b64 v[232:233],1,v[230:231]
	v_lshl_add_u64 v[234:235],s[18:19],0,v[232:233]
	global_load_ushort v205, v[234:235], off
	v_lshl_add_u64 v[2:3], s[62:63], 0, v[54:55]
	v_lshl_add_u64 v[8:9], s[18:19], 0, v[64:65]
	s_waitcnt vmcnt(42)
	v_lshlrev_b32_e32 v0, 16, v225
	v_mov_b32_e32 v231, v1
	v_add_u32_e32 v230,v87,v6
	v_lshlrev_b64 v[232:233],1,v[230:231]
	v_lshl_add_u64 v[234:235],s[18:19],0,v[232:233]
	global_load_ushort v225, v[234:235], off
	v_fmac_f32_e32 v34, v36, v0
	v_cvt_pk_bf16_f32 v0, v34, s0
	global_store_short v[52:53], v0, off
	v_lshlrev_b32_e32 v36, 16, v204
	v_mov_b32_e32 v231, v1
	v_add_u32_e32 v230,v78,v6
	v_lshlrev_b64 v[232:233],1,v[230:231]
	v_lshl_add_u64 v[234:235],s[62:63],0,v[232:233]
	global_load_ushort v204, v[234:235], off
	v_lshl_add_u64 v[2:3], s[62:63], 0, v[56:57]
	v_lshl_add_u64 v[34:35], s[18:19], 0, v[68:69]
	v_or_b32_e32 v56, 0x1ec00, v5
	s_waitcnt vmcnt(42)
	v_lshlrev_b32_e32 v0, 16, v212
	v_mov_b32_e32 v231, v1
	v_add_u32_e32 v230,v82,v6
	v_lshlrev_b64 v[232:233],1,v[230:231]
	v_lshl_add_u64 v[234:235],s[18:19],0,v[232:233]
	global_load_ushort v212, v[234:235], off
	v_fmac_f32_e32 v36, v37, v0
	v_cvt_pk_bf16_f32 v0, v36, s0
	global_store_short v[10:11], v0, off
	v_lshl_add_u64 v[10:11], s[18:19], 0, v[48:49]
	v_lshlrev_b32_e32 v36, 16, v216
	v_mov_b32_e32 v231, v1
	v_add_u32_e32 v230,v96,v6
	v_lshlrev_b64 v[232:233],1,v[230:231]
	v_lshl_add_u64 v[234:235],s[18:19],0,v[232:233]
	global_load_ushort v216, v[234:235], off
	v_lshl_add_u64 v[2:3], s[62:63], 0, v[58:59]
	s_waitcnt vmcnt(42)
	v_lshlrev_b32_e32 v0, 16, v220
	v_mov_b32_e32 v231, v1
	v_add_u32_e32 v230,v79,v6
	v_lshlrev_b64 v[232:233],1,v[230:231]
	v_lshl_add_u64 v[234:235],s[62:63],0,v[232:233]
	global_load_ushort v220, v[234:235], off
	v_fmac_f32_e32 v36, v38, v0
	v_cvt_pk_bf16_f32 v0, v36, s0
	global_store_short v[12:13], v0, off
	v_add_u32_e32 v0, v56, v4
	v_lshlrev_b64 v[4:5], 1, v[0:1]
	v_lshlrev_b32_e32 v0, 16, v215
	v_mov_b32_e32 v231, v1
	v_add_u32_e32 v230,v86,v6
	v_lshlrev_b64 v[232:233],1,v[230:231]
	v_lshl_add_u64 v[234:235],s[18:19],0,v[232:233]
	global_load_ushort v215, v[234:235], off
	v_lshl_add_u64 v[12:13], s[62:63], 0, v[60:61]
	v_lshl_add_u64 v[2:3], s[18:19], 0, v[4:5]
	v_lshl_add_u64 v[4:5], s[62:63], 0, v[4:5]
	s_waitcnt vmcnt(42)
	v_lshlrev_b32_e32 v36, 16, v227
	v_mov_b32_e32 v231, v1
	v_add_u32_e32 v230,v80,v6
	v_lshlrev_b64 v[232:233],1,v[230:231]
	v_lshl_add_u64 v[234:235],s[62:63],0,v[232:233]
	global_load_ushort v227, v[234:235], off
	v_fmac_f32_e32 v0, v39, v36
	v_cvt_pk_bf16_f32 v0, v0, s0
	global_store_short v[14:15], v0, off
	v_lshlrev_b32_e32 v14, 16, v201
	v_mov_b32_e32 v231, v1
	v_add_u32_e32 v230,v88,v6
	v_lshlrev_b64 v[232:233],1,v[230:231]
	v_lshl_add_u64 v[234:235],s[18:19],0,v[232:233]
	global_load_ushort v201, v[234:235], off
	v_lshl_add_u64 v[12:13], s[62:63], 0, v[64:65]
	s_waitcnt vmcnt(42)
	v_lshlrev_b32_e32 v0, 16, v195
	v_mov_b32_e32 v231, v1
	v_add_u32_e32 v230,v81,v6
	v_lshlrev_b64 v[232:233],1,v[230:231]
	v_lshl_add_u64 v[234:235],s[62:63],0,v[232:233]
	global_load_ushort v195, v[234:235], off
	v_fmac_f32_e32 v14, v40, v0
	v_cvt_pk_bf16_f32 v0, v14, s0
	global_store_short v[62:63], v0, off
	v_lshlrev_b32_e32 v14, 16, v203
	v_mov_b32_e32 v231, v1
	v_add_u32_e32 v230,v95,v6
	v_lshlrev_b64 v[232:233],1,v[230:231]
	v_lshl_add_u64 v[234:235],s[18:19],0,v[232:233]
	global_load_ushort v203, v[234:235], off
	v_lshl_add_u64 v[12:13], s[62:63], 0, v[66:67]
	s_waitcnt vmcnt(44)
	v_lshlrev_b32_e32 v0, 16, v213
	v_mov_b32_e32 v231, v1
	v_add_u32_e32 v230,v82,v6
	v_lshlrev_b64 v[232:233],1,v[230:231]
	v_lshl_add_u64 v[234:235],s[62:63],0,v[232:233]
	global_load_ushort v213, v[234:235], off
	v_fmac_f32_e32 v14, v41, v0
	v_cvt_pk_bf16_f32 v0, v14, s0
	global_store_short v[8:9], v0, off
	v_lshlrev_b32_e32 v12, 16, v211
	v_mov_b32_e32 v231, v1
	v_add_u32_e32 v230,v83,v6
	v_lshlrev_b64 v[232:233],1,v[230:231]
	v_lshl_add_u64 v[234:235],s[62:63],0,v[232:233]
	global_load_ushort v211, v[234:235], off
	v_lshl_add_u64 v[8:9], s[62:63], 0, v[68:69]
	s_waitcnt vmcnt(45)
	v_lshlrev_b32_e32 v0, 16, v226
	v_mov_b32_e32 v231, v1
	v_add_u32_e32 v230,v86,v6
	v_lshlrev_b64 v[232:233],1,v[230:231]
	v_lshl_add_u64 v[234:235],s[62:63],0,v[232:233]
	global_load_ushort v226, v[234:235], off
	v_fmac_f32_e32 v12, v42, v0
	v_cvt_pk_bf16_f32 v0, v12, s0
	global_store_short v[32:33], v0, off
	v_lshlrev_b32_e32 v12, 16, v219
	v_mov_b32_e32 v231, v1
	v_add_u32_e32 v230,v87,v6
	v_lshlrev_b64 v[232:233],1,v[230:231]
	v_lshl_add_u64 v[234:235],s[62:63],0,v[232:233]
	global_load_ushort v219, v[234:235], off
	v_lshl_add_u64 v[8:9], s[62:63], 0, v[70:71]
	s_waitcnt vmcnt(47)
	v_lshlrev_b32_e32 v0, 16, v221
	v_mov_b32_e32 v231, v1
	v_add_u32_e32 v230,v88,v6
	v_lshlrev_b64 v[232:233],1,v[230:231]
	v_lshl_add_u64 v[234:235],s[62:63],0,v[232:233]
	global_load_ushort v221, v[234:235], off
	v_fmac_f32_e32 v12, v43, v0
	v_cvt_pk_bf16_f32 v0, v12, s0
	global_store_short v[34:35], v0, off
	v_lshlrev_b32_e32 v12, 16, v194
	v_mov_b32_e32 v231, v1
	v_add_u32_e32 v230,v89,v6
	v_lshlrev_b64 v[232:233],1,v[230:231]
	v_lshl_add_u64 v[234:235],s[62:63],0,v[232:233]
	global_load_ushort v194, v[234:235], off
	v_lshl_add_u64 v[8:9], s[62:63], 0, v[48:49]
	s_waitcnt vmcnt(48)
	v_lshlrev_b32_e32 v0, 16, v229
	v_mov_b32_e32 v231, v1
	v_add_u32_e32 v230,v95,v6
	v_lshlrev_b64 v[232:233],1,v[230:231]
	v_lshl_add_u64 v[234:235],s[62:63],0,v[232:233]
	global_load_ushort v229, v[234:235], off
	v_fmac_f32_e32 v12, v44, v0
	v_cvt_pk_bf16_f32 v0, v12, s0
	global_store_short v[72:73], v0, off
	v_lshlrev_b32_e32 v12, 16, v224
	v_mov_b32_e32 v231, v1
	v_add_u32_e32 v230,v96,v6
	v_lshlrev_b64 v[232:233],1,v[230:231]
	v_lshl_add_u64 v[234:235],s[62:63],0,v[232:233]
	global_load_ushort v224, v[234:235], off
	v_lshl_add_u64 v[8:9], s[62:63], 0, v[50:51]
	s_waitcnt vmcnt(50)
	v_lshlrev_b32_e32 v0, 16, v214
	v_mov_b32_e32 v231, v1
	v_add_u32_e32 v230,v56,v6
	v_lshlrev_b64 v[232:233],1,v[230:231]
	v_lshl_add_u64 v[234:235],s[62:63],0,v[232:233]
	global_load_ushort v214, v[234:235], off
	v_fmac_f32_e32 v12, v45, v0
	v_cvt_pk_bf16_f32 v0, v12, s0
	global_store_short v[10:11], v0, off
	v_lshlrev_b32_e32 v8, 16, v196
	s_waitcnt vmcnt(50)
	v_lshlrev_b32_e32 v0, 16, v210
	v_fmac_f32_e32 v8, v46, v0
	v_cvt_pk_bf16_f32 v0, v8, s0
	global_store_short v[74:75], v0, off
	v_add_u32_e32 v0, v7, v6
	v_lshlrev_b64 v[4:5], 1, v[0:1]
	v_add_u32_e32 v0, v76, v6
	v_lshlrev_b64 v[10:11], 1, v[0:1]
	v_add_u32_e32 v0, v77, v6
	v_lshlrev_b64 v[12:13], 1, v[0:1]
	v_add_u32_e32 v0, v78, v6
	v_lshlrev_b64 v[14:15], 1, v[0:1]
	v_add_u32_e32 v0, v79, v6
	v_lshlrev_b64 v[32:33], 1, v[0:1]
	v_add_u32_e32 v0, v80, v6
	v_lshlrev_b64 v[34:35], 1, v[0:1]
	v_add_u32_e32 v0, v81, v6
	v_lshlrev_b64 v[36:37], 1, v[0:1]
	v_add_u32_e32 v0, v82, v6
	v_lshlrev_b64 v[38:39], 1, v[0:1]
	v_add_u32_e32 v0, v83, v6
	v_lshlrev_b64 v[40:41], 1, v[0:1]
	v_add_u32_e32 v0, v86, v6
	v_lshlrev_b64 v[42:43], 1, v[0:1]
	v_add_u32_e32 v0, v87, v6
	v_lshlrev_b64 v[44:45], 1, v[0:1]
	v_add_u32_e32 v0, v88, v6
	v_lshlrev_b64 v[48:49], 1, v[0:1]
	v_add_u32_e32 v0, v89, v6
	v_lshlrev_b64 v[50:51], 1, v[0:1]
	v_add_u32_e32 v0, v95, v6
	v_lshlrev_b64 v[52:53], 1, v[0:1]
	v_add_u32_e32 v0, v96, v6
	v_lshlrev_b64 v[54:55], 1, v[0:1]
	v_add_u32_e32 v0, v56, v6
	v_lshlrev_b64 v[6:7], 1, v[0:1]
	v_lshlrev_b32_e32 v0, 16, v228
	v_lshl_add_u64 v[8:9], s[18:19], 0, v[4:5]
	v_lshl_add_u64 v[56:57], s[18:19], 0, v[6:7]
	v_lshl_add_u64 v[4:5], s[62:63], 0, v[4:5]
	v_lshl_add_u64 v[58:59], s[18:19], 0, v[40:41]
	s_waitcnt vmcnt(50)
	v_lshlrev_b32_e32 v46, 16, v198
	v_fmac_f32_e32 v0, v47, v46
	v_cvt_pk_bf16_f32 v0, v0, s0
	global_store_short v[2:3], v0, off
	s_nop 0
	v_lshl_add_u64 v[2:3], s[18:19], 0, v[10:11]
	v_lshl_add_u64 v[4:5], s[62:63], 0, v[10:11]
	v_lshl_add_u64 v[10:11], s[18:19], 0, v[12:13]
	v_lshl_add_u64 v[46:47], s[18:19], 0, v[32:33]
	s_waitcnt vmcnt(48)
	v_lshlrev_b32_e32 v0, 16, v193
	s_waitcnt vmcnt(46)
	v_lshlrev_b32_e32 v60, 16, v192
	v_fmac_f32_e32 v0, v16, v60
	v_cvt_pk_bf16_f32 v0, v0, s0
	global_store_short v[8:9], v0, off
	s_waitcnt vmcnt(46)
	v_lshlrev_b32_e32 v16, 16, v206
	v_lshl_add_u64 v[8:9], s[18:19], 0, v[14:15]
	v_lshl_add_u64 v[4:5], s[62:63], 0, v[12:13]
	v_lshl_add_u64 v[12:13], s[18:19], 0, v[36:37]
	v_lshl_add_u64 v[60:61], s[18:19], 0, v[50:51]
	s_waitcnt vmcnt(40)
	v_lshlrev_b32_e32 v0, 16, v202
	v_fmac_f32_e32 v16, v17, v0
	v_cvt_pk_bf16_f32 v0, v16, s0
	global_store_short v[2:3], v0, off
	v_lshlrev_b32_e32 v16, 16, v207
	v_lshl_add_u64 v[4:5], s[18:19], 0, v[34:35]
	v_lshl_add_u64 v[2:3], s[62:63], 0, v[14:15]
	v_lshl_add_u64 v[14:15], s[18:19], 0, v[44:45]
	s_waitcnt vmcnt(35)
	v_lshlrev_b32_e32 v0, 16, v217
	v_fmac_f32_e32 v16, v18, v0
	v_cvt_pk_bf16_f32 v0, v16, s0
	global_store_short v[10:11], v0, off
	v_lshlrev_b32_e32 v18, 16, v199
	v_lshl_add_u64 v[10:11], s[18:19], 0, v[38:39]
	v_lshl_add_u64 v[2:3], s[62:63], 0, v[32:33]
	v_lshl_add_u64 v[16:17], s[18:19], 0, v[54:55]
	s_waitcnt vmcnt(31)
	v_lshlrev_b32_e32 v0, 16, v204
	v_fmac_f32_e32 v18, v19, v0
	v_cvt_pk_bf16_f32 v0, v18, s0
	global_store_short v[8:9], v0, off
	v_lshlrev_b32_e32 v18, 16, v218
	v_lshl_add_u64 v[2:3], s[62:63], 0, v[34:35]
	v_lshl_add_u64 v[8:9], s[18:19], 0, v[42:43]
	s_waitcnt vmcnt(28)
	v_lshlrev_b32_e32 v0, 16, v220
	v_fmac_f32_e32 v18, v20, v0
	v_cvt_pk_bf16_f32 v0, v18, s0
	global_store_short v[46:47], v0, off
	v_lshlrev_b32_e32 v20, 16, v205
	v_lshl_add_u64 v[2:3], s[62:63], 0, v[36:37]
	v_lshl_add_u64 v[18:19], s[18:19], 0, v[48:49]
	s_waitcnt vmcnt(26)
	v_lshlrev_b32_e32 v0, 16, v227
	v_fmac_f32_e32 v20, v21, v0
	v_cvt_pk_bf16_f32 v0, v20, s0
	global_store_short v[4:5], v0, off
	v_lshl_add_u64 v[4:5], s[18:19], 0, v[52:53]
	v_lshlrev_b32_e32 v20, 16, v222
	v_lshl_add_u64 v[2:3], s[62:63], 0, v[38:39]
	s_waitcnt vmcnt(24)
	v_lshlrev_b32_e32 v0, 16, v195
	v_fmac_f32_e32 v20, v22, v0
	v_cvt_pk_bf16_f32 v0, v20, s0
	global_store_short v[12:13], v0, off
	v_lshlrev_b32_e32 v12, 16, v212
	v_lshl_add_u64 v[2:3], s[62:63], 0, v[40:41]
	s_waitcnt vmcnt(22)
	v_lshlrev_b32_e32 v0, 16, v213
	v_fmac_f32_e32 v12, v23, v0
	v_cvt_pk_bf16_f32 v0, v12, s0
	global_store_short v[10:11], v0, off
	v_lshlrev_b32_e32 v10, 16, v197
	v_lshl_add_u64 v[2:3], s[62:63], 0, v[42:43]
	s_waitcnt vmcnt(21)
	v_lshlrev_b32_e32 v0, 16, v211
	v_fmac_f32_e32 v10, v24, v0
	v_cvt_pk_bf16_f32 v0, v10, s0
	global_store_short v[58:59], v0, off
	v_lshlrev_b32_e32 v10, 16, v215
	v_lshl_add_u64 v[2:3], s[62:63], 0, v[44:45]
	s_waitcnt vmcnt(21)
	v_lshlrev_b32_e32 v0, 16, v226
	v_fmac_f32_e32 v10, v25, v0
	v_cvt_pk_bf16_f32 v0, v10, s0
	global_store_short v[8:9], v0, off
	v_lshlrev_b32_e32 v8, 16, v225
	v_lshl_add_u64 v[2:3], s[62:63], 0, v[48:49]
	s_waitcnt vmcnt(20)
	v_lshlrev_b32_e32 v0, 16, v219
	v_fmac_f32_e32 v8, v26, v0
	v_cvt_pk_bf16_f32 v0, v8, s0
	global_store_short v[14:15], v0, off
	v_lshlrev_b32_e32 v8, 16, v201
	v_lshl_add_u64 v[2:3], s[62:63], 0, v[50:51]
	s_waitcnt vmcnt(20)
	v_lshlrev_b32_e32 v0, 16, v221
	v_fmac_f32_e32 v8, v27, v0
	v_cvt_pk_bf16_f32 v0, v8, s0
	global_store_short v[18:19], v0, off
	v_lshlrev_b32_e32 v8, 16, v223
	v_lshl_add_u64 v[2:3], s[62:63], 0, v[52:53]
	s_waitcnt vmcnt(19)
	v_lshlrev_b32_e32 v0, 16, v194
	v_fmac_f32_e32 v8, v28, v0
	v_cvt_pk_bf16_f32 v0, v8, s0
	global_store_short v[60:61], v0, off
	v_lshlrev_b32_e32 v8, 16, v203
	v_lshl_add_u64 v[2:3], s[62:63], 0, v[54:55]
	s_waitcnt vmcnt(19)
	v_lshlrev_b32_e32 v0, 16, v229
	v_fmac_f32_e32 v8, v29, v0
	v_cvt_pk_bf16_f32 v0, v8, s0
	global_store_short v[4:5], v0, off
	v_lshlrev_b32_e32 v2, 16, v216
	s_waitcnt vmcnt(18)
	v_lshlrev_b32_e32 v0, 16, v224
	v_fmac_f32_e32 v2, v30, v0
	v_cvt_pk_bf16_f32 v0, v2, s0
	global_store_short v[16:17], v0, off
	v_lshl_add_u64 v[2:3], s[62:63], 0, v[6:7]
	v_lshlrev_b32_e32 v2, 16, v209
	s_waitcnt vmcnt(18)
	v_lshlrev_b32_e32 v0, 16, v214
	v_fmac_f32_e32 v2, v31, v0
	v_cvt_pk_bf16_f32 v0, v2, s0
	global_store_short v[56:57], v0, off
.Ltep_e4_e:
	s_add_i32 s31, s31, s92
	s_cmpk_gt_i32 s31, 0x103
	s_cbranch_scc1 .LBB0_3413

.LBB0_3396:
	s_lshl_b64 s[14:15], s[0:1], 9
	s_lshl_b64 s[4:5], s[6:7], 9
	s_cmpk_lt_i32 s0, 0x4000
	s_cbranch_scc1 .Ltep_e3_f
	v_readfirstlane_b32 s64, v208
	s_bitcmp1_b32 s64, 8
	s_cbranch_scc0 .Ltep_e3_f
	s_waitcnt vmcnt(0)
	s_branch .Ltep_e3_e
.Ltep_e3_f:
	s_waitcnt vmcnt(0)
	v_mov_b32_e32 v0, v208
	v_mov_b32_e32 v2, v1
	v_lshrrev_b32_e32 v3, 1, v0
	v_and_b32_e32 v3, 0x3fff80, v3
	v_lshrrev_b32_e32 v4, 3, v0
	v_add_u32_e32 v3, s0, v3
	v_and_b32_e32 v0, 0xdf, v0
	v_and_or_b32 v3, v4, 4, v3
	v_or_b32_e32 v0, s6, v0
	v_add_u32_e32 v2, v0, v2
	v_lshlrev_b32_e32 v3, 10, v3
	v_add_u32_e32 v0, v3, v2
	v_or_b32_e32 v164, 0x400, v3
	v_lshl_add_u64 v[6:7], v[0:1], 1, s[18:19]
	v_add_u32_e32 v0, v164, v2
	v_or_b32_e32 v167, 0x800, v3
	v_lshl_add_u64 v[4:5], v[0:1], 1, s[18:19]
	v_add_u32_e32 v0, v167, v2
	v_or_b32_e32 v169, 0xc00, v3
	global_load_ushort v194, v[6:7], off
	global_load_ushort v195, v[4:5], off
	v_lshl_add_u64 v[230:231],v[0:1],1,s[18:19]
	global_load_ushort v196, v[230:231], off
	v_mov_b32_e32 v231, v1
	v_add_u32_e32 v230,v169,v2
	v_lshl_add_u64 v[232:233],v[230:231],1,s[18:19]
	global_load_ushort v197, v[232:233], off
	v_mov_b32_e32 v233, v1
	v_or_b32_e32 v231,0x2000,v3
	v_add_u32_e32 v232,v231,v2
	v_lshl_add_u64 v[234:235],v[232:233],1,s[18:19]
	global_load_ushort v198, v[234:235], off
	v_mov_b32_e32 v233, v1
	v_or_b32_e32 v231,0x2400,v3
	v_add_u32_e32 v232,v231,v2
	v_lshl_add_u64 v[234:235],v[232:233],1,s[18:19]
	global_load_ushort v199, v[234:235], off
	v_mov_b32_e32 v233, v1
	v_or_b32_e32 v231,0x2800,v3
	v_add_u32_e32 v232,v231,v2
	v_lshl_add_u64 v[234:235],v[232:233],1,s[18:19]
	global_load_ushort v201, v[234:235], off
	v_mov_b32_e32 v233, v1
	v_or_b32_e32 v231,0x2c00,v3
	v_add_u32_e32 v232,v231,v2
	v_lshl_add_u64 v[234:235],v[232:233],1,s[18:19]
	global_load_ushort v202, v[234:235], off
	v_mov_b32_e32 v233, v1
	v_or_b32_e32 v231,0x4000,v3
	v_add_u32_e32 v232,v231,v2
	v_lshl_add_u64 v[234:235],v[232:233],1,s[18:19]
	global_load_ushort v203, v[234:235], off
	v_mov_b32_e32 v233, v1
	v_or_b32_e32 v231,0x4400,v3
	v_add_u32_e32 v232,v231,v2
	v_lshl_add_u64 v[234:235],v[232:233],1,s[18:19]
	global_load_ushort v204, v[234:235], off
	v_mov_b32_e32 v233, v1
	v_or_b32_e32 v231,0x4800,v3
	v_add_u32_e32 v232,v231,v2
	v_lshl_add_u64 v[234:235],v[232:233],1,s[18:19]
	global_load_ushort v205, v[234:235], off
	v_mov_b32_e32 v233, v1
	v_or_b32_e32 v231,0x4c00,v3
	v_add_u32_e32 v232,v231,v2
	v_lshl_add_u64 v[234:235],v[232:233],1,s[18:19]
	global_load_ushort v206, v[234:235], off
	v_mov_b32_e32 v233, v1
	v_or_b32_e32 v231,0x6000,v3
	v_add_u32_e32 v232,v231,v2
	v_lshl_add_u64 v[234:235],v[232:233],1,s[18:19]
	global_load_ushort v207, v[234:235], off
	v_mov_b32_e32 v233, v1
	v_or_b32_e32 v231,0x6400,v3
	v_add_u32_e32 v232,v231,v2
	v_lshl_add_u64 v[234:235],v[232:233],1,s[18:19]
	global_load_ushort v209, v[234:235], off
	v_mov_b32_e32 v233, v1
	v_or_b32_e32 v231,0x6800,v3
	v_add_u32_e32 v232,v231,v2
	v_lshl_add_u64 v[234:235],v[232:233],1,s[18:19]
	global_load_ushort v210, v[234:235], off
	v_mov_b32_e32 v233, v1
	v_or_b32_e32 v231,0x6c00,v3
	v_add_u32_e32 v232,v231,v2
	v_lshl_add_u64 v[234:235],v[232:233],1,s[18:19]
	global_load_ushort v211, v[234:235], off
	v_mov_b32_e32 v233, v1
	v_add_u32_e32 v230,32,v2
	v_add_u32_e32 v232,v3,v230
	v_lshl_add_u64 v[234:235],v[232:233],1,s[18:19]
	global_load_ushort v212, v[234:235], off
	v_mov_b32_e32 v233, v1
	v_add_u32_e32 v230,32,v2
	v_add_u32_e32 v232,v167,v230
	v_lshl_add_u64 v[234:235],v[232:233],1,s[18:19]
	global_load_ushort v213, v[234:235], off
	v_mov_b32_e32 v233, v1
	v_add_u32_e32 v230,32,v2
	v_add_u32_e32 v232,v169,v230
	v_lshl_add_u64 v[234:235],v[232:233],1,s[18:19]
	global_load_ushort v214, v[234:235], off
	v_mov_b32_e32 v235, v1
	v_or_b32_e32 v231,0x2000,v3
	v_add_u32_e32 v232,32,v2
	v_add_u32_e32 v234,v231,v232
	v_lshl_add_u64 v[236:237],v[234:235],1,s[18:19]
	global_load_ushort v215, v[236:237], off
	v_mov_b32_e32 v235, v1
	v_or_b32_e32 v231,0x2400,v3
	v_add_u32_e32 v232,32,v2
	v_add_u32_e32 v234,v231,v232
	v_lshl_add_u64 v[236:237],v[234:235],1,s[18:19]
	global_load_ushort v216, v[236:237], off
	v_mov_b32_e32 v235, v1
	v_or_b32_e32 v231,0x2800,v3
	v_add_u32_e32 v232,32,v2
	v_add_u32_e32 v234,v231,v232
	v_lshl_add_u64 v[236:237],v[234:235],1,s[18:19]
	global_load_ushort v217, v[236:237], off
	v_mov_b32_e32 v235, v1
	v_or_b32_e32 v231,0x2c00,v3
	v_add_u32_e32 v232,32,v2
	v_add_u32_e32 v234,v231,v232
	v_lshl_add_u64 v[236:237],v[234:235],1,s[18:19]
	global_load_ushort v218, v[236:237], off
	v_mov_b32_e32 v233, v1
	v_add_u32_e32 v230,32,v2
	v_add_u32_e32 v232,v164,v230
	v_lshl_add_u64 v[234:235],v[232:233],1,s[18:19]
	global_load_ushort v219, v[234:235], off
	v_mov_b32_e32 v235, v1
	v_or_b32_e32 v231,0x4000,v3
	v_add_u32_e32 v232,32,v2
	v_add_u32_e32 v234,v231,v232
	v_lshl_add_u64 v[236:237],v[234:235],1,s[18:19]
	global_load_ushort v220, v[236:237], off
	v_mov_b32_e32 v235, v1
	v_or_b32_e32 v231,0x4400,v3
	v_add_u32_e32 v232,32,v2
	v_add_u32_e32 v234,v231,v232
	v_lshl_add_u64 v[236:237],v[234:235],1,s[18:19]
	global_load_ushort v221, v[236:237], off
	v_mov_b32_e32 v235, v1
	v_or_b32_e32 v231,0x4800,v3
	v_add_u32_e32 v232,32,v2
	v_add_u32_e32 v234,v231,v232
	v_lshl_add_u64 v[236:237],v[234:235],1,s[18:19]
	global_load_ushort v222, v[236:237], off
	v_mov_b32_e32 v235, v1
	v_or_b32_e32 v231,0x4c00,v3
	v_add_u32_e32 v232,32,v2
	v_add_u32_e32 v234,v231,v232
	v_lshl_add_u64 v[236:237],v[234:235],1,s[18:19]
	global_load_ushort v223, v[236:237], off
	v_mov_b32_e32 v235, v1
	v_or_b32_e32 v231,0x6000,v3
	v_add_u32_e32 v232,32,v2
	v_add_u32_e32 v234,v231,v232
	v_lshl_add_u64 v[236:237],v[234:235],1,s[18:19]
	global_load_ushort v224, v[236:237], off
	v_mov_b32_e32 v235, v1
	v_or_b32_e32 v231,0x6400,v3
	v_add_u32_e32 v232,32,v2
	v_add_u32_e32 v234,v231,v232
	v_lshl_add_u64 v[236:237],v[234:235],1,s[18:19]
	global_load_ushort v225, v[236:237], off
	v_mov_b32_e32 v235, v1
	v_or_b32_e32 v231,0x6800,v3
	v_add_u32_e32 v232,32,v2
	v_add_u32_e32 v234,v231,v232
	v_lshl_add_u64 v[236:237],v[234:235],1,s[18:19]
	global_load_ushort v226, v[236:237], off
	v_mov_b32_e32 v235, v1
	v_or_b32_e32 v231,0x6c00,v3
	v_add_u32_e32 v232,32,v2
	v_add_u32_e32 v234,v231,v232
	v_lshl_add_u64 v[236:237],v[234:235],1,s[18:19]
	global_load_ushort v227, v[236:237], off
	v_mov_b32_e32 v233, v1
	v_or_b32_e32 v231,0x8000,v3
	v_add_u32_e32 v232,v231,v2
	v_lshl_add_u64 v[234:235],v[232:233],1,s[18:19]
	global_load_ushort v228, v[234:235], off
	v_mov_b32_e32 v233, v1
	v_or_b32_e32 v230,0x8400,v3
	v_add_u32_e32 v232,v230,v2
	v_lshl_add_u64 v[234:235],v[232:233],1,s[18:19]
	global_load_ushort v229, v[234:235], off
	v_lshl_add_u64 v[8:9], v[0:1], 1, s[18:19]
	v_add_u32_e32 v0, v169, v2
	v_or_b32_e32 v171, 0x2000, v3
	v_lshl_add_u64 v[10:11], v[0:1], 1, s[18:19]
	v_add_u32_e32 v0, v171, v2
	v_or_b32_e32 v173, 0x2400, v3
	v_lshl_add_u64 v[12:13], v[0:1], 1, s[18:19]
	v_add_u32_e32 v0, v173, v2
	v_lshl_add_u64 v[14:15], v[0:1], 1, s[18:19]
	v_or_b32_e32 v175, 0x2800, v3
	v_add_u32_e32 v0, v175, v2
	v_lshl_add_u64 v[144:145], v[0:1], 1, s[18:19]
	v_or_b32_e32 v177, 0x2c00, v3
	v_add_u32_e32 v0, v177, v2
	v_lshl_add_u64 v[146:147], v[0:1], 1, s[18:19]
	v_or_b32_e32 v179, 0x4000, v3
	v_add_u32_e32 v0, v179, v2
	v_lshl_add_u64 v[148:149], v[0:1], 1, s[18:19]
	v_or_b32_e32 v181, 0x4400, v3
	v_add_u32_e32 v0, v181, v2
	v_lshl_add_u64 v[150:151], v[0:1], 1, s[18:19]
	v_or_b32_e32 v183, 0x4800, v3
	v_add_u32_e32 v0, v183, v2
	v_lshl_add_u64 v[152:153], v[0:1], 1, s[18:19]
	v_or_b32_e32 v185, 0x4c00, v3
	v_add_u32_e32 v0, v185, v2
	v_lshl_add_u64 v[154:155], v[0:1], 1, s[18:19]
	v_or_b32_e32 v187, 0x6000, v3
	v_add_u32_e32 v0, v187, v2
	v_lshl_add_u64 v[156:157], v[0:1], 1, s[18:19]
	v_or_b32_e32 v189, 0x6400, v3
	v_add_u32_e32 v0, v189, v2
	v_lshl_add_u64 v[158:159], v[0:1], 1, s[18:19]
	v_or_b32_e32 v191, 0x6800, v3
	v_add_u32_e32 v0, v191, v2
	v_or_b32_e32 v193, 0x6c00, v3
	v_lshl_add_u64 v[160:161], v[0:1], 1, s[18:19]
	v_add_u32_e32 v0, v193, v2
	v_lshl_add_u64 v[162:163], v[0:1], 1, s[18:19]
	s_waitcnt vmcnt(33)
	v_lshlrev_b32_e32 v165, 16, v194
	v_mov_b32_e32 v233, v1
	v_or_b32_e32 v231,0x8800,v3
	v_add_u32_e32 v232,v231,v2
	v_lshl_add_u64 v[234:235],v[232:233],1,s[18:19]
	global_load_ushort v194, v[234:235], off
	v_mul_f32_e32 v128, v128, v165
	s_waitcnt vmcnt(33)
	v_lshlrev_b32_e32 v165, 16, v195
	v_mov_b32_e32 v233, v1
	v_or_b32_e32 v231,0x8c00,v3
	v_add_u32_e32 v232,v231,v2
	v_lshl_add_u64 v[234:235],v[232:233],1,s[18:19]
	global_load_ushort v195, v[234:235], off
	v_mul_f32_e32 v129, v129, v165
	v_cvt_pk_bf16_f32 v129, v129, s0
	s_waitcnt vmcnt(33)
	v_lshlrev_b32_e32 v165, 16, v196
	v_mov_b32_e32 v233, v1
	v_or_b32_e32 v231,0xa000,v3
	v_add_u32_e32 v232,v231,v2
	v_lshl_add_u64 v[234:235],v[232:233],1,s[18:19]
	global_load_ushort v196, v[234:235], off
	v_mul_f32_e32 v130, v130, v165
	global_store_short v[4:5], v129, off
	v_cvt_pk_bf16_f32 v4, v130, s0
	s_waitcnt vmcnt(34)
	v_lshlrev_b32_e32 v165, 16, v197
	v_mov_b32_e32 v233, v1
	v_or_b32_e32 v231,0xa400,v3
	v_add_u32_e32 v232,v231,v2
	v_lshl_add_u64 v[234:235],v[232:233],1,s[18:19]
	global_load_ushort v197, v[234:235], off
	v_mul_f32_e32 v5, v131, v165
	global_store_short v[8:9], v4, off
	s_waitcnt vmcnt(35)
	v_lshlrev_b32_e32 v129, 16, v198
	v_mov_b32_e32 v233, v1
	v_or_b32_e32 v231,0xa800,v3
	v_add_u32_e32 v232,v231,v2
	v_lshl_add_u64 v[234:235],v[232:233],1,s[18:19]
	global_load_ushort v198, v[234:235], off
	v_cvt_pk_bf16_f32 v4, v5, s0
	v_mul_f32_e32 v5, v132, v129
	s_waitcnt vmcnt(35)
	v_lshlrev_b32_e32 v8, 16, v199
	v_mov_b32_e32 v233, v1
	v_or_b32_e32 v231,0xac00,v3
	v_add_u32_e32 v232,v231,v2
	v_lshl_add_u64 v[234:235],v[232:233],1,s[18:19]
	global_load_ushort v199, v[234:235], off
	global_store_short v[10:11], v4, off
	v_cvt_pk_bf16_f32 v4, v5, s0
	v_mul_f32_e32 v5, v133, v8
	global_store_short v[12:13], v4, off
	v_cvt_pk_bf16_f32 v4, v5, s0
	global_store_short v[14:15], v4, off
	s_waitcnt vmcnt(38)
	v_lshlrev_b32_e32 v4, 16, v201
	v_mov_b32_e32 v233, v1
	v_or_b32_e32 v231,0xc000,v3
	v_add_u32_e32 v232,v231,v2
	v_lshl_add_u64 v[234:235],v[232:233],1,s[18:19]
	global_load_ushort v201, v[234:235], off
	v_mul_f32_e32 v4, v134, v4
	v_cvt_pk_bf16_f32 v4, v4, s0
	global_store_short v[144:145], v4, off
	s_waitcnt vmcnt(39)
	v_lshlrev_b32_e32 v4, 16, v202
	v_mov_b32_e32 v233, v1
	v_or_b32_e32 v231,0xc400,v3
	v_add_u32_e32 v232,v231,v2
	v_lshl_add_u64 v[234:235],v[232:233],1,s[18:19]
	global_load_ushort v202, v[234:235], off
	v_mul_f32_e32 v4, v135, v4
	v_cvt_pk_bf16_f32 v4, v4, s0
	global_store_short v[146:147], v4, off
	s_waitcnt vmcnt(40)
	v_lshlrev_b32_e32 v4, 16, v203
	v_mov_b32_e32 v233, v1
	v_or_b32_e32 v231,0xc800,v3
	v_add_u32_e32 v232,v231,v2
	v_lshl_add_u64 v[234:235],v[232:233],1,s[18:19]
	global_load_ushort v203, v[234:235], off
	v_mul_f32_e32 v4, v136, v4
	v_cvt_pk_bf16_f32 v4, v4, s0
	global_store_short v[148:149], v4, off
	s_waitcnt vmcnt(41)
	v_lshlrev_b32_e32 v4, 16, v204
	v_mov_b32_e32 v233, v1
	v_or_b32_e32 v231,0xcc00,v3
	v_add_u32_e32 v232,v231,v2
	v_lshl_add_u64 v[234:235],v[232:233],1,s[18:19]
	global_load_ushort v204, v[234:235], off
	v_mul_f32_e32 v4, v137, v4
	v_cvt_pk_bf16_f32 v4, v4, s0
	global_store_short v[150:151], v4, off
	s_waitcnt vmcnt(42)
	v_lshlrev_b32_e32 v4, 16, v205
	v_mov_b32_e32 v233, v1
	v_or_b32_e32 v231,0xe000,v3
	v_add_u32_e32 v232,v231,v2
	v_lshl_add_u64 v[234:235],v[232:233],1,s[18:19]
	global_load_ushort v205, v[234:235], off
	v_mul_f32_e32 v4, v138, v4
	v_cvt_pk_bf16_f32 v4, v4, s0
	global_store_short v[152:153], v4, off
	s_waitcnt vmcnt(43)
	v_lshlrev_b32_e32 v4, 16, v206
	v_mov_b32_e32 v233, v1
	v_or_b32_e32 v231,0xe400,v3
	v_add_u32_e32 v232,v231,v2
	v_lshl_add_u64 v[234:235],v[232:233],1,s[18:19]
	global_load_ushort v206, v[234:235], off
	v_mul_f32_e32 v4, v139, v4
	v_cvt_pk_bf16_f32 v4, v4, s0
	global_store_short v[154:155], v4, off
	s_waitcnt vmcnt(44)
	v_lshlrev_b32_e32 v4, 16, v207
	v_mov_b32_e32 v233, v1
	v_or_b32_e32 v231,0xe800,v3
	v_add_u32_e32 v232,v231,v2
	v_lshl_add_u64 v[234:235],v[232:233],1,s[18:19]
	global_load_ushort v207, v[234:235], off
	v_mul_f32_e32 v4, v140, v4
	v_cvt_pk_bf16_f32 v4, v4, s0
	global_store_short v[156:157], v4, off
	s_waitcnt vmcnt(45)
	v_lshlrev_b32_e32 v4, 16, v209
	v_mov_b32_e32 v233, v1
	v_or_b32_e32 v231,0xec00,v3
	v_add_u32_e32 v232,v231,v2
	v_lshl_add_u64 v[234:235],v[232:233],1,s[18:19]
	global_load_ushort v209, v[234:235], off
	v_mul_f32_e32 v4, v141, v4
	v_cvt_pk_bf16_f32 v4, v4, s0
	global_store_short v[158:159], v4, off
	s_waitcnt vmcnt(46)
	v_lshlrev_b32_e32 v4, 16, v210
	v_mov_b32_e32 v233, v1
	v_add_u32_e32 v230,32,v2
	v_or_b32_e32 v231,0x8000,v3
	v_add_u32_e32 v232,v231,v230
	v_lshl_add_u64 v[234:235],v[232:233],1,s[18:19]
	global_load_ushort v210, v[234:235], off
	v_mul_f32_e32 v4, v142, v4
	s_waitcnt vmcnt(46)
	v_lshlrev_b32_e32 v0, 16, v211
	v_mov_b32_e32 v235, v1
	v_add_u32_e32 v230,32,v2
	v_or_b32_e32 v232,0x8400,v3
	v_add_u32_e32 v234,v232,v230
	v_lshl_add_u64 v[236:237],v[234:235],1,s[18:19]
	global_load_ushort v211, v[236:237], off
	v_cvt_pk_bf16_f32 v4, v4, s0
	v_mul_f32_e32 v0, v143, v0
	global_store_short v[160:161], v4, off
	v_cvt_pk_bf16_f32 v0, v0, s0
	v_add_u32_e32 v4, 32, v2
	global_store_short v[162:163], v0, off
	v_add_u32_e32 v0, v3, v4
	v_cvt_pk_bf16_f32 v128, v128, s0
	v_lshl_add_u64 v[8:9], v[0:1], 1, s[18:19]
	v_add_u32_e32 v0, v164, v4
	global_store_short v[6:7], v128, off
	v_lshl_add_u64 v[6:7], v[0:1], 1, s[18:19]
	v_add_u32_e32 v0, v167, v4
	v_lshl_add_u64 v[10:11], v[0:1], 1, s[18:19]
	v_add_u32_e32 v0, v169, v4
	v_lshl_add_u64 v[12:13], v[0:1], 1, s[18:19]
	v_add_u32_e32 v0, v171, v4
	v_lshl_add_u64 v[14:15], v[0:1], 1, s[18:19]
	v_add_u32_e32 v0, v173, v4
	v_lshl_add_u64 v[128:129], v[0:1], 1, s[18:19]
	v_add_u32_e32 v0, v175, v4
	v_lshl_add_u64 v[130:131], v[0:1], 1, s[18:19]
	v_add_u32_e32 v0, v177, v4
	v_lshl_add_u64 v[132:133], v[0:1], 1, s[18:19]
	v_add_u32_e32 v0, v179, v4
	v_lshl_add_u64 v[134:135], v[0:1], 1, s[18:19]
	v_add_u32_e32 v0, v181, v4
	v_lshl_add_u64 v[136:137], v[0:1], 1, s[18:19]
	v_add_u32_e32 v0, v183, v4
	v_lshl_add_u64 v[138:139], v[0:1], 1, s[18:19]
	v_add_u32_e32 v0, v185, v4
	v_lshl_add_u64 v[140:141], v[0:1], 1, s[18:19]
	v_add_u32_e32 v0, v187, v4
	v_lshl_add_u64 v[142:143], v[0:1], 1, s[18:19]
	v_add_u32_e32 v0, v189, v4
	v_lshl_add_u64 v[144:145], v[0:1], 1, s[18:19]
	v_add_u32_e32 v0, v191, v4
	v_lshl_add_u64 v[146:147], v[0:1], 1, s[18:19]
	v_add_u32_e32 v0, v193, v4
	v_lshl_add_u64 v[148:149], v[0:1], 1, s[18:19]
	s_waitcnt vmcnt(49)
	v_lshlrev_b32_e32 v5, 16, v212
	v_mov_b32_e32 v233, v1
	v_or_b32_e32 v231,0x8800,v3
	v_add_u32_e32 v232,v231,v4
	v_lshl_add_u64 v[234:235],v[232:233],1,s[18:19]
	global_load_ushort v212, v[234:235], off
	v_mul_f32_e32 v5, v112, v5
	v_cvt_pk_bf16_f32 v5, v5, s0
	global_store_short v[8:9], v5, off
	s_waitcnt vmcnt(44)
	v_lshlrev_b32_e32 v5, 16, v219
	v_mov_b32_e32 v233, v1
	v_or_b32_e32 v231,0x8c00,v3
	v_add_u32_e32 v232,v231,v4
	v_lshl_add_u64 v[234:235],v[232:233],1,s[18:19]
	global_load_ushort v219, v[234:235], off
	v_mul_f32_e32 v5, v113, v5
	v_cvt_pk_bf16_f32 v5, v5, s0
	global_store_short v[6:7], v5, off
	v_lshlrev_b32_e32 v5, 16, v213
	v_mov_b32_e32 v233, v1
	v_or_b32_e32 v231,0xa000,v3
	v_add_u32_e32 v232,v231,v4
	v_lshl_add_u64 v[234:235],v[232:233],1,s[18:19]
	global_load_ushort v213, v[234:235], off
	v_mul_f32_e32 v5, v114, v5
	v_cvt_pk_bf16_f32 v5, v5, s0
	global_store_short v[10:11], v5, off
	v_lshlrev_b32_e32 v5, 16, v214
	v_mov_b32_e32 v233, v1
	v_or_b32_e32 v231,0xa400,v3
	v_add_u32_e32 v232,v231,v4
	v_lshl_add_u64 v[234:235],v[232:233],1,s[18:19]
	global_load_ushort v214, v[234:235], off
	v_mul_f32_e32 v5, v115, v5
	v_cvt_pk_bf16_f32 v5, v5, s0
	global_store_short v[12:13], v5, off
	v_lshlrev_b32_e32 v5, 16, v215
	v_mov_b32_e32 v233, v1
	v_or_b32_e32 v231,0xa800,v3
	v_add_u32_e32 v232,v231,v4
	v_lshl_add_u64 v[234:235],v[232:233],1,s[18:19]
	global_load_ushort v215, v[234:235], off
	v_mul_f32_e32 v5, v116, v5
	v_cvt_pk_bf16_f32 v5, v5, s0
	global_store_short v[14:15], v5, off
	v_lshlrev_b32_e32 v5, 16, v216
	v_mov_b32_e32 v233, v1
	v_or_b32_e32 v231,0xac00,v3
	v_add_u32_e32 v232,v231,v4
	v_lshl_add_u64 v[234:235],v[232:233],1,s[18:19]
	global_load_ushort v216, v[234:235], off
	v_mul_f32_e32 v5, v117, v5
	v_cvt_pk_bf16_f32 v5, v5, s0
	global_store_short v[128:129], v5, off
	v_lshlrev_b32_e32 v5, 16, v217
	v_mov_b32_e32 v233, v1
	v_or_b32_e32 v231,0xc000,v3
	v_add_u32_e32 v232,v231,v4
	v_lshl_add_u64 v[234:235],v[232:233],1,s[18:19]
	global_load_ushort v217, v[234:235], off
	v_mul_f32_e32 v5, v118, v5
	v_cvt_pk_bf16_f32 v5, v5, s0
	global_store_short v[130:131], v5, off
	v_lshlrev_b32_e32 v5, 16, v218
	v_mov_b32_e32 v233, v1
	v_or_b32_e32 v231,0xc400,v3
	v_add_u32_e32 v232,v231,v4
	v_lshl_add_u64 v[234:235],v[232:233],1,s[18:19]
	global_load_ushort v218, v[234:235], off
	v_mul_f32_e32 v5, v119, v5
	v_cvt_pk_bf16_f32 v5, v5, s0
	global_store_short v[132:133], v5, off
	s_waitcnt vmcnt(57)
	v_lshlrev_b32_e32 v5, 16, v220
	v_mov_b32_e32 v233, v1
	v_or_b32_e32 v231,0xc800,v3
	v_add_u32_e32 v232,v231,v4
	v_lshl_add_u64 v[234:235],v[232:233],1,s[18:19]
	global_load_ushort v220, v[234:235], off
	v_mul_f32_e32 v5, v120, v5
	v_cvt_pk_bf16_f32 v5, v5, s0
	global_store_short v[134:135], v5, off
	s_waitcnt vmcnt(58)
	v_lshlrev_b32_e32 v5, 16, v221
	v_mov_b32_e32 v233, v1
	v_or_b32_e32 v231,0xcc00,v3
	v_add_u32_e32 v232,v231,v4
	v_lshl_add_u64 v[234:235],v[232:233],1,s[18:19]
	global_load_ushort v221, v[234:235], off
	v_mul_f32_e32 v5, v121, v5
	v_cvt_pk_bf16_f32 v5, v5, s0
	global_store_short v[136:137], v5, off
	s_waitcnt vmcnt(59)
	v_lshlrev_b32_e32 v5, 16, v222
	v_mov_b32_e32 v233, v1
	v_or_b32_e32 v231,0xe000,v3
	v_add_u32_e32 v232,v231,v4
	v_lshl_add_u64 v[234:235],v[232:233],1,s[18:19]
	global_load_ushort v222, v[234:235], off
	v_mul_f32_e32 v5, v122, v5
	v_cvt_pk_bf16_f32 v5, v5, s0
	global_store_short v[138:139], v5, off
	s_waitcnt vmcnt(60)
	v_lshlrev_b32_e32 v5, 16, v223
	v_mov_b32_e32 v233, v1
	v_or_b32_e32 v231,0xe400,v3
	v_add_u32_e32 v232,v231,v4
	v_lshl_add_u64 v[234:235],v[232:233],1,s[18:19]
	global_load_ushort v223, v[234:235], off
	v_mul_f32_e32 v5, v123, v5
	v_cvt_pk_bf16_f32 v5, v5, s0
	global_store_short v[140:141], v5, off
	s_waitcnt vmcnt(61)
	v_lshlrev_b32_e32 v5, 16, v224
	v_mov_b32_e32 v233, v1
	v_or_b32_e32 v231,0xe800,v3
	v_add_u32_e32 v232,v231,v4
	v_lshl_add_u64 v[234:235],v[232:233],1,s[18:19]
	global_load_ushort v224, v[234:235], off
	v_mul_f32_e32 v5, v124, v5
	v_cvt_pk_bf16_f32 v5, v5, s0
	s_waitcnt vmcnt(56)
	global_store_short v[142:143], v5, off
	v_lshlrev_b32_e32 v5, 16, v225
	v_mov_b32_e32 v233, v1
	v_or_b32_e32 v231,0xec00,v3
	v_add_u32_e32 v232,v231,v4
	v_lshl_add_u64 v[234:235],v[232:233],1,s[18:19]
	global_load_ushort v225, v[234:235], off
	v_mul_f32_e32 v5, v125, v5
	v_cvt_pk_bf16_f32 v5, v5, s0
	global_store_short v[144:145], v5, off
	v_lshlrev_b32_e32 v5, 16, v226
	v_mov_b32_e32 v233, v1
	v_or_b32_e32 v231,0x10000,v3
	v_add_u32_e32 v232,v231,v2
	v_lshl_add_u64 v[234:235],v[232:233],1,s[18:19]
	global_load_ushort v226, v[234:235], off
	v_lshlrev_b32_e32 v0, 16, v227
	v_mov_b32_e32 v233, v1
	v_or_b32_e32 v230,0x10400,v3
	v_add_u32_e32 v232,v230,v2
	v_lshl_add_u64 v[234:235],v[232:233],1,s[18:19]
	global_load_ushort v227, v[234:235], off
	v_mul_f32_e32 v5, v126, v5
	v_mul_f32_e32 v0, v127, v0
	v_cvt_pk_bf16_f32 v5, v5, s0
	v_cvt_pk_bf16_f32 v0, v0, s0
	global_store_short v[146:147], v5, off
	s_waitcnt vmcnt(56)
	global_store_short v[148:149], v0, off
	v_or_b32_e32 v5, 0x8000, v3
	v_add_u32_e32 v0, v5, v2
	v_or_b32_e32 v134, 0x8400, v3
	v_lshl_add_u64 v[6:7], v[0:1], 1, s[18:19]
	v_add_u32_e32 v0, v134, v2
	v_or_b32_e32 v137, 0x8800, v3
	v_lshl_add_u64 v[8:9], v[0:1], 1, s[18:19]
	v_add_u32_e32 v0, v137, v2
	v_or_b32_e32 v139, 0x8c00, v3
	v_lshl_add_u64 v[10:11], v[0:1], 1, s[18:19]
	v_add_u32_e32 v0, v139, v2
	v_or_b32_e32 v141, 0xa000, v3
	v_lshl_add_u64 v[12:13], v[0:1], 1, s[18:19]
	v_add_u32_e32 v0, v141, v2
	v_or_b32_e32 v143, 0xa400, v3
	v_lshl_add_u64 v[14:15], v[0:1], 1, s[18:19]
	v_add_u32_e32 v0, v143, v2
	v_or_b32_e32 v145, 0xa800, v3
	v_lshl_add_u64 v[112:113], v[0:1], 1, s[18:19]
	v_add_u32_e32 v0, v145, v2
	v_lshl_add_u64 v[114:115], v[0:1], 1, s[18:19]
	v_or_b32_e32 v147, 0xac00, v3
	v_add_u32_e32 v0, v147, v2
	v_lshl_add_u64 v[116:117], v[0:1], 1, s[18:19]
	v_or_b32_e32 v149, 0xc000, v3
	v_add_u32_e32 v0, v149, v2
	v_lshl_add_u64 v[118:119], v[0:1], 1, s[18:19]
	v_or_b32_e32 v151, 0xc400, v3
	v_add_u32_e32 v0, v151, v2
	v_lshl_add_u64 v[120:121], v[0:1], 1, s[18:19]
	v_or_b32_e32 v153, 0xc800, v3
	v_add_u32_e32 v0, v153, v2
	v_lshl_add_u64 v[122:123], v[0:1], 1, s[18:19]
	v_or_b32_e32 v155, 0xcc00, v3
	v_add_u32_e32 v0, v155, v2
	v_lshl_add_u64 v[124:125], v[0:1], 1, s[18:19]
	v_or_b32_e32 v157, 0xe000, v3
	v_add_u32_e32 v0, v157, v2
	v_lshl_add_u64 v[126:127], v[0:1], 1, s[18:19]
	v_or_b32_e32 v159, 0xe400, v3
	v_add_u32_e32 v0, v159, v2
	v_or_b32_e32 v161, 0xe800, v3
	v_lshl_add_u64 v[128:129], v[0:1], 1, s[18:19]
	v_add_u32_e32 v0, v161, v2
	v_or_b32_e32 v163, 0xec00, v3
	v_lshl_add_u64 v[130:131], v[0:1], 1, s[18:19]
	v_add_u32_e32 v0, v163, v2
	v_lshl_add_u64 v[132:133], v[0:1], 1, s[18:19]
	v_lshlrev_b32_e32 v135, 16, v228
	v_mov_b32_e32 v233, v1
	v_or_b32_e32 v231,0x10800,v3
	v_add_u32_e32 v232,v231,v2
	v_lshl_add_u64 v[234:235],v[232:233],1,s[18:19]
	global_load_ushort v228, v[234:235], off
	v_mul_f32_e32 v80, v80, v135
	v_lshlrev_b32_e32 v135, 16, v229
	v_mov_b32_e32 v233, v1
	v_or_b32_e32 v231,0x10c00,v3
	v_add_u32_e32 v232,v231,v2
	v_lshl_add_u64 v[234:235],v[232:233],1,s[18:19]
	global_load_ushort v229, v[234:235], off
	v_cvt_pk_bf16_f32 v80, v80, s0
	v_mul_f32_e32 v81, v81, v135
	v_lshlrev_b32_e32 v135, 16, v194
	v_mov_b32_e32 v233, v1
	v_or_b32_e32 v231,0x12000,v3
	v_add_u32_e32 v232,v231,v2
	v_lshl_add_u64 v[234:235],v[232:233],1,s[18:19]
	global_load_ushort v194, v[234:235], off
	global_store_short v[6:7], v80, off
	v_cvt_pk_bf16_f32 v6, v81, s0
	v_mul_f32_e32 v7, v82, v135
	v_lshlrev_b32_e32 v80, 16, v195
	v_mov_b32_e32 v233, v1
	v_or_b32_e32 v231,0x12400,v3
	v_add_u32_e32 v232,v231,v2
	v_lshl_add_u64 v[234:235],v[232:233],1,s[18:19]
	global_load_ushort v195, v[234:235], off
	s_waitcnt vmcnt(56)
	global_store_short v[8:9], v6, off
	v_cvt_pk_bf16_f32 v6, v7, s0
	v_mul_f32_e32 v7, v83, v80
	v_lshlrev_b32_e32 v8, 16, v196
	v_mov_b32_e32 v233, v1
	v_or_b32_e32 v231,0x12800,v3
	v_add_u32_e32 v232,v231,v2
	v_lshl_add_u64 v[234:235],v[232:233],1,s[18:19]
	global_load_ushort v196, v[234:235], off
	global_store_short v[10:11], v6, off
	v_cvt_pk_bf16_f32 v6, v7, s0
	v_mul_f32_e32 v7, v84, v8
	v_lshlrev_b32_e32 v8, 16, v197
	v_mov_b32_e32 v233, v1
	v_or_b32_e32 v231,0x12c00,v3
	v_add_u32_e32 v232,v231,v2
	v_lshl_add_u64 v[234:235],v[232:233],1,s[18:19]
	global_load_ushort v197, v[234:235], off
	global_store_short v[12:13], v6, off
	v_cvt_pk_bf16_f32 v6, v7, s0
	v_mul_f32_e32 v7, v85, v8
	v_lshlrev_b32_e32 v8, 16, v198
	v_mov_b32_e32 v233, v1
	v_or_b32_e32 v231,0x14000,v3
	v_add_u32_e32 v232,v231,v2
	v_lshl_add_u64 v[234:235],v[232:233],1,s[18:19]
	global_load_ushort v198, v[234:235], off
	s_waitcnt vmcnt(56)
	global_store_short v[14:15], v6, off
	v_cvt_pk_bf16_f32 v6, v7, s0
	v_mul_f32_e32 v7, v86, v8
	v_lshlrev_b32_e32 v8, 16, v199
	v_mov_b32_e32 v233, v1
	v_or_b32_e32 v231,0x14400,v3
	v_add_u32_e32 v232,v231,v2
	v_lshl_add_u64 v[234:235],v[232:233],1,s[18:19]
	global_load_ushort v199, v[234:235], off
	global_store_short v[112:113], v6, off
	v_cvt_pk_bf16_f32 v6, v7, s0
	global_store_short v[114:115], v6, off
	v_mul_f32_e32 v6, v87, v8
	v_cvt_pk_bf16_f32 v6, v6, s0
	global_store_short v[116:117], v6, off
	v_lshlrev_b32_e32 v6, 16, v201
	v_mov_b32_e32 v233, v1
	v_or_b32_e32 v231,0x14800,v3
	v_add_u32_e32 v232,v231,v2
	v_lshl_add_u64 v[234:235],v[232:233],1,s[18:19]
	global_load_ushort v201, v[234:235], off
	v_mul_f32_e32 v6, v88, v6
	v_cvt_pk_bf16_f32 v6, v6, s0
	s_waitcnt vmcnt(56)
	global_store_short v[118:119], v6, off
	v_lshlrev_b32_e32 v6, 16, v202
	v_mov_b32_e32 v233, v1
	v_or_b32_e32 v231,0x14c00,v3
	v_add_u32_e32 v232,v231,v2
	v_lshl_add_u64 v[234:235],v[232:233],1,s[18:19]
	global_load_ushort v202, v[234:235], off
	v_mul_f32_e32 v6, v89, v6
	v_cvt_pk_bf16_f32 v6, v6, s0
	global_store_short v[120:121], v6, off
	v_lshlrev_b32_e32 v6, 16, v203
	v_mov_b32_e32 v233, v1
	v_or_b32_e32 v231,0x16000,v3
	v_add_u32_e32 v232,v231,v2
	v_lshl_add_u64 v[234:235],v[232:233],1,s[18:19]
	global_load_ushort v203, v[234:235], off
	v_mul_f32_e32 v6, v90, v6
	v_cvt_pk_bf16_f32 v6, v6, s0
	global_store_short v[122:123], v6, off
	v_lshlrev_b32_e32 v6, 16, v204
	v_mov_b32_e32 v233, v1
	v_or_b32_e32 v231,0x16400,v3
	v_add_u32_e32 v232,v231,v2
	v_lshl_add_u64 v[234:235],v[232:233],1,s[18:19]
	global_load_ushort v204, v[234:235], off
	v_mul_f32_e32 v6, v91, v6
	v_cvt_pk_bf16_f32 v6, v6, s0
	s_waitcnt vmcnt(56)
	global_store_short v[124:125], v6, off
	v_lshlrev_b32_e32 v6, 16, v205
	v_mov_b32_e32 v233, v1
	v_or_b32_e32 v231,0x16800,v3
	v_add_u32_e32 v232,v231,v2
	v_lshl_add_u64 v[234:235],v[232:233],1,s[18:19]
	global_load_ushort v205, v[234:235], off
	v_mul_f32_e32 v6, v92, v6
	v_cvt_pk_bf16_f32 v6, v6, s0
	global_store_short v[126:127], v6, off
	v_lshlrev_b32_e32 v6, 16, v206
	v_mov_b32_e32 v233, v1
	v_or_b32_e32 v231,0x16c00,v3
	v_add_u32_e32 v232,v231,v2
	v_lshl_add_u64 v[234:235],v[232:233],1,s[18:19]
	global_load_ushort v206, v[234:235], off
	v_mul_f32_e32 v6, v93, v6
	v_cvt_pk_bf16_f32 v6, v6, s0
	v_lshlrev_b32_e32 v0, 16, v209
	v_mov_b32_e32 v233, v1
	v_or_b32_e32 v231,0x10000,v3
	v_add_u32_e32 v232,v231,v4
	v_lshl_add_u64 v[234:235],v[232:233],1,s[18:19]
	global_load_ushort v209, v[234:235], off
	global_store_short v[128:129], v6, off
	v_lshlrev_b32_e32 v6, 16, v207
	v_mov_b32_e32 v233, v1
	v_or_b32_e32 v230,0x10400,v3
	v_add_u32_e32 v232,v230,v4
	v_lshl_add_u64 v[234:235],v[232:233],1,s[18:19]
	s_waitcnt vmcnt(56)
	global_load_ushort v207, v[234:235], off
	v_mul_f32_e32 v0, v95, v0
	v_mul_f32_e32 v6, v94, v6
	v_cvt_pk_bf16_f32 v0, v0, s0
	v_cvt_pk_bf16_f32 v6, v6, s0
	global_store_short v[132:133], v0, off
	v_add_u32_e32 v0, v5, v4
	global_store_short v[130:131], v6, off
	v_lshl_add_u64 v[6:7], v[0:1], 1, s[18:19]
	v_add_u32_e32 v0, v134, v4
	v_lshl_add_u64 v[8:9], v[0:1], 1, s[18:19]
	v_add_u32_e32 v0, v137, v4
	v_lshl_add_u64 v[10:11], v[0:1], 1, s[18:19]
	v_add_u32_e32 v0, v139, v4
	v_lshl_add_u64 v[12:13], v[0:1], 1, s[18:19]
	v_add_u32_e32 v0, v141, v4
	v_lshl_add_u64 v[14:15], v[0:1], 1, s[18:19]
	v_add_u32_e32 v0, v143, v4
	v_lshl_add_u64 v[80:81], v[0:1], 1, s[18:19]
	v_add_u32_e32 v0, v145, v4
	v_lshl_add_u64 v[82:83], v[0:1], 1, s[18:19]
	v_add_u32_e32 v0, v147, v4
	v_lshl_add_u64 v[84:85], v[0:1], 1, s[18:19]
	v_add_u32_e32 v0, v149, v4
	v_lshl_add_u64 v[86:87], v[0:1], 1, s[18:19]
	v_add_u32_e32 v0, v151, v4
	v_lshl_add_u64 v[88:89], v[0:1], 1, s[18:19]
	v_add_u32_e32 v0, v153, v4
	v_lshl_add_u64 v[90:91], v[0:1], 1, s[18:19]
	v_add_u32_e32 v0, v155, v4
	v_lshl_add_u64 v[92:93], v[0:1], 1, s[18:19]
	v_add_u32_e32 v0, v157, v4
	v_lshl_add_u64 v[94:95], v[0:1], 1, s[18:19]
	v_add_u32_e32 v0, v159, v4
	v_lshl_add_u64 v[112:113], v[0:1], 1, s[18:19]
	v_add_u32_e32 v0, v161, v4
	v_lshl_add_u64 v[114:115], v[0:1], 1, s[18:19]
	v_add_u32_e32 v0, v163, v4
	v_lshl_add_u64 v[116:117], v[0:1], 1, s[18:19]
	v_lshlrev_b32_e32 v5, 16, v210
	v_mov_b32_e32 v233, v1
	v_or_b32_e32 v231,0x10800,v3
	v_add_u32_e32 v232,v231,v4
	v_lshl_add_u64 v[234:235],v[232:233],1,s[18:19]
	global_load_ushort v210, v[234:235], off
	v_lshlrev_b32_e32 v118, 16, v211
	v_mov_b32_e32 v233, v1
	v_or_b32_e32 v231,0x10c00,v3
	v_add_u32_e32 v232,v231,v4
	v_lshl_add_u64 v[234:235],v[232:233],1,s[18:19]
	global_load_ushort v211, v[234:235], off
	v_lshlrev_b32_e32 v119, 16, v212
	v_mov_b32_e32 v233, v1
	v_or_b32_e32 v231,0x12000,v3
	v_add_u32_e32 v232,v231,v4
	v_lshl_add_u64 v[234:235],v[232:233],1,s[18:19]
	global_load_ushort v212, v[234:235], off
	v_mul_f32_e32 v5, v48, v5
	v_mul_f32_e32 v48, v49, v118
	v_mul_f32_e32 v49, v50, v119
	v_cvt_pk_bf16_f32 v5, v5, s0
	v_cvt_pk_bf16_f32 v48, v48, s0
	s_waitcnt vmcnt(56)
	global_store_short v[6:7], v5, off
	global_store_short v[8:9], v48, off
	v_cvt_pk_bf16_f32 v5, v49, s0
	global_store_short v[10:11], v5, off
	v_lshlrev_b32_e32 v5, 16, v219
	v_mov_b32_e32 v233, v1
	v_or_b32_e32 v231,0x12400,v3
	v_add_u32_e32 v232,v231,v4
	v_lshl_add_u64 v[234:235],v[232:233],1,s[18:19]
	global_load_ushort v219, v[234:235], off
	v_mul_f32_e32 v5, v51, v5
	v_cvt_pk_bf16_f32 v5, v5, s0
	global_store_short v[12:13], v5, off
	v_lshlrev_b32_e32 v5, 16, v213
	v_mov_b32_e32 v233, v1
	v_or_b32_e32 v231,0x12800,v3
	v_add_u32_e32 v232,v231,v4
	v_lshl_add_u64 v[234:235],v[232:233],1,s[18:19]
	global_load_ushort v213, v[234:235], off
	v_mul_f32_e32 v5, v52, v5
	v_cvt_pk_bf16_f32 v5, v5, s0
	s_waitcnt vmcnt(56)
	global_store_short v[14:15], v5, off
	v_lshlrev_b32_e32 v5, 16, v214
	v_mov_b32_e32 v233, v1
	v_or_b32_e32 v231,0x12c00,v3
	v_add_u32_e32 v232,v231,v4
	v_lshl_add_u64 v[234:235],v[232:233],1,s[18:19]
	global_load_ushort v214, v[234:235], off
	v_mul_f32_e32 v5, v53, v5
	v_cvt_pk_bf16_f32 v5, v5, s0
	global_store_short v[80:81], v5, off
	v_lshlrev_b32_e32 v5, 16, v215
	v_mov_b32_e32 v233, v1
	v_or_b32_e32 v231,0x14000,v3
	v_add_u32_e32 v232,v231,v4
	v_lshl_add_u64 v[234:235],v[232:233],1,s[18:19]
	global_load_ushort v215, v[234:235], off
	v_mul_f32_e32 v5, v54, v5
	v_cvt_pk_bf16_f32 v5, v5, s0
	global_store_short v[82:83], v5, off
	v_lshlrev_b32_e32 v5, 16, v216
	v_mov_b32_e32 v233, v1
	v_or_b32_e32 v231,0x14400,v3
	v_add_u32_e32 v232,v231,v4
	v_lshl_add_u64 v[234:235],v[232:233],1,s[18:19]
	global_load_ushort v216, v[234:235], off
	v_mul_f32_e32 v5, v55, v5
	v_cvt_pk_bf16_f32 v5, v5, s0
	s_waitcnt vmcnt(56)
	global_store_short v[84:85], v5, off
	v_lshlrev_b32_e32 v5, 16, v217
	v_mov_b32_e32 v233, v1
	v_or_b32_e32 v231,0x14800,v3
	v_add_u32_e32 v232,v231,v4
	v_lshl_add_u64 v[234:235],v[232:233],1,s[18:19]
	global_load_ushort v217, v[234:235], off
	v_mul_f32_e32 v5, v56, v5
	v_cvt_pk_bf16_f32 v5, v5, s0
	global_store_short v[86:87], v5, off
	v_lshlrev_b32_e32 v5, 16, v218
	v_mov_b32_e32 v233, v1
	v_or_b32_e32 v231,0x14c00,v3
	v_add_u32_e32 v232,v231,v4
	v_lshl_add_u64 v[234:235],v[232:233],1,s[18:19]
	global_load_ushort v218, v[234:235], off
	v_mul_f32_e32 v5, v57, v5
	v_cvt_pk_bf16_f32 v5, v5, s0
	global_store_short v[88:89], v5, off
	v_lshlrev_b32_e32 v5, 16, v220
	v_mov_b32_e32 v233, v1
	v_or_b32_e32 v231,0x16000,v3
	v_add_u32_e32 v232,v231,v4
	v_lshl_add_u64 v[234:235],v[232:233],1,s[18:19]
	global_load_ushort v220, v[234:235], off
	v_mul_f32_e32 v5, v58, v5
	v_cvt_pk_bf16_f32 v5, v5, s0
	s_waitcnt vmcnt(56)
	global_store_short v[90:91], v5, off
	v_lshlrev_b32_e32 v5, 16, v221
	v_mov_b32_e32 v233, v1
	v_or_b32_e32 v231,0x16400,v3
	v_add_u32_e32 v232,v231,v4
	v_lshl_add_u64 v[234:235],v[232:233],1,s[18:19]
	global_load_ushort v221, v[234:235], off
	v_mul_f32_e32 v5, v59, v5
	v_cvt_pk_bf16_f32 v5, v5, s0
	global_store_short v[92:93], v5, off
	v_lshlrev_b32_e32 v5, 16, v222
	v_mov_b32_e32 v233, v1
	v_or_b32_e32 v231,0x16800,v3
	v_add_u32_e32 v232,v231,v4
	v_lshl_add_u64 v[234:235],v[232:233],1,s[18:19]
	global_load_ushort v222, v[234:235], off
	v_mul_f32_e32 v5, v60, v5
	v_cvt_pk_bf16_f32 v5, v5, s0
	global_store_short v[94:95], v5, off
	v_lshlrev_b32_e32 v5, 16, v223
	v_mov_b32_e32 v233, v1
	v_or_b32_e32 v231,0x16c00,v3
	v_add_u32_e32 v232,v231,v4
	v_lshl_add_u64 v[234:235],v[232:233],1,s[18:19]
	global_load_ushort v223, v[234:235], off
	v_mul_f32_e32 v5, v61, v5
	v_cvt_pk_bf16_f32 v5, v5, s0
	s_waitcnt vmcnt(56)
	global_store_short v[112:113], v5, off
	v_lshlrev_b32_e32 v5, 16, v224
	v_mov_b32_e32 v233, v1
	v_or_b32_e32 v231,0x18000,v3
	v_add_u32_e32 v232,v231,v2
	v_lshl_add_u64 v[234:235],v[232:233],1,s[18:19]
	global_load_ushort v224, v[234:235], off
	v_lshlrev_b32_e32 v0, 16, v225
	v_mov_b32_e32 v233, v1
	v_or_b32_e32 v230,0x18400,v3
	v_add_u32_e32 v232,v230,v2
	v_lshl_add_u64 v[234:235],v[232:233],1,s[18:19]
	global_load_ushort v225, v[234:235], off
	v_mul_f32_e32 v5, v62, v5
	v_mul_f32_e32 v0, v63, v0
	v_cvt_pk_bf16_f32 v5, v5, s0
	v_cvt_pk_bf16_f32 v0, v0, s0
	global_store_short v[114:115], v5, off
	global_store_short v[116:117], v0, off
	s_cmpk_lt_i32 s0, 0x4000
	s_cbranch_scc1 .Ltep_e3_c
	s_waitcnt vmcnt(0)
	s_branch .Ltep_e3_e
.Ltep_e3_c:
	v_or_b32_e32 v5, 0x10000, v3
	v_add_u32_e32 v0, v5, v2
	v_or_b32_e32 v86, 0x10400, v3
	v_lshl_add_u64 v[6:7], v[0:1], 1, s[18:19]
	v_add_u32_e32 v0, v86, v2
	v_or_b32_e32 v89, 0x10800, v3
	v_lshl_add_u64 v[8:9], v[0:1], 1, s[18:19]
	v_add_u32_e32 v0, v89, v2
	v_or_b32_e32 v91, 0x10c00, v3
	v_lshl_add_u64 v[10:11], v[0:1], 1, s[18:19]
	v_add_u32_e32 v0, v91, v2
	v_or_b32_e32 v93, 0x12000, v3
	v_lshl_add_u64 v[12:13], v[0:1], 1, s[18:19]
	v_add_u32_e32 v0, v93, v2
	v_or_b32_e32 v95, 0x12400, v3
	v_lshl_add_u64 v[14:15], v[0:1], 1, s[18:19]
	v_add_u32_e32 v0, v95, v2
	v_or_b32_e32 v113, 0x12800, v3
	v_lshl_add_u64 v[48:49], v[0:1], 1, s[18:19]
	v_add_u32_e32 v0, v113, v2
	v_lshl_add_u64 v[50:51], v[0:1], 1, s[18:19]
	v_or_b32_e32 v115, 0x12c00, v3
	v_add_u32_e32 v0, v115, v2
	v_lshl_add_u64 v[52:53], v[0:1], 1, s[18:19]
	v_or_b32_e32 v117, 0x14000, v3
	v_add_u32_e32 v0, v117, v2
	v_lshl_add_u64 v[54:55], v[0:1], 1, s[18:19]
	v_or_b32_e32 v119, 0x14400, v3
	v_add_u32_e32 v0, v119, v2
	v_lshl_add_u64 v[56:57], v[0:1], 1, s[18:19]
	v_or_b32_e32 v121, 0x14800, v3
	v_add_u32_e32 v0, v121, v2
	v_lshl_add_u64 v[58:59], v[0:1], 1, s[18:19]
	v_or_b32_e32 v123, 0x14c00, v3
	v_add_u32_e32 v0, v123, v2
	v_lshl_add_u64 v[60:61], v[0:1], 1, s[18:19]
	v_or_b32_e32 v125, 0x16000, v3
	v_add_u32_e32 v0, v125, v2
	v_lshl_add_u64 v[62:63], v[0:1], 1, s[18:19]
	v_or_b32_e32 v127, 0x16400, v3
	v_add_u32_e32 v0, v127, v2
	v_or_b32_e32 v129, 0x16800, v3
	v_lshl_add_u64 v[80:81], v[0:1], 1, s[18:19]
	v_add_u32_e32 v0, v129, v2
	v_or_b32_e32 v131, 0x16c00, v3
	v_lshl_add_u64 v[82:83], v[0:1], 1, s[18:19]
	v_add_u32_e32 v0, v131, v2
	v_lshl_add_u64 v[84:85], v[0:1], 1, s[18:19]
	v_lshlrev_b32_e32 v87, 16, v226
	v_mov_b32_e32 v233, v1
	v_or_b32_e32 v231,0x18800,v3
	v_add_u32_e32 v232,v231,v2
	v_lshl_add_u64 v[234:235],v[232:233],1,s[18:19]
	global_load_ushort v226, v[234:235], off
	v_mul_f32_e32 v87, v96, v87
	v_lshlrev_b32_e32 v88, 16, v227
	v_mov_b32_e32 v233, v1
	v_or_b32_e32 v231,0x18c00,v3
	v_add_u32_e32 v232,v231,v2
	v_lshl_add_u64 v[234:235],v[232:233],1,s[18:19]
	s_waitcnt vmcnt(56)
	global_load_ushort v227, v[234:235], off
	v_cvt_pk_bf16_f32 v87, v87, s0
	v_mul_f32_e32 v88, v97, v88
	v_lshlrev_b32_e32 v90, 16, v228
	v_mov_b32_e32 v233, v1
	v_or_b32_e32 v231,0x1a000,v3
	v_add_u32_e32 v232,v231,v2
	v_lshl_add_u64 v[234:235],v[232:233],1,s[18:19]
	global_load_ushort v228, v[234:235], off
	global_store_short v[6:7], v87, off
	v_cvt_pk_bf16_f32 v6, v88, s0
	v_mul_f32_e32 v7, v98, v90
	v_lshlrev_b32_e32 v87, 16, v229
	v_mov_b32_e32 v233, v1
	v_or_b32_e32 v231,0x1a400,v3
	v_add_u32_e32 v232,v231,v2
	v_lshl_add_u64 v[234:235],v[232:233],1,s[18:19]
	global_load_ushort v229, v[234:235], off
	global_store_short v[8:9], v6, off
	v_cvt_pk_bf16_f32 v6, v7, s0
	v_mul_f32_e32 v7, v99, v87
	v_lshlrev_b32_e32 v8, 16, v194
	v_mov_b32_e32 v233, v1
	v_or_b32_e32 v231,0x1a800,v3
	v_add_u32_e32 v232,v231,v2
	v_lshl_add_u64 v[234:235],v[232:233],1,s[18:19]
	global_load_ushort v194, v[234:235], off
	s_waitcnt vmcnt(56)
	global_store_short v[10:11], v6, off
	v_cvt_pk_bf16_f32 v6, v7, s0
	v_mul_f32_e32 v7, v100, v8
	v_lshlrev_b32_e32 v8, 16, v195
	v_mov_b32_e32 v233, v1
	v_or_b32_e32 v231,0x1ac00,v3
	v_add_u32_e32 v232,v231,v2
	v_lshl_add_u64 v[234:235],v[232:233],1,s[18:19]
	global_load_ushort v195, v[234:235], off
	global_store_short v[12:13], v6, off
	v_cvt_pk_bf16_f32 v6, v7, s0
	v_mul_f32_e32 v7, v101, v8
	v_lshlrev_b32_e32 v8, 16, v196
	v_mov_b32_e32 v233, v1
	v_or_b32_e32 v231,0x1c000,v3
	v_add_u32_e32 v232,v231,v2
	v_lshl_add_u64 v[234:235],v[232:233],1,s[18:19]
	global_load_ushort v196, v[234:235], off
	global_store_short v[14:15], v6, off
	v_cvt_pk_bf16_f32 v6, v7, s0
	v_mul_f32_e32 v7, v102, v8
	v_lshlrev_b32_e32 v8, 16, v197
	v_mov_b32_e32 v233, v1
	v_or_b32_e32 v231,0x1c400,v3
	v_add_u32_e32 v232,v231,v2
	v_lshl_add_u64 v[234:235],v[232:233],1,s[18:19]
	global_load_ushort v197, v[234:235], off
	s_waitcnt vmcnt(56)
	global_store_short v[48:49], v6, off
	v_cvt_pk_bf16_f32 v6, v7, s0
	global_store_short v[50:51], v6, off
	v_mul_f32_e32 v6, v103, v8
	v_cvt_pk_bf16_f32 v6, v6, s0
	global_store_short v[52:53], v6, off
	v_lshlrev_b32_e32 v6, 16, v198
	v_mov_b32_e32 v233, v1
	v_or_b32_e32 v231,0x1c800,v3
	v_add_u32_e32 v232,v231,v2
	v_lshl_add_u64 v[234:235],v[232:233],1,s[18:19]
	global_load_ushort v198, v[234:235], off
	v_mul_f32_e32 v6, v104, v6
	v_cvt_pk_bf16_f32 v6, v6, s0
	global_store_short v[54:55], v6, off
	v_lshlrev_b32_e32 v6, 16, v199
	v_mov_b32_e32 v233, v1
	v_or_b32_e32 v231,0x1cc00,v3
	v_add_u32_e32 v232,v231,v2
	v_lshl_add_u64 v[234:235],v[232:233],1,s[18:19]
	global_load_ushort v199, v[234:235], off
	v_mul_f32_e32 v6, v105, v6
	v_cvt_pk_bf16_f32 v6, v6, s0
	s_waitcnt vmcnt(56)
	global_store_short v[56:57], v6, off
	v_lshlrev_b32_e32 v6, 16, v201
	v_mov_b32_e32 v233, v1
	v_or_b32_e32 v231,0x1e000,v3
	v_add_u32_e32 v232,v231,v2
	v_lshl_add_u64 v[234:235],v[232:233],1,s[18:19]
	global_load_ushort v201, v[234:235], off
	v_mul_f32_e32 v6, v106, v6
	v_cvt_pk_bf16_f32 v6, v6, s0
	global_store_short v[58:59], v6, off
	v_lshlrev_b32_e32 v6, 16, v202
	v_mov_b32_e32 v233, v1
	v_or_b32_e32 v231,0x1e400,v3
	v_add_u32_e32 v232,v231,v2
	v_lshl_add_u64 v[234:235],v[232:233],1,s[18:19]
	global_load_ushort v202, v[234:235], off
	v_mul_f32_e32 v6, v107, v6
	v_cvt_pk_bf16_f32 v6, v6, s0
	global_store_short v[60:61], v6, off
	v_lshlrev_b32_e32 v6, 16, v203
	v_mov_b32_e32 v233, v1
	v_or_b32_e32 v231,0x1e800,v3
	v_add_u32_e32 v232,v231,v2
	v_lshl_add_u64 v[234:235],v[232:233],1,s[18:19]
	global_load_ushort v203, v[234:235], off
	v_mul_f32_e32 v6, v108, v6
	v_cvt_pk_bf16_f32 v6, v6, s0
	s_waitcnt vmcnt(56)
	global_store_short v[62:63], v6, off
	v_lshlrev_b32_e32 v6, 16, v204
	v_mov_b32_e32 v233, v1
	v_or_b32_e32 v231,0x1ec00,v3
	v_add_u32_e32 v232,v231,v2
	v_lshl_add_u64 v[234:235],v[232:233],1,s[18:19]
	global_load_ushort v204, v[234:235], off
	v_mul_f32_e32 v6, v109, v6
	v_cvt_pk_bf16_f32 v6, v6, s0
	v_lshlrev_b32_e32 v0, 16, v206
	v_mov_b32_e32 v233, v1
	v_or_b32_e32 v231,0x18000,v3
	v_add_u32_e32 v232,v231,v4
	v_lshl_add_u64 v[234:235],v[232:233],1,s[18:19]
	global_load_ushort v206, v[234:235], off
	global_store_short v[80:81], v6, off
	v_lshlrev_b32_e32 v6, 16, v205
	v_mov_b32_e32 v233, v1
	v_or_b32_e32 v230,0x18400,v3
	v_add_u32_e32 v232,v230,v4
	v_lshl_add_u64 v[234:235],v[232:233],1,s[18:19]
	global_load_ushort v205, v[234:235], off
	v_mul_f32_e32 v0, v111, v0
	v_mul_f32_e32 v6, v110, v6
	v_cvt_pk_bf16_f32 v0, v0, s0
	v_cvt_pk_bf16_f32 v6, v6, s0
	global_store_short v[84:85], v0, off
	v_add_u32_e32 v0, v5, v4
	s_waitcnt vmcnt(56)
	global_store_short v[82:83], v6, off
	v_lshl_add_u64 v[6:7], v[0:1], 1, s[18:19]
	v_add_u32_e32 v0, v86, v4
	v_lshl_add_u64 v[8:9], v[0:1], 1, s[18:19]
	v_add_u32_e32 v0, v89, v4
	v_lshl_add_u64 v[10:11], v[0:1], 1, s[18:19]
	v_add_u32_e32 v0, v91, v4
	v_lshl_add_u64 v[12:13], v[0:1], 1, s[18:19]
	v_add_u32_e32 v0, v93, v4
	v_lshl_add_u64 v[14:15], v[0:1], 1, s[18:19]
	v_add_u32_e32 v0, v95, v4
	v_lshl_add_u64 v[48:49], v[0:1], 1, s[18:19]
	v_add_u32_e32 v0, v113, v4
	v_lshl_add_u64 v[50:51], v[0:1], 1, s[18:19]
	v_add_u32_e32 v0, v115, v4
	v_lshl_add_u64 v[52:53], v[0:1], 1, s[18:19]
	v_add_u32_e32 v0, v117, v4
	v_lshl_add_u64 v[54:55], v[0:1], 1, s[18:19]
	v_add_u32_e32 v0, v119, v4
	v_lshl_add_u64 v[56:57], v[0:1], 1, s[18:19]
	v_add_u32_e32 v0, v121, v4
	v_lshl_add_u64 v[58:59], v[0:1], 1, s[18:19]
	v_add_u32_e32 v0, v123, v4
	v_lshl_add_u64 v[60:61], v[0:1], 1, s[18:19]
	v_add_u32_e32 v0, v125, v4
	v_lshl_add_u64 v[62:63], v[0:1], 1, s[18:19]
	v_add_u32_e32 v0, v127, v4
	v_lshl_add_u64 v[80:81], v[0:1], 1, s[18:19]
	v_add_u32_e32 v0, v129, v4
	v_lshl_add_u64 v[82:83], v[0:1], 1, s[18:19]
	v_add_u32_e32 v0, v131, v4
	v_lshl_add_u64 v[84:85], v[0:1], 1, s[18:19]
	v_lshlrev_b32_e32 v5, 16, v209
	v_mov_b32_e32 v233, v1
	v_or_b32_e32 v231,0x18800,v3
	v_add_u32_e32 v232,v231,v4
	v_lshl_add_u64 v[234:235],v[232:233],1,s[18:19]
	global_load_ushort v209, v[234:235], off
	v_lshlrev_b32_e32 v86, 16, v207
	v_mov_b32_e32 v233, v1
	v_or_b32_e32 v231,0x18c00,v3
	v_add_u32_e32 v232,v231,v4
	v_lshl_add_u64 v[234:235],v[232:233],1,s[18:19]
	global_load_ushort v207, v[234:235], off
	v_lshlrev_b32_e32 v87, 16, v210
	v_mov_b32_e32 v233, v1
	v_or_b32_e32 v231,0x1a000,v3
	v_add_u32_e32 v232,v231,v4
	v_lshl_add_u64 v[234:235],v[232:233],1,s[18:19]
	global_load_ushort v210, v[234:235], off
	v_mul_f32_e32 v5, v64, v5
	v_mul_f32_e32 v64, v65, v86
	v_mul_f32_e32 v65, v66, v87
	v_cvt_pk_bf16_f32 v5, v5, s0
	v_cvt_pk_bf16_f32 v64, v64, s0
	global_store_short v[6:7], v5, off
	global_store_short v[8:9], v64, off
	v_cvt_pk_bf16_f32 v5, v65, s0
	s_waitcnt vmcnt(56)
	global_store_short v[10:11], v5, off
	v_lshlrev_b32_e32 v5, 16, v211
	v_mov_b32_e32 v233, v1
	v_or_b32_e32 v231,0x1a400,v3
	v_add_u32_e32 v232,v231,v4
	v_lshl_add_u64 v[234:235],v[232:233],1,s[18:19]
	global_load_ushort v211, v[234:235], off
	v_mul_f32_e32 v5, v67, v5
	v_cvt_pk_bf16_f32 v5, v5, s0
	global_store_short v[12:13], v5, off
	v_lshlrev_b32_e32 v5, 16, v212
	v_mov_b32_e32 v233, v1
	v_or_b32_e32 v231,0x1a800,v3
	v_add_u32_e32 v232,v231,v4
	v_lshl_add_u64 v[234:235],v[232:233],1,s[18:19]
	global_load_ushort v212, v[234:235], off
	v_mul_f32_e32 v5, v68, v5
	v_cvt_pk_bf16_f32 v5, v5, s0
	global_store_short v[14:15], v5, off
	v_lshlrev_b32_e32 v5, 16, v219
	v_mov_b32_e32 v233, v1
	v_or_b32_e32 v231,0x1ac00,v3
	v_add_u32_e32 v232,v231,v4
	v_lshl_add_u64 v[234:235],v[232:233],1,s[18:19]
	global_load_ushort v219, v[234:235], off
	v_mul_f32_e32 v5, v69, v5
	v_cvt_pk_bf16_f32 v5, v5, s0
	s_waitcnt vmcnt(56)
	global_store_short v[48:49], v5, off
	v_lshlrev_b32_e32 v5, 16, v213
	v_mov_b32_e32 v233, v1
	v_or_b32_e32 v231,0x1c000,v3
	v_add_u32_e32 v232,v231,v4
	v_lshl_add_u64 v[234:235],v[232:233],1,s[18:19]
	global_load_ushort v213, v[234:235], off
	v_mul_f32_e32 v5, v70, v5
	v_cvt_pk_bf16_f32 v5, v5, s0
	global_store_short v[50:51], v5, off
	v_lshlrev_b32_e32 v5, 16, v214
	v_mov_b32_e32 v233, v1
	v_or_b32_e32 v231,0x1c400,v3
	v_add_u32_e32 v232,v231,v4
	v_lshl_add_u64 v[234:235],v[232:233],1,s[18:19]
	global_load_ushort v214, v[234:235], off
	v_mul_f32_e32 v5, v71, v5
	v_cvt_pk_bf16_f32 v5, v5, s0
	global_store_short v[52:53], v5, off
	v_lshlrev_b32_e32 v5, 16, v215
	v_mov_b32_e32 v233, v1
	v_or_b32_e32 v231,0x1c800,v3
	v_add_u32_e32 v232,v231,v4
	v_lshl_add_u64 v[234:235],v[232:233],1,s[18:19]
	global_load_ushort v215, v[234:235], off
	v_mul_f32_e32 v5, v72, v5
	v_cvt_pk_bf16_f32 v5, v5, s0
	s_waitcnt vmcnt(56)
	global_store_short v[54:55], v5, off
	v_lshlrev_b32_e32 v5, 16, v216
	v_mov_b32_e32 v233, v1
	v_or_b32_e32 v231,0x1cc00,v3
	v_add_u32_e32 v232,v231,v4
	v_lshl_add_u64 v[234:235],v[232:233],1,s[18:19]
	global_load_ushort v216, v[234:235], off
	v_mul_f32_e32 v5, v73, v5
	v_cvt_pk_bf16_f32 v5, v5, s0
	global_store_short v[56:57], v5, off
	v_lshlrev_b32_e32 v5, 16, v217
	v_mov_b32_e32 v233, v1
	v_or_b32_e32 v231,0x1e000,v3
	v_add_u32_e32 v232,v231,v4
	v_lshl_add_u64 v[234:235],v[232:233],1,s[18:19]
	global_load_ushort v217, v[234:235], off
	v_mul_f32_e32 v5, v74, v5
	v_cvt_pk_bf16_f32 v5, v5, s0
	global_store_short v[58:59], v5, off
	v_lshlrev_b32_e32 v5, 16, v218
	v_mov_b32_e32 v233, v1
	v_or_b32_e32 v231,0x1e400,v3
	v_add_u32_e32 v232,v231,v4
	v_lshl_add_u64 v[234:235],v[232:233],1,s[18:19]
	global_load_ushort v218, v[234:235], off
	v_mul_f32_e32 v5, v75, v5
	v_cvt_pk_bf16_f32 v5, v5, s0
	s_waitcnt vmcnt(56)
	global_store_short v[60:61], v5, off
	v_lshlrev_b32_e32 v5, 16, v220
	v_mov_b32_e32 v233, v1
	v_or_b32_e32 v231,0x1e800,v3
	v_add_u32_e32 v232,v231,v4
	v_lshl_add_u64 v[234:235],v[232:233],1,s[18:19]
	global_load_ushort v220, v[234:235], off
	v_mul_f32_e32 v5, v76, v5
	v_cvt_pk_bf16_f32 v5, v5, s0
	global_store_short v[62:63], v5, off
	v_lshlrev_b32_e32 v5, 16, v221
	v_mov_b32_e32 v233, v1
	v_or_b32_e32 v231,0x1ec00,v3
	v_add_u32_e32 v232,v231,v4
	v_lshl_add_u64 v[234:235],v[232:233],1,s[18:19]
	global_load_ushort v221, v[234:235], off
	v_mul_f32_e32 v5, v77, v5
	v_cvt_pk_bf16_f32 v5, v5, s0
	global_store_short v[80:81], v5, off
	v_lshlrev_b32_e32 v5, 16, v222
	v_lshlrev_b32_e32 v0, 16, v223
	v_mul_f32_e32 v5, v78, v5
	v_mul_f32_e32 v0, v79, v0
	v_cvt_pk_bf16_f32 v5, v5, s0
	v_cvt_pk_bf16_f32 v0, v0, s0
	global_store_short v[82:83], v5, off
	s_waitcnt vmcnt(56)
	global_store_short v[84:85], v0, off
	v_or_b32_e32 v5, 0x18000, v3
	v_add_u32_e32 v0, v5, v2
	v_or_b32_e32 v68, 0x18400, v3
	v_lshl_add_u64 v[6:7], v[0:1], 1, s[18:19]
	v_add_u32_e32 v0, v68, v2
	v_or_b32_e32 v71, 0x18800, v3
	v_lshl_add_u64 v[8:9], v[0:1], 1, s[18:19]
	v_add_u32_e32 v0, v71, v2
	v_or_b32_e32 v73, 0x18c00, v3
	v_lshl_add_u64 v[10:11], v[0:1], 1, s[18:19]
	v_add_u32_e32 v0, v73, v2
	v_or_b32_e32 v75, 0x1a000, v3
	v_lshl_add_u64 v[12:13], v[0:1], 1, s[18:19]
	v_add_u32_e32 v0, v75, v2
	v_or_b32_e32 v77, 0x1a400, v3
	v_lshl_add_u64 v[14:15], v[0:1], 1, s[18:19]
	v_add_u32_e32 v0, v77, v2
	v_or_b32_e32 v79, 0x1a800, v3
	v_lshl_add_u64 v[48:49], v[0:1], 1, s[18:19]
	v_add_u32_e32 v0, v79, v2
	v_lshl_add_u64 v[50:51], v[0:1], 1, s[18:19]
	v_or_b32_e32 v81, 0x1ac00, v3
	v_add_u32_e32 v0, v81, v2
	v_lshl_add_u64 v[52:53], v[0:1], 1, s[18:19]
	v_or_b32_e32 v83, 0x1c000, v3
	v_add_u32_e32 v0, v83, v2
	v_lshl_add_u64 v[54:55], v[0:1], 1, s[18:19]
	v_or_b32_e32 v85, 0x1c400, v3
	v_add_u32_e32 v0, v85, v2
	v_lshl_add_u64 v[56:57], v[0:1], 1, s[18:19]
	v_or_b32_e32 v87, 0x1c800, v3
	v_add_u32_e32 v0, v87, v2
	v_lshl_add_u64 v[58:59], v[0:1], 1, s[18:19]
	v_or_b32_e32 v89, 0x1cc00, v3
	v_add_u32_e32 v0, v89, v2
	v_lshl_add_u64 v[60:61], v[0:1], 1, s[18:19]
	v_or_b32_e32 v91, 0x1e000, v3
	v_add_u32_e32 v0, v91, v2
	v_lshl_add_u64 v[62:63], v[0:1], 1, s[18:19]
	v_or_b32_e32 v93, 0x1e400, v3
	v_add_u32_e32 v0, v93, v2
	v_or_b32_e32 v95, 0x1e800, v3
	v_lshl_add_u64 v[64:65], v[0:1], 1, s[18:19]
	v_add_u32_e32 v0, v95, v2
	v_or_b32_e32 v97, 0x1ec00, v3
	v_lshl_add_u64 v[66:67], v[0:1], 1, s[18:19]
	v_add_u32_e32 v0, v97, v2
	v_lshl_add_u64 v[2:3], v[0:1], 1, s[18:19]
	v_lshlrev_b32_e32 v69, 16, v224
	v_mul_f32_e32 v32, v32, v69
	v_lshlrev_b32_e32 v69, 16, v225
	v_cvt_pk_bf16_f32 v32, v32, s0
	v_mul_f32_e32 v33, v33, v69
	v_lshlrev_b32_e32 v69, 16, v226
	global_store_short v[6:7], v32, off
	v_cvt_pk_bf16_f32 v6, v33, s0
	v_mul_f32_e32 v7, v34, v69
	v_lshlrev_b32_e32 v32, 16, v227
	global_store_short v[8:9], v6, off
	v_cvt_pk_bf16_f32 v6, v7, s0
	v_mul_f32_e32 v7, v35, v32
	v_lshlrev_b32_e32 v8, 16, v228
	global_store_short v[10:11], v6, off
	v_cvt_pk_bf16_f32 v6, v7, s0
	v_mul_f32_e32 v7, v36, v8
	v_lshlrev_b32_e32 v8, 16, v229
	global_store_short v[12:13], v6, off
	v_cvt_pk_bf16_f32 v6, v7, s0
	v_mul_f32_e32 v7, v37, v8
	s_waitcnt vmcnt(59)
	v_lshlrev_b32_e32 v8, 16, v194
	global_store_short v[14:15], v6, off
	v_cvt_pk_bf16_f32 v6, v7, s0
	v_mul_f32_e32 v7, v38, v8
	s_waitcnt vmcnt(58)
	v_lshlrev_b32_e32 v8, 16, v195
	global_store_short v[48:49], v6, off
	v_cvt_pk_bf16_f32 v6, v7, s0
	global_store_short v[50:51], v6, off
	v_mul_f32_e32 v6, v39, v8
	v_cvt_pk_bf16_f32 v6, v6, s0
	global_store_short v[52:53], v6, off
	s_waitcnt vmcnt(59)
	v_lshlrev_b32_e32 v6, 16, v196
	v_mul_f32_e32 v6, v40, v6
	v_cvt_pk_bf16_f32 v6, v6, s0
	global_store_short v[54:55], v6, off
	s_waitcnt vmcnt(58)
	v_lshlrev_b32_e32 v6, 16, v197
	v_mul_f32_e32 v6, v41, v6
	v_cvt_pk_bf16_f32 v6, v6, s0
	global_store_short v[56:57], v6, off
	s_waitcnt vmcnt(55)
	v_lshlrev_b32_e32 v6, 16, v198
	v_mul_f32_e32 v6, v42, v6
	v_cvt_pk_bf16_f32 v6, v6, s0
	global_store_short v[58:59], v6, off
	s_waitcnt vmcnt(54)
	v_lshlrev_b32_e32 v6, 16, v199
	v_mul_f32_e32 v6, v43, v6
	v_cvt_pk_bf16_f32 v6, v6, s0
	global_store_short v[60:61], v6, off
	s_waitcnt vmcnt(53)
	v_lshlrev_b32_e32 v6, 16, v201
	v_mul_f32_e32 v6, v44, v6
	v_cvt_pk_bf16_f32 v6, v6, s0
	global_store_short v[62:63], v6, off
	s_waitcnt vmcnt(52)
	v_lshlrev_b32_e32 v6, 16, v202
	v_mul_f32_e32 v6, v45, v6
	s_waitcnt vmcnt(48)
	v_lshlrev_b32_e32 v0, 16, v204
	v_cvt_pk_bf16_f32 v6, v6, s0
	v_mul_f32_e32 v0, v47, v0
	global_store_short v[64:65], v6, off
	v_lshlrev_b32_e32 v6, 16, v203
	v_cvt_pk_bf16_f32 v0, v0, s0
	v_mul_f32_e32 v6, v46, v6
	global_store_short v[2:3], v0, off
	v_add_u32_e32 v0, v5, v4
	v_cvt_pk_bf16_f32 v6, v6, s0
	v_lshl_add_u64 v[2:3], v[0:1], 1, s[18:19]
	v_add_u32_e32 v0, v68, v4
	global_store_short v[66:67], v6, off
	v_lshl_add_u64 v[6:7], v[0:1], 1, s[18:19]
	v_add_u32_e32 v0, v71, v4
	v_lshl_add_u64 v[8:9], v[0:1], 1, s[18:19]
	v_add_u32_e32 v0, v73, v4
	v_lshl_add_u64 v[10:11], v[0:1], 1, s[18:19]
	v_add_u32_e32 v0, v75, v4
	v_lshl_add_u64 v[12:13], v[0:1], 1, s[18:19]
	v_add_u32_e32 v0, v77, v4
	v_lshl_add_u64 v[14:15], v[0:1], 1, s[18:19]
	v_add_u32_e32 v0, v79, v4
	v_lshl_add_u64 v[32:33], v[0:1], 1, s[18:19]
	v_add_u32_e32 v0, v81, v4
	v_lshl_add_u64 v[34:35], v[0:1], 1, s[18:19]
	v_add_u32_e32 v0, v83, v4
	v_lshl_add_u64 v[36:37], v[0:1], 1, s[18:19]
	v_add_u32_e32 v0, v85, v4
	v_lshl_add_u64 v[38:39], v[0:1], 1, s[18:19]
	v_add_u32_e32 v0, v87, v4
	v_lshl_add_u64 v[40:41], v[0:1], 1, s[18:19]
	v_add_u32_e32 v0, v89, v4
	v_lshl_add_u64 v[42:43], v[0:1], 1, s[18:19]
	v_add_u32_e32 v0, v91, v4
	v_lshl_add_u64 v[44:45], v[0:1], 1, s[18:19]
	v_add_u32_e32 v0, v93, v4
	v_lshl_add_u64 v[46:47], v[0:1], 1, s[18:19]
	v_add_u32_e32 v0, v95, v4
	v_lshl_add_u64 v[48:49], v[0:1], 1, s[18:19]
	v_add_u32_e32 v0, v97, v4
	v_lshl_add_u64 v[4:5], v[0:1], 1, s[18:19]
	s_waitcnt vmcnt(50)
	v_lshlrev_b32_e32 v50, 16, v206
	s_waitcnt vmcnt(48)
	v_lshlrev_b32_e32 v51, 16, v205
	s_waitcnt vmcnt(45)
	v_lshlrev_b32_e32 v52, 16, v209
	v_mul_f32_e32 v16, v16, v50
	v_mul_f32_e32 v17, v17, v51
	v_mul_f32_e32 v18, v18, v52
	v_cvt_pk_bf16_f32 v16, v16, s0
	v_cvt_pk_bf16_f32 v17, v17, s0
	global_store_short v[2:3], v16, off
	global_store_short v[6:7], v17, off
	v_cvt_pk_bf16_f32 v2, v18, s0
	global_store_short v[8:9], v2, off
	s_waitcnt vmcnt(47)
	v_lshlrev_b32_e32 v2, 16, v207
	v_mul_f32_e32 v2, v19, v2
	v_cvt_pk_bf16_f32 v2, v2, s0
	global_store_short v[10:11], v2, off
	s_waitcnt vmcnt(47)
	v_lshlrev_b32_e32 v2, 16, v210
	v_mul_f32_e32 v2, v20, v2
	v_cvt_pk_bf16_f32 v2, v2, s0
	global_store_short v[12:13], v2, off
	s_waitcnt vmcnt(44)
	v_lshlrev_b32_e32 v2, 16, v211
	v_mul_f32_e32 v2, v21, v2
	v_cvt_pk_bf16_f32 v2, v2, s0
	global_store_short v[14:15], v2, off
	s_waitcnt vmcnt(43)
	v_lshlrev_b32_e32 v2, 16, v212
	v_mul_f32_e32 v2, v22, v2
	v_cvt_pk_bf16_f32 v2, v2, s0
	global_store_short v[32:33], v2, off
	s_waitcnt vmcnt(42)
	v_lshlrev_b32_e32 v2, 16, v219
	v_mul_f32_e32 v2, v23, v2
	v_cvt_pk_bf16_f32 v2, v2, s0
	global_store_short v[34:35], v2, off
	s_waitcnt vmcnt(41)
	v_lshlrev_b32_e32 v2, 16, v213
	v_mul_f32_e32 v2, v24, v2
	v_cvt_pk_bf16_f32 v2, v2, s0
	global_store_short v[36:37], v2, off
	s_waitcnt vmcnt(40)
	v_lshlrev_b32_e32 v2, 16, v214
	v_mul_f32_e32 v2, v25, v2
	v_cvt_pk_bf16_f32 v2, v2, s0
	global_store_short v[38:39], v2, off
	s_waitcnt vmcnt(39)
	v_lshlrev_b32_e32 v2, 16, v215
	v_mul_f32_e32 v2, v26, v2
	v_cvt_pk_bf16_f32 v2, v2, s0
	global_store_short v[40:41], v2, off
	s_waitcnt vmcnt(38)
	v_lshlrev_b32_e32 v2, 16, v216
	v_mul_f32_e32 v2, v27, v2
	v_cvt_pk_bf16_f32 v2, v2, s0
	global_store_short v[42:43], v2, off
	s_waitcnt vmcnt(37)
	v_lshlrev_b32_e32 v2, 16, v217
	v_mul_f32_e32 v2, v28, v2
	v_cvt_pk_bf16_f32 v2, v2, s0
	global_store_short v[44:45], v2, off
	s_waitcnt vmcnt(36)
	v_lshlrev_b32_e32 v2, 16, v218
	v_mul_f32_e32 v2, v29, v2
	v_cvt_pk_bf16_f32 v2, v2, s0
	global_store_short v[46:47], v2, off
	s_waitcnt vmcnt(35)
	v_lshlrev_b32_e32 v2, 16, v220
	s_waitcnt vmcnt(33)
	v_lshlrev_b32_e32 v0, 16, v221
	v_mul_f32_e32 v2, v30, v2
	v_mul_f32_e32 v0, v31, v0
	v_cvt_pk_bf16_f32 v2, v2, s0
	v_cvt_pk_bf16_f32 v0, v0, s0
	global_store_short v[48:49], v2, off
	global_store_short v[4:5], v0, off
.Ltep_e3_e:
	v_mov_b32_e32 v0, v208
	s_lshl_b64 s[14:15], s[14:15], 1
	s_mov_b32 s1, 8
	s_add_u32 s14, s42, s14
	v_bfe_u32 v184, v0, 6, 2
	v_and_b32_e32 v185, 31, v0
	v_bfe_u32 v186, v0, 5, 1
	v_ashrrev_i32_e32 v2, 1, v0
	v_ashrrev_i32_e32 v35, 3, v0
	s_addc_u32 s15, s43, s15
	s_lshl_b64 s[4:5], s[4:5], 1
	v_lshlrev_b32_e32 v0, 4, v0
	s_add_u32 s4, s24, s4
	v_and_b32_e32 v34, 0x70, v0
	v_and_b32_e32 v187, 0xffffff80, v2
	s_addc_u32 s5, s25, s5
	v_lshl_or_b32 v0, v35, 10, v34
	s_cmp_gt_i32 s1, 1
	s_cselect_b32 s7, 0x80, 0
	v_add_u32_e32 v178, 0x10000, v0
	v_add_u32_e32 v180, 0x20000, v0
	v_add_u32_e32 v182, 0x30000, v0
	global_load_dwordx4 v[2:5], v0, s[14:15]
	global_load_dwordx4 v[6:9], v0, s[4:5]
	global_load_dwordx4 v[10:13], v178, s[14:15]
	global_load_dwordx4 v[14:17], v178, s[4:5]
	global_load_dwordx4 v[18:21], v180, s[14:15]
	global_load_dwordx4 v[22:25], v180, s[4:5]
	global_load_dwordx4 v[26:29], v182, s[14:15]
	global_load_dwordx4 v[30:33], v182, s[4:5]
	s_add_u32 s14, s14, s7
	s_addc_u32 s15, s15, 0
	s_add_u32 s4, s4, s7
	s_addc_u32 s5, s5, 0
	global_load_dwordx4 v[144:147], v0, s[14:15]
	global_load_dwordx4 v[156:159], v0, s[4:5]
	global_load_dwordx4 v[148:151], v178, s[14:15]
	global_load_dwordx4 v[152:155], v178, s[4:5]
	global_load_dwordx4 v[172:175], v180, s[14:15]
	global_load_dwordx4 v[160:163], v180, s[4:5]
	global_load_dwordx4 v[164:167], v182, s[14:15]
	global_load_dwordx4 v[168:171], v182, s[4:5]
	s_add_i32 s7, s1, -2
	v_mad_u64_u32 v[176:177], s[4:5], v35, s30, v[34:35]
	s_cmp_gt_i32 s1, 2
	s_cselect_b64 s[4:5], -1, 0
	v_mov_b32_e32 v179, v1
	v_mov_b32_e32 v181, v1
	v_mov_b32_e32 v183, v1
	s_mov_b64 s[14:15], -1
	s_and_b64 vcc, exec, s[12:13]
	s_waitcnt vmcnt(15)
	ds_write_b128 v176, v[2:5]
	s_waitcnt vmcnt(14)
	ds_write_b128 v176, v[6:9] offset:36864
	s_waitcnt vmcnt(13)
	ds_write_b128 v176, v[10:13] offset:9216
	s_waitcnt vmcnt(11)
	ds_write_b128 v176, v[18:21] offset:18432
	s_waitcnt vmcnt(9)
	ds_write_b128 v176, v[26:29] offset:27648
	ds_write_b128 v176, v[14:17] offset:46080
	ds_write_b128 v176, v[22:25] offset:55296
	s_waitcnt vmcnt(8)
	ds_write_b128 v176, v[30:33] offset:64512
	v_cndmask_b32_e64 v2, 0, 1, s[4:5]
	v_cmp_ne_u32_e64 s[4:5], 1, v2
	s_waitcnt lgkmcnt(0)
	s_cbranch_vccz .LBB0_3406
	s_and_b64 vcc, exec, s[4:5]
	s_barrier
	s_cbranch_vccnz .LBB0_3402
	s_add_u32 s12, s8, 0x13dbb00
	v_or_b32_e32 v2, v187, v185
	s_addc_u32 s13, s9, 0
	v_mul_lo_u32 v50, v2, s30
	v_lshlrev_b32_e32 v2, 3, v186
	v_lshl_or_b32 v3, v184, 6, v185
	v_lshl_add_u64 v[34:35], s[12:13], 0, v[0:1]
	v_lshl_add_u64 v[36:37], s[12:13], 0, v[178:179]
	v_lshl_add_u64 v[38:39], s[12:13], 0, v[180:181]
	v_lshl_add_u64 v[40:41], s[12:13], 0, v[182:183]
	s_add_u32 s12, s10, 0x4a0100
	v_mul_u32_u24_e32 v51, 0x90, v3
	s_addc_u32 s13, s11, 0
	v_mov_b32_e32 v80, 0
	v_lshlrev_b32_e32 v52, 1, v2
	s_waitcnt vmcnt(7)
	v_mov_b64_e32 v[2:3], v[144:145]
	s_waitcnt vmcnt(5)
	v_mov_b64_e32 v[6:7], v[148:149]
	s_waitcnt vmcnt(3)
	v_mov_b64_e32 v[10:11], v[172:173]
	s_waitcnt vmcnt(1)
	v_mov_b64_e32 v[14:15], v[164:165]
	v_mov_b64_e32 v[18:19], v[156:157]
	v_mov_b64_e32 v[26:27], v[152:153]
	v_mov_b64_e32 v[22:23], v[160:161]
	s_waitcnt vmcnt(0)
	v_mov_b64_e32 v[30:31], v[168:169]
	v_lshl_add_u64 v[42:43], s[12:13], 0, v[0:1]
	v_lshl_add_u64 v[44:45], s[12:13], 0, v[178:179]
	v_lshl_add_u64 v[46:47], s[12:13], 0, v[180:181]
	v_lshl_add_u64 v[48:49], s[12:13], 0, v[182:183]
	s_mov_b32 s14, 0
	s_mov_b64 s[12:13], s[90:91]
	v_mov_b64_e32 v[4:5], v[146:147]
	v_mov_b64_e32 v[8:9], v[150:151]
	v_mov_b64_e32 v[12:13], v[174:175]
	v_mov_b64_e32 v[16:17], v[166:167]
	v_mov_b64_e32 v[20:21], v[158:159]
	v_mov_b64_e32 v[28:29], v[154:155]
	v_mov_b64_e32 v[24:25], v[162:163]
	v_mov_b64_e32 v[32:33], v[170:171]
	v_mov_b32_e32 v81, v80
	v_mov_b32_e32 v82, v80
	v_mov_b32_e32 v83, v80
	v_mov_b32_e32 v84, v80
	v_mov_b32_e32 v85, v80
	v_mov_b32_e32 v86, v80
	v_mov_b32_e32 v87, v80
	v_mov_b32_e32 v88, v80
	v_mov_b32_e32 v89, v80
	v_mov_b32_e32 v90, v80
	v_mov_b32_e32 v91, v80
	v_mov_b32_e32 v92, v80
	v_mov_b32_e32 v93, v80
	v_mov_b32_e32 v94, v80
	v_mov_b32_e32 v95, v80
	v_mov_b32_e32 v96, v80
	v_mov_b32_e32 v97, v80
	v_mov_b32_e32 v98, v80
	v_mov_b32_e32 v99, v80
	v_mov_b32_e32 v100, v80
	v_mov_b32_e32 v101, v80
	v_mov_b32_e32 v102, v80
	v_mov_b32_e32 v103, v80
	v_mov_b32_e32 v104, v80
	v_mov_b32_e32 v105, v80
	v_mov_b32_e32 v106, v80
	v_mov_b32_e32 v107, v80
	v_mov_b32_e32 v108, v80
	v_mov_b32_e32 v109, v80
	v_mov_b32_e32 v110, v80
	v_mov_b32_e32 v111, v80
	v_mov_b32_e32 v112, v80
	v_mov_b32_e32 v113, v80
	v_mov_b32_e32 v114, v80
	v_mov_b32_e32 v115, v80
	v_mov_b32_e32 v116, v80
	v_mov_b32_e32 v117, v80
	v_mov_b32_e32 v118, v80
	v_mov_b32_e32 v119, v80
	v_mov_b32_e32 v120, v80
	v_mov_b32_e32 v121, v80
	v_mov_b32_e32 v122, v80
	v_mov_b32_e32 v123, v80
	v_mov_b32_e32 v124, v80
	v_mov_b32_e32 v125, v80
	v_mov_b32_e32 v126, v80
	v_mov_b32_e32 v127, v80
	v_mov_b32_e32 v128, v80
	v_mov_b32_e32 v129, v80
	v_mov_b32_e32 v130, v80
	v_mov_b32_e32 v131, v80
	v_mov_b32_e32 v132, v80
	v_mov_b32_e32 v133, v80
	v_mov_b32_e32 v134, v80
	v_mov_b32_e32 v135, v80
	v_mov_b32_e32 v136, v80
	v_mov_b32_e32 v137, v80
	v_mov_b32_e32 v138, v80
	v_mov_b32_e32 v139, v80
	v_mov_b32_e32 v140, v80
	v_mov_b32_e32 v141, v80
	v_mov_b32_e32 v142, v80
	v_mov_b32_e32 v143, v80
